# GEMM units start from a peeled first K-iteration with C=0 MFMAs (accumulator zeroing moves removed) + canonicalizing v_max removed in epilogues; on top of MFMA-head trim + barrier XGEN-first
# speedup vs baseline: 1.0058x; 1.0058x over previous
; #define PG8_STAGE(bufoff, gbase, voff) do { _Pragma("unroll") for (int _i = 0; _i < 2; ++_i) \
;         __builtin_amdgcn_global_load_lds((const unsigned*)((const char*)(gbase) + (voff)[_i]), (LAS unsigned*)(lds + (bufoff) + ldsw + _i * 8192), 16, 0, 0); } while (0)
; #define PG8_LDA(dst, b, h) do { _Pragma("unroll") for (int m = 0; m < 4; ++m) _Pragma("unroll") for (int k = 0; k < 2; ++k) dst[m][k] = *(const LAS bf16x8*)(lds + PG8_SA(b, h) + aoff + m * 2048 + k * 1024); } while (0)
; #define PG8_WAIT_V(n) asm volatile("s_waitcnt vmcnt(" #n ")" ::: "memory")
; #define PG8_WAIT_L(n) asm volatile("s_waitcnt lgkmcnt(" #n ")" ::: "memory")
; #define PG8_BAR __builtin_amdgcn_s_barrier()
; template <class Epi, class Sched, bool ABLK = false, bool ALIGN_EPI = true, bool SP2 = true, bool BBLK = true>
; __device__ __forceinline__ void gemm_phase(LAS unsigned char* lds, const Gemm g, const Sched& S, const Epi& E) {
;     ...
;     f32x4 acc[2][2][4][2];
; #pragma unroll
;     for (int a = 0; a < 2; ++a)
; #pragma unroll
;         for (int b = 0; b < 2; ++b)
; #pragma unroll
;             for (int m = 0; m < 4; ++m)
; #pragma unroll
;                 for (int n = 0; n < 2; ++n) acc[a][b][m][n] = (f32x4){0.f, 0.f, 0.f, 0.f};
;     ...
;         const bool has_next = S.next(ui + 1, nxt);
;         const int nt = cur.nt;
;         const char* nuA = has_next ? a_unit(nxt) : uA; const int ntbA = has_next ? nxt.k0 / BK : tbA; const char* nB = has_next ? (const char*)g.Bt + (size_t)nxt.pn * tstepB + b_k0(nxt.k0) : cB;
;         for (int t = 0; t < nt; t += 2) {
;             const bool last = (t == nt - 2);
;             const char* a1 = a_tile(uA, tbA + t + 1);
;             const char* a2 = last ? a_tile(nuA, ntbA) : a_tile(uA, tbA + t + 2); const char* b2 = last ? nB : cB + (size_t)(t + 2) * kstepB;
;             const char* a3 = last ? a_tile(nuA, ntbA + 1) : a_tile(uA, tbA + t + 3); const char* b3 = b2 + kstepB;
;             if (last && has_next) S.a_ready(nxt);
;             if constexpr (SP2) {
;             PG8_LDB(B0, 0, 0); PG8_LDB(B1, 0, 1); PG8_SCHED; PG8_LDA(At, 0, 0); PG8_STAGE(PG8_SA(1, 1), a1 + hstepA, voffA);
;             PG8_WAIT_V(8); PG8_WAIT_L(0); PG8_BAR; PG8_MMA(0, 0, At, B0); PG8_MMA(0, 1, At, B1); PG8_BAR; PG8_SCHED;
;             PG8_LDA(At, 0, 1); PG8_STAGE(PG8_SB(0, 0), b2, voffB); PG8_STAGE(PG8_SB(0, 1), b2 + hstepB, voffB); PG8_STAGE(PG8_SA(0, 0), a2, voffA);
.LBB0_349:
	s_ashr_i32 s9, s8, 31
	s_lshl_b64 s[4:5], s[8:9], 20
	s_add_u32 s12, s36, s4
	s_addc_u32 s13, s37, s5
	s_and_b64 s[4:5], s[14:15], exec
	s_cselect_b32 s4, s13, s25
	s_cselect_b32 s5, s12, s24
	s_ashr_i32 s11, s10, 31
	s_lshl_b64 s[18:19], s[10:11], 20
	s_add_u32 s18, s0, s18
	s_addc_u32 s19, s1, s19
	s_and_b64 s[28:29], s[14:15], exec
	s_cselect_b32 s9, s19, s27
	s_cselect_b32 s11, s18, s26
	s_add_u32 s50, s5, 0x80
	s_addc_u32 s51, s4, 0
	s_add_u32 s52, s26, 0x10000
	v_mov_b32_e32 v2, 0
	s_addc_u32 s53, s27, 0
	v_lshl_add_u64 v[142:143], s[24:25], 0, v[138:139]
	v_lshl_add_u64 v[144:145], s[24:25], 0, v[140:141]
	s_mov_b32 s54, -2
	s_mov_b64 s[26:27], 0
	ds_read_b128 v[152:155], v148
	ds_read_b128 v[156:159], v148 offset:1024
	ds_read_b128 v[160:163], v148 offset:2048
	ds_read_b128 v[164:167], v148 offset:3072
	ds_read_b128 v[168:171], v149
	ds_read_b128 v[172:175], v149 offset:1024
	ds_read_b128 v[176:179], v149 offset:2048
	ds_read_b128 v[180:183], v149 offset:3072
	s_add_u32 s28, s24, s26
	s_addc_u32 s29, s25, s27
	s_add_u32 s34, s28, 0x100
	s_addc_u32 s35, s29, 0
	s_add_u32 s28, s28, 0x180
	s_addc_u32 s29, s29, 0
	s_cmpk_eq_i32 s26, 0xf00
	s_cselect_b32 s29, s51, s29
	s_cselect_b32 s28, s50, s28
	s_cselect_b32 s31, s9, s53
	s_cselect_b32 s30, s11, s52
	s_cselect_b32 s35, s4, s35
	s_cselect_b32 s34, s5, s34
	s_mov_b32 m0, s49
	v_lshl_add_u64 v[216:217], v[142:143], 0, s[26:27]
	ds_read_b128 v[184:187], v150
	ds_read_b128 v[188:191], v150 offset:1024
	ds_read_b128 v[192:195], v150 offset:2048
	ds_read_b128 v[196:199], v150 offset:3072
	ds_read_b128 v[200:203], v150 offset:4096
	ds_read_b128 v[204:207], v150 offset:5120
	ds_read_b128 v[208:211], v150 offset:6144
	ds_read_b128 v[212:215], v150 offset:7168
	global_load_lds_dwordx4 v[216:217], off
	v_lshl_add_u64 v[216:217], v[144:145], 0, s[26:27]
	s_add_i32 m0, s21, 0xe000
	s_nop 0
	global_load_lds_dwordx4 v[216:217], off
	s_waitcnt vmcnt(8)
	s_waitcnt lgkmcnt(0)
	s_barrier
	v_mfma_f32_16x16x32_bf16 v[122:125], v[152:155], v[184:187], 0
	v_mfma_f32_16x16x32_bf16 v[118:121], v[160:163], v[184:187], 0
	v_mfma_f32_16x16x32_bf16 v[106:109], v[152:155], v[192:195], 0
	v_mfma_f32_16x16x32_bf16 v[102:105], v[160:163], v[192:195], 0
	v_mfma_f32_16x16x32_bf16 v[90:93], v[152:155], v[200:203], 0
	v_mfma_f32_16x16x32_bf16 v[86:89], v[160:163], v[200:203], 0
	v_mfma_f32_16x16x32_bf16 v[74:77], v[152:155], v[208:211], 0
	v_mfma_f32_16x16x32_bf16 v[70:73], v[160:163], v[208:211], 0
	v_mfma_f32_16x16x32_bf16 v[122:125], v[156:159], v[188:191], v[122:125]
	v_mfma_f32_16x16x32_bf16 v[118:121], v[164:167], v[188:191], v[118:121]
	v_mfma_f32_16x16x32_bf16 v[106:109], v[156:159], v[196:199], v[106:109]
	v_mfma_f32_16x16x32_bf16 v[102:105], v[164:167], v[196:199], v[102:105]
	v_mfma_f32_16x16x32_bf16 v[90:93], v[156:159], v[204:207], v[90:93]
	v_mfma_f32_16x16x32_bf16 v[86:89], v[164:167], v[204:207], v[86:89]
	v_mfma_f32_16x16x32_bf16 v[74:77], v[156:159], v[212:215], v[74:77]
	v_mfma_f32_16x16x32_bf16 v[70:73], v[164:167], v[212:215], v[70:73]
	v_mfma_f32_16x16x32_bf16 v[126:129], v[168:171], v[184:187], 0
	v_mfma_f32_16x16x32_bf16 v[114:117], v[176:179], v[184:187], 0
	v_mfma_f32_16x16x32_bf16 v[110:113], v[168:171], v[192:195], 0
	v_mfma_f32_16x16x32_bf16 v[98:101], v[176:179], v[192:195], 0
	v_mfma_f32_16x16x32_bf16 v[94:97], v[168:171], v[200:203], 0
	v_mfma_f32_16x16x32_bf16 v[82:85], v[176:179], v[200:203], 0
	v_mfma_f32_16x16x32_bf16 v[78:81], v[168:171], v[208:211], 0
	v_mfma_f32_16x16x32_bf16 v[66:69], v[176:179], v[208:211], 0
	v_mfma_f32_16x16x32_bf16 v[126:129], v[172:175], v[188:191], v[126:129]
	v_mfma_f32_16x16x32_bf16 v[114:117], v[180:183], v[188:191], v[114:117]
	v_mfma_f32_16x16x32_bf16 v[110:113], v[172:175], v[196:199], v[110:113]
	v_mfma_f32_16x16x32_bf16 v[98:101], v[180:183], v[196:199], v[98:101]
	v_mfma_f32_16x16x32_bf16 v[94:97], v[172:175], v[204:207], v[94:97]
	v_mfma_f32_16x16x32_bf16 v[82:85], v[180:183], v[204:207], v[82:85]
	v_mfma_f32_16x16x32_bf16 v[78:81], v[172:175], v[212:215], v[78:81]
	v_mfma_f32_16x16x32_bf16 v[66:69], v[180:183], v[212:215], v[66:69]
	s_barrier
	s_add_i32 s55, s44, s33
	v_lshl_add_u64 v[216:217], s[30:31], 0, v[134:135]
	s_mov_b32 m0, s55
	ds_read_b128 v[184:187], v150 offset:16384
	ds_read_b128 v[188:191], v150 offset:17408
	ds_read_b128 v[192:195], v150 offset:18432
	ds_read_b128 v[196:199], v150 offset:19456
	ds_read_b128 v[200:203], v150 offset:20480
	ds_read_b128 v[204:207], v150 offset:21504
	ds_read_b128 v[208:211], v150 offset:22528
	ds_read_b128 v[212:215], v150 offset:23552
	global_load_lds_dwordx4 v[216:217], off
	s_add_i32 m0, s55, 0x2000
	s_add_u32 s56, s30, 0x4000
	v_lshl_add_u64 v[216:217], s[30:31], 0, v[130:131]
	s_addc_u32 s57, s31, 0
	s_add_i32 s55, s45, s33
	global_load_lds_dwordx4 v[216:217], off
	v_lshl_add_u64 v[216:217], s[56:57], 0, v[134:135]
	s_mov_b32 m0, s55
	s_nop 0
	global_load_lds_dwordx4 v[216:217], off
	v_lshl_add_u64 v[216:217], s[56:57], 0, v[130:131]
	s_add_i32 m0, s55, 0x2000
	s_nop 0
	global_load_lds_dwordx4 v[216:217], off
	v_lshl_add_u64 v[216:217], s[34:35], 0, v[136:137]
	s_mov_b32 m0, s21
	s_nop 0
	global_load_lds_dwordx4 v[216:217], off
	v_lshl_add_u64 v[216:217], s[34:35], 0, v[132:133]
	s_mov_b32 m0, s23
	s_nop 0
	global_load_lds_dwordx4 v[216:217], off
	s_waitcnt vmcnt(8)
	s_waitcnt lgkmcnt(0)
	s_barrier
; #define PG8_STAGE(bufoff, gbase, voff) do { _Pragma("unroll") for (int _i = 0; _i < 2; ++_i) \
;         __builtin_amdgcn_global_load_lds((const unsigned*)((const char*)(gbase) + (voff)[_i]), (LAS unsigned*)(lds + (bufoff) + ldsw + _i * 8192), 16, 0, 0); } while (0)
; #define PG8_LDA(dst, b, h) do { _Pragma("unroll") for (int m = 0; m < 4; ++m) _Pragma("unroll") for (int k = 0; k < 2; ++k) dst[m][k] = *(const LAS bf16x8*)(lds + PG8_SA(b, h) + aoff + m * 2048 + k * 1024); } while (0)
; #define PG8_LDB(dst, b, h) do { _Pragma("unroll") for (int n = 0; n < 2; ++n) _Pragma("unroll") for (int k = 0; k < 2; ++k) dst[n][k] = *(const LAS bf16x8*)(lds + PG8_SB(b, h) + boff + n * 2048 + k * 1024); } while (0)
; #define PG8_MMA(ai, bj, At, Bt) do { __builtin_amdgcn_s_setprio(1); _Pragma("unroll") for (int m = 0; m < 4; ++m) _Pragma("unroll") for (int n = 0; n < 2; ++n) _Pragma("unroll") for (int k = 0; k < 2; ++k) \
;         acc[ai][bj][m][n] = __builtin_amdgcn_mfma_f32_16x16x32_bf16(Bt[n][k], At[m][k], acc[ai][bj][m][n], 0, 0, 0); __builtin_amdgcn_s_setprio(0); } while (0)
; #define PG8_WAIT_V(n) asm volatile("s_waitcnt vmcnt(" #n ")" ::: "memory")
; #define PG8_WAIT_L(n) asm volatile("s_waitcnt lgkmcnt(" #n ")" ::: "memory")
; #define PG8_BAR __builtin_amdgcn_s_barrier()
; #define PG8_SCHED __builtin_amdgcn_sched_barrier(0)
; template <class Epi, class Sched, bool ABLK = false, bool ALIGN_EPI = true, bool SP2 = true, bool BBLK = true>
; __device__ __forceinline__ void gemm_phase(LAS unsigned char* lds, const Gemm g, const Sched& S, const Epi& E) {
;     ...
;             PG8_WAIT_V(8); PG8_WAIT_L(0); PG8_BAR; PG8_MMA(1, 0, At, B0); PG8_MMA(1, 1, At, B1); PG8_BAR; PG8_SCHED;
;             PG8_LDB(B0, 1, 0); PG8_LDB(B1, 1, 1); PG8_SCHED; PG8_LDA(At, 1, 0); PG8_STAGE(PG8_SA(0, 1), a2 + hstepA, voffA);
;             PG8_WAIT_V(8); PG8_WAIT_L(0); PG8_BAR; PG8_MMA(0, 0, At, B0); PG8_MMA(0, 1, At, B1); PG8_BAR; PG8_SCHED;
	v_mfma_f32_16x16x32_bf16 v[58:61], v[152:155], v[184:187], 0
	v_mfma_f32_16x16x32_bf16 v[54:57], v[160:163], v[184:187], 0
	v_mfma_f32_16x16x32_bf16 v[42:45], v[152:155], v[192:195], 0
	v_mfma_f32_16x16x32_bf16 v[38:41], v[160:163], v[192:195], 0
	v_mfma_f32_16x16x32_bf16 v[26:29], v[152:155], v[200:203], 0
	v_mfma_f32_16x16x32_bf16 v[22:25], v[160:163], v[200:203], 0
	v_mfma_f32_16x16x32_bf16 v[10:13], v[152:155], v[208:211], 0
	v_mfma_f32_16x16x32_bf16 v[6:9], v[160:163], v[208:211], 0
	v_mfma_f32_16x16x32_bf16 v[58:61], v[156:159], v[188:191], v[58:61]
	v_mfma_f32_16x16x32_bf16 v[54:57], v[164:167], v[188:191], v[54:57]
	v_mfma_f32_16x16x32_bf16 v[42:45], v[156:159], v[196:199], v[42:45]
	v_mfma_f32_16x16x32_bf16 v[38:41], v[164:167], v[196:199], v[38:41]
	v_mfma_f32_16x16x32_bf16 v[26:29], v[156:159], v[204:207], v[26:29]
	v_mfma_f32_16x16x32_bf16 v[22:25], v[164:167], v[204:207], v[22:25]
	v_mfma_f32_16x16x32_bf16 v[10:13], v[156:159], v[212:215], v[10:13]
	v_mfma_f32_16x16x32_bf16 v[6:9], v[164:167], v[212:215], v[6:9]
	v_mfma_f32_16x16x32_bf16 v[62:65], v[168:171], v[184:187], 0
	v_mfma_f32_16x16x32_bf16 v[50:53], v[176:179], v[184:187], 0
	v_mfma_f32_16x16x32_bf16 v[46:49], v[168:171], v[192:195], 0
	v_mfma_f32_16x16x32_bf16 v[34:37], v[176:179], v[192:195], 0
	v_mfma_f32_16x16x32_bf16 v[30:33], v[168:171], v[200:203], 0
	v_mfma_f32_16x16x32_bf16 v[18:21], v[176:179], v[200:203], 0
	v_mfma_f32_16x16x32_bf16 v[14:17], v[168:171], v[208:211], 0
	v_mfma_f32_16x16x32_bf16 v[2:5], v[176:179], v[208:211], 0
	v_mfma_f32_16x16x32_bf16 v[62:65], v[172:175], v[188:191], v[62:65]
	v_mfma_f32_16x16x32_bf16 v[50:53], v[180:183], v[188:191], v[50:53]
	v_mfma_f32_16x16x32_bf16 v[46:49], v[172:175], v[196:199], v[46:49]
	v_mfma_f32_16x16x32_bf16 v[34:37], v[180:183], v[196:199], v[34:37]
	v_mfma_f32_16x16x32_bf16 v[30:33], v[172:175], v[204:207], v[30:33]
	v_mfma_f32_16x16x32_bf16 v[18:21], v[180:183], v[204:207], v[18:21]
	v_mfma_f32_16x16x32_bf16 v[14:17], v[172:175], v[212:215], v[14:17]
	v_mfma_f32_16x16x32_bf16 v[2:5], v[180:183], v[212:215], v[2:5]
	s_barrier
	s_add_i32 s55, 0, 0x18000
	v_add_u32_e32 v151, s55, v146
	s_add_i32 s56, 0, 0x1c000
	ds_read_b128 v[152:155], v151
	ds_read_b128 v[156:159], v151 offset:1024
	ds_read_b128 v[160:163], v151 offset:2048
	ds_read_b128 v[164:167], v151 offset:3072
	v_add_u32_e32 v151, s56, v146
	ds_read_b128 v[168:171], v151
	ds_read_b128 v[172:175], v151 offset:1024
	ds_read_b128 v[176:179], v151 offset:2048
	ds_read_b128 v[180:183], v151 offset:3072
	s_add_u32 s34, s34, 0x80000
	s_addc_u32 s35, s35, 0
	s_mov_b32 m0, s39
	v_lshl_add_u64 v[216:217], s[34:35], 0, v[136:137]
	ds_read_b128 v[184:187], v150 offset:32768
	ds_read_b128 v[188:191], v150 offset:33792
	ds_read_b128 v[192:195], v150 offset:34816
	ds_read_b128 v[196:199], v150 offset:35840
	ds_read_b128 v[200:203], v150 offset:36864
	ds_read_b128 v[204:207], v150 offset:37888
	ds_read_b128 v[208:211], v150 offset:38912
	ds_read_b128 v[212:215], v150 offset:39936
	global_load_lds_dwordx4 v[216:217], off
	v_lshl_add_u64 v[216:217], s[34:35], 0, v[132:133]
	s_mov_b32 m0, s40
	s_nop 0
	global_load_lds_dwordx4 v[216:217], off
	s_waitcnt vmcnt(8)
	s_waitcnt lgkmcnt(0)
	s_barrier
	v_mfma_f32_16x16x32_bf16 v[122:125], v[152:155], v[184:187], v[122:125]
	v_mfma_f32_16x16x32_bf16 v[118:121], v[160:163], v[184:187], v[118:121]
	v_mfma_f32_16x16x32_bf16 v[106:109], v[152:155], v[192:195], v[106:109]
	v_mfma_f32_16x16x32_bf16 v[102:105], v[160:163], v[192:195], v[102:105]
	v_mfma_f32_16x16x32_bf16 v[90:93], v[152:155], v[200:203], v[90:93]
	v_mfma_f32_16x16x32_bf16 v[86:89], v[160:163], v[200:203], v[86:89]
	v_mfma_f32_16x16x32_bf16 v[74:77], v[152:155], v[208:211], v[74:77]
	v_mfma_f32_16x16x32_bf16 v[70:73], v[160:163], v[208:211], v[70:73]
	v_mfma_f32_16x16x32_bf16 v[122:125], v[156:159], v[188:191], v[122:125]
	v_mfma_f32_16x16x32_bf16 v[118:121], v[164:167], v[188:191], v[118:121]
	v_mfma_f32_16x16x32_bf16 v[106:109], v[156:159], v[196:199], v[106:109]
	v_mfma_f32_16x16x32_bf16 v[102:105], v[164:167], v[196:199], v[102:105]
	v_mfma_f32_16x16x32_bf16 v[90:93], v[156:159], v[204:207], v[90:93]
	v_mfma_f32_16x16x32_bf16 v[86:89], v[164:167], v[204:207], v[86:89]
	v_mfma_f32_16x16x32_bf16 v[74:77], v[156:159], v[212:215], v[74:77]
	v_mfma_f32_16x16x32_bf16 v[70:73], v[164:167], v[212:215], v[70:73]
	v_mfma_f32_16x16x32_bf16 v[126:129], v[168:171], v[184:187], v[126:129]
	v_mfma_f32_16x16x32_bf16 v[114:117], v[176:179], v[184:187], v[114:117]
	v_mfma_f32_16x16x32_bf16 v[110:113], v[168:171], v[192:195], v[110:113]
	v_mfma_f32_16x16x32_bf16 v[98:101], v[176:179], v[192:195], v[98:101]
	v_mfma_f32_16x16x32_bf16 v[94:97], v[168:171], v[200:203], v[94:97]
	v_mfma_f32_16x16x32_bf16 v[82:85], v[176:179], v[200:203], v[82:85]
	v_mfma_f32_16x16x32_bf16 v[78:81], v[168:171], v[208:211], v[78:81]
	v_mfma_f32_16x16x32_bf16 v[66:69], v[176:179], v[208:211], v[66:69]
	v_mfma_f32_16x16x32_bf16 v[126:129], v[172:175], v[188:191], v[126:129]
	v_mfma_f32_16x16x32_bf16 v[114:117], v[180:183], v[188:191], v[114:117]
	v_mfma_f32_16x16x32_bf16 v[110:113], v[172:175], v[196:199], v[110:113]
	v_mfma_f32_16x16x32_bf16 v[98:101], v[180:183], v[196:199], v[98:101]
	v_mfma_f32_16x16x32_bf16 v[94:97], v[172:175], v[204:207], v[94:97]
	v_mfma_f32_16x16x32_bf16 v[82:85], v[180:183], v[204:207], v[82:85]
	v_mfma_f32_16x16x32_bf16 v[78:81], v[172:175], v[212:215], v[78:81]
	v_mfma_f32_16x16x32_bf16 v[66:69], v[180:183], v[212:215], v[66:69]
	s_barrier
; #define PG8_STAGE(bufoff, gbase, voff) do { _Pragma("unroll") for (int _i = 0; _i < 2; ++_i) \
;         __builtin_amdgcn_global_load_lds((const unsigned*)((const char*)(gbase) + (voff)[_i]), (LAS unsigned*)(lds + (bufoff) + ldsw + _i * 8192), 16, 0, 0); } while (0)
; #define PG8_LDA(dst, b, h) do { _Pragma("unroll") for (int m = 0; m < 4; ++m) _Pragma("unroll") for (int k = 0; k < 2; ++k) dst[m][k] = *(const LAS bf16x8*)(lds + PG8_SA(b, h) + aoff + m * 2048 + k * 1024); } while (0)
; #define PG8_WAIT_V(n) asm volatile("s_waitcnt vmcnt(" #n ")" ::: "memory")
; #define PG8_WAIT_L(n) asm volatile("s_waitcnt lgkmcnt(" #n ")" ::: "memory")
; template <class Epi, class Sched, bool ABLK = false, bool ALIGN_EPI = true, bool SP2 = true, bool BBLK = true>
; __device__ __forceinline__ void gemm_phase(LAS unsigned char* lds, const Gemm g, const Sched& S, const Epi& E) {
;     ...
;         for (int t = 0; t < nt; t += 2) {
;             const bool last = (t == nt - 2);
;             const char* a1 = a_tile(uA, tbA + t + 1);
;             const char* a2 = last ? a_tile(nuA, ntbA) : a_tile(uA, tbA + t + 2); const char* b2 = last ? nB : cB + (size_t)(t + 2) * kstepB;
;             const char* a3 = last ? a_tile(nuA, ntbA + 1) : a_tile(uA, tbA + t + 3); const char* b3 = b2 + kstepB;
;             if (last && has_next) S.a_ready(nxt);
;             if constexpr (SP2) {
;             PG8_LDB(B0, 0, 0); PG8_LDB(B1, 0, 1); PG8_SCHED; PG8_LDA(At, 0, 0); PG8_STAGE(PG8_SA(1, 1), a1 + hstepA, voffA);
;             PG8_WAIT_V(8); PG8_WAIT_L(0); PG8_BAR; PG8_MMA(0, 0, At, B0); PG8_MMA(0, 1, At, B1); PG8_BAR; PG8_SCHED;
;             PG8_LDA(At, 0, 1); PG8_STAGE(PG8_SB(0, 0), b2, voffB); PG8_STAGE(PG8_SB(0, 1), b2 + hstepB, voffB); PG8_STAGE(PG8_SA(0, 0), a2, voffA);
;             PG8_WAIT_V(8); PG8_WAIT_L(0); PG8_BAR; PG8_MMA(1, 0, At, B0); PG8_MMA(1, 1, At, B1); PG8_BAR; PG8_SCHED;
;             PG8_LDB(B0, 1, 0); PG8_LDB(B1, 1, 1); PG8_SCHED; PG8_LDA(At, 1, 0); PG8_STAGE(PG8_SA(0, 1), a2 + hstepA, voffA);
;             PG8_WAIT_V(8); PG8_WAIT_L(0); PG8_BAR; PG8_MMA(0, 0, At, B0); PG8_MMA(0, 1, At, B1); PG8_BAR; PG8_SCHED;
;             PG8_LDA(At, 1, 1); PG8_STAGE(PG8_SB(1, 0), b3, voffB); PG8_STAGE(PG8_SB(1, 1), b3 + hstepB, voffB); PG8_STAGE(PG8_SA(1, 0), a3, voffA);
;             PG8_WAIT_V(8); PG8_WAIT_L(0); PG8_BAR; PG8_MMA(1, 0, At, B0); PG8_MMA(1, 1, At, B1); PG8_BAR; PG8_SCHED;
	s_add_u32 s34, s30, 0x8000
	s_addc_u32 s35, s31, 0
	s_add_i32 s55, s55, s33
	v_lshl_add_u64 v[216:217], s[34:35], 0, v[134:135]
	s_mov_b32 m0, s55
	ds_read_b128 v[184:187], v150 offset:49152
	ds_read_b128 v[188:191], v150 offset:50176
	ds_read_b128 v[192:195], v150 offset:51200
	ds_read_b128 v[196:199], v150 offset:52224
	ds_read_b128 v[200:203], v150 offset:53248
	ds_read_b128 v[204:207], v150 offset:54272
	ds_read_b128 v[208:211], v150 offset:55296
	ds_read_b128 v[212:215], v150 offset:56320
	global_load_lds_dwordx4 v[216:217], off
	s_add_i32 m0, s55, 0x2000
	s_add_u32 s30, s30, 0xc000
	v_lshl_add_u64 v[216:217], s[34:35], 0, v[130:131]
	s_addc_u32 s31, s31, 0
	s_add_i32 s34, s56, s33
	global_load_lds_dwordx4 v[216:217], off
	v_lshl_add_u64 v[216:217], s[30:31], 0, v[134:135]
	s_mov_b32 m0, s34
	s_nop 0
	global_load_lds_dwordx4 v[216:217], off
	v_lshl_add_u64 v[216:217], s[30:31], 0, v[130:131]
	s_add_i32 m0, s34, 0x2000
	s_nop 0
	global_load_lds_dwordx4 v[216:217], off
	v_lshl_add_u64 v[216:217], s[28:29], 0, v[136:137]
	s_mov_b32 m0, s42
	s_nop 0
	global_load_lds_dwordx4 v[216:217], off
	v_lshl_add_u64 v[216:217], s[28:29], 0, v[132:133]
	s_mov_b32 m0, s43
	s_nop 0
	global_load_lds_dwordx4 v[216:217], off
	s_waitcnt vmcnt(8)
	s_waitcnt lgkmcnt(0)
	s_barrier
	v_mfma_f32_16x16x32_bf16 v[58:61], v[152:155], v[184:187], v[58:61]
	v_mfma_f32_16x16x32_bf16 v[54:57], v[160:163], v[184:187], v[54:57]
	v_mfma_f32_16x16x32_bf16 v[42:45], v[152:155], v[192:195], v[42:45]
	v_mfma_f32_16x16x32_bf16 v[38:41], v[160:163], v[192:195], v[38:41]
	v_mfma_f32_16x16x32_bf16 v[26:29], v[152:155], v[200:203], v[26:29]
	v_mfma_f32_16x16x32_bf16 v[22:25], v[160:163], v[200:203], v[22:25]
	v_mfma_f32_16x16x32_bf16 v[10:13], v[152:155], v[208:211], v[10:13]
	v_mfma_f32_16x16x32_bf16 v[6:9], v[160:163], v[208:211], v[6:9]
	v_mfma_f32_16x16x32_bf16 v[58:61], v[156:159], v[188:191], v[58:61]
	v_mfma_f32_16x16x32_bf16 v[54:57], v[164:167], v[188:191], v[54:57]
	v_mfma_f32_16x16x32_bf16 v[42:45], v[156:159], v[196:199], v[42:45]
	v_mfma_f32_16x16x32_bf16 v[38:41], v[164:167], v[196:199], v[38:41]
	v_mfma_f32_16x16x32_bf16 v[26:29], v[156:159], v[204:207], v[26:29]
	v_mfma_f32_16x16x32_bf16 v[22:25], v[164:167], v[204:207], v[22:25]
	v_mfma_f32_16x16x32_bf16 v[10:13], v[156:159], v[212:215], v[10:13]
	v_mfma_f32_16x16x32_bf16 v[6:9], v[164:167], v[212:215], v[6:9]
	v_mfma_f32_16x16x32_bf16 v[62:65], v[168:171], v[184:187], v[62:65]
	v_mfma_f32_16x16x32_bf16 v[50:53], v[176:179], v[184:187], v[50:53]
	v_mfma_f32_16x16x32_bf16 v[46:49], v[168:171], v[192:195], v[46:49]
	v_mfma_f32_16x16x32_bf16 v[34:37], v[176:179], v[192:195], v[34:37]
	v_mfma_f32_16x16x32_bf16 v[30:33], v[168:171], v[200:203], v[30:33]
	v_mfma_f32_16x16x32_bf16 v[18:21], v[176:179], v[200:203], v[18:21]
	v_mfma_f32_16x16x32_bf16 v[14:17], v[168:171], v[208:211], v[14:17]
	v_mfma_f32_16x16x32_bf16 v[2:5], v[176:179], v[208:211], v[2:5]
	v_mfma_f32_16x16x32_bf16 v[62:65], v[172:175], v[188:191], v[62:65]
	v_mfma_f32_16x16x32_bf16 v[50:53], v[180:183], v[188:191], v[50:53]
	v_mfma_f32_16x16x32_bf16 v[46:49], v[172:175], v[196:199], v[46:49]
	v_mfma_f32_16x16x32_bf16 v[34:37], v[180:183], v[196:199], v[34:37]
	v_mfma_f32_16x16x32_bf16 v[30:33], v[172:175], v[204:207], v[30:33]
	v_mfma_f32_16x16x32_bf16 v[18:21], v[180:183], v[204:207], v[18:21]
	v_mfma_f32_16x16x32_bf16 v[14:17], v[172:175], v[212:215], v[14:17]
	v_mfma_f32_16x16x32_bf16 v[2:5], v[180:183], v[212:215], v[2:5]
	s_barrier
	s_add_i32 s54, s54, 2
	s_add_u32 s26, s26, 0x100
	s_addc_u32 s27, s27, 0
	s_add_u32 s52, s52, 0x10000
	s_addc_u32 s53, s53, 0
	s_cmp_gt_u32 s54, 29

; #define PG8_STAGE(bufoff, gbase, voff) do { _Pragma("unroll") for (int _i = 0; _i < 2; ++_i) \
;         __builtin_amdgcn_global_load_lds((const unsigned*)((const char*)(gbase) + (voff)[_i]), (LAS unsigned*)(lds + (bufoff) + ldsw + _i * 8192), 16, 0, 0); } while (0)
; #define PG8_LDA(dst, b, h) do { _Pragma("unroll") for (int m = 0; m < 4; ++m) _Pragma("unroll") for (int k = 0; k < 2; ++k) dst[m][k] = *(const LAS bf16x8*)(lds + PG8_SA(b, h) + aoff + m * 2048 + k * 1024); } while (0)
; #define PG8_WAIT_V(n) asm volatile("s_waitcnt vmcnt(" #n ")" ::: "memory")
; #define PG8_WAIT_L(n) asm volatile("s_waitcnt lgkmcnt(" #n ")" ::: "memory")
; #define PG8_BAR __builtin_amdgcn_s_barrier()
; template <class Epi, class Sched, bool ABLK = false, bool ALIGN_EPI = true, bool SP2 = true, bool BBLK = true>
; __device__ __forceinline__ void gemm_phase(LAS unsigned char* lds, const Gemm g, const Sched& S, const Epi& E) {
;     ...
;     f32x4 acc[2][2][4][2];
; #pragma unroll
;     for (int a = 0; a < 2; ++a)
; #pragma unroll
;         for (int b = 0; b < 2; ++b)
; #pragma unroll
;             for (int m = 0; m < 4; ++m)
; #pragma unroll
;                 for (int n = 0; n < 2; ++n) acc[a][b][m][n] = (f32x4){0.f, 0.f, 0.f, 0.f};
;     ...
;         const bool has_next = S.next(ui + 1, nxt);
;         const int nt = cur.nt;
;         const char* nuA = has_next ? a_unit(nxt) : uA; const int ntbA = has_next ? nxt.k0 / BK : tbA; const char* nB = has_next ? (const char*)g.Bt + (size_t)nxt.pn * tstepB + b_k0(nxt.k0) : cB;
;         for (int t = 0; t < nt; t += 2) {
;             const bool last = (t == nt - 2);
;             const char* a1 = a_tile(uA, tbA + t + 1);
;             const char* a2 = last ? a_tile(nuA, ntbA) : a_tile(uA, tbA + t + 2); const char* b2 = last ? nB : cB + (size_t)(t + 2) * kstepB;
;             const char* a3 = last ? a_tile(nuA, ntbA + 1) : a_tile(uA, tbA + t + 3); const char* b3 = b2 + kstepB;
;             if (last && has_next) S.a_ready(nxt);
;             if constexpr (SP2) {
;             PG8_LDB(B0, 0, 0); PG8_LDB(B1, 0, 1); PG8_SCHED; PG8_LDA(At, 0, 0); PG8_STAGE(PG8_SA(1, 1), a1 + hstepA, voffA);
;             PG8_WAIT_V(8); PG8_WAIT_L(0); PG8_BAR; PG8_MMA(0, 0, At, B0); PG8_MMA(0, 1, At, B1); PG8_BAR; PG8_SCHED;
;             PG8_LDA(At, 0, 1); PG8_STAGE(PG8_SB(0, 0), b2, voffB); PG8_STAGE(PG8_SB(0, 1), b2 + hstepB, voffB); PG8_STAGE(PG8_SA(0, 0), a2, voffA);
.LBB0_474:
	s_ashr_i32 s11, s10, 31
	s_lshl_b64 s[4:5], s[10:11], 20
	s_add_u32 s14, s41, s4
	s_addc_u32 s15, s42, s5
	s_and_b64 s[4:5], s[18:19], exec
	s_cselect_b32 s4, s15, s27
	s_cselect_b32 s5, s14, s26
	s_ashr_i32 s13, s12, 31
	s_lshl_b64 s[20:21], s[12:13], 20
	s_add_u32 s20, s0, s20
	s_addc_u32 s21, s39, s21
	s_and_b64 s[30:31], s[18:19], exec
	s_cselect_b32 s11, s21, s29
	s_cselect_b32 s13, s20, s28
	s_add_u32 s23, s5, 0x80
	s_addc_u32 s57, s4, 0
	s_add_u32 s58, s28, 0x10000
	v_mov_b32_e32 v2, 0
	s_addc_u32 s59, s29, 0
	v_lshl_add_u64 v[164:165], s[26:27], 0, v[160:161]
	v_lshl_add_u64 v[166:167], s[26:27], 0, v[162:163]
	s_mov_b32 s60, -2
	s_mov_b64 s[28:29], 0
	ds_read_b128 v[172:175], v168
	ds_read_b128 v[176:179], v168 offset:1024
	ds_read_b128 v[180:183], v168 offset:2048
	ds_read_b128 v[184:187], v168 offset:3072
	ds_read_b128 v[188:191], v169
	ds_read_b128 v[192:195], v169 offset:1024
	ds_read_b128 v[196:199], v169 offset:2048
	ds_read_b128 v[200:203], v169 offset:3072
	s_add_u32 s30, s26, s28
	s_addc_u32 s31, s27, s29
	s_add_u32 s36, s30, 0x100
	s_addc_u32 s37, s31, 0
	s_add_u32 s30, s30, 0x180
	s_addc_u32 s31, s31, 0
	s_cmpk_eq_i32 s28, 0xf00
	s_cselect_b32 s31, s57, s31
	s_cselect_b32 s30, s23, s30
	s_cselect_b32 s35, s11, s59
	s_cselect_b32 s34, s13, s58
	s_cselect_b32 s37, s4, s37
	s_cselect_b32 s36, s5, s36
	s_mov_b32 m0, s53
	v_lshl_add_u64 v[236:237], v[164:165], 0, s[28:29]
	ds_read_b128 v[204:207], v170
	ds_read_b128 v[208:211], v170 offset:1024
	ds_read_b128 v[212:215], v170 offset:2048
	ds_read_b128 v[216:219], v170 offset:3072
	ds_read_b128 v[220:223], v170 offset:4096
	ds_read_b128 v[224:227], v170 offset:5120
	ds_read_b128 v[228:231], v170 offset:6144
	ds_read_b128 v[232:235], v170 offset:7168
	global_load_lds_dwordx4 v[236:237], off
	v_lshl_add_u64 v[236:237], v[166:167], 0, s[28:29]
	s_mov_b32 m0, s54
	s_nop 0
	global_load_lds_dwordx4 v[236:237], off
	s_waitcnt vmcnt(8)
	s_waitcnt lgkmcnt(0)
	s_barrier
	v_mfma_f32_16x16x32_bf16 v[126:129], v[172:175], v[204:207], 0
	v_mfma_f32_16x16x32_bf16 v[122:125], v[180:183], v[204:207], 0
	v_mfma_f32_16x16x32_bf16 v[110:113], v[172:175], v[212:215], 0
	v_mfma_f32_16x16x32_bf16 v[106:109], v[180:183], v[212:215], 0
	v_mfma_f32_16x16x32_bf16 v[94:97], v[172:175], v[220:223], 0
	v_mfma_f32_16x16x32_bf16 v[90:93], v[180:183], v[220:223], 0
	v_mfma_f32_16x16x32_bf16 v[78:81], v[172:175], v[228:231], 0
	v_mfma_f32_16x16x32_bf16 v[74:77], v[180:183], v[228:231], 0
	v_mfma_f32_16x16x32_bf16 v[126:129], v[176:179], v[208:211], v[126:129]
	v_mfma_f32_16x16x32_bf16 v[122:125], v[184:187], v[208:211], v[122:125]
	v_mfma_f32_16x16x32_bf16 v[110:113], v[176:179], v[216:219], v[110:113]
	v_mfma_f32_16x16x32_bf16 v[106:109], v[184:187], v[216:219], v[106:109]
	v_mfma_f32_16x16x32_bf16 v[94:97], v[176:179], v[224:227], v[94:97]
	v_mfma_f32_16x16x32_bf16 v[90:93], v[184:187], v[224:227], v[90:93]
	v_mfma_f32_16x16x32_bf16 v[78:81], v[176:179], v[232:235], v[78:81]
	v_mfma_f32_16x16x32_bf16 v[74:77], v[184:187], v[232:235], v[74:77]
	v_mfma_f32_16x16x32_bf16 v[118:121], v[188:191], v[204:207], 0
	v_mfma_f32_16x16x32_bf16 v[114:117], v[196:199], v[204:207], 0
	v_mfma_f32_16x16x32_bf16 v[102:105], v[188:191], v[212:215], 0
	v_mfma_f32_16x16x32_bf16 v[98:101], v[196:199], v[212:215], 0
	v_mfma_f32_16x16x32_bf16 v[86:89], v[188:191], v[220:223], 0
	v_mfma_f32_16x16x32_bf16 v[82:85], v[196:199], v[220:223], 0
	v_mfma_f32_16x16x32_bf16 v[70:73], v[188:191], v[228:231], 0
	v_mfma_f32_16x16x32_bf16 v[66:69], v[196:199], v[228:231], 0
	v_mfma_f32_16x16x32_bf16 v[118:121], v[192:195], v[208:211], v[118:121]
	v_mfma_f32_16x16x32_bf16 v[114:117], v[200:203], v[208:211], v[114:117]
	v_mfma_f32_16x16x32_bf16 v[102:105], v[192:195], v[216:219], v[102:105]
	v_mfma_f32_16x16x32_bf16 v[98:101], v[200:203], v[216:219], v[98:101]
	v_mfma_f32_16x16x32_bf16 v[86:89], v[192:195], v[224:227], v[86:89]
	v_mfma_f32_16x16x32_bf16 v[82:85], v[200:203], v[224:227], v[82:85]
	v_mfma_f32_16x16x32_bf16 v[70:73], v[192:195], v[232:235], v[70:73]
	v_mfma_f32_16x16x32_bf16 v[66:69], v[200:203], v[232:235], v[66:69]
	s_barrier
	s_mov_b32 m0, s55
	v_lshl_add_u64 v[236:237], s[34:35], 0, v[134:135]
	s_add_u32 s62, s34, 0x4000
	ds_read_b128 v[204:207], v170 offset:16384
	ds_read_b128 v[208:211], v170 offset:17408
	ds_read_b128 v[212:215], v170 offset:18432
	ds_read_b128 v[216:219], v170 offset:19456
	ds_read_b128 v[220:223], v170 offset:20480
	ds_read_b128 v[224:227], v170 offset:21504
	ds_read_b128 v[228:231], v170 offset:22528
	ds_read_b128 v[232:235], v170 offset:23552
	global_load_lds_dwordx4 v[236:237], off
	v_lshl_add_u64 v[236:237], s[34:35], 0, v[130:131]
	s_mov_b32 m0, s56
	s_addc_u32 s63, s35, 0
	s_add_i32 s61, s52, s40
	global_load_lds_dwordx4 v[236:237], off
	v_lshl_add_u64 v[236:237], s[62:63], 0, v[134:135]
	s_mov_b32 m0, s61
	s_nop 0
	global_load_lds_dwordx4 v[236:237], off
	v_lshl_add_u64 v[236:237], s[62:63], 0, v[130:131]
	s_add_i32 m0, s61, 0x2000
	s_nop 0
	global_load_lds_dwordx4 v[236:237], off
	v_lshl_add_u64 v[236:237], s[36:37], 0, v[136:137]
	s_mov_b32 m0, s25
	s_nop 0
	global_load_lds_dwordx4 v[236:237], off
	v_lshl_add_u64 v[236:237], s[36:37], 0, v[132:133]
	s_mov_b32 m0, s43
	s_nop 0
	global_load_lds_dwordx4 v[236:237], off
	s_waitcnt vmcnt(8)
	s_waitcnt lgkmcnt(0)
	s_barrier
; #define PG8_STAGE(bufoff, gbase, voff) do { _Pragma("unroll") for (int _i = 0; _i < 2; ++_i) \
;         __builtin_amdgcn_global_load_lds((const unsigned*)((const char*)(gbase) + (voff)[_i]), (LAS unsigned*)(lds + (bufoff) + ldsw + _i * 8192), 16, 0, 0); } while (0)
; #define PG8_LDA(dst, b, h) do { _Pragma("unroll") for (int m = 0; m < 4; ++m) _Pragma("unroll") for (int k = 0; k < 2; ++k) dst[m][k] = *(const LAS bf16x8*)(lds + PG8_SA(b, h) + aoff + m * 2048 + k * 1024); } while (0)
; #define PG8_LDB(dst, b, h) do { _Pragma("unroll") for (int n = 0; n < 2; ++n) _Pragma("unroll") for (int k = 0; k < 2; ++k) dst[n][k] = *(const LAS bf16x8*)(lds + PG8_SB(b, h) + boff + n * 2048 + k * 1024); } while (0)
; #define PG8_MMA(ai, bj, At, Bt) do { __builtin_amdgcn_s_setprio(1); _Pragma("unroll") for (int m = 0; m < 4; ++m) _Pragma("unroll") for (int n = 0; n < 2; ++n) _Pragma("unroll") for (int k = 0; k < 2; ++k) \
;         acc[ai][bj][m][n] = __builtin_amdgcn_mfma_f32_16x16x32_bf16(Bt[n][k], At[m][k], acc[ai][bj][m][n], 0, 0, 0); __builtin_amdgcn_s_setprio(0); } while (0)
; #define PG8_WAIT_V(n) asm volatile("s_waitcnt vmcnt(" #n ")" ::: "memory")
; #define PG8_WAIT_L(n) asm volatile("s_waitcnt lgkmcnt(" #n ")" ::: "memory")
; #define PG8_BAR __builtin_amdgcn_s_barrier()
; #define PG8_SCHED __builtin_amdgcn_sched_barrier(0)
; template <class Epi, class Sched, bool ABLK = false, bool ALIGN_EPI = true, bool SP2 = true, bool BBLK = true>
; __device__ __forceinline__ void gemm_phase(LAS unsigned char* lds, const Gemm g, const Sched& S, const Epi& E) {
;     ...
;             PG8_WAIT_V(8); PG8_WAIT_L(0); PG8_BAR; PG8_MMA(1, 0, At, B0); PG8_MMA(1, 1, At, B1); PG8_BAR; PG8_SCHED;
;             PG8_LDB(B0, 1, 0); PG8_LDB(B1, 1, 1); PG8_SCHED; PG8_LDA(At, 1, 0); PG8_STAGE(PG8_SA(0, 1), a2 + hstepA, voffA);
;             PG8_WAIT_V(8); PG8_WAIT_L(0); PG8_BAR; PG8_MMA(0, 0, At, B0); PG8_MMA(0, 1, At, B1); PG8_BAR; PG8_SCHED;
	v_mfma_f32_16x16x32_bf16 v[62:65], v[172:175], v[204:207], 0
	v_mfma_f32_16x16x32_bf16 v[58:61], v[180:183], v[204:207], 0
	v_mfma_f32_16x16x32_bf16 v[46:49], v[172:175], v[212:215], 0
	v_mfma_f32_16x16x32_bf16 v[42:45], v[180:183], v[212:215], 0
	v_mfma_f32_16x16x32_bf16 v[30:33], v[172:175], v[220:223], 0
	v_mfma_f32_16x16x32_bf16 v[26:29], v[180:183], v[220:223], 0
	v_mfma_f32_16x16x32_bf16 v[14:17], v[172:175], v[228:231], 0
	v_mfma_f32_16x16x32_bf16 v[10:13], v[180:183], v[228:231], 0
	v_mfma_f32_16x16x32_bf16 v[62:65], v[176:179], v[208:211], v[62:65]
	v_mfma_f32_16x16x32_bf16 v[58:61], v[184:187], v[208:211], v[58:61]
	v_mfma_f32_16x16x32_bf16 v[46:49], v[176:179], v[216:219], v[46:49]
	v_mfma_f32_16x16x32_bf16 v[42:45], v[184:187], v[216:219], v[42:45]
	v_mfma_f32_16x16x32_bf16 v[30:33], v[176:179], v[224:227], v[30:33]
	v_mfma_f32_16x16x32_bf16 v[26:29], v[184:187], v[224:227], v[26:29]
	v_mfma_f32_16x16x32_bf16 v[14:17], v[176:179], v[232:235], v[14:17]
	v_mfma_f32_16x16x32_bf16 v[10:13], v[184:187], v[232:235], v[10:13]
	v_mfma_f32_16x16x32_bf16 v[54:57], v[188:191], v[204:207], 0
	v_mfma_f32_16x16x32_bf16 v[50:53], v[196:199], v[204:207], 0
	v_mfma_f32_16x16x32_bf16 v[38:41], v[188:191], v[212:215], 0
	v_mfma_f32_16x16x32_bf16 v[34:37], v[196:199], v[212:215], 0
	v_mfma_f32_16x16x32_bf16 v[22:25], v[188:191], v[220:223], 0
	v_mfma_f32_16x16x32_bf16 v[18:21], v[196:199], v[220:223], 0
	v_mfma_f32_16x16x32_bf16 v[6:9], v[188:191], v[228:231], 0
	v_mfma_f32_16x16x32_bf16 v[2:5], v[196:199], v[228:231], 0
	v_mfma_f32_16x16x32_bf16 v[54:57], v[192:195], v[208:211], v[54:57]
	v_mfma_f32_16x16x32_bf16 v[50:53], v[200:203], v[208:211], v[50:53]
	v_mfma_f32_16x16x32_bf16 v[38:41], v[192:195], v[216:219], v[38:41]
	v_mfma_f32_16x16x32_bf16 v[34:37], v[200:203], v[216:219], v[34:37]
	v_mfma_f32_16x16x32_bf16 v[22:25], v[192:195], v[224:227], v[22:25]
	v_mfma_f32_16x16x32_bf16 v[18:21], v[200:203], v[224:227], v[18:21]
	v_mfma_f32_16x16x32_bf16 v[6:9], v[192:195], v[232:235], v[6:9]
	v_mfma_f32_16x16x32_bf16 v[2:5], v[200:203], v[232:235], v[2:5]
	s_barrier
	s_add_i32 s61, 0, 0x18000
	v_add_u32_e32 v171, s61, v1
	s_add_i32 s62, 0, 0x1c000
	ds_read_b128 v[172:175], v171
	ds_read_b128 v[176:179], v171 offset:1024
	ds_read_b128 v[180:183], v171 offset:2048
	ds_read_b128 v[184:187], v171 offset:3072
	v_add_u32_e32 v171, s62, v1
	ds_read_b128 v[188:191], v171
	ds_read_b128 v[192:195], v171 offset:1024
	ds_read_b128 v[196:199], v171 offset:2048
	ds_read_b128 v[200:203], v171 offset:3072
	s_add_u32 s36, s36, 0x80000
	s_addc_u32 s37, s37, 0
	s_mov_b32 m0, s46
	v_lshl_add_u64 v[236:237], s[36:37], 0, v[136:137]
	ds_read_b128 v[204:207], v170 offset:32768
	ds_read_b128 v[208:211], v170 offset:33792
	ds_read_b128 v[212:215], v170 offset:34816
	ds_read_b128 v[216:219], v170 offset:35840
	ds_read_b128 v[220:223], v170 offset:36864
	ds_read_b128 v[224:227], v170 offset:37888
	ds_read_b128 v[228:231], v170 offset:38912
	ds_read_b128 v[232:235], v170 offset:39936
	global_load_lds_dwordx4 v[236:237], off
	v_lshl_add_u64 v[236:237], s[36:37], 0, v[132:133]
	s_mov_b32 m0, s47
	s_nop 0
	global_load_lds_dwordx4 v[236:237], off
	s_waitcnt vmcnt(8)
	s_waitcnt lgkmcnt(0)
	s_barrier
	v_mfma_f32_16x16x32_bf16 v[126:129], v[172:175], v[204:207], v[126:129]
	v_mfma_f32_16x16x32_bf16 v[122:125], v[180:183], v[204:207], v[122:125]
	v_mfma_f32_16x16x32_bf16 v[110:113], v[172:175], v[212:215], v[110:113]
	v_mfma_f32_16x16x32_bf16 v[106:109], v[180:183], v[212:215], v[106:109]
	v_mfma_f32_16x16x32_bf16 v[94:97], v[172:175], v[220:223], v[94:97]
	v_mfma_f32_16x16x32_bf16 v[90:93], v[180:183], v[220:223], v[90:93]
	v_mfma_f32_16x16x32_bf16 v[78:81], v[172:175], v[228:231], v[78:81]
	v_mfma_f32_16x16x32_bf16 v[74:77], v[180:183], v[228:231], v[74:77]
	v_mfma_f32_16x16x32_bf16 v[126:129], v[176:179], v[208:211], v[126:129]
	v_mfma_f32_16x16x32_bf16 v[122:125], v[184:187], v[208:211], v[122:125]
	v_mfma_f32_16x16x32_bf16 v[110:113], v[176:179], v[216:219], v[110:113]
	v_mfma_f32_16x16x32_bf16 v[106:109], v[184:187], v[216:219], v[106:109]
	v_mfma_f32_16x16x32_bf16 v[94:97], v[176:179], v[224:227], v[94:97]
	v_mfma_f32_16x16x32_bf16 v[90:93], v[184:187], v[224:227], v[90:93]
	v_mfma_f32_16x16x32_bf16 v[78:81], v[176:179], v[232:235], v[78:81]
	v_mfma_f32_16x16x32_bf16 v[74:77], v[184:187], v[232:235], v[74:77]
	v_mfma_f32_16x16x32_bf16 v[118:121], v[188:191], v[204:207], v[118:121]
	v_mfma_f32_16x16x32_bf16 v[114:117], v[196:199], v[204:207], v[114:117]
	v_mfma_f32_16x16x32_bf16 v[102:105], v[188:191], v[212:215], v[102:105]
	v_mfma_f32_16x16x32_bf16 v[98:101], v[196:199], v[212:215], v[98:101]
	v_mfma_f32_16x16x32_bf16 v[86:89], v[188:191], v[220:223], v[86:89]
	v_mfma_f32_16x16x32_bf16 v[82:85], v[196:199], v[220:223], v[82:85]
	v_mfma_f32_16x16x32_bf16 v[70:73], v[188:191], v[228:231], v[70:73]
	v_mfma_f32_16x16x32_bf16 v[66:69], v[196:199], v[228:231], v[66:69]
	v_mfma_f32_16x16x32_bf16 v[118:121], v[192:195], v[208:211], v[118:121]
	v_mfma_f32_16x16x32_bf16 v[114:117], v[200:203], v[208:211], v[114:117]
	v_mfma_f32_16x16x32_bf16 v[102:105], v[192:195], v[216:219], v[102:105]
	v_mfma_f32_16x16x32_bf16 v[98:101], v[200:203], v[216:219], v[98:101]
	v_mfma_f32_16x16x32_bf16 v[86:89], v[192:195], v[224:227], v[86:89]
	v_mfma_f32_16x16x32_bf16 v[82:85], v[200:203], v[224:227], v[82:85]
	v_mfma_f32_16x16x32_bf16 v[70:73], v[192:195], v[232:235], v[70:73]
	v_mfma_f32_16x16x32_bf16 v[66:69], v[200:203], v[232:235], v[66:69]
	s_barrier
; #define PG8_STAGE(bufoff, gbase, voff) do { _Pragma("unroll") for (int _i = 0; _i < 2; ++_i) \
;         __builtin_amdgcn_global_load_lds((const unsigned*)((const char*)(gbase) + (voff)[_i]), (LAS unsigned*)(lds + (bufoff) + ldsw + _i * 8192), 16, 0, 0); } while (0)
; #define PG8_LDA(dst, b, h) do { _Pragma("unroll") for (int m = 0; m < 4; ++m) _Pragma("unroll") for (int k = 0; k < 2; ++k) dst[m][k] = *(const LAS bf16x8*)(lds + PG8_SA(b, h) + aoff + m * 2048 + k * 1024); } while (0)
; #define PG8_WAIT_V(n) asm volatile("s_waitcnt vmcnt(" #n ")" ::: "memory")
; #define PG8_WAIT_L(n) asm volatile("s_waitcnt lgkmcnt(" #n ")" ::: "memory")
; template <class Epi, class Sched, bool ABLK = false, bool ALIGN_EPI = true, bool SP2 = true, bool BBLK = true>
; __device__ __forceinline__ void gemm_phase(LAS unsigned char* lds, const Gemm g, const Sched& S, const Epi& E) {
;     ...
;         for (int t = 0; t < nt; t += 2) {
;             const bool last = (t == nt - 2);
;             const char* a1 = a_tile(uA, tbA + t + 1);
;             const char* a2 = last ? a_tile(nuA, ntbA) : a_tile(uA, tbA + t + 2); const char* b2 = last ? nB : cB + (size_t)(t + 2) * kstepB;
;             const char* a3 = last ? a_tile(nuA, ntbA + 1) : a_tile(uA, tbA + t + 3); const char* b3 = b2 + kstepB;
;             if (last && has_next) S.a_ready(nxt);
;             if constexpr (SP2) {
;             PG8_LDB(B0, 0, 0); PG8_LDB(B1, 0, 1); PG8_SCHED; PG8_LDA(At, 0, 0); PG8_STAGE(PG8_SA(1, 1), a1 + hstepA, voffA);
;             PG8_WAIT_V(8); PG8_WAIT_L(0); PG8_BAR; PG8_MMA(0, 0, At, B0); PG8_MMA(0, 1, At, B1); PG8_BAR; PG8_SCHED;
;             PG8_LDA(At, 0, 1); PG8_STAGE(PG8_SB(0, 0), b2, voffB); PG8_STAGE(PG8_SB(0, 1), b2 + hstepB, voffB); PG8_STAGE(PG8_SA(0, 0), a2, voffA);
;             PG8_WAIT_V(8); PG8_WAIT_L(0); PG8_BAR; PG8_MMA(1, 0, At, B0); PG8_MMA(1, 1, At, B1); PG8_BAR; PG8_SCHED;
;             PG8_LDB(B0, 1, 0); PG8_LDB(B1, 1, 1); PG8_SCHED; PG8_LDA(At, 1, 0); PG8_STAGE(PG8_SA(0, 1), a2 + hstepA, voffA);
;             PG8_WAIT_V(8); PG8_WAIT_L(0); PG8_BAR; PG8_MMA(0, 0, At, B0); PG8_MMA(0, 1, At, B1); PG8_BAR; PG8_SCHED;
;             PG8_LDA(At, 1, 1); PG8_STAGE(PG8_SB(1, 0), b3, voffB); PG8_STAGE(PG8_SB(1, 1), b3 + hstepB, voffB); PG8_STAGE(PG8_SA(1, 0), a3, voffA);
;             PG8_WAIT_V(8); PG8_WAIT_L(0); PG8_BAR; PG8_MMA(1, 0, At, B0); PG8_MMA(1, 1, At, B1); PG8_BAR; PG8_SCHED;
	s_add_u32 s36, s34, 0x8000
	s_addc_u32 s37, s35, 0
	s_add_i32 s61, s61, s40
	v_lshl_add_u64 v[236:237], s[36:37], 0, v[134:135]
	s_mov_b32 m0, s61
	ds_read_b128 v[204:207], v170 offset:49152
	ds_read_b128 v[208:211], v170 offset:50176
	ds_read_b128 v[212:215], v170 offset:51200
	ds_read_b128 v[216:219], v170 offset:52224
	ds_read_b128 v[220:223], v170 offset:53248
	ds_read_b128 v[224:227], v170 offset:54272
	ds_read_b128 v[228:231], v170 offset:55296
	ds_read_b128 v[232:235], v170 offset:56320
	global_load_lds_dwordx4 v[236:237], off
	s_add_i32 m0, s61, 0x2000
	s_add_u32 s34, s34, 0xc000
	v_lshl_add_u64 v[236:237], s[36:37], 0, v[130:131]
	s_addc_u32 s35, s35, 0
	s_add_i32 s36, s62, s40
	global_load_lds_dwordx4 v[236:237], off
	v_lshl_add_u64 v[236:237], s[34:35], 0, v[134:135]
	s_mov_b32 m0, s36
	s_nop 0
	global_load_lds_dwordx4 v[236:237], off
	v_lshl_add_u64 v[236:237], s[34:35], 0, v[130:131]
	s_add_i32 m0, s36, 0x2000
	s_nop 0
	global_load_lds_dwordx4 v[236:237], off
	v_lshl_add_u64 v[236:237], s[30:31], 0, v[136:137]
	s_mov_b32 m0, s50
	s_nop 0
	global_load_lds_dwordx4 v[236:237], off
	v_lshl_add_u64 v[236:237], s[30:31], 0, v[132:133]
	s_mov_b32 m0, s51
	s_nop 0
	global_load_lds_dwordx4 v[236:237], off
	s_waitcnt vmcnt(8)
	s_waitcnt lgkmcnt(0)
	s_barrier
	v_mfma_f32_16x16x32_bf16 v[62:65], v[172:175], v[204:207], v[62:65]
	v_mfma_f32_16x16x32_bf16 v[58:61], v[180:183], v[204:207], v[58:61]
	v_mfma_f32_16x16x32_bf16 v[46:49], v[172:175], v[212:215], v[46:49]
	v_mfma_f32_16x16x32_bf16 v[42:45], v[180:183], v[212:215], v[42:45]
	v_mfma_f32_16x16x32_bf16 v[30:33], v[172:175], v[220:223], v[30:33]
	v_mfma_f32_16x16x32_bf16 v[26:29], v[180:183], v[220:223], v[26:29]
	v_mfma_f32_16x16x32_bf16 v[14:17], v[172:175], v[228:231], v[14:17]
	v_mfma_f32_16x16x32_bf16 v[10:13], v[180:183], v[228:231], v[10:13]
	v_mfma_f32_16x16x32_bf16 v[62:65], v[176:179], v[208:211], v[62:65]
	v_mfma_f32_16x16x32_bf16 v[58:61], v[184:187], v[208:211], v[58:61]
	v_mfma_f32_16x16x32_bf16 v[46:49], v[176:179], v[216:219], v[46:49]
	v_mfma_f32_16x16x32_bf16 v[42:45], v[184:187], v[216:219], v[42:45]
	v_mfma_f32_16x16x32_bf16 v[30:33], v[176:179], v[224:227], v[30:33]
	v_mfma_f32_16x16x32_bf16 v[26:29], v[184:187], v[224:227], v[26:29]
	v_mfma_f32_16x16x32_bf16 v[14:17], v[176:179], v[232:235], v[14:17]
	v_mfma_f32_16x16x32_bf16 v[10:13], v[184:187], v[232:235], v[10:13]
	v_mfma_f32_16x16x32_bf16 v[54:57], v[188:191], v[204:207], v[54:57]
	v_mfma_f32_16x16x32_bf16 v[50:53], v[196:199], v[204:207], v[50:53]
	v_mfma_f32_16x16x32_bf16 v[38:41], v[188:191], v[212:215], v[38:41]
	v_mfma_f32_16x16x32_bf16 v[34:37], v[196:199], v[212:215], v[34:37]
	v_mfma_f32_16x16x32_bf16 v[22:25], v[188:191], v[220:223], v[22:25]
	v_mfma_f32_16x16x32_bf16 v[18:21], v[196:199], v[220:223], v[18:21]
	v_mfma_f32_16x16x32_bf16 v[6:9], v[188:191], v[228:231], v[6:9]
	v_mfma_f32_16x16x32_bf16 v[2:5], v[196:199], v[228:231], v[2:5]
	v_mfma_f32_16x16x32_bf16 v[54:57], v[192:195], v[208:211], v[54:57]
	v_mfma_f32_16x16x32_bf16 v[50:53], v[200:203], v[208:211], v[50:53]
	v_mfma_f32_16x16x32_bf16 v[38:41], v[192:195], v[216:219], v[38:41]
	v_mfma_f32_16x16x32_bf16 v[34:37], v[200:203], v[216:219], v[34:37]
	v_mfma_f32_16x16x32_bf16 v[22:25], v[192:195], v[224:227], v[22:25]
	v_mfma_f32_16x16x32_bf16 v[18:21], v[200:203], v[224:227], v[18:21]
	v_mfma_f32_16x16x32_bf16 v[6:9], v[192:195], v[232:235], v[6:9]
	v_mfma_f32_16x16x32_bf16 v[2:5], v[200:203], v[232:235], v[2:5]
	s_barrier
	s_add_i32 s60, s60, 2
	s_add_u32 s28, s28, 0x100
	s_addc_u32 s29, s29, 0
	s_add_u32 s58, s58, 0x10000
	s_addc_u32 s59, s59, 0
	s_cmp_gt_u32 s60, 29

; __device__ __forceinline__ unsigned pk2(float lo, float hi) { const f32x2 v = {lo, hi}; return __builtin_bit_cast(unsigned, __builtin_convertvector(v, bf16x2_t)); }
; __device__ __forceinline__ u32x4 ror8(u32x4 v) { u32x4 r;
; #pragma unroll
;     for (int i = 0; i < 4; ++i) r[i] = (unsigned)__builtin_amdgcn_mov_dpp((int)v[i], 0x128, 0xf, 0xf, true);
;     return r; }
; __device__ __forceinline__ void store_pair(unsigned char* own, size_t stride8, int hi_off, u32x4 lo, u32x4 hi, bool upper) {
;     const u32x4 tlo = ror8(lo), thi = ror8(hi);
;     const u32x4 A = upper ? thi : lo, B = upper ? hi : tlo;
;     unsigned char* pa = upper ? own - stride8 + hi_off : own;
;     unsigned char* pb = upper ? own + hi_off : own + stride8;
;     *(u32x4*)pa = A; *(u32x4*)pb = B;
; }
;     __device__ __forceinline__ void operator()(const f32x4 (&acc)[2][2][4][2], const Unit& u, int wr, int wc, int fr, int fq) const {
; #pragma unroll
;         for (int ai = 0; ai < 2; ++ai)
; #pragma unroll
;             for (int m = 0; m < 4; ++m) { unsigned char* rowp = (unsigned char*)(H + ((size_t)(u.pm * (FF / 64) + u.pn * 4 + wc) * 256 + (wr * 64 + fr + ai * 128 + m * 16)) * 64 + 8 * fq); u32x4 w[2];
; #pragma unroll
;                 for (int bj = 0; bj < 2; ++bj) { f32x4 v0 = acc[ai][bj][m][0], v1 = acc[ai][bj][m][1];
; #pragma unroll
;                     for (int j = 0; j < 4; ++j) { const float a = fmaxf(v0[j], 0.f), b = fmaxf(v1[j], 0.f); v0[j] = a * a; v1[j] = b * b; }
;                     w[bj].x = pk2(v0[0], v0[1]); w[bj].y = pk2(v0[2], v0[3]); w[bj].z = pk2(v1[0], v1[1]); w[bj].w = pk2(v1[2], v1[3]); }
;                 store_pair(rowp, (size_t)8 * 64 * 2, 64, w[0], w[1], fr >= 8); }
.LBB0_478:
	s_lshl_b32 s4, s22, 7
	s_lshl_b32 s5, s24, 2
	s_add_i32 s5, s5, s4
	s_or_b32 s4, s5, s49
	s_ashr_i32 s5, s4, 31
	s_lshl_b64 s[4:5], s[4:5], 15
	s_add_u32 s22, s1, s4
	v_max_f32_e32 v126, 0, v126
	v_max_f32_e32 v122, 0, v122
	v_max_f32_e32 v127, 0, v127
	v_max_f32_e32 v123, 0, v123
	v_max_f32_e32 v128, 0, v128
	v_max_f32_e32 v124, 0, v124
	v_max_f32_e32 v129, 0, v129
	v_max_f32_e32 v125, 0, v125
	v_max_f32_e32 v118, 0, v118
	v_max_f32_e32 v114, 0, v114
	v_max_f32_e32 v119, 0, v119
	v_max_f32_e32 v115, 0, v115
	v_max_f32_e32 v120, 0, v120
	v_max_f32_e32 v116, 0, v116
	v_max_f32_e32 v121, 0, v121
	v_max_f32_e32 v117, 0, v117
	s_addc_u32 s23, s33, s5
	v_pk_mul_f32 v[126:127], v[126:127], v[126:127]
	v_pk_mul_f32 v[122:123], v[122:123], v[122:123]
	v_pk_mul_f32 v[128:129], v[128:129], v[128:129]
	v_pk_mul_f32 v[124:125], v[124:125], v[124:125]
	v_pk_mul_f32 v[118:119], v[118:119], v[118:119]
	v_pk_mul_f32 v[114:115], v[114:115], v[114:115]
	v_pk_mul_f32 v[120:121], v[120:121], v[120:121]
	v_pk_mul_f32 v[116:117], v[116:117], v[116:117]
	v_lshl_add_u64 v[164:165], s[22:23], 0, v[144:145]
	v_cvt_pk_bf16_f32 v126, v126, v127
	v_cvt_pk_bf16_f32 v127, v128, v129
	v_cvt_pk_bf16_f32 v128, v122, v123
	v_cvt_pk_bf16_f32 v129, v124, v125
	v_cvt_pk_bf16_f32 v118, v118, v119
	v_cvt_pk_bf16_f32 v119, v120, v121
	v_cvt_pk_bf16_f32 v114, v114, v115
	v_cvt_pk_bf16_f32 v115, v116, v117
	v_lshl_add_u64 v[122:123], v[164:165], 0, v[138:139]
	v_mov_b32_dpp v120, v126 row_ror:8 row_mask:0xf bank_mask:0xf bound_ctrl:1
	v_mov_b32_dpp v121, v127 row_ror:8 row_mask:0xf bank_mask:0xf bound_ctrl:1
	v_mov_b32_dpp v116, v128 row_ror:8 row_mask:0xf bank_mask:0xf bound_ctrl:1
	v_mov_b32_dpp v117, v129 row_ror:8 row_mask:0xf bank_mask:0xf bound_ctrl:1
	v_mov_b32_dpp v164, v118 row_ror:8 row_mask:0xf bank_mask:0xf bound_ctrl:1
	v_mov_b32_dpp v165, v119 row_ror:8 row_mask:0xf bank_mask:0xf bound_ctrl:1
	v_mov_b32_dpp v166, v114 row_ror:8 row_mask:0xf bank_mask:0xf bound_ctrl:1
	v_mov_b32_dpp v167, v115 row_ror:8 row_mask:0xf bank_mask:0xf bound_ctrl:1
	v_max_f32_e32 v110, 0, v110
	v_max_f32_e32 v106, 0, v106
	v_max_f32_e32 v111, 0, v111
	v_max_f32_e32 v107, 0, v107
	v_max_f32_e32 v112, 0, v112
	v_max_f32_e32 v108, 0, v108
	v_max_f32_e32 v113, 0, v113
	v_max_f32_e32 v109, 0, v109
	v_max_f32_e32 v102, 0, v102
	v_max_f32_e32 v98, 0, v98
	v_max_f32_e32 v103, 0, v103
	v_max_f32_e32 v99, 0, v99
	v_max_f32_e32 v104, 0, v104
	v_max_f32_e32 v100, 0, v100
	v_max_f32_e32 v105, 0, v105
	v_max_f32_e32 v101, 0, v101
	v_lshl_add_u64 v[124:125], v[122:123], 0, v[140:141]
	v_cndmask_b32_e64 v117, v117, v115, s[6:7]
	v_cndmask_b32_e64 v116, v116, v114, s[6:7]
	v_cndmask_b32_e64 v115, v121, v119, s[6:7]
	v_cndmask_b32_e64 v114, v120, v118, s[6:7]
	v_cndmask_b32_e64 v121, v129, v167, s[6:7]
	v_cndmask_b32_e64 v120, v128, v166, s[6:7]
	v_cndmask_b32_e64 v119, v127, v165, s[6:7]
	v_cndmask_b32_e64 v118, v126, v164, s[6:7]
	v_pk_mul_f32 v[110:111], v[110:111], v[110:111]
	v_pk_mul_f32 v[106:107], v[106:107], v[106:107]
	v_pk_mul_f32 v[112:113], v[112:113], v[112:113]
	v_pk_mul_f32 v[108:109], v[108:109], v[108:109]
	v_pk_mul_f32 v[102:103], v[102:103], v[102:103]
	v_pk_mul_f32 v[98:99], v[98:99], v[98:99]
	v_pk_mul_f32 v[104:105], v[104:105], v[104:105]
	v_pk_mul_f32 v[100:101], v[100:101], v[100:101]
	v_lshl_add_u64 v[122:123], v[122:123], 0, v[142:143]
	global_store_dwordx4 v[124:125], v[118:121], off
	global_store_dwordx4 v[122:123], v[114:117], off
	v_cvt_pk_bf16_f32 v110, v110, v111
	v_cvt_pk_bf16_f32 v111, v112, v113
	v_lshl_add_u64 v[114:115], s[22:23], 0, v[146:147]
	v_cvt_pk_bf16_f32 v112, v106, v107
	v_cvt_pk_bf16_f32 v113, v108, v109
	v_cvt_pk_bf16_f32 v102, v102, v103
	v_cvt_pk_bf16_f32 v103, v104, v105
	v_cvt_pk_bf16_f32 v98, v98, v99
	v_cvt_pk_bf16_f32 v99, v100, v101
	v_lshl_add_u64 v[106:107], v[114:115], 0, v[138:139]
	v_mov_b32_dpp v104, v110 row_ror:8 row_mask:0xf bank_mask:0xf bound_ctrl:1
	v_mov_b32_dpp v105, v111 row_ror:8 row_mask:0xf bank_mask:0xf bound_ctrl:1
	v_mov_b32_dpp v100, v112 row_ror:8 row_mask:0xf bank_mask:0xf bound_ctrl:1
	v_mov_b32_dpp v101, v113 row_ror:8 row_mask:0xf bank_mask:0xf bound_ctrl:1
	v_mov_b32_dpp v114, v102 row_ror:8 row_mask:0xf bank_mask:0xf bound_ctrl:1
	v_mov_b32_dpp v115, v103 row_ror:8 row_mask:0xf bank_mask:0xf bound_ctrl:1
	v_mov_b32_dpp v116, v98 row_ror:8 row_mask:0xf bank_mask:0xf bound_ctrl:1
	v_mov_b32_dpp v117, v99 row_ror:8 row_mask:0xf bank_mask:0xf bound_ctrl:1
	v_max_f32_e32 v94, 0, v94
	v_max_f32_e32 v90, 0, v90
	v_max_f32_e32 v95, 0, v95
	v_max_f32_e32 v91, 0, v91
	v_max_f32_e32 v96, 0, v96
	v_max_f32_e32 v92, 0, v92
	v_max_f32_e32 v97, 0, v97
	v_max_f32_e32 v93, 0, v93
	v_max_f32_e32 v86, 0, v86
	v_max_f32_e32 v82, 0, v82
	v_max_f32_e32 v87, 0, v87
	v_max_f32_e32 v83, 0, v83
	v_max_f32_e32 v88, 0, v88
	v_max_f32_e32 v84, 0, v84
	v_max_f32_e32 v89, 0, v89
	v_max_f32_e32 v85, 0, v85
	v_lshl_add_u64 v[108:109], v[106:107], 0, v[140:141]
	v_cndmask_b32_e64 v101, v101, v99, s[6:7]
	v_cndmask_b32_e64 v100, v100, v98, s[6:7]
	v_cndmask_b32_e64 v99, v105, v103, s[6:7]
	v_cndmask_b32_e64 v98, v104, v102, s[6:7]
	v_cndmask_b32_e64 v105, v113, v117, s[6:7]
	v_cndmask_b32_e64 v104, v112, v116, s[6:7]
	v_cndmask_b32_e64 v103, v111, v115, s[6:7]
	v_cndmask_b32_e64 v102, v110, v114, s[6:7]
	v_pk_mul_f32 v[94:95], v[94:95], v[94:95]
	v_pk_mul_f32 v[90:91], v[90:91], v[90:91]
	v_pk_mul_f32 v[96:97], v[96:97], v[96:97]
	v_pk_mul_f32 v[92:93], v[92:93], v[92:93]
	v_pk_mul_f32 v[86:87], v[86:87], v[86:87]
	v_pk_mul_f32 v[82:83], v[82:83], v[82:83]
	v_pk_mul_f32 v[88:89], v[88:89], v[88:89]
	v_pk_mul_f32 v[84:85], v[84:85], v[84:85]
; __device__ __forceinline__ unsigned pk2(float lo, float hi) { const f32x2 v = {lo, hi}; return __builtin_bit_cast(unsigned, __builtin_convertvector(v, bf16x2_t)); }
; __device__ __forceinline__ u32x4 ror8(u32x4 v) { u32x4 r;
; #pragma unroll
;     for (int i = 0; i < 4; ++i) r[i] = (unsigned)__builtin_amdgcn_mov_dpp((int)v[i], 0x128, 0xf, 0xf, true);
;     return r; }
; __device__ __forceinline__ void store_pair(unsigned char* own, size_t stride8, int hi_off, u32x4 lo, u32x4 hi, bool upper) {
;     const u32x4 tlo = ror8(lo), thi = ror8(hi);
;     const u32x4 A = upper ? thi : lo, B = upper ? hi : tlo;
;     unsigned char* pa = upper ? own - stride8 + hi_off : own;
;     unsigned char* pb = upper ? own + hi_off : own + stride8;
;     *(u32x4*)pa = A; *(u32x4*)pb = B;
; }
;     __device__ __forceinline__ void operator()(const f32x4 (&acc)[2][2][4][2], const Unit& u, int wr, int wc, int fr, int fq) const {
; #pragma unroll
;         for (int ai = 0; ai < 2; ++ai)
; #pragma unroll
;             for (int m = 0; m < 4; ++m) { unsigned char* rowp = (unsigned char*)(H + ((size_t)(u.pm * (FF / 64) + u.pn * 4 + wc) * 256 + (wr * 64 + fr + ai * 128 + m * 16)) * 64 + 8 * fq); u32x4 w[2];
; #pragma unroll
;                 for (int bj = 0; bj < 2; ++bj) { f32x4 v0 = acc[ai][bj][m][0], v1 = acc[ai][bj][m][1];
; #pragma unroll
;                     for (int j = 0; j < 4; ++j) { const float a = fmaxf(v0[j], 0.f), b = fmaxf(v1[j], 0.f); v0[j] = a * a; v1[j] = b * b; }
;                     w[bj].x = pk2(v0[0], v0[1]); w[bj].y = pk2(v0[2], v0[3]); w[bj].z = pk2(v1[0], v1[1]); w[bj].w = pk2(v1[2], v1[3]); }
;                 store_pair(rowp, (size_t)8 * 64 * 2, 64, w[0], w[1], fr >= 8); }
	v_lshl_add_u64 v[106:107], v[106:107], 0, v[142:143]
	global_store_dwordx4 v[108:109], v[102:105], off
	global_store_dwordx4 v[106:107], v[98:101], off
	v_cvt_pk_bf16_f32 v94, v94, v95
	v_cvt_pk_bf16_f32 v95, v96, v97
	v_lshl_add_u64 v[98:99], s[22:23], 0, v[148:149]
	v_cvt_pk_bf16_f32 v96, v90, v91
	v_cvt_pk_bf16_f32 v97, v92, v93
	v_cvt_pk_bf16_f32 v86, v86, v87
	v_cvt_pk_bf16_f32 v87, v88, v89
	v_cvt_pk_bf16_f32 v82, v82, v83
	v_cvt_pk_bf16_f32 v83, v84, v85
	v_lshl_add_u64 v[90:91], v[98:99], 0, v[138:139]
	v_mov_b32_dpp v88, v94 row_ror:8 row_mask:0xf bank_mask:0xf bound_ctrl:1
	v_mov_b32_dpp v89, v95 row_ror:8 row_mask:0xf bank_mask:0xf bound_ctrl:1
	v_mov_b32_dpp v84, v96 row_ror:8 row_mask:0xf bank_mask:0xf bound_ctrl:1
	v_mov_b32_dpp v85, v97 row_ror:8 row_mask:0xf bank_mask:0xf bound_ctrl:1
	v_mov_b32_dpp v98, v86 row_ror:8 row_mask:0xf bank_mask:0xf bound_ctrl:1
	v_mov_b32_dpp v99, v87 row_ror:8 row_mask:0xf bank_mask:0xf bound_ctrl:1
	v_mov_b32_dpp v100, v82 row_ror:8 row_mask:0xf bank_mask:0xf bound_ctrl:1
	v_mov_b32_dpp v101, v83 row_ror:8 row_mask:0xf bank_mask:0xf bound_ctrl:1
	v_max_f32_e32 v78, 0, v78
	v_max_f32_e32 v74, 0, v74
	v_max_f32_e32 v79, 0, v79
	v_max_f32_e32 v75, 0, v75
	v_max_f32_e32 v80, 0, v80
	v_max_f32_e32 v76, 0, v76
	v_max_f32_e32 v81, 0, v81
	v_max_f32_e32 v77, 0, v77
	v_max_f32_e32 v70, 0, v70
	v_max_f32_e32 v66, 0, v66
	v_max_f32_e32 v71, 0, v71
	v_max_f32_e32 v67, 0, v67
	v_max_f32_e32 v72, 0, v72
	v_max_f32_e32 v68, 0, v68
	v_max_f32_e32 v73, 0, v73
	v_max_f32_e32 v69, 0, v69
	v_lshl_add_u64 v[92:93], v[90:91], 0, v[140:141]
	v_cndmask_b32_e64 v85, v85, v83, s[6:7]
	v_cndmask_b32_e64 v84, v84, v82, s[6:7]
	v_cndmask_b32_e64 v83, v89, v87, s[6:7]
	v_cndmask_b32_e64 v82, v88, v86, s[6:7]
	v_cndmask_b32_e64 v89, v97, v101, s[6:7]
	v_cndmask_b32_e64 v88, v96, v100, s[6:7]
	v_cndmask_b32_e64 v87, v95, v99, s[6:7]
	v_cndmask_b32_e64 v86, v94, v98, s[6:7]
	v_pk_mul_f32 v[78:79], v[78:79], v[78:79]
	v_pk_mul_f32 v[74:75], v[74:75], v[74:75]
	v_pk_mul_f32 v[80:81], v[80:81], v[80:81]
	v_pk_mul_f32 v[76:77], v[76:77], v[76:77]
	v_pk_mul_f32 v[70:71], v[70:71], v[70:71]
	v_pk_mul_f32 v[66:67], v[66:67], v[66:67]
	v_pk_mul_f32 v[72:73], v[72:73], v[72:73]
	v_pk_mul_f32 v[68:69], v[68:69], v[68:69]
	v_lshl_add_u64 v[90:91], v[90:91], 0, v[142:143]
	global_store_dwordx4 v[92:93], v[86:89], off
	global_store_dwordx4 v[90:91], v[82:85], off
	v_cvt_pk_bf16_f32 v78, v78, v79
	v_cvt_pk_bf16_f32 v79, v80, v81
	v_lshl_add_u64 v[82:83], s[22:23], 0, v[150:151]
	v_cvt_pk_bf16_f32 v80, v74, v75
	v_cvt_pk_bf16_f32 v81, v76, v77
	v_cvt_pk_bf16_f32 v70, v70, v71
	v_cvt_pk_bf16_f32 v71, v72, v73
	v_cvt_pk_bf16_f32 v66, v66, v67
	v_cvt_pk_bf16_f32 v67, v68, v69
	v_lshl_add_u64 v[74:75], v[82:83], 0, v[138:139]
	v_mov_b32_dpp v72, v78 row_ror:8 row_mask:0xf bank_mask:0xf bound_ctrl:1
	v_mov_b32_dpp v73, v79 row_ror:8 row_mask:0xf bank_mask:0xf bound_ctrl:1
	v_mov_b32_dpp v68, v80 row_ror:8 row_mask:0xf bank_mask:0xf bound_ctrl:1
	v_mov_b32_dpp v69, v81 row_ror:8 row_mask:0xf bank_mask:0xf bound_ctrl:1
	v_mov_b32_dpp v82, v70 row_ror:8 row_mask:0xf bank_mask:0xf bound_ctrl:1
	v_mov_b32_dpp v83, v71 row_ror:8 row_mask:0xf bank_mask:0xf bound_ctrl:1
	v_mov_b32_dpp v84, v66 row_ror:8 row_mask:0xf bank_mask:0xf bound_ctrl:1
	v_mov_b32_dpp v85, v67 row_ror:8 row_mask:0xf bank_mask:0xf bound_ctrl:1
	v_max_f32_e32 v62, 0, v62
	v_max_f32_e32 v58, 0, v58
	v_max_f32_e32 v63, 0, v63
	v_max_f32_e32 v59, 0, v59
	v_max_f32_e32 v64, 0, v64
	v_max_f32_e32 v60, 0, v60
	v_max_f32_e32 v65, 0, v65
	v_max_f32_e32 v61, 0, v61
	v_max_f32_e32 v54, 0, v54
	v_max_f32_e32 v50, 0, v50
	v_max_f32_e32 v55, 0, v55
	v_max_f32_e32 v51, 0, v51
	v_max_f32_e32 v56, 0, v56
	v_max_f32_e32 v52, 0, v52
	v_max_f32_e32 v57, 0, v57
	v_max_f32_e32 v53, 0, v53
	v_lshl_add_u64 v[76:77], v[74:75], 0, v[140:141]
	v_cndmask_b32_e64 v69, v69, v67, s[6:7]
	v_cndmask_b32_e64 v68, v68, v66, s[6:7]
	v_cndmask_b32_e64 v67, v73, v71, s[6:7]
	v_cndmask_b32_e64 v66, v72, v70, s[6:7]
	v_cndmask_b32_e64 v73, v81, v85, s[6:7]
	v_cndmask_b32_e64 v72, v80, v84, s[6:7]
	v_cndmask_b32_e64 v71, v79, v83, s[6:7]
	v_cndmask_b32_e64 v70, v78, v82, s[6:7]
	v_pk_mul_f32 v[62:63], v[62:63], v[62:63]
	v_pk_mul_f32 v[58:59], v[58:59], v[58:59]
	v_pk_mul_f32 v[64:65], v[64:65], v[64:65]
	v_pk_mul_f32 v[60:61], v[60:61], v[60:61]
	v_pk_mul_f32 v[54:55], v[54:55], v[54:55]
	v_pk_mul_f32 v[50:51], v[50:51], v[50:51]
	v_pk_mul_f32 v[56:57], v[56:57], v[56:57]
	v_pk_mul_f32 v[52:53], v[52:53], v[52:53]
	v_lshl_add_u64 v[74:75], v[74:75], 0, v[142:143]
	global_store_dwordx4 v[76:77], v[70:73], off
	global_store_dwordx4 v[74:75], v[66:69], off
	v_cvt_pk_bf16_f32 v62, v62, v63
	v_cvt_pk_bf16_f32 v63, v64, v65
	v_lshl_add_u64 v[66:67], s[22:23], 0, v[152:153]
	v_cvt_pk_bf16_f32 v64, v58, v59
	v_cvt_pk_bf16_f32 v65, v60, v61
	v_cvt_pk_bf16_f32 v54, v54, v55
	v_cvt_pk_bf16_f32 v55, v56, v57
	v_cvt_pk_bf16_f32 v50, v50, v51
	v_cvt_pk_bf16_f32 v51, v52, v53
	v_lshl_add_u64 v[58:59], v[66:67], 0, v[138:139]
	v_mov_b32_dpp v56, v62 row_ror:8 row_mask:0xf bank_mask:0xf bound_ctrl:1
	v_mov_b32_dpp v57, v63 row_ror:8 row_mask:0xf bank_mask:0xf bound_ctrl:1
	v_mov_b32_dpp v52, v64 row_ror:8 row_mask:0xf bank_mask:0xf bound_ctrl:1
	v_mov_b32_dpp v53, v65 row_ror:8 row_mask:0xf bank_mask:0xf bound_ctrl:1
	v_mov_b32_dpp v66, v54 row_ror:8 row_mask:0xf bank_mask:0xf bound_ctrl:1
	v_mov_b32_dpp v67, v55 row_ror:8 row_mask:0xf bank_mask:0xf bound_ctrl:1
	v_mov_b32_dpp v68, v50 row_ror:8 row_mask:0xf bank_mask:0xf bound_ctrl:1
	v_mov_b32_dpp v69, v51 row_ror:8 row_mask:0xf bank_mask:0xf bound_ctrl:1
	v_max_f32_e32 v46, 0, v46
; __device__ __forceinline__ unsigned pk2(float lo, float hi) { const f32x2 v = {lo, hi}; return __builtin_bit_cast(unsigned, __builtin_convertvector(v, bf16x2_t)); }
; __device__ __forceinline__ u32x4 ror8(u32x4 v) { u32x4 r;
; #pragma unroll
;     for (int i = 0; i < 4; ++i) r[i] = (unsigned)__builtin_amdgcn_mov_dpp((int)v[i], 0x128, 0xf, 0xf, true);
;     return r; }
; __device__ __forceinline__ void store_pair(unsigned char* own, size_t stride8, int hi_off, u32x4 lo, u32x4 hi, bool upper) {
;     const u32x4 tlo = ror8(lo), thi = ror8(hi);
;     const u32x4 A = upper ? thi : lo, B = upper ? hi : tlo;
;     unsigned char* pa = upper ? own - stride8 + hi_off : own;
;     unsigned char* pb = upper ? own + hi_off : own + stride8;
;     *(u32x4*)pa = A; *(u32x4*)pb = B;
; }
;     __device__ __forceinline__ void operator()(const f32x4 (&acc)[2][2][4][2], const Unit& u, int wr, int wc, int fr, int fq) const {
; #pragma unroll
;         for (int ai = 0; ai < 2; ++ai)
; #pragma unroll
;             for (int m = 0; m < 4; ++m) { unsigned char* rowp = (unsigned char*)(H + ((size_t)(u.pm * (FF / 64) + u.pn * 4 + wc) * 256 + (wr * 64 + fr + ai * 128 + m * 16)) * 64 + 8 * fq); u32x4 w[2];
; #pragma unroll
;                 for (int bj = 0; bj < 2; ++bj) { f32x4 v0 = acc[ai][bj][m][0], v1 = acc[ai][bj][m][1];
; #pragma unroll
;                     for (int j = 0; j < 4; ++j) { const float a = fmaxf(v0[j], 0.f), b = fmaxf(v1[j], 0.f); v0[j] = a * a; v1[j] = b * b; }
;                     w[bj].x = pk2(v0[0], v0[1]); w[bj].y = pk2(v0[2], v0[3]); w[bj].z = pk2(v1[0], v1[1]); w[bj].w = pk2(v1[2], v1[3]); }
;                 store_pair(rowp, (size_t)8 * 64 * 2, 64, w[0], w[1], fr >= 8); }
	v_max_f32_e32 v42, 0, v42
	v_max_f32_e32 v47, 0, v47
	v_max_f32_e32 v43, 0, v43
	v_max_f32_e32 v48, 0, v48
	v_max_f32_e32 v44, 0, v44
	v_max_f32_e32 v49, 0, v49
	v_max_f32_e32 v45, 0, v45
	v_max_f32_e32 v38, 0, v38
	v_max_f32_e32 v34, 0, v34
	v_max_f32_e32 v39, 0, v39
	v_max_f32_e32 v35, 0, v35
	v_max_f32_e32 v40, 0, v40
	v_max_f32_e32 v36, 0, v36
	v_max_f32_e32 v41, 0, v41
	v_max_f32_e32 v37, 0, v37
	v_lshl_add_u64 v[60:61], v[58:59], 0, v[140:141]
	v_cndmask_b32_e64 v53, v53, v51, s[6:7]
	v_cndmask_b32_e64 v52, v52, v50, s[6:7]
	v_cndmask_b32_e64 v51, v57, v55, s[6:7]
	v_cndmask_b32_e64 v50, v56, v54, s[6:7]
	v_cndmask_b32_e64 v57, v65, v69, s[6:7]
	v_cndmask_b32_e64 v56, v64, v68, s[6:7]
	v_cndmask_b32_e64 v55, v63, v67, s[6:7]
	v_cndmask_b32_e64 v54, v62, v66, s[6:7]
	v_pk_mul_f32 v[46:47], v[46:47], v[46:47]
	v_pk_mul_f32 v[42:43], v[42:43], v[42:43]
	v_pk_mul_f32 v[48:49], v[48:49], v[48:49]
	v_pk_mul_f32 v[44:45], v[44:45], v[44:45]
	v_pk_mul_f32 v[38:39], v[38:39], v[38:39]
	v_pk_mul_f32 v[34:35], v[34:35], v[34:35]
	v_pk_mul_f32 v[40:41], v[40:41], v[40:41]
	v_pk_mul_f32 v[36:37], v[36:37], v[36:37]
	v_lshl_add_u64 v[58:59], v[58:59], 0, v[142:143]
	global_store_dwordx4 v[60:61], v[54:57], off
	global_store_dwordx4 v[58:59], v[50:53], off
	v_cvt_pk_bf16_f32 v46, v46, v47
	v_cvt_pk_bf16_f32 v47, v48, v49
	v_lshl_add_u64 v[50:51], s[22:23], 0, v[154:155]
	v_cvt_pk_bf16_f32 v48, v42, v43
	v_cvt_pk_bf16_f32 v49, v44, v45
	v_cvt_pk_bf16_f32 v38, v38, v39
	v_cvt_pk_bf16_f32 v39, v40, v41
	v_cvt_pk_bf16_f32 v34, v34, v35
	v_cvt_pk_bf16_f32 v35, v36, v37
	v_lshl_add_u64 v[42:43], v[50:51], 0, v[138:139]
	v_mov_b32_dpp v40, v46 row_ror:8 row_mask:0xf bank_mask:0xf bound_ctrl:1
	v_mov_b32_dpp v41, v47 row_ror:8 row_mask:0xf bank_mask:0xf bound_ctrl:1
	v_mov_b32_dpp v36, v48 row_ror:8 row_mask:0xf bank_mask:0xf bound_ctrl:1
	v_mov_b32_dpp v37, v49 row_ror:8 row_mask:0xf bank_mask:0xf bound_ctrl:1
	v_mov_b32_dpp v50, v38 row_ror:8 row_mask:0xf bank_mask:0xf bound_ctrl:1
	v_mov_b32_dpp v51, v39 row_ror:8 row_mask:0xf bank_mask:0xf bound_ctrl:1
	v_mov_b32_dpp v52, v34 row_ror:8 row_mask:0xf bank_mask:0xf bound_ctrl:1
	v_mov_b32_dpp v53, v35 row_ror:8 row_mask:0xf bank_mask:0xf bound_ctrl:1
	v_max_f32_e32 v30, 0, v30
	v_max_f32_e32 v26, 0, v26
	v_max_f32_e32 v31, 0, v31
	v_max_f32_e32 v27, 0, v27
	v_max_f32_e32 v32, 0, v32
	v_max_f32_e32 v28, 0, v28
	v_max_f32_e32 v33, 0, v33
	v_max_f32_e32 v29, 0, v29
	v_max_f32_e32 v22, 0, v22
	v_max_f32_e32 v18, 0, v18
	v_max_f32_e32 v23, 0, v23
	v_max_f32_e32 v19, 0, v19
	v_max_f32_e32 v24, 0, v24
	v_max_f32_e32 v20, 0, v20
	v_max_f32_e32 v25, 0, v25
	v_max_f32_e32 v21, 0, v21
	v_lshl_add_u64 v[44:45], v[42:43], 0, v[140:141]
	v_cndmask_b32_e64 v37, v37, v35, s[6:7]
	v_cndmask_b32_e64 v36, v36, v34, s[6:7]
	v_cndmask_b32_e64 v35, v41, v39, s[6:7]
	v_cndmask_b32_e64 v34, v40, v38, s[6:7]
	v_cndmask_b32_e64 v41, v49, v53, s[6:7]
	v_cndmask_b32_e64 v40, v48, v52, s[6:7]
	v_cndmask_b32_e64 v39, v47, v51, s[6:7]
	v_cndmask_b32_e64 v38, v46, v50, s[6:7]
	v_pk_mul_f32 v[30:31], v[30:31], v[30:31]
	v_pk_mul_f32 v[26:27], v[26:27], v[26:27]
	v_pk_mul_f32 v[32:33], v[32:33], v[32:33]
	v_pk_mul_f32 v[28:29], v[28:29], v[28:29]
	v_pk_mul_f32 v[22:23], v[22:23], v[22:23]
	v_pk_mul_f32 v[18:19], v[18:19], v[18:19]
	v_pk_mul_f32 v[24:25], v[24:25], v[24:25]
	v_pk_mul_f32 v[20:21], v[20:21], v[20:21]
	v_lshl_add_u64 v[42:43], v[42:43], 0, v[142:143]
	global_store_dwordx4 v[44:45], v[38:41], off
	global_store_dwordx4 v[42:43], v[34:37], off
	v_cvt_pk_bf16_f32 v30, v30, v31
	v_cvt_pk_bf16_f32 v31, v32, v33
	v_lshl_add_u64 v[34:35], s[22:23], 0, v[156:157]
	v_cvt_pk_bf16_f32 v32, v26, v27
; __device__ __forceinline__ unsigned pk2(float lo, float hi) { const f32x2 v = {lo, hi}; return __builtin_bit_cast(unsigned, __builtin_convertvector(v, bf16x2_t)); }
; #define PG8_BAR __builtin_amdgcn_s_barrier()
; template <class Epi, class Sched, bool ABLK = false, bool ALIGN_EPI = true, bool SP2 = true, bool BBLK = true>
; __device__ __forceinline__ void gemm_phase(LAS unsigned char* lds, const Gemm g, const Sched& S, const Epi& E) {
;     ...
;         if constexpr (ALIGN_EPI) { if (wr == 0) PG8_BAR; }
;         E(acc, cur, wr, wc, fr, fq); S.done(cur);
;         if (!has_next) break;
; #pragma unroll
;         for (int a = 0; a < 2; ++a)
; #pragma unroll
;             for (int b = 0; b < 2; ++b)
; #pragma unroll
;                 for (int m = 0; m < 4; ++m)
; #pragma unroll
;                     for (int n = 0; n < 2; ++n) acc[a][b][m][n] = (f32x4){0.f, 0.f, 0.f, 0.f};
;         cur = nxt; uA = nuA; tbA = ntbA; cB = nB; ++ui;
;         if constexpr (ALIGN_EPI) { if (wr == 1) PG8_BAR; }
;     __device__ __forceinline__ void operator()(const f32x4 (&acc)[2][2][4][2], const Unit& u, int wr, int wc, int fr, int fq) const {
; #pragma unroll
;         for (int ai = 0; ai < 2; ++ai)
; #pragma unroll
;             for (int m = 0; m < 4; ++m) { unsigned char* rowp = (unsigned char*)(H + ((size_t)(u.pm * (FF / 64) + u.pn * 4 + wc) * 256 + (wr * 64 + fr + ai * 128 + m * 16)) * 64 + 8 * fq); u32x4 w[2];
; #pragma unroll
;                 for (int bj = 0; bj < 2; ++bj) { f32x4 v0 = acc[ai][bj][m][0], v1 = acc[ai][bj][m][1];
; #pragma unroll
;                     for (int j = 0; j < 4; ++j) { const float a = fmaxf(v0[j], 0.f), b = fmaxf(v1[j], 0.f); v0[j] = a * a; v1[j] = b * b; }
;                     w[bj].x = pk2(v0[0], v0[1]); w[bj].y = pk2(v0[2], v0[3]); w[bj].z = pk2(v1[0], v1[1]); w[bj].w = pk2(v1[2], v1[3]); }
;                 store_pair(rowp, (size_t)8 * 64 * 2, 64, w[0], w[1], fr >= 8); }
	v_cvt_pk_bf16_f32 v33, v28, v29
	v_cvt_pk_bf16_f32 v22, v22, v23
	v_cvt_pk_bf16_f32 v23, v24, v25
	v_cvt_pk_bf16_f32 v18, v18, v19
	v_cvt_pk_bf16_f32 v19, v20, v21
	v_lshl_add_u64 v[26:27], v[34:35], 0, v[138:139]
	v_mov_b32_dpp v24, v30 row_ror:8 row_mask:0xf bank_mask:0xf bound_ctrl:1
	v_mov_b32_dpp v25, v31 row_ror:8 row_mask:0xf bank_mask:0xf bound_ctrl:1
	v_mov_b32_dpp v20, v32 row_ror:8 row_mask:0xf bank_mask:0xf bound_ctrl:1
	v_mov_b32_dpp v21, v33 row_ror:8 row_mask:0xf bank_mask:0xf bound_ctrl:1
	v_mov_b32_dpp v34, v22 row_ror:8 row_mask:0xf bank_mask:0xf bound_ctrl:1
	v_mov_b32_dpp v35, v23 row_ror:8 row_mask:0xf bank_mask:0xf bound_ctrl:1
	v_mov_b32_dpp v36, v18 row_ror:8 row_mask:0xf bank_mask:0xf bound_ctrl:1
	v_mov_b32_dpp v37, v19 row_ror:8 row_mask:0xf bank_mask:0xf bound_ctrl:1
	v_max_f32_e32 v14, 0, v14
	v_max_f32_e32 v10, 0, v10
	v_max_f32_e32 v15, 0, v15
	v_max_f32_e32 v11, 0, v11
	v_max_f32_e32 v16, 0, v16
	v_max_f32_e32 v12, 0, v12
	v_max_f32_e32 v17, 0, v17
	v_max_f32_e32 v13, 0, v13
	v_max_f32_e32 v6, 0, v6
	v_max_f32_e32 v2, 0, v2
	v_max_f32_e32 v7, 0, v7
	v_max_f32_e32 v3, 0, v3
	v_max_f32_e32 v8, 0, v8
	v_max_f32_e32 v4, 0, v4
	v_max_f32_e32 v9, 0, v9
	v_max_f32_e32 v5, 0, v5
	v_lshl_add_u64 v[28:29], v[26:27], 0, v[140:141]
	v_cndmask_b32_e64 v21, v21, v19, s[6:7]
	v_cndmask_b32_e64 v20, v20, v18, s[6:7]
	v_cndmask_b32_e64 v19, v25, v23, s[6:7]
	v_cndmask_b32_e64 v18, v24, v22, s[6:7]
	v_cndmask_b32_e64 v25, v33, v37, s[6:7]
	v_cndmask_b32_e64 v24, v32, v36, s[6:7]
	v_cndmask_b32_e64 v23, v31, v35, s[6:7]
	v_cndmask_b32_e64 v22, v30, v34, s[6:7]
	v_pk_mul_f32 v[14:15], v[14:15], v[14:15]
	v_pk_mul_f32 v[10:11], v[10:11], v[10:11]
	v_pk_mul_f32 v[16:17], v[16:17], v[16:17]
	v_pk_mul_f32 v[12:13], v[12:13], v[12:13]
	v_pk_mul_f32 v[6:7], v[6:7], v[6:7]
	v_pk_mul_f32 v[2:3], v[2:3], v[2:3]
	v_pk_mul_f32 v[8:9], v[8:9], v[8:9]
	v_pk_mul_f32 v[4:5], v[4:5], v[4:5]
	v_lshl_add_u64 v[26:27], v[26:27], 0, v[142:143]
	global_store_dwordx4 v[28:29], v[22:25], off
	global_store_dwordx4 v[26:27], v[18:21], off
	v_cvt_pk_bf16_f32 v14, v14, v15
	v_cvt_pk_bf16_f32 v15, v16, v17
	v_lshl_add_u64 v[18:19], s[22:23], 0, v[158:159]
	v_cvt_pk_bf16_f32 v16, v10, v11
	v_cvt_pk_bf16_f32 v17, v12, v13
	v_cvt_pk_bf16_f32 v6, v6, v7
	v_cvt_pk_bf16_f32 v7, v8, v9
	v_cvt_pk_bf16_f32 v2, v2, v3
	v_cvt_pk_bf16_f32 v3, v4, v5
	v_lshl_add_u64 v[10:11], v[18:19], 0, v[138:139]
	v_mov_b32_dpp v8, v14 row_ror:8 row_mask:0xf bank_mask:0xf bound_ctrl:1
	v_mov_b32_dpp v9, v15 row_ror:8 row_mask:0xf bank_mask:0xf bound_ctrl:1
	v_mov_b32_dpp v4, v16 row_ror:8 row_mask:0xf bank_mask:0xf bound_ctrl:1
	v_mov_b32_dpp v5, v17 row_ror:8 row_mask:0xf bank_mask:0xf bound_ctrl:1
	v_mov_b32_dpp v18, v6 row_ror:8 row_mask:0xf bank_mask:0xf bound_ctrl:1
	v_mov_b32_dpp v19, v7 row_ror:8 row_mask:0xf bank_mask:0xf bound_ctrl:1
	v_mov_b32_dpp v20, v2 row_ror:8 row_mask:0xf bank_mask:0xf bound_ctrl:1
	v_mov_b32_dpp v21, v3 row_ror:8 row_mask:0xf bank_mask:0xf bound_ctrl:1
	v_lshl_add_u64 v[12:13], v[10:11], 0, v[140:141]
	v_cndmask_b32_e64 v5, v5, v3, s[6:7]
	v_cndmask_b32_e64 v4, v4, v2, s[6:7]
	v_cndmask_b32_e64 v3, v9, v7, s[6:7]
	v_cndmask_b32_e64 v2, v8, v6, s[6:7]
	v_cndmask_b32_e64 v9, v17, v21, s[6:7]
	v_cndmask_b32_e64 v8, v16, v20, s[6:7]
	v_cndmask_b32_e64 v7, v15, v19, s[6:7]
	v_cndmask_b32_e64 v6, v14, v18, s[6:7]
	s_andn2_b64 vcc, exec, s[18:19]
	s_mov_b64 s[4:5], -1
	v_lshl_add_u64 v[10:11], v[10:11], 0, v[142:143]
	global_store_dwordx4 v[12:13], v[6:9], off
	global_store_dwordx4 v[10:11], v[2:5], off
	s_cbranch_vccnz .LBB0_471
	s_andn2_b64 vcc, exec, s[2:3]
	s_cbranch_vccnz .LBB0_470
	s_barrier
	s_branch .LBB0_470

; #define PG8_STAGE(bufoff, gbase, voff) do { _Pragma("unroll") for (int _i = 0; _i < 2; ++_i) \
;         __builtin_amdgcn_global_load_lds((const unsigned*)((const char*)(gbase) + (voff)[_i]), (LAS unsigned*)(lds + (bufoff) + ldsw + _i * 8192), 16, 0, 0); } while (0)
; #define PG8_LDA(dst, b, h) do { _Pragma("unroll") for (int m = 0; m < 4; ++m) _Pragma("unroll") for (int k = 0; k < 2; ++k) dst[m][k] = *(const LAS bf16x8*)(lds + PG8_SA(b, h) + aoff + m * 2048 + k * 1024); } while (0)
; #define PG8_WAIT_V(n) asm volatile("s_waitcnt vmcnt(" #n ")" ::: "memory")
; #define PG8_WAIT_L(n) asm volatile("s_waitcnt lgkmcnt(" #n ")" ::: "memory")
; #define PG8_BAR __builtin_amdgcn_s_barrier()
; template <class Epi, class Sched, bool ABLK = false, bool ALIGN_EPI = true, bool SP2 = true, bool BBLK = true>
; __device__ __forceinline__ void gemm_phase(LAS unsigned char* lds, const Gemm g, const Sched& S, const Epi& E) {
;     ...
;     f32x4 acc[2][2][4][2];
; #pragma unroll
;     for (int a = 0; a < 2; ++a)
; #pragma unroll
;         for (int b = 0; b < 2; ++b)
; #pragma unroll
;             for (int m = 0; m < 4; ++m)
; #pragma unroll
;                 for (int n = 0; n < 2; ++n) acc[a][b][m][n] = (f32x4){0.f, 0.f, 0.f, 0.f};
;     ...
;         const bool has_next = S.next(ui + 1, nxt);
;         const int nt = cur.nt;
;         const char* nuA = has_next ? a_unit(nxt) : uA; const int ntbA = has_next ? nxt.k0 / BK : tbA; const char* nB = has_next ? (const char*)g.Bt + (size_t)nxt.pn * tstepB + b_k0(nxt.k0) : cB;
;         for (int t = 0; t < nt; t += 2) {
;             const bool last = (t == nt - 2);
;             const char* a1 = a_tile(uA, tbA + t + 1);
;             const char* a2 = last ? a_tile(nuA, ntbA) : a_tile(uA, tbA + t + 2); const char* b2 = last ? nB : cB + (size_t)(t + 2) * kstepB;
;             const char* a3 = last ? a_tile(nuA, ntbA + 1) : a_tile(uA, tbA + t + 3); const char* b3 = b2 + kstepB;
;             if (last && has_next) S.a_ready(nxt);
;             if constexpr (SP2) {
;             PG8_LDB(B0, 0, 0); PG8_LDB(B1, 0, 1); PG8_SCHED; PG8_LDA(At, 0, 0); PG8_STAGE(PG8_SA(1, 1), a1 + hstepA, voffA);
;             PG8_WAIT_V(8); PG8_WAIT_L(0); PG8_BAR; PG8_MMA(0, 0, At, B0); PG8_MMA(0, 1, At, B1); PG8_BAR; PG8_SCHED;
;             PG8_LDA(At, 0, 1); PG8_STAGE(PG8_SB(0, 0), b2, voffB); PG8_STAGE(PG8_SB(0, 1), b2 + hstepB, voffB); PG8_STAGE(PG8_SA(0, 0), a2, voffA);
.LBB0_539:
	s_ashr_i32 s81, s80, 31
	s_andn2_b64 vcc, exec, s[4:5]
	s_lshl_b64 s[30:31], s[80:81], 22
	s_add_u32 s30, s1, s30
	s_addc_u32 s31, s33, s31
	s_and_b64 s[34:35], s[4:5], exec
	s_cselect_b32 s47, s31, s43
	s_cselect_b32 s60, s30, s42
	s_ashr_i32 s34, s0, 31
	s_lshr_b32 s34, s34, 26
	s_add_i32 s34, s0, s34
	s_ashr_i32 s34, s34, 6
	s_and_b64 s[36:37], s[4:5], exec
	s_cselect_b32 s48, s34, s46
	s_ashr_i32 s79, s78, 31
	s_lshl_b64 s[36:37], s[78:79], 22
	s_add_u32 s49, s39, s36
	s_addc_u32 s61, s50, s37
	s_ashr_i32 s35, s34, 31
	s_lshl_b64 s[36:37], s[34:35], 15
	s_add_u32 s36, s49, s36
	s_addc_u32 s37, s61, s37
	v_cndmask_b32_e64 v2, 0, 1, s[4:5]
	s_and_b64 s[4:5], s[4:5], exec
	s_cselect_b32 s4, s37, s41
	s_cselect_b32 s5, s36, s40
	s_ashr_i32 s49, s48, 31
	s_lshl_b64 s[48:49], s[48:49], 15
	s_add_u32 s35, s60, s48
	s_addc_u32 s63, s47, s49
	s_add_u32 s64, s35, 0x8000
	s_addc_u32 s65, s63, 0
	s_add_u32 s66, s40, 0x10000
	s_addc_u32 s67, s41, 0
	s_ashr_i32 s47, s46, 31
	v_cmp_ne_u32_e64 s[8:9], 1, v2
	s_lshl_b64 s[40:41], s[46:47], 15
	v_lshl_add_u64 v[2:3], s[42:43], 0, v[138:139]
	s_add_u32 s75, s42, s40
	v_lshl_add_u64 v[142:143], v[2:3], 0, s[40:41]
	v_lshl_add_u64 v[2:3], s[42:43], 0, v[140:141]
	s_addc_u32 s76, s43, s41
	v_lshl_add_u64 v[144:145], v[2:3], 0, s[40:41]
	s_lshl_b32 s40, s59, 15
	s_add_i32 s40, s40, 0xfff00000
	v_mov_b32_e32 v2, 0
	s_add_u32 s77, s40, 0xf0000
	s_mov_b32 s79, 0
	s_mov_b64 s[40:41], 0
	ds_read_b128 v[152:155], v148
	ds_read_b128 v[156:159], v148 offset:1024
	ds_read_b128 v[160:163], v148 offset:2048
	ds_read_b128 v[164:167], v148 offset:3072
	ds_read_b128 v[168:171], v149
	ds_read_b128 v[172:175], v149 offset:1024
	ds_read_b128 v[176:179], v149 offset:2048
	ds_read_b128 v[180:183], v149 offset:3072
	s_add_u32 s42, s75, s40
	s_addc_u32 s43, s76, s41
	s_add_u32 s48, s42, 0x10000
	s_addc_u32 s49, s43, 0
	s_add_i32 s79, s79, 2
	s_add_u32 s46, s66, s40
	s_addc_u32 s47, s67, s41
	s_add_u32 s42, s42, 0x18000
	s_addc_u32 s43, s43, 0
	s_cmp_eq_u32 s77, s40
	s_cselect_b32 s43, s65, s43
	s_cselect_b32 s42, s64, s42
	s_cselect_b32 s47, s4, s47
	s_cselect_b32 s46, s5, s46
	s_cselect_b32 s49, s63, s49
	s_cselect_b32 s48, s35, s48
	v_lshl_add_u64 v[216:217], v[142:143], 0, s[40:41]
	s_add_i32 m0, s52, 0xc000
	ds_read_b128 v[184:187], v150
	ds_read_b128 v[188:191], v150 offset:1024
	ds_read_b128 v[192:195], v150 offset:2048
	ds_read_b128 v[196:199], v150 offset:3072
	ds_read_b128 v[200:203], v150 offset:4096
	ds_read_b128 v[204:207], v150 offset:5120
	ds_read_b128 v[208:211], v150 offset:6144
	ds_read_b128 v[212:215], v150 offset:7168
	global_load_lds_dwordx4 v[216:217], off
	v_lshl_add_u64 v[216:217], v[144:145], 0, s[40:41]
	s_add_i32 m0, s52, 0xe000
	s_nop 0
	global_load_lds_dwordx4 v[216:217], off
	s_waitcnt vmcnt(8)
	s_waitcnt lgkmcnt(0)
	s_barrier
	v_mfma_f32_16x16x32_bf16 v[126:129], v[152:155], v[184:187], 0
	v_mfma_f32_16x16x32_bf16 v[122:125], v[160:163], v[184:187], 0
	v_mfma_f32_16x16x32_bf16 v[110:113], v[152:155], v[192:195], 0
	v_mfma_f32_16x16x32_bf16 v[106:109], v[160:163], v[192:195], 0
	v_mfma_f32_16x16x32_bf16 v[94:97], v[152:155], v[200:203], 0
	v_mfma_f32_16x16x32_bf16 v[90:93], v[160:163], v[200:203], 0
	v_mfma_f32_16x16x32_bf16 v[78:81], v[152:155], v[208:211], 0
	v_mfma_f32_16x16x32_bf16 v[74:77], v[160:163], v[208:211], 0
	v_mfma_f32_16x16x32_bf16 v[126:129], v[156:159], v[188:191], v[126:129]
	v_mfma_f32_16x16x32_bf16 v[122:125], v[164:167], v[188:191], v[122:125]
	v_mfma_f32_16x16x32_bf16 v[110:113], v[156:159], v[196:199], v[110:113]
	v_mfma_f32_16x16x32_bf16 v[106:109], v[164:167], v[196:199], v[106:109]
	v_mfma_f32_16x16x32_bf16 v[94:97], v[156:159], v[204:207], v[94:97]
	v_mfma_f32_16x16x32_bf16 v[90:93], v[164:167], v[204:207], v[90:93]
	v_mfma_f32_16x16x32_bf16 v[78:81], v[156:159], v[212:215], v[78:81]
	v_mfma_f32_16x16x32_bf16 v[74:77], v[164:167], v[212:215], v[74:77]
	v_mfma_f32_16x16x32_bf16 v[118:121], v[168:171], v[184:187], 0
	v_mfma_f32_16x16x32_bf16 v[114:117], v[176:179], v[184:187], 0
	v_mfma_f32_16x16x32_bf16 v[102:105], v[168:171], v[192:195], 0
	v_mfma_f32_16x16x32_bf16 v[98:101], v[176:179], v[192:195], 0
	v_mfma_f32_16x16x32_bf16 v[86:89], v[168:171], v[200:203], 0
	v_mfma_f32_16x16x32_bf16 v[82:85], v[176:179], v[200:203], 0
	v_mfma_f32_16x16x32_bf16 v[70:73], v[168:171], v[208:211], 0
	v_mfma_f32_16x16x32_bf16 v[66:69], v[176:179], v[208:211], 0
	v_mfma_f32_16x16x32_bf16 v[118:121], v[172:175], v[188:191], v[118:121]
	v_mfma_f32_16x16x32_bf16 v[114:117], v[180:183], v[188:191], v[114:117]
	v_mfma_f32_16x16x32_bf16 v[102:105], v[172:175], v[196:199], v[102:105]
	v_mfma_f32_16x16x32_bf16 v[98:101], v[180:183], v[196:199], v[98:101]
	v_mfma_f32_16x16x32_bf16 v[86:89], v[172:175], v[204:207], v[86:89]
	v_mfma_f32_16x16x32_bf16 v[82:85], v[180:183], v[204:207], v[82:85]
	v_mfma_f32_16x16x32_bf16 v[70:73], v[172:175], v[212:215], v[70:73]
	v_mfma_f32_16x16x32_bf16 v[66:69], v[180:183], v[212:215], v[66:69]
	s_barrier
	s_add_i32 s60, s72, s51
	v_lshl_add_u64 v[216:217], s[46:47], 0, v[130:131]
	s_mov_b32 m0, s60
	ds_read_b128 v[184:187], v150 offset:16384
	ds_read_b128 v[188:191], v150 offset:17408
	ds_read_b128 v[192:195], v150 offset:18432
	ds_read_b128 v[196:199], v150 offset:19456
	ds_read_b128 v[200:203], v150 offset:20480
	ds_read_b128 v[204:207], v150 offset:21504
	ds_read_b128 v[208:211], v150 offset:22528
	ds_read_b128 v[212:215], v150 offset:23552
	global_load_lds_dwordx4 v[216:217], off
	s_add_i32 m0, s60, 0x2000
	s_add_u32 s60, s46, 0x4000
	v_lshl_add_u64 v[216:217], s[46:47], 0, v[132:133]
	s_addc_u32 s61, s47, 0
	s_add_i32 s81, s73, s51
	global_load_lds_dwordx4 v[216:217], off
	v_lshl_add_u64 v[216:217], s[60:61], 0, v[130:131]
	s_mov_b32 m0, s81
	s_nop 0
	global_load_lds_dwordx4 v[216:217], off
	v_lshl_add_u64 v[216:217], s[60:61], 0, v[132:133]
	s_add_i32 m0, s81, 0x2000
	s_nop 0
	global_load_lds_dwordx4 v[216:217], off
	v_lshl_add_u64 v[216:217], s[48:49], 0, v[130:131]
	s_mov_b32 m0, s52
	s_nop 0
	global_load_lds_dwordx4 v[216:217], off
	v_lshl_add_u64 v[216:217], s[48:49], 0, v[132:133]
	s_mov_b32 m0, s53
	s_nop 0
	global_load_lds_dwordx4 v[216:217], off
	s_waitcnt vmcnt(8)
	s_waitcnt lgkmcnt(0)
	s_barrier
; #define PG8_STAGE(bufoff, gbase, voff) do { _Pragma("unroll") for (int _i = 0; _i < 2; ++_i) \
;         __builtin_amdgcn_global_load_lds((const unsigned*)((const char*)(gbase) + (voff)[_i]), (LAS unsigned*)(lds + (bufoff) + ldsw + _i * 8192), 16, 0, 0); } while (0)
; #define PG8_LDA(dst, b, h) do { _Pragma("unroll") for (int m = 0; m < 4; ++m) _Pragma("unroll") for (int k = 0; k < 2; ++k) dst[m][k] = *(const LAS bf16x8*)(lds + PG8_SA(b, h) + aoff + m * 2048 + k * 1024); } while (0)
; #define PG8_LDB(dst, b, h) do { _Pragma("unroll") for (int n = 0; n < 2; ++n) _Pragma("unroll") for (int k = 0; k < 2; ++k) dst[n][k] = *(const LAS bf16x8*)(lds + PG8_SB(b, h) + boff + n * 2048 + k * 1024); } while (0)
; #define PG8_MMA(ai, bj, At, Bt) do { __builtin_amdgcn_s_setprio(1); _Pragma("unroll") for (int m = 0; m < 4; ++m) _Pragma("unroll") for (int n = 0; n < 2; ++n) _Pragma("unroll") for (int k = 0; k < 2; ++k) \
;         acc[ai][bj][m][n] = __builtin_amdgcn_mfma_f32_16x16x32_bf16(Bt[n][k], At[m][k], acc[ai][bj][m][n], 0, 0, 0); __builtin_amdgcn_s_setprio(0); } while (0)
; #define PG8_WAIT_V(n) asm volatile("s_waitcnt vmcnt(" #n ")" ::: "memory")
; #define PG8_WAIT_L(n) asm volatile("s_waitcnt lgkmcnt(" #n ")" ::: "memory")
; #define PG8_BAR __builtin_amdgcn_s_barrier()
; #define PG8_SCHED __builtin_amdgcn_sched_barrier(0)
; template <class Epi, class Sched, bool ABLK = false, bool ALIGN_EPI = true, bool SP2 = true, bool BBLK = true>
; __device__ __forceinline__ void gemm_phase(LAS unsigned char* lds, const Gemm g, const Sched& S, const Epi& E) {
;     ...
;             PG8_WAIT_V(8); PG8_WAIT_L(0); PG8_BAR; PG8_MMA(1, 0, At, B0); PG8_MMA(1, 1, At, B1); PG8_BAR; PG8_SCHED;
;             PG8_LDB(B0, 1, 0); PG8_LDB(B1, 1, 1); PG8_SCHED; PG8_LDA(At, 1, 0); PG8_STAGE(PG8_SA(0, 1), a2 + hstepA, voffA);
;             PG8_WAIT_V(8); PG8_WAIT_L(0); PG8_BAR; PG8_MMA(0, 0, At, B0); PG8_MMA(0, 1, At, B1); PG8_BAR; PG8_SCHED;
	v_mfma_f32_16x16x32_bf16 v[62:65], v[152:155], v[184:187], 0
	v_mfma_f32_16x16x32_bf16 v[58:61], v[160:163], v[184:187], 0
	v_mfma_f32_16x16x32_bf16 v[46:49], v[152:155], v[192:195], 0
	v_mfma_f32_16x16x32_bf16 v[42:45], v[160:163], v[192:195], 0
	v_mfma_f32_16x16x32_bf16 v[30:33], v[152:155], v[200:203], 0
	v_mfma_f32_16x16x32_bf16 v[26:29], v[160:163], v[200:203], 0
	v_mfma_f32_16x16x32_bf16 v[14:17], v[152:155], v[208:211], 0
	v_mfma_f32_16x16x32_bf16 v[10:13], v[160:163], v[208:211], 0
	v_mfma_f32_16x16x32_bf16 v[62:65], v[156:159], v[188:191], v[62:65]
	v_mfma_f32_16x16x32_bf16 v[58:61], v[164:167], v[188:191], v[58:61]
	v_mfma_f32_16x16x32_bf16 v[46:49], v[156:159], v[196:199], v[46:49]
	v_mfma_f32_16x16x32_bf16 v[42:45], v[164:167], v[196:199], v[42:45]
	v_mfma_f32_16x16x32_bf16 v[30:33], v[156:159], v[204:207], v[30:33]
	v_mfma_f32_16x16x32_bf16 v[26:29], v[164:167], v[204:207], v[26:29]
	v_mfma_f32_16x16x32_bf16 v[14:17], v[156:159], v[212:215], v[14:17]
	v_mfma_f32_16x16x32_bf16 v[10:13], v[164:167], v[212:215], v[10:13]
	v_mfma_f32_16x16x32_bf16 v[54:57], v[168:171], v[184:187], 0
	v_mfma_f32_16x16x32_bf16 v[50:53], v[176:179], v[184:187], 0
	v_mfma_f32_16x16x32_bf16 v[38:41], v[168:171], v[192:195], 0
	v_mfma_f32_16x16x32_bf16 v[34:37], v[176:179], v[192:195], 0
	v_mfma_f32_16x16x32_bf16 v[22:25], v[168:171], v[200:203], 0
	v_mfma_f32_16x16x32_bf16 v[18:21], v[176:179], v[200:203], 0
	v_mfma_f32_16x16x32_bf16 v[6:9], v[168:171], v[208:211], 0
	v_mfma_f32_16x16x32_bf16 v[2:5], v[176:179], v[208:211], 0
	v_mfma_f32_16x16x32_bf16 v[54:57], v[172:175], v[188:191], v[54:57]
	v_mfma_f32_16x16x32_bf16 v[50:53], v[180:183], v[188:191], v[50:53]
	v_mfma_f32_16x16x32_bf16 v[38:41], v[172:175], v[196:199], v[38:41]
	v_mfma_f32_16x16x32_bf16 v[34:37], v[180:183], v[196:199], v[34:37]
	v_mfma_f32_16x16x32_bf16 v[22:25], v[172:175], v[204:207], v[22:25]
	v_mfma_f32_16x16x32_bf16 v[18:21], v[180:183], v[204:207], v[18:21]
	v_mfma_f32_16x16x32_bf16 v[6:9], v[172:175], v[212:215], v[6:9]
	v_mfma_f32_16x16x32_bf16 v[2:5], v[180:183], v[212:215], v[2:5]
	s_barrier
	s_add_i32 s60, 0, 0x18000
	v_add_u32_e32 v151, s60, v146
	s_add_i32 s61, 0, 0x1c000
	ds_read_b128 v[152:155], v151
	ds_read_b128 v[156:159], v151 offset:1024
	ds_read_b128 v[160:163], v151 offset:2048
	ds_read_b128 v[164:167], v151 offset:3072
	v_add_u32_e32 v151, s61, v146
	ds_read_b128 v[168:171], v151
	ds_read_b128 v[172:175], v151 offset:1024
	ds_read_b128 v[176:179], v151 offset:2048
	ds_read_b128 v[180:183], v151 offset:3072
	s_add_u32 s48, s48, 0x4000
	s_addc_u32 s49, s49, 0
	s_mov_b32 m0, s54
	v_lshl_add_u64 v[216:217], s[48:49], 0, v[130:131]
	ds_read_b128 v[184:187], v150 offset:32768
	ds_read_b128 v[188:191], v150 offset:33792
	ds_read_b128 v[192:195], v150 offset:34816
	ds_read_b128 v[196:199], v150 offset:35840
	ds_read_b128 v[200:203], v150 offset:36864
	ds_read_b128 v[204:207], v150 offset:37888
	ds_read_b128 v[208:211], v150 offset:38912
	ds_read_b128 v[212:215], v150 offset:39936
	global_load_lds_dwordx4 v[216:217], off
	v_lshl_add_u64 v[216:217], s[48:49], 0, v[132:133]
	s_mov_b32 m0, s55
	s_nop 0
	global_load_lds_dwordx4 v[216:217], off
	s_waitcnt vmcnt(8)
	s_waitcnt lgkmcnt(0)
	s_barrier
	v_mfma_f32_16x16x32_bf16 v[126:129], v[152:155], v[184:187], v[126:129]
	v_mfma_f32_16x16x32_bf16 v[122:125], v[160:163], v[184:187], v[122:125]
	v_mfma_f32_16x16x32_bf16 v[110:113], v[152:155], v[192:195], v[110:113]
	v_mfma_f32_16x16x32_bf16 v[106:109], v[160:163], v[192:195], v[106:109]
	v_mfma_f32_16x16x32_bf16 v[94:97], v[152:155], v[200:203], v[94:97]
	v_mfma_f32_16x16x32_bf16 v[90:93], v[160:163], v[200:203], v[90:93]
	v_mfma_f32_16x16x32_bf16 v[78:81], v[152:155], v[208:211], v[78:81]
	v_mfma_f32_16x16x32_bf16 v[74:77], v[160:163], v[208:211], v[74:77]
	v_mfma_f32_16x16x32_bf16 v[126:129], v[156:159], v[188:191], v[126:129]
	v_mfma_f32_16x16x32_bf16 v[122:125], v[164:167], v[188:191], v[122:125]
	v_mfma_f32_16x16x32_bf16 v[110:113], v[156:159], v[196:199], v[110:113]
	v_mfma_f32_16x16x32_bf16 v[106:109], v[164:167], v[196:199], v[106:109]
	v_mfma_f32_16x16x32_bf16 v[94:97], v[156:159], v[204:207], v[94:97]
	v_mfma_f32_16x16x32_bf16 v[90:93], v[164:167], v[204:207], v[90:93]
	v_mfma_f32_16x16x32_bf16 v[78:81], v[156:159], v[212:215], v[78:81]
	v_mfma_f32_16x16x32_bf16 v[74:77], v[164:167], v[212:215], v[74:77]
	v_mfma_f32_16x16x32_bf16 v[118:121], v[168:171], v[184:187], v[118:121]
	v_mfma_f32_16x16x32_bf16 v[114:117], v[176:179], v[184:187], v[114:117]
	v_mfma_f32_16x16x32_bf16 v[102:105], v[168:171], v[192:195], v[102:105]
	v_mfma_f32_16x16x32_bf16 v[98:101], v[176:179], v[192:195], v[98:101]
	v_mfma_f32_16x16x32_bf16 v[86:89], v[168:171], v[200:203], v[86:89]
	v_mfma_f32_16x16x32_bf16 v[82:85], v[176:179], v[200:203], v[82:85]
	v_mfma_f32_16x16x32_bf16 v[70:73], v[168:171], v[208:211], v[70:73]
	v_mfma_f32_16x16x32_bf16 v[66:69], v[176:179], v[208:211], v[66:69]
	v_mfma_f32_16x16x32_bf16 v[118:121], v[172:175], v[188:191], v[118:121]
	v_mfma_f32_16x16x32_bf16 v[114:117], v[180:183], v[188:191], v[114:117]
	v_mfma_f32_16x16x32_bf16 v[102:105], v[172:175], v[196:199], v[102:105]
	v_mfma_f32_16x16x32_bf16 v[98:101], v[180:183], v[196:199], v[98:101]
	v_mfma_f32_16x16x32_bf16 v[86:89], v[172:175], v[204:207], v[86:89]
	v_mfma_f32_16x16x32_bf16 v[82:85], v[180:183], v[204:207], v[82:85]
	v_mfma_f32_16x16x32_bf16 v[70:73], v[172:175], v[212:215], v[70:73]
	v_mfma_f32_16x16x32_bf16 v[66:69], v[180:183], v[212:215], v[66:69]
	s_barrier
; #define PG8_STAGE(bufoff, gbase, voff) do { _Pragma("unroll") for (int _i = 0; _i < 2; ++_i) \
;         __builtin_amdgcn_global_load_lds((const unsigned*)((const char*)(gbase) + (voff)[_i]), (LAS unsigned*)(lds + (bufoff) + ldsw + _i * 8192), 16, 0, 0); } while (0)
; #define PG8_LDA(dst, b, h) do { _Pragma("unroll") for (int m = 0; m < 4; ++m) _Pragma("unroll") for (int k = 0; k < 2; ++k) dst[m][k] = *(const LAS bf16x8*)(lds + PG8_SA(b, h) + aoff + m * 2048 + k * 1024); } while (0)
; #define PG8_WAIT_V(n) asm volatile("s_waitcnt vmcnt(" #n ")" ::: "memory")
; #define PG8_WAIT_L(n) asm volatile("s_waitcnt lgkmcnt(" #n ")" ::: "memory")
; template <class Epi, class Sched, bool ABLK = false, bool ALIGN_EPI = true, bool SP2 = true, bool BBLK = true>
; __device__ __forceinline__ void gemm_phase(LAS unsigned char* lds, const Gemm g, const Sched& S, const Epi& E) {
;     ...
;         for (int t = 0; t < nt; t += 2) {
;             const bool last = (t == nt - 2);
;             const char* a1 = a_tile(uA, tbA + t + 1);
;             const char* a2 = last ? a_tile(nuA, ntbA) : a_tile(uA, tbA + t + 2); const char* b2 = last ? nB : cB + (size_t)(t + 2) * kstepB;
;             const char* a3 = last ? a_tile(nuA, ntbA + 1) : a_tile(uA, tbA + t + 3); const char* b3 = b2 + kstepB;
;             if (last && has_next) S.a_ready(nxt);
;             if constexpr (SP2) {
;             PG8_LDB(B0, 0, 0); PG8_LDB(B1, 0, 1); PG8_SCHED; PG8_LDA(At, 0, 0); PG8_STAGE(PG8_SA(1, 1), a1 + hstepA, voffA);
;             PG8_WAIT_V(8); PG8_WAIT_L(0); PG8_BAR; PG8_MMA(0, 0, At, B0); PG8_MMA(0, 1, At, B1); PG8_BAR; PG8_SCHED;
;             PG8_LDA(At, 0, 1); PG8_STAGE(PG8_SB(0, 0), b2, voffB); PG8_STAGE(PG8_SB(0, 1), b2 + hstepB, voffB); PG8_STAGE(PG8_SA(0, 0), a2, voffA);
;             PG8_WAIT_V(8); PG8_WAIT_L(0); PG8_BAR; PG8_MMA(1, 0, At, B0); PG8_MMA(1, 1, At, B1); PG8_BAR; PG8_SCHED;
;             PG8_LDB(B0, 1, 0); PG8_LDB(B1, 1, 1); PG8_SCHED; PG8_LDA(At, 1, 0); PG8_STAGE(PG8_SA(0, 1), a2 + hstepA, voffA);
;             PG8_WAIT_V(8); PG8_WAIT_L(0); PG8_BAR; PG8_MMA(0, 0, At, B0); PG8_MMA(0, 1, At, B1); PG8_BAR; PG8_SCHED;
;             PG8_LDA(At, 1, 1); PG8_STAGE(PG8_SB(1, 0), b3, voffB); PG8_STAGE(PG8_SB(1, 1), b3 + hstepB, voffB); PG8_STAGE(PG8_SA(1, 0), a3, voffA);
;             PG8_WAIT_V(8); PG8_WAIT_L(0); PG8_BAR; PG8_MMA(1, 0, At, B0); PG8_MMA(1, 1, At, B1); PG8_BAR; PG8_SCHED;
	s_add_u32 s48, s46, 0x8000
	s_addc_u32 s49, s47, 0
	s_add_i32 s81, s60, s51
	v_lshl_add_u64 v[216:217], s[48:49], 0, v[130:131]
	s_mov_b32 m0, s81
	ds_read_b128 v[184:187], v150 offset:49152
	ds_read_b128 v[188:191], v150 offset:50176
	ds_read_b128 v[192:195], v150 offset:51200
	ds_read_b128 v[196:199], v150 offset:52224
	ds_read_b128 v[200:203], v150 offset:53248
	ds_read_b128 v[204:207], v150 offset:54272
	ds_read_b128 v[208:211], v150 offset:55296
	ds_read_b128 v[212:215], v150 offset:56320
	global_load_lds_dwordx4 v[216:217], off
	s_add_i32 m0, s81, 0x2000
	s_add_u32 s46, s46, 0xc000
	v_lshl_add_u64 v[216:217], s[48:49], 0, v[132:133]
	s_addc_u32 s47, s47, 0
	s_add_i32 s48, s61, s51
	global_load_lds_dwordx4 v[216:217], off
	v_lshl_add_u64 v[216:217], s[46:47], 0, v[130:131]
	s_mov_b32 m0, s48
	s_nop 0
	global_load_lds_dwordx4 v[216:217], off
	v_lshl_add_u64 v[216:217], s[46:47], 0, v[132:133]
	s_add_i32 m0, s48, 0x2000
	s_nop 0
	global_load_lds_dwordx4 v[216:217], off
	v_lshl_add_u64 v[216:217], s[42:43], 0, v[130:131]
	s_mov_b32 m0, s56
	s_nop 0
	global_load_lds_dwordx4 v[216:217], off
	v_lshl_add_u64 v[216:217], s[42:43], 0, v[132:133]
	s_mov_b32 m0, s57
	s_nop 0
	global_load_lds_dwordx4 v[216:217], off
	s_waitcnt vmcnt(8)
	s_waitcnt lgkmcnt(0)
	s_barrier
	v_mfma_f32_16x16x32_bf16 v[62:65], v[152:155], v[184:187], v[62:65]
	v_mfma_f32_16x16x32_bf16 v[58:61], v[160:163], v[184:187], v[58:61]
	v_mfma_f32_16x16x32_bf16 v[46:49], v[152:155], v[192:195], v[46:49]
	v_mfma_f32_16x16x32_bf16 v[42:45], v[160:163], v[192:195], v[42:45]
	v_mfma_f32_16x16x32_bf16 v[30:33], v[152:155], v[200:203], v[30:33]
	v_mfma_f32_16x16x32_bf16 v[26:29], v[160:163], v[200:203], v[26:29]
	v_mfma_f32_16x16x32_bf16 v[14:17], v[152:155], v[208:211], v[14:17]
	v_mfma_f32_16x16x32_bf16 v[10:13], v[160:163], v[208:211], v[10:13]
	v_mfma_f32_16x16x32_bf16 v[62:65], v[156:159], v[188:191], v[62:65]
	v_mfma_f32_16x16x32_bf16 v[58:61], v[164:167], v[188:191], v[58:61]
	v_mfma_f32_16x16x32_bf16 v[46:49], v[156:159], v[196:199], v[46:49]
	v_mfma_f32_16x16x32_bf16 v[42:45], v[164:167], v[196:199], v[42:45]
	v_mfma_f32_16x16x32_bf16 v[30:33], v[156:159], v[204:207], v[30:33]
	v_mfma_f32_16x16x32_bf16 v[26:29], v[164:167], v[204:207], v[26:29]
	v_mfma_f32_16x16x32_bf16 v[14:17], v[156:159], v[212:215], v[14:17]
	v_mfma_f32_16x16x32_bf16 v[10:13], v[164:167], v[212:215], v[10:13]
	v_mfma_f32_16x16x32_bf16 v[54:57], v[168:171], v[184:187], v[54:57]
	v_mfma_f32_16x16x32_bf16 v[50:53], v[176:179], v[184:187], v[50:53]
	v_mfma_f32_16x16x32_bf16 v[38:41], v[168:171], v[192:195], v[38:41]
	v_mfma_f32_16x16x32_bf16 v[34:37], v[176:179], v[192:195], v[34:37]
	v_mfma_f32_16x16x32_bf16 v[22:25], v[168:171], v[200:203], v[22:25]
	v_mfma_f32_16x16x32_bf16 v[18:21], v[176:179], v[200:203], v[18:21]
	v_mfma_f32_16x16x32_bf16 v[6:9], v[168:171], v[208:211], v[6:9]
	v_mfma_f32_16x16x32_bf16 v[2:5], v[176:179], v[208:211], v[2:5]
	v_mfma_f32_16x16x32_bf16 v[54:57], v[172:175], v[188:191], v[54:57]
	v_mfma_f32_16x16x32_bf16 v[50:53], v[180:183], v[188:191], v[50:53]
	v_mfma_f32_16x16x32_bf16 v[38:41], v[172:175], v[196:199], v[38:41]
	v_mfma_f32_16x16x32_bf16 v[34:37], v[180:183], v[196:199], v[34:37]
	v_mfma_f32_16x16x32_bf16 v[22:25], v[172:175], v[204:207], v[22:25]
	v_mfma_f32_16x16x32_bf16 v[18:21], v[180:183], v[204:207], v[18:21]
	v_mfma_f32_16x16x32_bf16 v[6:9], v[172:175], v[212:215], v[6:9]
	v_mfma_f32_16x16x32_bf16 v[2:5], v[180:183], v[212:215], v[2:5]
	s_barrier
	s_add_u32 s40, s40, 0x10000
	s_addc_u32 s41, s41, 0
	s_cmp_ge_u32 s79, s59

; #define PG8_STAGE(bufoff, gbase, voff) do { _Pragma("unroll") for (int _i = 0; _i < 2; ++_i) \
;         __builtin_amdgcn_global_load_lds((const unsigned*)((const char*)(gbase) + (voff)[_i]), (LAS unsigned*)(lds + (bufoff) + ldsw + _i * 8192), 16, 0, 0); } while (0)
; #define PG8_LDA(dst, b, h) do { _Pragma("unroll") for (int m = 0; m < 4; ++m) _Pragma("unroll") for (int k = 0; k < 2; ++k) dst[m][k] = *(const LAS bf16x8*)(lds + PG8_SA(b, h) + aoff + m * 2048 + k * 1024); } while (0)
; #define PG8_WAIT_V(n) asm volatile("s_waitcnt vmcnt(" #n ")" ::: "memory")
; #define PG8_WAIT_L(n) asm volatile("s_waitcnt lgkmcnt(" #n ")" ::: "memory")
; #define PG8_BAR __builtin_amdgcn_s_barrier()
; template <class Epi, class Sched, bool ABLK = false, bool ALIGN_EPI = true, bool SP2 = true, bool BBLK = true>
; __device__ __forceinline__ void gemm_phase(LAS unsigned char* lds, const Gemm g, const Sched& S, const Epi& E) {
;     ...
;     f32x4 acc[2][2][4][2];
; #pragma unroll
;     for (int a = 0; a < 2; ++a)
; #pragma unroll
;         for (int b = 0; b < 2; ++b)
; #pragma unroll
;             for (int m = 0; m < 4; ++m)
; #pragma unroll
;                 for (int n = 0; n < 2; ++n) acc[a][b][m][n] = (f32x4){0.f, 0.f, 0.f, 0.f};
;     ...
;         const bool has_next = S.next(ui + 1, nxt);
;         const int nt = cur.nt;
;         const char* nuA = has_next ? a_unit(nxt) : uA; const int ntbA = has_next ? nxt.k0 / BK : tbA; const char* nB = has_next ? (const char*)g.Bt + (size_t)nxt.pn * tstepB + b_k0(nxt.k0) : cB;
;         for (int t = 0; t < nt; t += 2) {
;             const bool last = (t == nt - 2);
;             const char* a1 = a_tile(uA, tbA + t + 1);
;             const char* a2 = last ? a_tile(nuA, ntbA) : a_tile(uA, tbA + t + 2); const char* b2 = last ? nB : cB + (size_t)(t + 2) * kstepB;
;             const char* a3 = last ? a_tile(nuA, ntbA + 1) : a_tile(uA, tbA + t + 3); const char* b3 = b2 + kstepB;
;             if (last && has_next) S.a_ready(nxt);
;             if constexpr (SP2) {
;             PG8_LDB(B0, 0, 0); PG8_LDB(B1, 0, 1); PG8_SCHED; PG8_LDA(At, 0, 0); PG8_STAGE(PG8_SA(1, 1), a1 + hstepA, voffA);
;             PG8_WAIT_V(8); PG8_WAIT_L(0); PG8_BAR; PG8_MMA(0, 0, At, B0); PG8_MMA(0, 1, At, B1); PG8_BAR; PG8_SCHED;
;             PG8_LDA(At, 0, 1); PG8_STAGE(PG8_SB(0, 0), b2, voffB); PG8_STAGE(PG8_SB(0, 1), b2 + hstepB, voffB); PG8_STAGE(PG8_SA(0, 0), a2, voffA);
.LBB0_667:
	s_ashr_i32 s15, s14, 31
	s_lshl_b64 s[4:5], s[14:15], 20
	s_add_u32 s18, s59, s4
	s_addc_u32 s19, s62, s5
	s_and_b64 s[4:5], s[20:21], exec
	s_cselect_b32 s2, s19, s27
	s_cselect_b32 s4, s18, s26
	s_ashr_i32 s17, s16, 31
	s_lshl_b64 s[22:23], s[16:17], 20
	s_add_u32 s22, s39, s22
	s_addc_u32 s23, s40, s23
	s_and_b64 s[30:31], s[20:21], exec
	s_cselect_b32 s5, s23, s29
	s_cselect_b32 s9, s22, s28
	s_add_u32 s15, s4, 0x80
	s_addc_u32 s17, s2, 0
	s_add_u32 s52, s28, 0x10000
	v_mov_b32_e32 v2, 0
	s_addc_u32 s53, s29, 0
	v_lshl_add_u64 v[180:181], s[26:27], 0, v[176:177]
	v_lshl_add_u64 v[182:183], s[26:27], 0, v[178:179]
	s_mov_b32 s54, -2
	s_mov_b64 s[28:29], 0
	ds_read_b128 v[184:187], v153
	ds_read_b128 v[188:191], v153 offset:1024
	ds_read_b128 v[192:195], v153 offset:2048
	ds_read_b128 v[196:199], v153 offset:3072
	ds_read_b128 v[200:203], v157
	ds_read_b128 v[204:207], v157 offset:1024
	ds_read_b128 v[208:211], v157 offset:2048
	ds_read_b128 v[212:215], v157 offset:3072
	s_add_u32 s30, s26, s28
	s_addc_u32 s31, s27, s29
	s_add_u32 s36, s30, 0x100
	s_addc_u32 s37, s31, 0
	s_add_u32 s30, s30, 0x180
	s_addc_u32 s31, s31, 0
	s_cmpk_eq_i32 s28, 0xf00
	s_cselect_b32 s31, s17, s31
	s_cselect_b32 s30, s15, s30
	s_cselect_b32 s35, s5, s53
	s_cselect_b32 s34, s9, s52
	s_cselect_b32 s37, s2, s37
	s_cselect_b32 s36, s4, s36
	v_lshl_add_u64 v[248:249], v[180:181], 0, s[28:29]
	s_add_i32 m0, s25, 0xc000
	ds_read_b128 v[216:219], v149
	ds_read_b128 v[220:223], v149 offset:1024
	ds_read_b128 v[224:227], v149 offset:2048
	ds_read_b128 v[228:231], v149 offset:3072
	ds_read_b128 v[232:235], v149 offset:4096
	ds_read_b128 v[236:239], v149 offset:5120
	ds_read_b128 v[240:243], v149 offset:6144
	ds_read_b128 v[244:247], v149 offset:7168
	global_load_lds_dwordx4 v[248:249], off
	v_lshl_add_u64 v[248:249], v[182:183], 0, s[28:29]
	s_add_i32 m0, s25, 0xe000
	s_nop 0
	global_load_lds_dwordx4 v[248:249], off
	s_waitcnt vmcnt(8)
	s_waitcnt lgkmcnt(0)
	s_barrier
	v_mfma_f32_16x16x32_bf16 v[126:129], v[184:187], v[216:219], 0
	v_mfma_f32_16x16x32_bf16 v[122:125], v[192:195], v[216:219], 0
	v_mfma_f32_16x16x32_bf16 v[110:113], v[184:187], v[224:227], 0
	v_mfma_f32_16x16x32_bf16 v[106:109], v[192:195], v[224:227], 0
	v_mfma_f32_16x16x32_bf16 v[94:97], v[184:187], v[232:235], 0
	v_mfma_f32_16x16x32_bf16 v[90:93], v[192:195], v[232:235], 0
	v_mfma_f32_16x16x32_bf16 v[78:81], v[184:187], v[240:243], 0
	v_mfma_f32_16x16x32_bf16 v[74:77], v[192:195], v[240:243], 0
	v_mfma_f32_16x16x32_bf16 v[126:129], v[188:191], v[220:223], v[126:129]
	v_mfma_f32_16x16x32_bf16 v[122:125], v[196:199], v[220:223], v[122:125]
	v_mfma_f32_16x16x32_bf16 v[110:113], v[188:191], v[228:231], v[110:113]
	v_mfma_f32_16x16x32_bf16 v[106:109], v[196:199], v[228:231], v[106:109]
	v_mfma_f32_16x16x32_bf16 v[94:97], v[188:191], v[236:239], v[94:97]
	v_mfma_f32_16x16x32_bf16 v[90:93], v[196:199], v[236:239], v[90:93]
	v_mfma_f32_16x16x32_bf16 v[78:81], v[188:191], v[244:247], v[78:81]
	v_mfma_f32_16x16x32_bf16 v[74:77], v[196:199], v[244:247], v[74:77]
	v_mfma_f32_16x16x32_bf16 v[118:121], v[200:203], v[216:219], 0
	v_mfma_f32_16x16x32_bf16 v[114:117], v[208:211], v[216:219], 0
	v_mfma_f32_16x16x32_bf16 v[102:105], v[200:203], v[224:227], 0
	v_mfma_f32_16x16x32_bf16 v[98:101], v[208:211], v[224:227], 0
	v_mfma_f32_16x16x32_bf16 v[86:89], v[200:203], v[232:235], 0
	v_mfma_f32_16x16x32_bf16 v[82:85], v[208:211], v[232:235], 0
	v_mfma_f32_16x16x32_bf16 v[70:73], v[200:203], v[240:243], 0
	v_mfma_f32_16x16x32_bf16 v[66:69], v[208:211], v[240:243], 0
	v_mfma_f32_16x16x32_bf16 v[118:121], v[204:207], v[220:223], v[118:121]
	v_mfma_f32_16x16x32_bf16 v[114:117], v[212:215], v[220:223], v[114:117]
	v_mfma_f32_16x16x32_bf16 v[102:105], v[204:207], v[228:231], v[102:105]
	v_mfma_f32_16x16x32_bf16 v[98:101], v[212:215], v[228:231], v[98:101]
	v_mfma_f32_16x16x32_bf16 v[86:89], v[204:207], v[236:239], v[86:89]
	v_mfma_f32_16x16x32_bf16 v[82:85], v[212:215], v[236:239], v[82:85]
	v_mfma_f32_16x16x32_bf16 v[70:73], v[204:207], v[244:247], v[70:73]
	v_mfma_f32_16x16x32_bf16 v[66:69], v[212:215], v[244:247], v[66:69]
	s_barrier
	s_add_i32 s55, s72, s41
	v_lshl_add_u64 v[248:249], s[34:35], 0, v[132:133]
	s_mov_b32 m0, s55
	ds_read_b128 v[216:219], v149 offset:16384
	ds_read_b128 v[220:223], v149 offset:17408
	ds_read_b128 v[224:227], v149 offset:18432
	ds_read_b128 v[228:231], v149 offset:19456
	ds_read_b128 v[232:235], v149 offset:20480
	ds_read_b128 v[236:239], v149 offset:21504
	ds_read_b128 v[240:243], v149 offset:22528
	ds_read_b128 v[244:247], v149 offset:23552
	global_load_lds_dwordx4 v[248:249], off
	s_add_i32 m0, s55, 0x2000
	s_add_u32 s56, s34, 0x4000
	v_lshl_add_u64 v[248:249], s[34:35], 0, v[136:137]
	s_addc_u32 s57, s35, 0
	s_add_i32 s55, s73, s41
	global_load_lds_dwordx4 v[248:249], off
	v_lshl_add_u64 v[248:249], s[56:57], 0, v[132:133]
	s_mov_b32 m0, s55
	s_nop 0
	global_load_lds_dwordx4 v[248:249], off
	v_lshl_add_u64 v[248:249], s[56:57], 0, v[136:137]
	s_add_i32 m0, s55, 0x2000
	s_nop 0
	global_load_lds_dwordx4 v[248:249], off
	v_lshl_add_u64 v[248:249], s[36:37], 0, v[130:131]
	s_mov_b32 m0, s25
	s_nop 0
	global_load_lds_dwordx4 v[248:249], off
	v_lshl_add_u64 v[248:249], s[36:37], 0, v[134:135]
	s_mov_b32 m0, s42
	s_nop 0
	global_load_lds_dwordx4 v[248:249], off
	s_waitcnt vmcnt(8)
	s_waitcnt lgkmcnt(0)
	s_barrier
; #define PG8_STAGE(bufoff, gbase, voff) do { _Pragma("unroll") for (int _i = 0; _i < 2; ++_i) \
;         __builtin_amdgcn_global_load_lds((const unsigned*)((const char*)(gbase) + (voff)[_i]), (LAS unsigned*)(lds + (bufoff) + ldsw + _i * 8192), 16, 0, 0); } while (0)
; #define PG8_LDA(dst, b, h) do { _Pragma("unroll") for (int m = 0; m < 4; ++m) _Pragma("unroll") for (int k = 0; k < 2; ++k) dst[m][k] = *(const LAS bf16x8*)(lds + PG8_SA(b, h) + aoff + m * 2048 + k * 1024); } while (0)
; #define PG8_LDB(dst, b, h) do { _Pragma("unroll") for (int n = 0; n < 2; ++n) _Pragma("unroll") for (int k = 0; k < 2; ++k) dst[n][k] = *(const LAS bf16x8*)(lds + PG8_SB(b, h) + boff + n * 2048 + k * 1024); } while (0)
; #define PG8_MMA(ai, bj, At, Bt) do { __builtin_amdgcn_s_setprio(1); _Pragma("unroll") for (int m = 0; m < 4; ++m) _Pragma("unroll") for (int n = 0; n < 2; ++n) _Pragma("unroll") for (int k = 0; k < 2; ++k) \
;         acc[ai][bj][m][n] = __builtin_amdgcn_mfma_f32_16x16x32_bf16(Bt[n][k], At[m][k], acc[ai][bj][m][n], 0, 0, 0); __builtin_amdgcn_s_setprio(0); } while (0)
; #define PG8_WAIT_V(n) asm volatile("s_waitcnt vmcnt(" #n ")" ::: "memory")
; #define PG8_WAIT_L(n) asm volatile("s_waitcnt lgkmcnt(" #n ")" ::: "memory")
; #define PG8_BAR __builtin_amdgcn_s_barrier()
; #define PG8_SCHED __builtin_amdgcn_sched_barrier(0)
; template <class Epi, class Sched, bool ABLK = false, bool ALIGN_EPI = true, bool SP2 = true, bool BBLK = true>
; __device__ __forceinline__ void gemm_phase(LAS unsigned char* lds, const Gemm g, const Sched& S, const Epi& E) {
;     ...
;             PG8_WAIT_V(8); PG8_WAIT_L(0); PG8_BAR; PG8_MMA(1, 0, At, B0); PG8_MMA(1, 1, At, B1); PG8_BAR; PG8_SCHED;
;             PG8_LDB(B0, 1, 0); PG8_LDB(B1, 1, 1); PG8_SCHED; PG8_LDA(At, 1, 0); PG8_STAGE(PG8_SA(0, 1), a2 + hstepA, voffA);
;             PG8_WAIT_V(8); PG8_WAIT_L(0); PG8_BAR; PG8_MMA(0, 0, At, B0); PG8_MMA(0, 1, At, B1); PG8_BAR; PG8_SCHED;
	v_mfma_f32_16x16x32_bf16 v[62:65], v[184:187], v[216:219], 0
	v_mfma_f32_16x16x32_bf16 v[58:61], v[192:195], v[216:219], 0
	v_mfma_f32_16x16x32_bf16 v[46:49], v[184:187], v[224:227], 0
	v_mfma_f32_16x16x32_bf16 v[42:45], v[192:195], v[224:227], 0
	v_mfma_f32_16x16x32_bf16 v[30:33], v[184:187], v[232:235], 0
	v_mfma_f32_16x16x32_bf16 v[26:29], v[192:195], v[232:235], 0
	v_mfma_f32_16x16x32_bf16 v[14:17], v[184:187], v[240:243], 0
	v_mfma_f32_16x16x32_bf16 v[10:13], v[192:195], v[240:243], 0
	v_mfma_f32_16x16x32_bf16 v[62:65], v[188:191], v[220:223], v[62:65]
	v_mfma_f32_16x16x32_bf16 v[58:61], v[196:199], v[220:223], v[58:61]
	v_mfma_f32_16x16x32_bf16 v[46:49], v[188:191], v[228:231], v[46:49]
	v_mfma_f32_16x16x32_bf16 v[42:45], v[196:199], v[228:231], v[42:45]
	v_mfma_f32_16x16x32_bf16 v[30:33], v[188:191], v[236:239], v[30:33]
	v_mfma_f32_16x16x32_bf16 v[26:29], v[196:199], v[236:239], v[26:29]
	v_mfma_f32_16x16x32_bf16 v[14:17], v[188:191], v[244:247], v[14:17]
	v_mfma_f32_16x16x32_bf16 v[10:13], v[196:199], v[244:247], v[10:13]
	v_mfma_f32_16x16x32_bf16 v[54:57], v[200:203], v[216:219], 0
	v_mfma_f32_16x16x32_bf16 v[50:53], v[208:211], v[216:219], 0
	v_mfma_f32_16x16x32_bf16 v[38:41], v[200:203], v[224:227], 0
	v_mfma_f32_16x16x32_bf16 v[34:37], v[208:211], v[224:227], 0
	v_mfma_f32_16x16x32_bf16 v[22:25], v[200:203], v[232:235], 0
	v_mfma_f32_16x16x32_bf16 v[18:21], v[208:211], v[232:235], 0
	v_mfma_f32_16x16x32_bf16 v[6:9], v[200:203], v[240:243], 0
	v_mfma_f32_16x16x32_bf16 v[2:5], v[208:211], v[240:243], 0
	v_mfma_f32_16x16x32_bf16 v[54:57], v[204:207], v[220:223], v[54:57]
	v_mfma_f32_16x16x32_bf16 v[50:53], v[212:215], v[220:223], v[50:53]
	v_mfma_f32_16x16x32_bf16 v[38:41], v[204:207], v[228:231], v[38:41]
	v_mfma_f32_16x16x32_bf16 v[34:37], v[212:215], v[228:231], v[34:37]
	v_mfma_f32_16x16x32_bf16 v[22:25], v[204:207], v[236:239], v[22:25]
	v_mfma_f32_16x16x32_bf16 v[18:21], v[212:215], v[236:239], v[18:21]
	v_mfma_f32_16x16x32_bf16 v[6:9], v[204:207], v[244:247], v[6:9]
	v_mfma_f32_16x16x32_bf16 v[2:5], v[212:215], v[244:247], v[2:5]
	s_barrier
	v_add_u32_e32 v138, s60, v1
	ds_read_b128 v[184:187], v138
	ds_read_b128 v[188:191], v138 offset:1024
	ds_read_b128 v[192:195], v138 offset:2048
	ds_read_b128 v[196:199], v138 offset:3072
	v_add_u32_e32 v138, s61, v1
	ds_read_b128 v[200:203], v138
	ds_read_b128 v[204:207], v138 offset:1024
	ds_read_b128 v[208:211], v138 offset:2048
	ds_read_b128 v[212:215], v138 offset:3072
	s_add_u32 s36, s36, 0x80000
	s_addc_u32 s37, s37, 0
	s_mov_b32 m0, s43
	v_lshl_add_u64 v[248:249], s[36:37], 0, v[130:131]
	ds_read_b128 v[216:219], v149 offset:32768
	ds_read_b128 v[220:223], v149 offset:33792
	ds_read_b128 v[224:227], v149 offset:34816
	ds_read_b128 v[228:231], v149 offset:35840
	ds_read_b128 v[232:235], v149 offset:36864
	ds_read_b128 v[236:239], v149 offset:37888
	ds_read_b128 v[240:243], v149 offset:38912
	ds_read_b128 v[244:247], v149 offset:39936
	global_load_lds_dwordx4 v[248:249], off
	v_lshl_add_u64 v[248:249], s[36:37], 0, v[134:135]
	s_mov_b32 m0, s46
	s_nop 0
	global_load_lds_dwordx4 v[248:249], off
	s_waitcnt vmcnt(8)
	s_waitcnt lgkmcnt(0)
	s_barrier
	v_mfma_f32_16x16x32_bf16 v[126:129], v[184:187], v[216:219], v[126:129]
	v_mfma_f32_16x16x32_bf16 v[122:125], v[192:195], v[216:219], v[122:125]
	v_mfma_f32_16x16x32_bf16 v[110:113], v[184:187], v[224:227], v[110:113]
	v_mfma_f32_16x16x32_bf16 v[106:109], v[192:195], v[224:227], v[106:109]
	v_mfma_f32_16x16x32_bf16 v[94:97], v[184:187], v[232:235], v[94:97]
	v_mfma_f32_16x16x32_bf16 v[90:93], v[192:195], v[232:235], v[90:93]
	v_mfma_f32_16x16x32_bf16 v[78:81], v[184:187], v[240:243], v[78:81]
	v_mfma_f32_16x16x32_bf16 v[74:77], v[192:195], v[240:243], v[74:77]
	v_mfma_f32_16x16x32_bf16 v[126:129], v[188:191], v[220:223], v[126:129]
	v_mfma_f32_16x16x32_bf16 v[122:125], v[196:199], v[220:223], v[122:125]
	v_mfma_f32_16x16x32_bf16 v[110:113], v[188:191], v[228:231], v[110:113]
	v_mfma_f32_16x16x32_bf16 v[106:109], v[196:199], v[228:231], v[106:109]
	v_mfma_f32_16x16x32_bf16 v[94:97], v[188:191], v[236:239], v[94:97]
	v_mfma_f32_16x16x32_bf16 v[90:93], v[196:199], v[236:239], v[90:93]
	v_mfma_f32_16x16x32_bf16 v[78:81], v[188:191], v[244:247], v[78:81]
	v_mfma_f32_16x16x32_bf16 v[74:77], v[196:199], v[244:247], v[74:77]
	v_mfma_f32_16x16x32_bf16 v[118:121], v[200:203], v[216:219], v[118:121]
	v_mfma_f32_16x16x32_bf16 v[114:117], v[208:211], v[216:219], v[114:117]
	v_mfma_f32_16x16x32_bf16 v[102:105], v[200:203], v[224:227], v[102:105]
	v_mfma_f32_16x16x32_bf16 v[98:101], v[208:211], v[224:227], v[98:101]
	v_mfma_f32_16x16x32_bf16 v[86:89], v[200:203], v[232:235], v[86:89]
	v_mfma_f32_16x16x32_bf16 v[82:85], v[208:211], v[232:235], v[82:85]
	v_mfma_f32_16x16x32_bf16 v[70:73], v[200:203], v[240:243], v[70:73]
	v_mfma_f32_16x16x32_bf16 v[66:69], v[208:211], v[240:243], v[66:69]
	v_mfma_f32_16x16x32_bf16 v[118:121], v[204:207], v[220:223], v[118:121]
	v_mfma_f32_16x16x32_bf16 v[114:117], v[212:215], v[220:223], v[114:117]
	v_mfma_f32_16x16x32_bf16 v[102:105], v[204:207], v[228:231], v[102:105]
	v_mfma_f32_16x16x32_bf16 v[98:101], v[212:215], v[228:231], v[98:101]
	v_mfma_f32_16x16x32_bf16 v[86:89], v[204:207], v[236:239], v[86:89]
	v_mfma_f32_16x16x32_bf16 v[82:85], v[212:215], v[236:239], v[82:85]
	v_mfma_f32_16x16x32_bf16 v[70:73], v[204:207], v[244:247], v[70:73]
	v_mfma_f32_16x16x32_bf16 v[66:69], v[212:215], v[244:247], v[66:69]
	s_barrier
; #define PG8_STAGE(bufoff, gbase, voff) do { _Pragma("unroll") for (int _i = 0; _i < 2; ++_i) \
;         __builtin_amdgcn_global_load_lds((const unsigned*)((const char*)(gbase) + (voff)[_i]), (LAS unsigned*)(lds + (bufoff) + ldsw + _i * 8192), 16, 0, 0); } while (0)
; #define PG8_LDA(dst, b, h) do { _Pragma("unroll") for (int m = 0; m < 4; ++m) _Pragma("unroll") for (int k = 0; k < 2; ++k) dst[m][k] = *(const LAS bf16x8*)(lds + PG8_SA(b, h) + aoff + m * 2048 + k * 1024); } while (0)
; #define PG8_WAIT_V(n) asm volatile("s_waitcnt vmcnt(" #n ")" ::: "memory")
; #define PG8_WAIT_L(n) asm volatile("s_waitcnt lgkmcnt(" #n ")" ::: "memory")
; template <class Epi, class Sched, bool ABLK = false, bool ALIGN_EPI = true, bool SP2 = true, bool BBLK = true>
; __device__ __forceinline__ void gemm_phase(LAS unsigned char* lds, const Gemm g, const Sched& S, const Epi& E) {
;     ...
;         for (int t = 0; t < nt; t += 2) {
;             const bool last = (t == nt - 2);
;             const char* a1 = a_tile(uA, tbA + t + 1);
;             const char* a2 = last ? a_tile(nuA, ntbA) : a_tile(uA, tbA + t + 2); const char* b2 = last ? nB : cB + (size_t)(t + 2) * kstepB;
;             const char* a3 = last ? a_tile(nuA, ntbA + 1) : a_tile(uA, tbA + t + 3); const char* b3 = b2 + kstepB;
;             if (last && has_next) S.a_ready(nxt);
;             if constexpr (SP2) {
;             PG8_LDB(B0, 0, 0); PG8_LDB(B1, 0, 1); PG8_SCHED; PG8_LDA(At, 0, 0); PG8_STAGE(PG8_SA(1, 1), a1 + hstepA, voffA);
;             PG8_WAIT_V(8); PG8_WAIT_L(0); PG8_BAR; PG8_MMA(0, 0, At, B0); PG8_MMA(0, 1, At, B1); PG8_BAR; PG8_SCHED;
;             PG8_LDA(At, 0, 1); PG8_STAGE(PG8_SB(0, 0), b2, voffB); PG8_STAGE(PG8_SB(0, 1), b2 + hstepB, voffB); PG8_STAGE(PG8_SA(0, 0), a2, voffA);
;             PG8_WAIT_V(8); PG8_WAIT_L(0); PG8_BAR; PG8_MMA(1, 0, At, B0); PG8_MMA(1, 1, At, B1); PG8_BAR; PG8_SCHED;
;             PG8_LDB(B0, 1, 0); PG8_LDB(B1, 1, 1); PG8_SCHED; PG8_LDA(At, 1, 0); PG8_STAGE(PG8_SA(0, 1), a2 + hstepA, voffA);
;             PG8_WAIT_V(8); PG8_WAIT_L(0); PG8_BAR; PG8_MMA(0, 0, At, B0); PG8_MMA(0, 1, At, B1); PG8_BAR; PG8_SCHED;
;             PG8_LDA(At, 1, 1); PG8_STAGE(PG8_SB(1, 0), b3, voffB); PG8_STAGE(PG8_SB(1, 1), b3 + hstepB, voffB); PG8_STAGE(PG8_SA(1, 0), a3, voffA);
;             PG8_WAIT_V(8); PG8_WAIT_L(0); PG8_BAR; PG8_MMA(1, 0, At, B0); PG8_MMA(1, 1, At, B1); PG8_BAR; PG8_SCHED;
	s_add_u32 s36, s34, 0x8000
	s_addc_u32 s37, s35, 0
	s_add_i32 s55, s60, s41
	v_lshl_add_u64 v[248:249], s[36:37], 0, v[132:133]
	s_mov_b32 m0, s55
	ds_read_b128 v[216:219], v149 offset:49152
	ds_read_b128 v[220:223], v149 offset:50176
	ds_read_b128 v[224:227], v149 offset:51200
	ds_read_b128 v[228:231], v149 offset:52224
	ds_read_b128 v[232:235], v149 offset:53248
	ds_read_b128 v[236:239], v149 offset:54272
	ds_read_b128 v[240:243], v149 offset:55296
	ds_read_b128 v[244:247], v149 offset:56320
	global_load_lds_dwordx4 v[248:249], off
	s_add_i32 m0, s55, 0x2000
	s_add_u32 s34, s34, 0xc000
	v_lshl_add_u64 v[248:249], s[36:37], 0, v[136:137]
	s_addc_u32 s35, s35, 0
	s_add_i32 s36, s61, s41
	global_load_lds_dwordx4 v[248:249], off
	v_lshl_add_u64 v[248:249], s[34:35], 0, v[132:133]
	s_mov_b32 m0, s36
	s_nop 0
	global_load_lds_dwordx4 v[248:249], off
	v_lshl_add_u64 v[248:249], s[34:35], 0, v[136:137]
	s_add_i32 m0, s36, 0x2000
	s_nop 0
	global_load_lds_dwordx4 v[248:249], off
	v_lshl_add_u64 v[248:249], s[30:31], 0, v[130:131]
	s_mov_b32 m0, s47
	s_nop 0
	global_load_lds_dwordx4 v[248:249], off
	v_lshl_add_u64 v[248:249], s[30:31], 0, v[134:135]
	s_mov_b32 m0, s48
	s_nop 0
	global_load_lds_dwordx4 v[248:249], off
	s_waitcnt vmcnt(8)
	s_waitcnt lgkmcnt(0)
	s_barrier
	v_mfma_f32_16x16x32_bf16 v[62:65], v[184:187], v[216:219], v[62:65]
	v_mfma_f32_16x16x32_bf16 v[58:61], v[192:195], v[216:219], v[58:61]
	v_mfma_f32_16x16x32_bf16 v[46:49], v[184:187], v[224:227], v[46:49]
	v_mfma_f32_16x16x32_bf16 v[42:45], v[192:195], v[224:227], v[42:45]
	v_mfma_f32_16x16x32_bf16 v[30:33], v[184:187], v[232:235], v[30:33]
	v_mfma_f32_16x16x32_bf16 v[26:29], v[192:195], v[232:235], v[26:29]
	v_mfma_f32_16x16x32_bf16 v[14:17], v[184:187], v[240:243], v[14:17]
	v_mfma_f32_16x16x32_bf16 v[10:13], v[192:195], v[240:243], v[10:13]
	v_mfma_f32_16x16x32_bf16 v[62:65], v[188:191], v[220:223], v[62:65]
	v_mfma_f32_16x16x32_bf16 v[58:61], v[196:199], v[220:223], v[58:61]
	v_mfma_f32_16x16x32_bf16 v[46:49], v[188:191], v[228:231], v[46:49]
	v_mfma_f32_16x16x32_bf16 v[42:45], v[196:199], v[228:231], v[42:45]
	v_mfma_f32_16x16x32_bf16 v[30:33], v[188:191], v[236:239], v[30:33]
	v_mfma_f32_16x16x32_bf16 v[26:29], v[196:199], v[236:239], v[26:29]
	v_mfma_f32_16x16x32_bf16 v[14:17], v[188:191], v[244:247], v[14:17]
	v_mfma_f32_16x16x32_bf16 v[10:13], v[196:199], v[244:247], v[10:13]
	v_mfma_f32_16x16x32_bf16 v[54:57], v[200:203], v[216:219], v[54:57]
	v_mfma_f32_16x16x32_bf16 v[50:53], v[208:211], v[216:219], v[50:53]
	v_mfma_f32_16x16x32_bf16 v[38:41], v[200:203], v[224:227], v[38:41]
	v_mfma_f32_16x16x32_bf16 v[34:37], v[208:211], v[224:227], v[34:37]
	v_mfma_f32_16x16x32_bf16 v[22:25], v[200:203], v[232:235], v[22:25]
	v_mfma_f32_16x16x32_bf16 v[18:21], v[208:211], v[232:235], v[18:21]
	v_mfma_f32_16x16x32_bf16 v[6:9], v[200:203], v[240:243], v[6:9]
	v_mfma_f32_16x16x32_bf16 v[2:5], v[208:211], v[240:243], v[2:5]
	v_mfma_f32_16x16x32_bf16 v[54:57], v[204:207], v[220:223], v[54:57]
	v_mfma_f32_16x16x32_bf16 v[50:53], v[212:215], v[220:223], v[50:53]
	v_mfma_f32_16x16x32_bf16 v[38:41], v[204:207], v[228:231], v[38:41]
	v_mfma_f32_16x16x32_bf16 v[34:37], v[212:215], v[228:231], v[34:37]
	v_mfma_f32_16x16x32_bf16 v[22:25], v[204:207], v[236:239], v[22:25]
	v_mfma_f32_16x16x32_bf16 v[18:21], v[212:215], v[236:239], v[18:21]
	v_mfma_f32_16x16x32_bf16 v[6:9], v[204:207], v[244:247], v[6:9]
	v_mfma_f32_16x16x32_bf16 v[2:5], v[212:215], v[244:247], v[2:5]
	s_barrier
	s_add_i32 s54, s54, 2
	s_add_u32 s28, s28, 0x100
	s_addc_u32 s29, s29, 0
	s_add_u32 s52, s52, 0x10000
	s_addc_u32 s53, s53, 0
	s_cmp_gt_u32 s54, 29

; #define PG8_STAGE(bufoff, gbase, voff) do { _Pragma("unroll") for (int _i = 0; _i < 2; ++_i) \
;         __builtin_amdgcn_global_load_lds((const unsigned*)((const char*)(gbase) + (voff)[_i]), (LAS unsigned*)(lds + (bufoff) + ldsw + _i * 8192), 16, 0, 0); } while (0)
; #define PG8_LDA(dst, b, h) do { _Pragma("unroll") for (int m = 0; m < 4; ++m) _Pragma("unroll") for (int k = 0; k < 2; ++k) dst[m][k] = *(const LAS bf16x8*)(lds + PG8_SA(b, h) + aoff + m * 2048 + k * 1024); } while (0)
; #define PG8_WAIT_V(n) asm volatile("s_waitcnt vmcnt(" #n ")" ::: "memory")
; #define PG8_WAIT_L(n) asm volatile("s_waitcnt lgkmcnt(" #n ")" ::: "memory")
; #define PG8_BAR __builtin_amdgcn_s_barrier()
; template <class Epi, class Sched, bool ABLK = false, bool ALIGN_EPI = true, bool SP2 = true, bool BBLK = true>
; __device__ __forceinline__ void gemm_phase(LAS unsigned char* lds, const Gemm g, const Sched& S, const Epi& E) {
;     ...
;     f32x4 acc[2][2][4][2];
; #pragma unroll
;     for (int a = 0; a < 2; ++a)
; #pragma unroll
;         for (int b = 0; b < 2; ++b)
; #pragma unroll
;             for (int m = 0; m < 4; ++m)
; #pragma unroll
;                 for (int n = 0; n < 2; ++n) acc[a][b][m][n] = (f32x4){0.f, 0.f, 0.f, 0.f};
;     ...
;         const bool has_next = S.next(ui + 1, nxt);
;         const int nt = cur.nt;
;         const char* nuA = has_next ? a_unit(nxt) : uA; const int ntbA = has_next ? nxt.k0 / BK : tbA; const char* nB = has_next ? (const char*)g.Bt + (size_t)nxt.pn * tstepB + b_k0(nxt.k0) : cB;
;         for (int t = 0; t < nt; t += 2) {
;             const bool last = (t == nt - 2);
;             const char* a1 = a_tile(uA, tbA + t + 1);
;             const char* a2 = last ? a_tile(nuA, ntbA) : a_tile(uA, tbA + t + 2); const char* b2 = last ? nB : cB + (size_t)(t + 2) * kstepB;
;             const char* a3 = last ? a_tile(nuA, ntbA + 1) : a_tile(uA, tbA + t + 3); const char* b3 = b2 + kstepB;
;             if (last && has_next) S.a_ready(nxt);
;             if constexpr (SP2) {
;             PG8_LDB(B0, 0, 0); PG8_LDB(B1, 0, 1); PG8_SCHED; PG8_LDA(At, 0, 0); PG8_STAGE(PG8_SA(1, 1), a1 + hstepA, voffA);
;             PG8_WAIT_V(8); PG8_WAIT_L(0); PG8_BAR; PG8_MMA(0, 0, At, B0); PG8_MMA(0, 1, At, B1); PG8_BAR; PG8_SCHED;
;             PG8_LDA(At, 0, 1); PG8_STAGE(PG8_SB(0, 0), b2, voffB); PG8_STAGE(PG8_SB(0, 1), b2 + hstepB, voffB); PG8_STAGE(PG8_SA(0, 0), a2, voffA);
.LBB0_1037:
	s_ashr_i32 s81, s80, 31
	s_andn2_b64 vcc, exec, s[4:5]
	s_lshl_b64 s[14:15], s[80:81], 20
	s_add_u32 s14, s28, s14
	s_addc_u32 s15, s29, s15
	s_and_b64 s[16:17], s[4:5], exec
	s_cselect_b32 s25, s15, s23
	s_cselect_b32 s48, s14, s22
	s_ashr_i32 s16, s63, 31
	s_lshr_b32 s16, s16, 26
	s_add_i32 s16, s63, s16
	s_ashr_i32 s16, s16, 6
	s_and_b64 s[18:19], s[4:5], exec
	s_cselect_b32 s26, s16, s24
	s_ashr_i32 s79, s78, 31
	s_lshl_b64 s[18:19], s[78:79], 20
	s_add_u32 s27, s30, s18
	s_addc_u32 s49, s31, s19
	s_ashr_i32 s17, s16, 31
	s_lshl_b64 s[18:19], s[16:17], 15
	s_add_u32 s18, s27, s18
	s_addc_u32 s19, s49, s19
	v_cndmask_b32_e64 v2, 0, 1, s[4:5]
	s_and_b64 s[4:5], s[4:5], exec
	s_cselect_b32 s4, s19, s21
	s_cselect_b32 s5, s18, s20
	s_ashr_i32 s27, s26, 31
	s_lshl_b64 s[26:27], s[26:27], 7
	s_add_u32 s17, s48, s26
	s_addc_u32 s48, s25, s27
	s_add_u32 s49, s17, 0x80
	s_addc_u32 s50, s48, 0
	s_add_u32 s51, s20, 0x10000
	s_addc_u32 s55, s21, 0
	s_ashr_i32 s25, s24, 31
	v_cmp_ne_u32_e64 s[8:9], 1, v2
	s_lshl_b64 s[20:21], s[24:25], 7
	v_lshl_add_u64 v[2:3], s[22:23], 0, v[142:143]
	s_add_u32 s56, s22, s20
	v_lshl_add_u64 v[146:147], v[2:3], 0, s[20:21]
	v_lshl_add_u64 v[2:3], s[22:23], 0, v[144:145]
	s_addc_u32 s57, s23, s21
	v_lshl_add_u64 v[148:149], v[2:3], 0, s[20:21]
	s_lshl_b32 s20, s46, 7
	s_addk_i32 s20, 0xfc00
	v_mov_b32_e32 v2, 0
	s_add_u32 s64, s20, 0x300
	s_mov_b32 s65, 0
	s_mov_b64 s[20:21], 0
	ds_read_b128 v[156:159], v153
	ds_read_b128 v[160:163], v153 offset:1024
	ds_read_b128 v[164:167], v153 offset:2048
	ds_read_b128 v[168:171], v153 offset:3072
	ds_read_b128 v[172:175], v154
	ds_read_b128 v[176:179], v154 offset:1024
	ds_read_b128 v[180:183], v154 offset:2048
	ds_read_b128 v[184:187], v154 offset:3072
	s_add_u32 s22, s56, s20
	s_addc_u32 s23, s57, s21
	s_add_u32 s26, s22, 0x100
	s_addc_u32 s27, s23, 0
	s_add_i32 s65, s65, 2
	s_add_u32 s22, s22, 0x180
	s_addc_u32 s23, s23, 0
	s_cmp_eq_u32 s64, s20
	s_cselect_b32 s23, s50, s23
	s_cselect_b32 s22, s49, s22
	s_cselect_b32 s25, s4, s55
	s_cselect_b32 s24, s5, s51
	s_cselect_b32 s27, s48, s27
	s_cselect_b32 s26, s17, s26
	v_lshl_add_u64 v[220:221], v[146:147], 0, s[20:21]
	s_add_i32 m0, s35, 0xc000
	ds_read_b128 v[188:191], v155
	ds_read_b128 v[192:195], v155 offset:1024
	ds_read_b128 v[196:199], v155 offset:2048
	ds_read_b128 v[200:203], v155 offset:3072
	ds_read_b128 v[204:207], v155 offset:4096
	ds_read_b128 v[208:211], v155 offset:5120
	ds_read_b128 v[212:215], v155 offset:6144
	ds_read_b128 v[216:219], v155 offset:7168
	global_load_lds_dwordx4 v[220:221], off
	v_lshl_add_u64 v[220:221], v[148:149], 0, s[20:21]
	s_add_i32 m0, s35, 0xe000
	s_nop 0
	global_load_lds_dwordx4 v[220:221], off
	s_waitcnt vmcnt(8)
	s_waitcnt lgkmcnt(0)
	s_barrier
	v_mfma_f32_16x16x32_bf16 v[126:129], v[156:159], v[188:191], 0
	v_mfma_f32_16x16x32_bf16 v[122:125], v[164:167], v[188:191], 0
	v_mfma_f32_16x16x32_bf16 v[110:113], v[156:159], v[196:199], 0
	v_mfma_f32_16x16x32_bf16 v[106:109], v[164:167], v[196:199], 0
	v_mfma_f32_16x16x32_bf16 v[94:97], v[156:159], v[204:207], 0
	v_mfma_f32_16x16x32_bf16 v[90:93], v[164:167], v[204:207], 0
	v_mfma_f32_16x16x32_bf16 v[78:81], v[156:159], v[212:215], 0
	v_mfma_f32_16x16x32_bf16 v[74:77], v[164:167], v[212:215], 0
	v_mfma_f32_16x16x32_bf16 v[126:129], v[160:163], v[192:195], v[126:129]
	v_mfma_f32_16x16x32_bf16 v[122:125], v[168:171], v[192:195], v[122:125]
	v_mfma_f32_16x16x32_bf16 v[110:113], v[160:163], v[200:203], v[110:113]
	v_mfma_f32_16x16x32_bf16 v[106:109], v[168:171], v[200:203], v[106:109]
	v_mfma_f32_16x16x32_bf16 v[94:97], v[160:163], v[208:211], v[94:97]
	v_mfma_f32_16x16x32_bf16 v[90:93], v[168:171], v[208:211], v[90:93]
	v_mfma_f32_16x16x32_bf16 v[78:81], v[160:163], v[216:219], v[78:81]
	v_mfma_f32_16x16x32_bf16 v[74:77], v[168:171], v[216:219], v[74:77]
	v_mfma_f32_16x16x32_bf16 v[118:121], v[172:175], v[188:191], 0
	v_mfma_f32_16x16x32_bf16 v[114:117], v[180:183], v[188:191], 0
	v_mfma_f32_16x16x32_bf16 v[102:105], v[172:175], v[196:199], 0
	v_mfma_f32_16x16x32_bf16 v[98:101], v[180:183], v[196:199], 0
	v_mfma_f32_16x16x32_bf16 v[86:89], v[172:175], v[204:207], 0
	v_mfma_f32_16x16x32_bf16 v[82:85], v[180:183], v[204:207], 0
	v_mfma_f32_16x16x32_bf16 v[70:73], v[172:175], v[212:215], 0
	v_mfma_f32_16x16x32_bf16 v[66:69], v[180:183], v[212:215], 0
	v_mfma_f32_16x16x32_bf16 v[118:121], v[176:179], v[192:195], v[118:121]
	v_mfma_f32_16x16x32_bf16 v[114:117], v[184:187], v[192:195], v[114:117]
	v_mfma_f32_16x16x32_bf16 v[102:105], v[176:179], v[200:203], v[102:105]
	v_mfma_f32_16x16x32_bf16 v[98:101], v[184:187], v[200:203], v[98:101]
	v_mfma_f32_16x16x32_bf16 v[86:89], v[176:179], v[208:211], v[86:89]
	v_mfma_f32_16x16x32_bf16 v[82:85], v[184:187], v[208:211], v[82:85]
	v_mfma_f32_16x16x32_bf16 v[70:73], v[176:179], v[216:219], v[70:73]
	v_mfma_f32_16x16x32_bf16 v[66:69], v[184:187], v[216:219], v[66:69]
	s_barrier
	s_add_i32 s66, s72, s34
	v_lshl_add_u64 v[220:221], s[24:25], 0, v[132:133]
	s_mov_b32 m0, s66
	ds_read_b128 v[188:191], v155 offset:16384
	ds_read_b128 v[192:195], v155 offset:17408
	ds_read_b128 v[196:199], v155 offset:18432
	ds_read_b128 v[200:203], v155 offset:19456
	ds_read_b128 v[204:207], v155 offset:20480
	ds_read_b128 v[208:211], v155 offset:21504
	ds_read_b128 v[212:215], v155 offset:22528
	ds_read_b128 v[216:219], v155 offset:23552
	global_load_lds_dwordx4 v[220:221], off
	s_add_i32 m0, s66, 0x2000
	s_add_u32 s66, s24, 0x4000
	v_lshl_add_u64 v[220:221], s[24:25], 0, v[136:137]
	s_addc_u32 s67, s25, 0
	s_add_i32 s75, s73, s34
	global_load_lds_dwordx4 v[220:221], off
	v_lshl_add_u64 v[220:221], s[66:67], 0, v[132:133]
	s_mov_b32 m0, s75
	s_nop 0
	global_load_lds_dwordx4 v[220:221], off
	v_lshl_add_u64 v[220:221], s[66:67], 0, v[136:137]
	s_add_i32 m0, s75, 0x2000
	s_nop 0
	global_load_lds_dwordx4 v[220:221], off
	v_lshl_add_u64 v[220:221], s[26:27], 0, v[130:131]
	s_mov_b32 m0, s35
	s_nop 0
	global_load_lds_dwordx4 v[220:221], off
	v_lshl_add_u64 v[220:221], s[26:27], 0, v[134:135]
	s_mov_b32 m0, s36
	s_nop 0
	global_load_lds_dwordx4 v[220:221], off
	s_waitcnt vmcnt(8)
	s_waitcnt lgkmcnt(0)
	s_barrier
; #define PG8_STAGE(bufoff, gbase, voff) do { _Pragma("unroll") for (int _i = 0; _i < 2; ++_i) \
;         __builtin_amdgcn_global_load_lds((const unsigned*)((const char*)(gbase) + (voff)[_i]), (LAS unsigned*)(lds + (bufoff) + ldsw + _i * 8192), 16, 0, 0); } while (0)
; #define PG8_LDA(dst, b, h) do { _Pragma("unroll") for (int m = 0; m < 4; ++m) _Pragma("unroll") for (int k = 0; k < 2; ++k) dst[m][k] = *(const LAS bf16x8*)(lds + PG8_SA(b, h) + aoff + m * 2048 + k * 1024); } while (0)
; #define PG8_LDB(dst, b, h) do { _Pragma("unroll") for (int n = 0; n < 2; ++n) _Pragma("unroll") for (int k = 0; k < 2; ++k) dst[n][k] = *(const LAS bf16x8*)(lds + PG8_SB(b, h) + boff + n * 2048 + k * 1024); } while (0)
; #define PG8_MMA(ai, bj, At, Bt) do { __builtin_amdgcn_s_setprio(1); _Pragma("unroll") for (int m = 0; m < 4; ++m) _Pragma("unroll") for (int n = 0; n < 2; ++n) _Pragma("unroll") for (int k = 0; k < 2; ++k) \
;         acc[ai][bj][m][n] = __builtin_amdgcn_mfma_f32_16x16x32_bf16(Bt[n][k], At[m][k], acc[ai][bj][m][n], 0, 0, 0); __builtin_amdgcn_s_setprio(0); } while (0)
; #define PG8_WAIT_V(n) asm volatile("s_waitcnt vmcnt(" #n ")" ::: "memory")
; #define PG8_WAIT_L(n) asm volatile("s_waitcnt lgkmcnt(" #n ")" ::: "memory")
; #define PG8_BAR __builtin_amdgcn_s_barrier()
; #define PG8_SCHED __builtin_amdgcn_sched_barrier(0)
; template <class Epi, class Sched, bool ABLK = false, bool ALIGN_EPI = true, bool SP2 = true, bool BBLK = true>
; __device__ __forceinline__ void gemm_phase(LAS unsigned char* lds, const Gemm g, const Sched& S, const Epi& E) {
;     ...
;             PG8_WAIT_V(8); PG8_WAIT_L(0); PG8_BAR; PG8_MMA(1, 0, At, B0); PG8_MMA(1, 1, At, B1); PG8_BAR; PG8_SCHED;
;             PG8_LDB(B0, 1, 0); PG8_LDB(B1, 1, 1); PG8_SCHED; PG8_LDA(At, 1, 0); PG8_STAGE(PG8_SA(0, 1), a2 + hstepA, voffA);
;             PG8_WAIT_V(8); PG8_WAIT_L(0); PG8_BAR; PG8_MMA(0, 0, At, B0); PG8_MMA(0, 1, At, B1); PG8_BAR; PG8_SCHED;
	v_mfma_f32_16x16x32_bf16 v[62:65], v[156:159], v[188:191], 0
	v_mfma_f32_16x16x32_bf16 v[58:61], v[164:167], v[188:191], 0
	v_mfma_f32_16x16x32_bf16 v[46:49], v[156:159], v[196:199], 0
	v_mfma_f32_16x16x32_bf16 v[42:45], v[164:167], v[196:199], 0
	v_mfma_f32_16x16x32_bf16 v[30:33], v[156:159], v[204:207], 0
	v_mfma_f32_16x16x32_bf16 v[26:29], v[164:167], v[204:207], 0
	v_mfma_f32_16x16x32_bf16 v[14:17], v[156:159], v[212:215], 0
	v_mfma_f32_16x16x32_bf16 v[10:13], v[164:167], v[212:215], 0
	v_mfma_f32_16x16x32_bf16 v[62:65], v[160:163], v[192:195], v[62:65]
	v_mfma_f32_16x16x32_bf16 v[58:61], v[168:171], v[192:195], v[58:61]
	v_mfma_f32_16x16x32_bf16 v[46:49], v[160:163], v[200:203], v[46:49]
	v_mfma_f32_16x16x32_bf16 v[42:45], v[168:171], v[200:203], v[42:45]
	v_mfma_f32_16x16x32_bf16 v[30:33], v[160:163], v[208:211], v[30:33]
	v_mfma_f32_16x16x32_bf16 v[26:29], v[168:171], v[208:211], v[26:29]
	v_mfma_f32_16x16x32_bf16 v[14:17], v[160:163], v[216:219], v[14:17]
	v_mfma_f32_16x16x32_bf16 v[10:13], v[168:171], v[216:219], v[10:13]
	v_mfma_f32_16x16x32_bf16 v[54:57], v[172:175], v[188:191], 0
	v_mfma_f32_16x16x32_bf16 v[50:53], v[180:183], v[188:191], 0
	v_mfma_f32_16x16x32_bf16 v[38:41], v[172:175], v[196:199], 0
	v_mfma_f32_16x16x32_bf16 v[34:37], v[180:183], v[196:199], 0
	v_mfma_f32_16x16x32_bf16 v[22:25], v[172:175], v[204:207], 0
	v_mfma_f32_16x16x32_bf16 v[18:21], v[180:183], v[204:207], 0
	v_mfma_f32_16x16x32_bf16 v[6:9], v[172:175], v[212:215], 0
	v_mfma_f32_16x16x32_bf16 v[2:5], v[180:183], v[212:215], 0
	v_mfma_f32_16x16x32_bf16 v[54:57], v[176:179], v[192:195], v[54:57]
	v_mfma_f32_16x16x32_bf16 v[50:53], v[184:187], v[192:195], v[50:53]
	v_mfma_f32_16x16x32_bf16 v[38:41], v[176:179], v[200:203], v[38:41]
	v_mfma_f32_16x16x32_bf16 v[34:37], v[184:187], v[200:203], v[34:37]
	v_mfma_f32_16x16x32_bf16 v[22:25], v[176:179], v[208:211], v[22:25]
	v_mfma_f32_16x16x32_bf16 v[18:21], v[184:187], v[208:211], v[18:21]
	v_mfma_f32_16x16x32_bf16 v[6:9], v[176:179], v[216:219], v[6:9]
	v_mfma_f32_16x16x32_bf16 v[2:5], v[184:187], v[216:219], v[2:5]
	s_barrier
	v_add_u32_e32 v168, s60, v151
	v_add_u32_e32 v184, s61, v151
	ds_read_b128 v[156:159], v168
	ds_read_b128 v[160:163], v168 offset:1024
	ds_read_b128 v[164:167], v168 offset:2048
	ds_read_b128 v[168:171], v168 offset:3072
	ds_read_b128 v[172:175], v184
	ds_read_b128 v[176:179], v184 offset:1024
	ds_read_b128 v[180:183], v184 offset:2048
	ds_read_b128 v[184:187], v184 offset:3072
	s_add_u32 s26, s26, 0x80000
	s_addc_u32 s27, s27, 0
	s_mov_b32 m0, s37
	v_lshl_add_u64 v[220:221], s[26:27], 0, v[130:131]
	ds_read_b128 v[188:191], v155 offset:32768
	ds_read_b128 v[192:195], v155 offset:33792
	ds_read_b128 v[196:199], v155 offset:34816
	ds_read_b128 v[200:203], v155 offset:35840
	ds_read_b128 v[204:207], v155 offset:36864
	ds_read_b128 v[208:211], v155 offset:37888
	ds_read_b128 v[212:215], v155 offset:38912
	ds_read_b128 v[216:219], v155 offset:39936
	global_load_lds_dwordx4 v[220:221], off
	v_lshl_add_u64 v[220:221], s[26:27], 0, v[134:135]
	s_mov_b32 m0, s40
	s_nop 0
	global_load_lds_dwordx4 v[220:221], off
	s_waitcnt vmcnt(8)
	s_waitcnt lgkmcnt(0)
	s_barrier
	v_mfma_f32_16x16x32_bf16 v[126:129], v[156:159], v[188:191], v[126:129]
	v_mfma_f32_16x16x32_bf16 v[122:125], v[164:167], v[188:191], v[122:125]
	v_mfma_f32_16x16x32_bf16 v[110:113], v[156:159], v[196:199], v[110:113]
	v_mfma_f32_16x16x32_bf16 v[106:109], v[164:167], v[196:199], v[106:109]
	v_mfma_f32_16x16x32_bf16 v[94:97], v[156:159], v[204:207], v[94:97]
	v_mfma_f32_16x16x32_bf16 v[90:93], v[164:167], v[204:207], v[90:93]
	v_mfma_f32_16x16x32_bf16 v[78:81], v[156:159], v[212:215], v[78:81]
	v_mfma_f32_16x16x32_bf16 v[74:77], v[164:167], v[212:215], v[74:77]
	v_mfma_f32_16x16x32_bf16 v[126:129], v[160:163], v[192:195], v[126:129]
	v_mfma_f32_16x16x32_bf16 v[122:125], v[168:171], v[192:195], v[122:125]
	v_mfma_f32_16x16x32_bf16 v[110:113], v[160:163], v[200:203], v[110:113]
	v_mfma_f32_16x16x32_bf16 v[106:109], v[168:171], v[200:203], v[106:109]
	v_mfma_f32_16x16x32_bf16 v[94:97], v[160:163], v[208:211], v[94:97]
	v_mfma_f32_16x16x32_bf16 v[90:93], v[168:171], v[208:211], v[90:93]
	v_mfma_f32_16x16x32_bf16 v[78:81], v[160:163], v[216:219], v[78:81]
	v_mfma_f32_16x16x32_bf16 v[74:77], v[168:171], v[216:219], v[74:77]
	v_mfma_f32_16x16x32_bf16 v[118:121], v[172:175], v[188:191], v[118:121]
	v_mfma_f32_16x16x32_bf16 v[114:117], v[180:183], v[188:191], v[114:117]
	v_mfma_f32_16x16x32_bf16 v[102:105], v[172:175], v[196:199], v[102:105]
	v_mfma_f32_16x16x32_bf16 v[98:101], v[180:183], v[196:199], v[98:101]
	v_mfma_f32_16x16x32_bf16 v[86:89], v[172:175], v[204:207], v[86:89]
	v_mfma_f32_16x16x32_bf16 v[82:85], v[180:183], v[204:207], v[82:85]
	v_mfma_f32_16x16x32_bf16 v[70:73], v[172:175], v[212:215], v[70:73]
	v_mfma_f32_16x16x32_bf16 v[66:69], v[180:183], v[212:215], v[66:69]
	v_mfma_f32_16x16x32_bf16 v[118:121], v[176:179], v[192:195], v[118:121]
	v_mfma_f32_16x16x32_bf16 v[114:117], v[184:187], v[192:195], v[114:117]
	v_mfma_f32_16x16x32_bf16 v[102:105], v[176:179], v[200:203], v[102:105]
	v_mfma_f32_16x16x32_bf16 v[98:101], v[184:187], v[200:203], v[98:101]
	v_mfma_f32_16x16x32_bf16 v[86:89], v[176:179], v[208:211], v[86:89]
	v_mfma_f32_16x16x32_bf16 v[82:85], v[184:187], v[208:211], v[82:85]
	v_mfma_f32_16x16x32_bf16 v[70:73], v[176:179], v[216:219], v[70:73]
	v_mfma_f32_16x16x32_bf16 v[66:69], v[184:187], v[216:219], v[66:69]
	s_barrier
; #define PG8_STAGE(bufoff, gbase, voff) do { _Pragma("unroll") for (int _i = 0; _i < 2; ++_i) \
;         __builtin_amdgcn_global_load_lds((const unsigned*)((const char*)(gbase) + (voff)[_i]), (LAS unsigned*)(lds + (bufoff) + ldsw + _i * 8192), 16, 0, 0); } while (0)
; #define PG8_LDA(dst, b, h) do { _Pragma("unroll") for (int m = 0; m < 4; ++m) _Pragma("unroll") for (int k = 0; k < 2; ++k) dst[m][k] = *(const LAS bf16x8*)(lds + PG8_SA(b, h) + aoff + m * 2048 + k * 1024); } while (0)
; #define PG8_WAIT_V(n) asm volatile("s_waitcnt vmcnt(" #n ")" ::: "memory")
; #define PG8_WAIT_L(n) asm volatile("s_waitcnt lgkmcnt(" #n ")" ::: "memory")
; template <class Epi, class Sched, bool ABLK = false, bool ALIGN_EPI = true, bool SP2 = true, bool BBLK = true>
; __device__ __forceinline__ void gemm_phase(LAS unsigned char* lds, const Gemm g, const Sched& S, const Epi& E) {
;     ...
;         for (int t = 0; t < nt; t += 2) {
;             const bool last = (t == nt - 2);
;             const char* a1 = a_tile(uA, tbA + t + 1);
;             const char* a2 = last ? a_tile(nuA, ntbA) : a_tile(uA, tbA + t + 2); const char* b2 = last ? nB : cB + (size_t)(t + 2) * kstepB;
;             const char* a3 = last ? a_tile(nuA, ntbA + 1) : a_tile(uA, tbA + t + 3); const char* b3 = b2 + kstepB;
;             if (last && has_next) S.a_ready(nxt);
;             if constexpr (SP2) {
;             PG8_LDB(B0, 0, 0); PG8_LDB(B1, 0, 1); PG8_SCHED; PG8_LDA(At, 0, 0); PG8_STAGE(PG8_SA(1, 1), a1 + hstepA, voffA);
;             PG8_WAIT_V(8); PG8_WAIT_L(0); PG8_BAR; PG8_MMA(0, 0, At, B0); PG8_MMA(0, 1, At, B1); PG8_BAR; PG8_SCHED;
;             PG8_LDA(At, 0, 1); PG8_STAGE(PG8_SB(0, 0), b2, voffB); PG8_STAGE(PG8_SB(0, 1), b2 + hstepB, voffB); PG8_STAGE(PG8_SA(0, 0), a2, voffA);
;             PG8_WAIT_V(8); PG8_WAIT_L(0); PG8_BAR; PG8_MMA(1, 0, At, B0); PG8_MMA(1, 1, At, B1); PG8_BAR; PG8_SCHED;
;             PG8_LDB(B0, 1, 0); PG8_LDB(B1, 1, 1); PG8_SCHED; PG8_LDA(At, 1, 0); PG8_STAGE(PG8_SA(0, 1), a2 + hstepA, voffA);
;             PG8_WAIT_V(8); PG8_WAIT_L(0); PG8_BAR; PG8_MMA(0, 0, At, B0); PG8_MMA(0, 1, At, B1); PG8_BAR; PG8_SCHED;
;             PG8_LDA(At, 1, 1); PG8_STAGE(PG8_SB(1, 0), b3, voffB); PG8_STAGE(PG8_SB(1, 1), b3 + hstepB, voffB); PG8_STAGE(PG8_SA(1, 0), a3, voffA);
;             PG8_WAIT_V(8); PG8_WAIT_L(0); PG8_BAR; PG8_MMA(1, 0, At, B0); PG8_MMA(1, 1, At, B1); PG8_BAR; PG8_SCHED;
	s_add_u32 s26, s24, 0x8000
	s_addc_u32 s27, s25, 0
	s_add_i32 s66, s60, s34
	v_lshl_add_u64 v[220:221], s[26:27], 0, v[132:133]
	s_mov_b32 m0, s66
	ds_read_b128 v[188:191], v155 offset:49152
	ds_read_b128 v[192:195], v155 offset:50176
	ds_read_b128 v[196:199], v155 offset:51200
	ds_read_b128 v[200:203], v155 offset:52224
	ds_read_b128 v[204:207], v155 offset:53248
	ds_read_b128 v[208:211], v155 offset:54272
	ds_read_b128 v[212:215], v155 offset:55296
	ds_read_b128 v[216:219], v155 offset:56320
	global_load_lds_dwordx4 v[220:221], off
	s_add_i32 m0, s66, 0x2000
	s_add_u32 s24, s24, 0xc000
	v_lshl_add_u64 v[220:221], s[26:27], 0, v[136:137]
	s_addc_u32 s25, s25, 0
	s_add_i32 s26, s61, s34
	global_load_lds_dwordx4 v[220:221], off
	v_lshl_add_u64 v[220:221], s[24:25], 0, v[132:133]
	s_mov_b32 m0, s26
	s_nop 0
	global_load_lds_dwordx4 v[220:221], off
	v_lshl_add_u64 v[220:221], s[24:25], 0, v[136:137]
	s_add_i32 m0, s26, 0x2000
	s_nop 0
	global_load_lds_dwordx4 v[220:221], off
	v_lshl_add_u64 v[220:221], s[22:23], 0, v[130:131]
	s_mov_b32 m0, s41
	s_nop 0
	global_load_lds_dwordx4 v[220:221], off
	v_lshl_add_u64 v[220:221], s[22:23], 0, v[134:135]
	s_mov_b32 m0, s42
	s_nop 0
	global_load_lds_dwordx4 v[220:221], off
	s_waitcnt vmcnt(8)
	s_waitcnt lgkmcnt(0)
	s_barrier
	v_mfma_f32_16x16x32_bf16 v[62:65], v[156:159], v[188:191], v[62:65]
	v_mfma_f32_16x16x32_bf16 v[58:61], v[164:167], v[188:191], v[58:61]
	v_mfma_f32_16x16x32_bf16 v[46:49], v[156:159], v[196:199], v[46:49]
	v_mfma_f32_16x16x32_bf16 v[42:45], v[164:167], v[196:199], v[42:45]
	v_mfma_f32_16x16x32_bf16 v[30:33], v[156:159], v[204:207], v[30:33]
	v_mfma_f32_16x16x32_bf16 v[26:29], v[164:167], v[204:207], v[26:29]
	v_mfma_f32_16x16x32_bf16 v[14:17], v[156:159], v[212:215], v[14:17]
	v_mfma_f32_16x16x32_bf16 v[10:13], v[164:167], v[212:215], v[10:13]
	v_mfma_f32_16x16x32_bf16 v[62:65], v[160:163], v[192:195], v[62:65]
	v_mfma_f32_16x16x32_bf16 v[58:61], v[168:171], v[192:195], v[58:61]
	v_mfma_f32_16x16x32_bf16 v[46:49], v[160:163], v[200:203], v[46:49]
	v_mfma_f32_16x16x32_bf16 v[42:45], v[168:171], v[200:203], v[42:45]
	v_mfma_f32_16x16x32_bf16 v[30:33], v[160:163], v[208:211], v[30:33]
	v_mfma_f32_16x16x32_bf16 v[26:29], v[168:171], v[208:211], v[26:29]
	v_mfma_f32_16x16x32_bf16 v[14:17], v[160:163], v[216:219], v[14:17]
	v_mfma_f32_16x16x32_bf16 v[10:13], v[168:171], v[216:219], v[10:13]
	v_mfma_f32_16x16x32_bf16 v[54:57], v[172:175], v[188:191], v[54:57]
	v_mfma_f32_16x16x32_bf16 v[50:53], v[180:183], v[188:191], v[50:53]
	v_mfma_f32_16x16x32_bf16 v[38:41], v[172:175], v[196:199], v[38:41]
	v_mfma_f32_16x16x32_bf16 v[34:37], v[180:183], v[196:199], v[34:37]
	v_mfma_f32_16x16x32_bf16 v[22:25], v[172:175], v[204:207], v[22:25]
	v_mfma_f32_16x16x32_bf16 v[18:21], v[180:183], v[204:207], v[18:21]
	v_mfma_f32_16x16x32_bf16 v[6:9], v[172:175], v[212:215], v[6:9]
	v_mfma_f32_16x16x32_bf16 v[2:5], v[180:183], v[212:215], v[2:5]
	v_mfma_f32_16x16x32_bf16 v[54:57], v[176:179], v[192:195], v[54:57]
	v_mfma_f32_16x16x32_bf16 v[50:53], v[184:187], v[192:195], v[50:53]
	v_mfma_f32_16x16x32_bf16 v[38:41], v[176:179], v[200:203], v[38:41]
	v_mfma_f32_16x16x32_bf16 v[34:37], v[184:187], v[200:203], v[34:37]
	v_mfma_f32_16x16x32_bf16 v[22:25], v[176:179], v[208:211], v[22:25]
	v_mfma_f32_16x16x32_bf16 v[18:21], v[184:187], v[208:211], v[18:21]
	v_mfma_f32_16x16x32_bf16 v[6:9], v[176:179], v[216:219], v[6:9]
	v_mfma_f32_16x16x32_bf16 v[2:5], v[184:187], v[216:219], v[2:5]
	s_barrier
	s_add_u32 s51, s51, 0x10000
	s_addc_u32 s55, s55, 0
	s_add_u32 s20, s20, 0x100
	s_addc_u32 s21, s21, 0
	s_cmp_ge_u32 s65, s46

; #define PG8_STAGE(bufoff, gbase, voff) do { _Pragma("unroll") for (int _i = 0; _i < 2; ++_i) \
;         __builtin_amdgcn_global_load_lds((const unsigned*)((const char*)(gbase) + (voff)[_i]), (LAS unsigned*)(lds + (bufoff) + ldsw + _i * 8192), 16, 0, 0); } while (0)
; #define PG8_LDA(dst, b, h) do { _Pragma("unroll") for (int m = 0; m < 4; ++m) _Pragma("unroll") for (int k = 0; k < 2; ++k) dst[m][k] = *(const LAS bf16x8*)(lds + PG8_SA(b, h) + aoff + m * 2048 + k * 1024); } while (0)
; #define PG8_WAIT_V(n) asm volatile("s_waitcnt vmcnt(" #n ")" ::: "memory")
; #define PG8_WAIT_L(n) asm volatile("s_waitcnt lgkmcnt(" #n ")" ::: "memory")
; #define PG8_BAR __builtin_amdgcn_s_barrier()
; template <class Epi, class Sched, bool ABLK = false, bool ALIGN_EPI = true, bool SP2 = true, bool BBLK = true>
; __device__ __forceinline__ void gemm_phase(LAS unsigned char* lds, const Gemm g, const Sched& S, const Epi& E) {
;     ...
;     f32x4 acc[2][2][4][2];
; #pragma unroll
;     for (int a = 0; a < 2; ++a)
; #pragma unroll
;         for (int b = 0; b < 2; ++b)
; #pragma unroll
;             for (int m = 0; m < 4; ++m)
; #pragma unroll
;                 for (int n = 0; n < 2; ++n) acc[a][b][m][n] = (f32x4){0.f, 0.f, 0.f, 0.f};
;     ...
;         const bool has_next = S.next(ui + 1, nxt);
;         const int nt = cur.nt;
;         const char* nuA = has_next ? a_unit(nxt) : uA; const int ntbA = has_next ? nxt.k0 / BK : tbA; const char* nB = has_next ? (const char*)g.Bt + (size_t)nxt.pn * tstepB + b_k0(nxt.k0) : cB;
;         for (int t = 0; t < nt; t += 2) {
;             const bool last = (t == nt - 2);
;             const char* a1 = a_tile(uA, tbA + t + 1);
;             const char* a2 = last ? a_tile(nuA, ntbA) : a_tile(uA, tbA + t + 2); const char* b2 = last ? nB : cB + (size_t)(t + 2) * kstepB;
;             const char* a3 = last ? a_tile(nuA, ntbA + 1) : a_tile(uA, tbA + t + 3); const char* b3 = b2 + kstepB;
;             if (last && has_next) S.a_ready(nxt);
;             if constexpr (SP2) {
;             PG8_LDB(B0, 0, 0); PG8_LDB(B1, 0, 1); PG8_SCHED; PG8_LDA(At, 0, 0); PG8_STAGE(PG8_SA(1, 1), a1 + hstepA, voffA);
;             PG8_WAIT_V(8); PG8_WAIT_L(0); PG8_BAR; PG8_MMA(0, 0, At, B0); PG8_MMA(0, 1, At, B1); PG8_BAR; PG8_SCHED;
;             PG8_LDA(At, 0, 1); PG8_STAGE(PG8_SB(0, 0), b2, voffB); PG8_STAGE(PG8_SB(0, 1), b2 + hstepB, voffB); PG8_STAGE(PG8_SA(0, 0), a2, voffA);
.LBB0_1163:
	s_ashr_i32 s11, s10, 31
	s_lshl_b64 s[4:5], s[10:11], 20
	s_add_u32 s16, s59, s4
	s_addc_u32 s17, s62, s5
	s_and_b64 s[4:5], s[18:19], exec
	s_cselect_b32 s4, s17, s27
	s_cselect_b32 s5, s16, s26
	s_ashr_i32 s15, s14, 31
	s_lshl_b64 s[20:21], s[14:15], 20
	s_add_u32 s20, s40, s20
	s_addc_u32 s21, s41, s21
	s_and_b64 s[30:31], s[18:19], exec
	s_cselect_b32 s11, s21, s29
	s_cselect_b32 s15, s20, s28
	s_add_u32 s23, s5, 0x80
	s_addc_u32 s57, s4, 0
	s_add_u32 s64, s28, 0x10000
	v_mov_b32_e32 v2, 0
	s_addc_u32 s65, s29, 0
	v_lshl_add_u64 v[164:165], s[26:27], 0, v[160:161]
	v_lshl_add_u64 v[166:167], s[26:27], 0, v[162:163]
	s_mov_b32 s66, -2
	s_mov_b64 s[28:29], 0
	ds_read_b128 v[172:175], v169
	ds_read_b128 v[176:179], v169 offset:1024
	ds_read_b128 v[180:183], v169 offset:2048
	ds_read_b128 v[184:187], v169 offset:3072
	ds_read_b128 v[188:191], v170
	ds_read_b128 v[192:195], v170 offset:1024
	ds_read_b128 v[196:199], v170 offset:2048
	ds_read_b128 v[200:203], v170 offset:3072
	s_add_u32 s30, s26, s28
	s_addc_u32 s31, s27, s29
	s_add_u32 s36, s30, 0x100
	s_addc_u32 s37, s31, 0
	s_add_u32 s30, s30, 0x180
	s_addc_u32 s31, s31, 0
	s_cmpk_eq_i32 s28, 0xf00
	s_cselect_b32 s31, s57, s31
	s_cselect_b32 s30, s23, s30
	s_cselect_b32 s35, s11, s65
	s_cselect_b32 s34, s15, s64
	s_cselect_b32 s37, s4, s37
	s_cselect_b32 s36, s5, s36
	s_mov_b32 m0, s50
	v_lshl_add_u64 v[236:237], v[164:165], 0, s[28:29]
	ds_read_b128 v[204:207], v171
	ds_read_b128 v[208:211], v171 offset:1024
	ds_read_b128 v[212:215], v171 offset:2048
	ds_read_b128 v[216:219], v171 offset:3072
	ds_read_b128 v[220:223], v171 offset:4096
	ds_read_b128 v[224:227], v171 offset:5120
	ds_read_b128 v[228:231], v171 offset:6144
	ds_read_b128 v[232:235], v171 offset:7168
	global_load_lds_dwordx4 v[236:237], off
	v_lshl_add_u64 v[236:237], v[166:167], 0, s[28:29]
	s_mov_b32 m0, s51
	s_nop 0
	global_load_lds_dwordx4 v[236:237], off
	s_waitcnt vmcnt(8)
	s_waitcnt lgkmcnt(0)
	s_barrier
	v_mfma_f32_16x16x32_bf16 v[126:129], v[172:175], v[204:207], 0
	v_mfma_f32_16x16x32_bf16 v[122:125], v[180:183], v[204:207], 0
	v_mfma_f32_16x16x32_bf16 v[110:113], v[172:175], v[212:215], 0
	v_mfma_f32_16x16x32_bf16 v[106:109], v[180:183], v[212:215], 0
	v_mfma_f32_16x16x32_bf16 v[94:97], v[172:175], v[220:223], 0
	v_mfma_f32_16x16x32_bf16 v[90:93], v[180:183], v[220:223], 0
	v_mfma_f32_16x16x32_bf16 v[78:81], v[172:175], v[228:231], 0
	v_mfma_f32_16x16x32_bf16 v[74:77], v[180:183], v[228:231], 0
	v_mfma_f32_16x16x32_bf16 v[126:129], v[176:179], v[208:211], v[126:129]
	v_mfma_f32_16x16x32_bf16 v[122:125], v[184:187], v[208:211], v[122:125]
	v_mfma_f32_16x16x32_bf16 v[110:113], v[176:179], v[216:219], v[110:113]
	v_mfma_f32_16x16x32_bf16 v[106:109], v[184:187], v[216:219], v[106:109]
	v_mfma_f32_16x16x32_bf16 v[94:97], v[176:179], v[224:227], v[94:97]
	v_mfma_f32_16x16x32_bf16 v[90:93], v[184:187], v[224:227], v[90:93]
	v_mfma_f32_16x16x32_bf16 v[78:81], v[176:179], v[232:235], v[78:81]
	v_mfma_f32_16x16x32_bf16 v[74:77], v[184:187], v[232:235], v[74:77]
	v_mfma_f32_16x16x32_bf16 v[118:121], v[188:191], v[204:207], 0
	v_mfma_f32_16x16x32_bf16 v[114:117], v[196:199], v[204:207], 0
	v_mfma_f32_16x16x32_bf16 v[102:105], v[188:191], v[212:215], 0
	v_mfma_f32_16x16x32_bf16 v[98:101], v[196:199], v[212:215], 0
	v_mfma_f32_16x16x32_bf16 v[86:89], v[188:191], v[220:223], 0
	v_mfma_f32_16x16x32_bf16 v[82:85], v[196:199], v[220:223], 0
	v_mfma_f32_16x16x32_bf16 v[70:73], v[188:191], v[228:231], 0
	v_mfma_f32_16x16x32_bf16 v[66:69], v[196:199], v[228:231], 0
	v_mfma_f32_16x16x32_bf16 v[118:121], v[192:195], v[208:211], v[118:121]
	v_mfma_f32_16x16x32_bf16 v[114:117], v[200:203], v[208:211], v[114:117]
	v_mfma_f32_16x16x32_bf16 v[102:105], v[192:195], v[216:219], v[102:105]
	v_mfma_f32_16x16x32_bf16 v[98:101], v[200:203], v[216:219], v[98:101]
	v_mfma_f32_16x16x32_bf16 v[86:89], v[192:195], v[224:227], v[86:89]
	v_mfma_f32_16x16x32_bf16 v[82:85], v[200:203], v[224:227], v[82:85]
	v_mfma_f32_16x16x32_bf16 v[70:73], v[192:195], v[232:235], v[70:73]
	v_mfma_f32_16x16x32_bf16 v[66:69], v[200:203], v[232:235], v[66:69]
	s_barrier
	s_mov_b32 m0, s55
	v_lshl_add_u64 v[236:237], s[34:35], 0, v[134:135]
	s_add_u32 s76, s34, 0x4000
	ds_read_b128 v[204:207], v171 offset:16384
	ds_read_b128 v[208:211], v171 offset:17408
	ds_read_b128 v[212:215], v171 offset:18432
	ds_read_b128 v[216:219], v171 offset:19456
	ds_read_b128 v[220:223], v171 offset:20480
	ds_read_b128 v[224:227], v171 offset:21504
	ds_read_b128 v[228:231], v171 offset:22528
	ds_read_b128 v[232:235], v171 offset:23552
	global_load_lds_dwordx4 v[236:237], off
	v_lshl_add_u64 v[236:237], s[34:35], 0, v[130:131]
	s_mov_b32 m0, s56
	s_addc_u32 s77, s35, 0
	s_add_i32 s67, s73, s42
	global_load_lds_dwordx4 v[236:237], off
	v_lshl_add_u64 v[236:237], s[76:77], 0, v[134:135]
	s_mov_b32 m0, s67
	s_nop 0
	global_load_lds_dwordx4 v[236:237], off
	v_lshl_add_u64 v[236:237], s[76:77], 0, v[130:131]
	s_add_i32 m0, s67, 0x2000
	s_nop 0
	global_load_lds_dwordx4 v[236:237], off
	v_lshl_add_u64 v[236:237], s[36:37], 0, v[136:137]
	s_mov_b32 m0, s25
	s_nop 0
	global_load_lds_dwordx4 v[236:237], off
	v_lshl_add_u64 v[236:237], s[36:37], 0, v[132:133]
	s_mov_b32 m0, s43
	s_nop 0
	global_load_lds_dwordx4 v[236:237], off
	s_waitcnt vmcnt(8)
	s_waitcnt lgkmcnt(0)
	s_barrier
; #define PG8_STAGE(bufoff, gbase, voff) do { _Pragma("unroll") for (int _i = 0; _i < 2; ++_i) \
;         __builtin_amdgcn_global_load_lds((const unsigned*)((const char*)(gbase) + (voff)[_i]), (LAS unsigned*)(lds + (bufoff) + ldsw + _i * 8192), 16, 0, 0); } while (0)
; #define PG8_LDA(dst, b, h) do { _Pragma("unroll") for (int m = 0; m < 4; ++m) _Pragma("unroll") for (int k = 0; k < 2; ++k) dst[m][k] = *(const LAS bf16x8*)(lds + PG8_SA(b, h) + aoff + m * 2048 + k * 1024); } while (0)
; #define PG8_LDB(dst, b, h) do { _Pragma("unroll") for (int n = 0; n < 2; ++n) _Pragma("unroll") for (int k = 0; k < 2; ++k) dst[n][k] = *(const LAS bf16x8*)(lds + PG8_SB(b, h) + boff + n * 2048 + k * 1024); } while (0)
; #define PG8_MMA(ai, bj, At, Bt) do { __builtin_amdgcn_s_setprio(1); _Pragma("unroll") for (int m = 0; m < 4; ++m) _Pragma("unroll") for (int n = 0; n < 2; ++n) _Pragma("unroll") for (int k = 0; k < 2; ++k) \
;         acc[ai][bj][m][n] = __builtin_amdgcn_mfma_f32_16x16x32_bf16(Bt[n][k], At[m][k], acc[ai][bj][m][n], 0, 0, 0); __builtin_amdgcn_s_setprio(0); } while (0)
; #define PG8_WAIT_V(n) asm volatile("s_waitcnt vmcnt(" #n ")" ::: "memory")
; #define PG8_WAIT_L(n) asm volatile("s_waitcnt lgkmcnt(" #n ")" ::: "memory")
; #define PG8_BAR __builtin_amdgcn_s_barrier()
; #define PG8_SCHED __builtin_amdgcn_sched_barrier(0)
; template <class Epi, class Sched, bool ABLK = false, bool ALIGN_EPI = true, bool SP2 = true, bool BBLK = true>
; __device__ __forceinline__ void gemm_phase(LAS unsigned char* lds, const Gemm g, const Sched& S, const Epi& E) {
;     ...
;             PG8_WAIT_V(8); PG8_WAIT_L(0); PG8_BAR; PG8_MMA(1, 0, At, B0); PG8_MMA(1, 1, At, B1); PG8_BAR; PG8_SCHED;
;             PG8_LDB(B0, 1, 0); PG8_LDB(B1, 1, 1); PG8_SCHED; PG8_LDA(At, 1, 0); PG8_STAGE(PG8_SA(0, 1), a2 + hstepA, voffA);
;             PG8_WAIT_V(8); PG8_WAIT_L(0); PG8_BAR; PG8_MMA(0, 0, At, B0); PG8_MMA(0, 1, At, B1); PG8_BAR; PG8_SCHED;
	v_mfma_f32_16x16x32_bf16 v[62:65], v[172:175], v[204:207], 0
	v_mfma_f32_16x16x32_bf16 v[58:61], v[180:183], v[204:207], 0
	v_mfma_f32_16x16x32_bf16 v[46:49], v[172:175], v[212:215], 0
	v_mfma_f32_16x16x32_bf16 v[42:45], v[180:183], v[212:215], 0
	v_mfma_f32_16x16x32_bf16 v[30:33], v[172:175], v[220:223], 0
	v_mfma_f32_16x16x32_bf16 v[26:29], v[180:183], v[220:223], 0
	v_mfma_f32_16x16x32_bf16 v[14:17], v[172:175], v[228:231], 0
	v_mfma_f32_16x16x32_bf16 v[10:13], v[180:183], v[228:231], 0
	v_mfma_f32_16x16x32_bf16 v[62:65], v[176:179], v[208:211], v[62:65]
	v_mfma_f32_16x16x32_bf16 v[58:61], v[184:187], v[208:211], v[58:61]
	v_mfma_f32_16x16x32_bf16 v[46:49], v[176:179], v[216:219], v[46:49]
	v_mfma_f32_16x16x32_bf16 v[42:45], v[184:187], v[216:219], v[42:45]
	v_mfma_f32_16x16x32_bf16 v[30:33], v[176:179], v[224:227], v[30:33]
	v_mfma_f32_16x16x32_bf16 v[26:29], v[184:187], v[224:227], v[26:29]
	v_mfma_f32_16x16x32_bf16 v[14:17], v[176:179], v[232:235], v[14:17]
	v_mfma_f32_16x16x32_bf16 v[10:13], v[184:187], v[232:235], v[10:13]
	v_mfma_f32_16x16x32_bf16 v[54:57], v[188:191], v[204:207], 0
	v_mfma_f32_16x16x32_bf16 v[50:53], v[196:199], v[204:207], 0
	v_mfma_f32_16x16x32_bf16 v[38:41], v[188:191], v[212:215], 0
	v_mfma_f32_16x16x32_bf16 v[34:37], v[196:199], v[212:215], 0
	v_mfma_f32_16x16x32_bf16 v[22:25], v[188:191], v[220:223], 0
	v_mfma_f32_16x16x32_bf16 v[18:21], v[196:199], v[220:223], 0
	v_mfma_f32_16x16x32_bf16 v[6:9], v[188:191], v[228:231], 0
	v_mfma_f32_16x16x32_bf16 v[2:5], v[196:199], v[228:231], 0
	v_mfma_f32_16x16x32_bf16 v[54:57], v[192:195], v[208:211], v[54:57]
	v_mfma_f32_16x16x32_bf16 v[50:53], v[200:203], v[208:211], v[50:53]
	v_mfma_f32_16x16x32_bf16 v[38:41], v[192:195], v[216:219], v[38:41]
	v_mfma_f32_16x16x32_bf16 v[34:37], v[200:203], v[216:219], v[34:37]
	v_mfma_f32_16x16x32_bf16 v[22:25], v[192:195], v[224:227], v[22:25]
	v_mfma_f32_16x16x32_bf16 v[18:21], v[200:203], v[224:227], v[18:21]
	v_mfma_f32_16x16x32_bf16 v[6:9], v[192:195], v[232:235], v[6:9]
	v_mfma_f32_16x16x32_bf16 v[2:5], v[200:203], v[232:235], v[2:5]
	s_barrier
	v_add_u32_e32 v184, s60, v168
	v_add_u32_e32 v200, s61, v168
	ds_read_b128 v[172:175], v184
	ds_read_b128 v[176:179], v184 offset:1024
	ds_read_b128 v[180:183], v184 offset:2048
	ds_read_b128 v[184:187], v184 offset:3072
	ds_read_b128 v[188:191], v200
	ds_read_b128 v[192:195], v200 offset:1024
	ds_read_b128 v[196:199], v200 offset:2048
	ds_read_b128 v[200:203], v200 offset:3072
	s_add_u32 s36, s36, 0x80000
	s_addc_u32 s37, s37, 0
	s_mov_b32 m0, s44
	v_lshl_add_u64 v[236:237], s[36:37], 0, v[136:137]
	ds_read_b128 v[204:207], v171 offset:32768
	ds_read_b128 v[208:211], v171 offset:33792
	ds_read_b128 v[212:215], v171 offset:34816
	ds_read_b128 v[216:219], v171 offset:35840
	ds_read_b128 v[220:223], v171 offset:36864
	ds_read_b128 v[224:227], v171 offset:37888
	ds_read_b128 v[228:231], v171 offset:38912
	ds_read_b128 v[232:235], v171 offset:39936
	global_load_lds_dwordx4 v[236:237], off
	v_lshl_add_u64 v[236:237], s[36:37], 0, v[132:133]
	s_mov_b32 m0, s45
	s_nop 0
	global_load_lds_dwordx4 v[236:237], off
	s_waitcnt vmcnt(8)
	s_waitcnt lgkmcnt(0)
	s_barrier
	v_mfma_f32_16x16x32_bf16 v[126:129], v[172:175], v[204:207], v[126:129]
	v_mfma_f32_16x16x32_bf16 v[122:125], v[180:183], v[204:207], v[122:125]
	v_mfma_f32_16x16x32_bf16 v[110:113], v[172:175], v[212:215], v[110:113]
	v_mfma_f32_16x16x32_bf16 v[106:109], v[180:183], v[212:215], v[106:109]
	v_mfma_f32_16x16x32_bf16 v[94:97], v[172:175], v[220:223], v[94:97]
	v_mfma_f32_16x16x32_bf16 v[90:93], v[180:183], v[220:223], v[90:93]
	v_mfma_f32_16x16x32_bf16 v[78:81], v[172:175], v[228:231], v[78:81]
	v_mfma_f32_16x16x32_bf16 v[74:77], v[180:183], v[228:231], v[74:77]
	v_mfma_f32_16x16x32_bf16 v[126:129], v[176:179], v[208:211], v[126:129]
	v_mfma_f32_16x16x32_bf16 v[122:125], v[184:187], v[208:211], v[122:125]
	v_mfma_f32_16x16x32_bf16 v[110:113], v[176:179], v[216:219], v[110:113]
	v_mfma_f32_16x16x32_bf16 v[106:109], v[184:187], v[216:219], v[106:109]
	v_mfma_f32_16x16x32_bf16 v[94:97], v[176:179], v[224:227], v[94:97]
	v_mfma_f32_16x16x32_bf16 v[90:93], v[184:187], v[224:227], v[90:93]
	v_mfma_f32_16x16x32_bf16 v[78:81], v[176:179], v[232:235], v[78:81]
	v_mfma_f32_16x16x32_bf16 v[74:77], v[184:187], v[232:235], v[74:77]
	v_mfma_f32_16x16x32_bf16 v[118:121], v[188:191], v[204:207], v[118:121]
	v_mfma_f32_16x16x32_bf16 v[114:117], v[196:199], v[204:207], v[114:117]
	v_mfma_f32_16x16x32_bf16 v[102:105], v[188:191], v[212:215], v[102:105]
	v_mfma_f32_16x16x32_bf16 v[98:101], v[196:199], v[212:215], v[98:101]
	v_mfma_f32_16x16x32_bf16 v[86:89], v[188:191], v[220:223], v[86:89]
	v_mfma_f32_16x16x32_bf16 v[82:85], v[196:199], v[220:223], v[82:85]
	v_mfma_f32_16x16x32_bf16 v[70:73], v[188:191], v[228:231], v[70:73]
	v_mfma_f32_16x16x32_bf16 v[66:69], v[196:199], v[228:231], v[66:69]
	v_mfma_f32_16x16x32_bf16 v[118:121], v[192:195], v[208:211], v[118:121]
	v_mfma_f32_16x16x32_bf16 v[114:117], v[200:203], v[208:211], v[114:117]
	v_mfma_f32_16x16x32_bf16 v[102:105], v[192:195], v[216:219], v[102:105]
	v_mfma_f32_16x16x32_bf16 v[98:101], v[200:203], v[216:219], v[98:101]
	v_mfma_f32_16x16x32_bf16 v[86:89], v[192:195], v[224:227], v[86:89]
	v_mfma_f32_16x16x32_bf16 v[82:85], v[200:203], v[224:227], v[82:85]
	v_mfma_f32_16x16x32_bf16 v[70:73], v[192:195], v[232:235], v[70:73]
	v_mfma_f32_16x16x32_bf16 v[66:69], v[200:203], v[232:235], v[66:69]
	s_barrier
; #define PG8_STAGE(bufoff, gbase, voff) do { _Pragma("unroll") for (int _i = 0; _i < 2; ++_i) \
;         __builtin_amdgcn_global_load_lds((const unsigned*)((const char*)(gbase) + (voff)[_i]), (LAS unsigned*)(lds + (bufoff) + ldsw + _i * 8192), 16, 0, 0); } while (0)
; #define PG8_LDA(dst, b, h) do { _Pragma("unroll") for (int m = 0; m < 4; ++m) _Pragma("unroll") for (int k = 0; k < 2; ++k) dst[m][k] = *(const LAS bf16x8*)(lds + PG8_SA(b, h) + aoff + m * 2048 + k * 1024); } while (0)
; #define PG8_WAIT_V(n) asm volatile("s_waitcnt vmcnt(" #n ")" ::: "memory")
; #define PG8_WAIT_L(n) asm volatile("s_waitcnt lgkmcnt(" #n ")" ::: "memory")
; template <class Epi, class Sched, bool ABLK = false, bool ALIGN_EPI = true, bool SP2 = true, bool BBLK = true>
; __device__ __forceinline__ void gemm_phase(LAS unsigned char* lds, const Gemm g, const Sched& S, const Epi& E) {
;     ...
;         for (int t = 0; t < nt; t += 2) {
;             const bool last = (t == nt - 2);
;             const char* a1 = a_tile(uA, tbA + t + 1);
;             const char* a2 = last ? a_tile(nuA, ntbA) : a_tile(uA, tbA + t + 2); const char* b2 = last ? nB : cB + (size_t)(t + 2) * kstepB;
;             const char* a3 = last ? a_tile(nuA, ntbA + 1) : a_tile(uA, tbA + t + 3); const char* b3 = b2 + kstepB;
;             if (last && has_next) S.a_ready(nxt);
;             if constexpr (SP2) {
;             PG8_LDB(B0, 0, 0); PG8_LDB(B1, 0, 1); PG8_SCHED; PG8_LDA(At, 0, 0); PG8_STAGE(PG8_SA(1, 1), a1 + hstepA, voffA);
;             PG8_WAIT_V(8); PG8_WAIT_L(0); PG8_BAR; PG8_MMA(0, 0, At, B0); PG8_MMA(0, 1, At, B1); PG8_BAR; PG8_SCHED;
;             PG8_LDA(At, 0, 1); PG8_STAGE(PG8_SB(0, 0), b2, voffB); PG8_STAGE(PG8_SB(0, 1), b2 + hstepB, voffB); PG8_STAGE(PG8_SA(0, 0), a2, voffA);
;             PG8_WAIT_V(8); PG8_WAIT_L(0); PG8_BAR; PG8_MMA(1, 0, At, B0); PG8_MMA(1, 1, At, B1); PG8_BAR; PG8_SCHED;
;             PG8_LDB(B0, 1, 0); PG8_LDB(B1, 1, 1); PG8_SCHED; PG8_LDA(At, 1, 0); PG8_STAGE(PG8_SA(0, 1), a2 + hstepA, voffA);
;             PG8_WAIT_V(8); PG8_WAIT_L(0); PG8_BAR; PG8_MMA(0, 0, At, B0); PG8_MMA(0, 1, At, B1); PG8_BAR; PG8_SCHED;
;             PG8_LDA(At, 1, 1); PG8_STAGE(PG8_SB(1, 0), b3, voffB); PG8_STAGE(PG8_SB(1, 1), b3 + hstepB, voffB); PG8_STAGE(PG8_SA(1, 0), a3, voffA);
;             PG8_WAIT_V(8); PG8_WAIT_L(0); PG8_BAR; PG8_MMA(1, 0, At, B0); PG8_MMA(1, 1, At, B1); PG8_BAR; PG8_SCHED;
	s_add_u32 s36, s34, 0x8000
	s_addc_u32 s37, s35, 0
	s_add_i32 s67, s60, s42
	v_lshl_add_u64 v[236:237], s[36:37], 0, v[134:135]
	s_mov_b32 m0, s67
	ds_read_b128 v[204:207], v171 offset:49152
	ds_read_b128 v[208:211], v171 offset:50176
	ds_read_b128 v[212:215], v171 offset:51200
	ds_read_b128 v[216:219], v171 offset:52224
	ds_read_b128 v[220:223], v171 offset:53248
	ds_read_b128 v[224:227], v171 offset:54272
	ds_read_b128 v[228:231], v171 offset:55296
	ds_read_b128 v[232:235], v171 offset:56320
	global_load_lds_dwordx4 v[236:237], off
	s_add_i32 m0, s67, 0x2000
	s_add_u32 s34, s34, 0xc000
	v_lshl_add_u64 v[236:237], s[36:37], 0, v[130:131]
	s_addc_u32 s35, s35, 0
	s_add_i32 s36, s61, s42
	global_load_lds_dwordx4 v[236:237], off
	v_lshl_add_u64 v[236:237], s[34:35], 0, v[134:135]
	s_mov_b32 m0, s36
	s_nop 0
	global_load_lds_dwordx4 v[236:237], off
	v_lshl_add_u64 v[236:237], s[34:35], 0, v[130:131]
	s_add_i32 m0, s36, 0x2000
	s_nop 0
	global_load_lds_dwordx4 v[236:237], off
	v_lshl_add_u64 v[236:237], s[30:31], 0, v[136:137]
	s_mov_b32 m0, s48
	s_nop 0
	global_load_lds_dwordx4 v[236:237], off
	v_lshl_add_u64 v[236:237], s[30:31], 0, v[132:133]
	s_mov_b32 m0, s49
	s_nop 0
	global_load_lds_dwordx4 v[236:237], off
	s_waitcnt vmcnt(8)
	s_waitcnt lgkmcnt(0)
	s_barrier
	v_mfma_f32_16x16x32_bf16 v[62:65], v[172:175], v[204:207], v[62:65]
	v_mfma_f32_16x16x32_bf16 v[58:61], v[180:183], v[204:207], v[58:61]
	v_mfma_f32_16x16x32_bf16 v[46:49], v[172:175], v[212:215], v[46:49]
	v_mfma_f32_16x16x32_bf16 v[42:45], v[180:183], v[212:215], v[42:45]
	v_mfma_f32_16x16x32_bf16 v[30:33], v[172:175], v[220:223], v[30:33]
	v_mfma_f32_16x16x32_bf16 v[26:29], v[180:183], v[220:223], v[26:29]
	v_mfma_f32_16x16x32_bf16 v[14:17], v[172:175], v[228:231], v[14:17]
	v_mfma_f32_16x16x32_bf16 v[10:13], v[180:183], v[228:231], v[10:13]
	v_mfma_f32_16x16x32_bf16 v[62:65], v[176:179], v[208:211], v[62:65]
	v_mfma_f32_16x16x32_bf16 v[58:61], v[184:187], v[208:211], v[58:61]
	v_mfma_f32_16x16x32_bf16 v[46:49], v[176:179], v[216:219], v[46:49]
	v_mfma_f32_16x16x32_bf16 v[42:45], v[184:187], v[216:219], v[42:45]
	v_mfma_f32_16x16x32_bf16 v[30:33], v[176:179], v[224:227], v[30:33]
	v_mfma_f32_16x16x32_bf16 v[26:29], v[184:187], v[224:227], v[26:29]
	v_mfma_f32_16x16x32_bf16 v[14:17], v[176:179], v[232:235], v[14:17]
	v_mfma_f32_16x16x32_bf16 v[10:13], v[184:187], v[232:235], v[10:13]
	v_mfma_f32_16x16x32_bf16 v[54:57], v[188:191], v[204:207], v[54:57]
	v_mfma_f32_16x16x32_bf16 v[50:53], v[196:199], v[204:207], v[50:53]
	v_mfma_f32_16x16x32_bf16 v[38:41], v[188:191], v[212:215], v[38:41]
	v_mfma_f32_16x16x32_bf16 v[34:37], v[196:199], v[212:215], v[34:37]
	v_mfma_f32_16x16x32_bf16 v[22:25], v[188:191], v[220:223], v[22:25]
	v_mfma_f32_16x16x32_bf16 v[18:21], v[196:199], v[220:223], v[18:21]
	v_mfma_f32_16x16x32_bf16 v[6:9], v[188:191], v[228:231], v[6:9]
	v_mfma_f32_16x16x32_bf16 v[2:5], v[196:199], v[228:231], v[2:5]
	v_mfma_f32_16x16x32_bf16 v[54:57], v[192:195], v[208:211], v[54:57]
	v_mfma_f32_16x16x32_bf16 v[50:53], v[200:203], v[208:211], v[50:53]
	v_mfma_f32_16x16x32_bf16 v[38:41], v[192:195], v[216:219], v[38:41]
	v_mfma_f32_16x16x32_bf16 v[34:37], v[200:203], v[216:219], v[34:37]
	v_mfma_f32_16x16x32_bf16 v[22:25], v[192:195], v[224:227], v[22:25]
	v_mfma_f32_16x16x32_bf16 v[18:21], v[200:203], v[224:227], v[18:21]
	v_mfma_f32_16x16x32_bf16 v[6:9], v[192:195], v[232:235], v[6:9]
	v_mfma_f32_16x16x32_bf16 v[2:5], v[200:203], v[232:235], v[2:5]
	s_barrier
	s_add_i32 s66, s66, 2
	s_add_u32 s28, s28, 0x100
	s_addc_u32 s29, s29, 0
	s_add_u32 s64, s64, 0x10000
	s_addc_u32 s65, s65, 0
	s_cmp_gt_u32 s66, 29

; __device__ __forceinline__ unsigned pk2(float lo, float hi) { const f32x2 v = {lo, hi}; return __builtin_bit_cast(unsigned, __builtin_convertvector(v, bf16x2_t)); }
; __device__ __forceinline__ u32x4 ror8(u32x4 v) { u32x4 r;
; #pragma unroll
;     for (int i = 0; i < 4; ++i) r[i] = (unsigned)__builtin_amdgcn_mov_dpp((int)v[i], 0x128, 0xf, 0xf, true);
;     return r; }
; __device__ __forceinline__ void store_pair(unsigned char* own, size_t stride8, int hi_off, u32x4 lo, u32x4 hi, bool upper) {
;     const u32x4 tlo = ror8(lo), thi = ror8(hi);
;     const u32x4 A = upper ? thi : lo, B = upper ? hi : tlo;
;     unsigned char* pa = upper ? own - stride8 + hi_off : own;
;     unsigned char* pb = upper ? own + hi_off : own + stride8;
;     *(u32x4*)pa = A; *(u32x4*)pb = B;
; }
;     __device__ __forceinline__ void operator()(const f32x4 (&acc)[2][2][4][2], const Unit& u, int wr, int wc, int fr, int fq) const {
; #pragma unroll
;         for (int ai = 0; ai < 2; ++ai)
; #pragma unroll
;             for (int m = 0; m < 4; ++m) { unsigned char* rowp = (unsigned char*)(H + ((size_t)(u.pm * (FF / 64) + u.pn * 4 + wc) * 256 + (wr * 64 + fr + ai * 128 + m * 16)) * 64 + 8 * fq); u32x4 w[2];
; #pragma unroll
;                 for (int bj = 0; bj < 2; ++bj) { f32x4 v0 = acc[ai][bj][m][0], v1 = acc[ai][bj][m][1];
; #pragma unroll
;                     for (int j = 0; j < 4; ++j) { const float a = fmaxf(v0[j], 0.f), b = fmaxf(v1[j], 0.f); v0[j] = a * a; v1[j] = b * b; }
;                     w[bj].x = pk2(v0[0], v0[1]); w[bj].y = pk2(v0[2], v0[3]); w[bj].z = pk2(v1[0], v1[1]); w[bj].w = pk2(v1[2], v1[3]); }
;                 store_pair(rowp, (size_t)8 * 64 * 2, 64, w[0], w[1], fr >= 8); }
;     }
.LBB0_1167:
	s_lshl_b32 s4, s22, 7
	s_lshl_b32 s5, s24, 2
	s_add_i32 s5, s5, s4
	s_or_b32 s4, s5, s47
	s_ashr_i32 s5, s4, 31
	s_lshl_b64 s[4:5], s[4:5], 15
	s_add_u32 s22, s1, s4
	v_max_f32_e32 v126, 0, v126
	v_max_f32_e32 v122, 0, v122
	v_max_f32_e32 v127, 0, v127
	v_max_f32_e32 v123, 0, v123
	v_max_f32_e32 v128, 0, v128
	v_max_f32_e32 v124, 0, v124
	v_max_f32_e32 v129, 0, v129
	v_max_f32_e32 v125, 0, v125
	v_max_f32_e32 v118, 0, v118
	v_max_f32_e32 v114, 0, v114
	v_max_f32_e32 v119, 0, v119
	v_max_f32_e32 v115, 0, v115
	v_max_f32_e32 v120, 0, v120
	v_max_f32_e32 v116, 0, v116
	v_max_f32_e32 v121, 0, v121
	v_max_f32_e32 v117, 0, v117
	s_addc_u32 s23, s33, s5
	v_pk_mul_f32 v[126:127], v[126:127], v[126:127]
	v_pk_mul_f32 v[122:123], v[122:123], v[122:123]
	v_pk_mul_f32 v[128:129], v[128:129], v[128:129]
	v_pk_mul_f32 v[124:125], v[124:125], v[124:125]
	v_pk_mul_f32 v[118:119], v[118:119], v[118:119]
	v_pk_mul_f32 v[114:115], v[114:115], v[114:115]
	v_pk_mul_f32 v[120:121], v[120:121], v[120:121]
	v_pk_mul_f32 v[116:117], v[116:117], v[116:117]
	v_lshl_add_u64 v[164:165], s[22:23], 0, v[144:145]
	v_cvt_pk_bf16_f32 v126, v126, v127
	v_cvt_pk_bf16_f32 v127, v128, v129
	v_cvt_pk_bf16_f32 v128, v122, v123
	v_cvt_pk_bf16_f32 v129, v124, v125
	v_cvt_pk_bf16_f32 v118, v118, v119
	v_cvt_pk_bf16_f32 v119, v120, v121
	v_cvt_pk_bf16_f32 v114, v114, v115
	v_cvt_pk_bf16_f32 v115, v116, v117
	v_lshl_add_u64 v[122:123], v[164:165], 0, v[138:139]
	v_mov_b32_dpp v120, v126 row_ror:8 row_mask:0xf bank_mask:0xf bound_ctrl:1
	v_mov_b32_dpp v121, v127 row_ror:8 row_mask:0xf bank_mask:0xf bound_ctrl:1
	v_mov_b32_dpp v116, v128 row_ror:8 row_mask:0xf bank_mask:0xf bound_ctrl:1
	v_mov_b32_dpp v117, v129 row_ror:8 row_mask:0xf bank_mask:0xf bound_ctrl:1
	v_mov_b32_dpp v164, v118 row_ror:8 row_mask:0xf bank_mask:0xf bound_ctrl:1
	v_mov_b32_dpp v165, v119 row_ror:8 row_mask:0xf bank_mask:0xf bound_ctrl:1
	v_mov_b32_dpp v166, v114 row_ror:8 row_mask:0xf bank_mask:0xf bound_ctrl:1
	v_mov_b32_dpp v167, v115 row_ror:8 row_mask:0xf bank_mask:0xf bound_ctrl:1
	v_max_f32_e32 v110, 0, v110
	v_max_f32_e32 v106, 0, v106
	v_max_f32_e32 v111, 0, v111
	v_max_f32_e32 v107, 0, v107
	v_max_f32_e32 v112, 0, v112
	v_max_f32_e32 v108, 0, v108
	v_max_f32_e32 v113, 0, v113
	v_max_f32_e32 v109, 0, v109
	v_max_f32_e32 v102, 0, v102
	v_max_f32_e32 v98, 0, v98
	v_max_f32_e32 v103, 0, v103
	v_max_f32_e32 v99, 0, v99
	v_max_f32_e32 v104, 0, v104
	v_max_f32_e32 v100, 0, v100
	v_max_f32_e32 v105, 0, v105
	v_max_f32_e32 v101, 0, v101
	v_lshl_add_u64 v[124:125], v[122:123], 0, v[140:141]
	v_cndmask_b32_e64 v117, v117, v115, s[8:9]
	v_cndmask_b32_e64 v116, v116, v114, s[8:9]
	v_cndmask_b32_e64 v115, v121, v119, s[8:9]
	v_cndmask_b32_e64 v114, v120, v118, s[8:9]
	v_cndmask_b32_e64 v121, v129, v167, s[8:9]
	v_cndmask_b32_e64 v120, v128, v166, s[8:9]
	v_cndmask_b32_e64 v119, v127, v165, s[8:9]
	v_cndmask_b32_e64 v118, v126, v164, s[8:9]
	v_pk_mul_f32 v[110:111], v[110:111], v[110:111]
	v_pk_mul_f32 v[106:107], v[106:107], v[106:107]
	v_pk_mul_f32 v[112:113], v[112:113], v[112:113]
	v_pk_mul_f32 v[108:109], v[108:109], v[108:109]
	v_pk_mul_f32 v[102:103], v[102:103], v[102:103]
	v_pk_mul_f32 v[98:99], v[98:99], v[98:99]
	v_pk_mul_f32 v[104:105], v[104:105], v[104:105]
	v_pk_mul_f32 v[100:101], v[100:101], v[100:101]
	v_lshl_add_u64 v[122:123], v[122:123], 0, v[142:143]
	global_store_dwordx4 v[124:125], v[118:121], off
	global_store_dwordx4 v[122:123], v[114:117], off
	v_cvt_pk_bf16_f32 v110, v110, v111
	v_cvt_pk_bf16_f32 v111, v112, v113
	v_lshl_add_u64 v[114:115], s[22:23], 0, v[146:147]
	v_cvt_pk_bf16_f32 v112, v106, v107
	v_cvt_pk_bf16_f32 v113, v108, v109
	v_cvt_pk_bf16_f32 v102, v102, v103
	v_cvt_pk_bf16_f32 v103, v104, v105
	v_cvt_pk_bf16_f32 v98, v98, v99
	v_cvt_pk_bf16_f32 v99, v100, v101
	v_lshl_add_u64 v[106:107], v[114:115], 0, v[138:139]
	v_mov_b32_dpp v104, v110 row_ror:8 row_mask:0xf bank_mask:0xf bound_ctrl:1
	v_mov_b32_dpp v105, v111 row_ror:8 row_mask:0xf bank_mask:0xf bound_ctrl:1
	v_mov_b32_dpp v100, v112 row_ror:8 row_mask:0xf bank_mask:0xf bound_ctrl:1
	v_mov_b32_dpp v101, v113 row_ror:8 row_mask:0xf bank_mask:0xf bound_ctrl:1
	v_mov_b32_dpp v114, v102 row_ror:8 row_mask:0xf bank_mask:0xf bound_ctrl:1
	v_mov_b32_dpp v115, v103 row_ror:8 row_mask:0xf bank_mask:0xf bound_ctrl:1
	v_mov_b32_dpp v116, v98 row_ror:8 row_mask:0xf bank_mask:0xf bound_ctrl:1
	v_mov_b32_dpp v117, v99 row_ror:8 row_mask:0xf bank_mask:0xf bound_ctrl:1
	v_max_f32_e32 v94, 0, v94
	v_max_f32_e32 v90, 0, v90
	v_max_f32_e32 v95, 0, v95
	v_max_f32_e32 v91, 0, v91
	v_max_f32_e32 v96, 0, v96
	v_max_f32_e32 v92, 0, v92
	v_max_f32_e32 v97, 0, v97
	v_max_f32_e32 v93, 0, v93
	v_max_f32_e32 v86, 0, v86
	v_max_f32_e32 v82, 0, v82
	v_max_f32_e32 v87, 0, v87
	v_max_f32_e32 v83, 0, v83
	v_max_f32_e32 v88, 0, v88
	v_max_f32_e32 v84, 0, v84
	v_max_f32_e32 v89, 0, v89
	v_max_f32_e32 v85, 0, v85
	v_lshl_add_u64 v[108:109], v[106:107], 0, v[140:141]
	v_cndmask_b32_e64 v101, v101, v99, s[8:9]
	v_cndmask_b32_e64 v100, v100, v98, s[8:9]
	v_cndmask_b32_e64 v99, v105, v103, s[8:9]
	v_cndmask_b32_e64 v98, v104, v102, s[8:9]
	v_cndmask_b32_e64 v105, v113, v117, s[8:9]
	v_cndmask_b32_e64 v104, v112, v116, s[8:9]
	v_cndmask_b32_e64 v103, v111, v115, s[8:9]
	v_cndmask_b32_e64 v102, v110, v114, s[8:9]
	v_pk_mul_f32 v[94:95], v[94:95], v[94:95]
	v_pk_mul_f32 v[90:91], v[90:91], v[90:91]
	v_pk_mul_f32 v[96:97], v[96:97], v[96:97]
	v_pk_mul_f32 v[92:93], v[92:93], v[92:93]
	v_pk_mul_f32 v[86:87], v[86:87], v[86:87]
	v_pk_mul_f32 v[82:83], v[82:83], v[82:83]
	v_pk_mul_f32 v[88:89], v[88:89], v[88:89]
	v_pk_mul_f32 v[84:85], v[84:85], v[84:85]
; __device__ __forceinline__ unsigned pk2(float lo, float hi) { const f32x2 v = {lo, hi}; return __builtin_bit_cast(unsigned, __builtin_convertvector(v, bf16x2_t)); }
; __device__ __forceinline__ u32x4 ror8(u32x4 v) { u32x4 r;
; #pragma unroll
;     for (int i = 0; i < 4; ++i) r[i] = (unsigned)__builtin_amdgcn_mov_dpp((int)v[i], 0x128, 0xf, 0xf, true);
;     return r; }
; __device__ __forceinline__ void store_pair(unsigned char* own, size_t stride8, int hi_off, u32x4 lo, u32x4 hi, bool upper) {
;     const u32x4 tlo = ror8(lo), thi = ror8(hi);
;     const u32x4 A = upper ? thi : lo, B = upper ? hi : tlo;
;     unsigned char* pa = upper ? own - stride8 + hi_off : own;
;     unsigned char* pb = upper ? own + hi_off : own + stride8;
;     *(u32x4*)pa = A; *(u32x4*)pb = B;
; }
;     __device__ __forceinline__ void operator()(const f32x4 (&acc)[2][2][4][2], const Unit& u, int wr, int wc, int fr, int fq) const {
; #pragma unroll
;         for (int ai = 0; ai < 2; ++ai)
; #pragma unroll
;             for (int m = 0; m < 4; ++m) { unsigned char* rowp = (unsigned char*)(H + ((size_t)(u.pm * (FF / 64) + u.pn * 4 + wc) * 256 + (wr * 64 + fr + ai * 128 + m * 16)) * 64 + 8 * fq); u32x4 w[2];
; #pragma unroll
;                 for (int bj = 0; bj < 2; ++bj) { f32x4 v0 = acc[ai][bj][m][0], v1 = acc[ai][bj][m][1];
; #pragma unroll
;                     for (int j = 0; j < 4; ++j) { const float a = fmaxf(v0[j], 0.f), b = fmaxf(v1[j], 0.f); v0[j] = a * a; v1[j] = b * b; }
;                     w[bj].x = pk2(v0[0], v0[1]); w[bj].y = pk2(v0[2], v0[3]); w[bj].z = pk2(v1[0], v1[1]); w[bj].w = pk2(v1[2], v1[3]); }
;                 store_pair(rowp, (size_t)8 * 64 * 2, 64, w[0], w[1], fr >= 8); }
;     }
	v_lshl_add_u64 v[106:107], v[106:107], 0, v[142:143]
	global_store_dwordx4 v[108:109], v[102:105], off
	global_store_dwordx4 v[106:107], v[98:101], off
	v_cvt_pk_bf16_f32 v94, v94, v95
	v_cvt_pk_bf16_f32 v95, v96, v97
	v_lshl_add_u64 v[98:99], s[22:23], 0, v[148:149]
	v_cvt_pk_bf16_f32 v96, v90, v91
	v_cvt_pk_bf16_f32 v97, v92, v93
	v_cvt_pk_bf16_f32 v86, v86, v87
	v_cvt_pk_bf16_f32 v87, v88, v89
	v_cvt_pk_bf16_f32 v82, v82, v83
	v_cvt_pk_bf16_f32 v83, v84, v85
	v_lshl_add_u64 v[90:91], v[98:99], 0, v[138:139]
	v_mov_b32_dpp v88, v94 row_ror:8 row_mask:0xf bank_mask:0xf bound_ctrl:1
	v_mov_b32_dpp v89, v95 row_ror:8 row_mask:0xf bank_mask:0xf bound_ctrl:1
	v_mov_b32_dpp v84, v96 row_ror:8 row_mask:0xf bank_mask:0xf bound_ctrl:1
	v_mov_b32_dpp v85, v97 row_ror:8 row_mask:0xf bank_mask:0xf bound_ctrl:1
	v_mov_b32_dpp v98, v86 row_ror:8 row_mask:0xf bank_mask:0xf bound_ctrl:1
	v_mov_b32_dpp v99, v87 row_ror:8 row_mask:0xf bank_mask:0xf bound_ctrl:1
	v_mov_b32_dpp v100, v82 row_ror:8 row_mask:0xf bank_mask:0xf bound_ctrl:1
	v_mov_b32_dpp v101, v83 row_ror:8 row_mask:0xf bank_mask:0xf bound_ctrl:1
	v_max_f32_e32 v78, 0, v78
	v_max_f32_e32 v74, 0, v74
	v_max_f32_e32 v79, 0, v79
	v_max_f32_e32 v75, 0, v75
	v_max_f32_e32 v80, 0, v80
	v_max_f32_e32 v76, 0, v76
	v_max_f32_e32 v81, 0, v81
	v_max_f32_e32 v77, 0, v77
	v_max_f32_e32 v70, 0, v70
	v_max_f32_e32 v66, 0, v66
	v_max_f32_e32 v71, 0, v71
	v_max_f32_e32 v67, 0, v67
	v_max_f32_e32 v72, 0, v72
	v_max_f32_e32 v68, 0, v68
	v_max_f32_e32 v73, 0, v73
	v_max_f32_e32 v69, 0, v69
	v_lshl_add_u64 v[92:93], v[90:91], 0, v[140:141]
	v_cndmask_b32_e64 v85, v85, v83, s[8:9]
	v_cndmask_b32_e64 v84, v84, v82, s[8:9]
	v_cndmask_b32_e64 v83, v89, v87, s[8:9]
	v_cndmask_b32_e64 v82, v88, v86, s[8:9]
	v_cndmask_b32_e64 v89, v97, v101, s[8:9]
	v_cndmask_b32_e64 v88, v96, v100, s[8:9]
	v_cndmask_b32_e64 v87, v95, v99, s[8:9]
	v_cndmask_b32_e64 v86, v94, v98, s[8:9]
	v_pk_mul_f32 v[78:79], v[78:79], v[78:79]
	v_pk_mul_f32 v[74:75], v[74:75], v[74:75]
	v_pk_mul_f32 v[80:81], v[80:81], v[80:81]
	v_pk_mul_f32 v[76:77], v[76:77], v[76:77]
	v_pk_mul_f32 v[70:71], v[70:71], v[70:71]
	v_pk_mul_f32 v[66:67], v[66:67], v[66:67]
	v_pk_mul_f32 v[72:73], v[72:73], v[72:73]
	v_pk_mul_f32 v[68:69], v[68:69], v[68:69]
	v_lshl_add_u64 v[90:91], v[90:91], 0, v[142:143]
	global_store_dwordx4 v[92:93], v[86:89], off
	global_store_dwordx4 v[90:91], v[82:85], off
	v_cvt_pk_bf16_f32 v78, v78, v79
	v_cvt_pk_bf16_f32 v79, v80, v81
	v_lshl_add_u64 v[82:83], s[22:23], 0, v[150:151]
	v_cvt_pk_bf16_f32 v80, v74, v75
	v_cvt_pk_bf16_f32 v81, v76, v77
	v_cvt_pk_bf16_f32 v70, v70, v71
	v_cvt_pk_bf16_f32 v71, v72, v73
	v_cvt_pk_bf16_f32 v66, v66, v67
	v_cvt_pk_bf16_f32 v67, v68, v69
	v_lshl_add_u64 v[74:75], v[82:83], 0, v[138:139]
	v_mov_b32_dpp v72, v78 row_ror:8 row_mask:0xf bank_mask:0xf bound_ctrl:1
	v_mov_b32_dpp v73, v79 row_ror:8 row_mask:0xf bank_mask:0xf bound_ctrl:1
	v_mov_b32_dpp v68, v80 row_ror:8 row_mask:0xf bank_mask:0xf bound_ctrl:1
	v_mov_b32_dpp v69, v81 row_ror:8 row_mask:0xf bank_mask:0xf bound_ctrl:1
	v_mov_b32_dpp v82, v70 row_ror:8 row_mask:0xf bank_mask:0xf bound_ctrl:1
	v_mov_b32_dpp v83, v71 row_ror:8 row_mask:0xf bank_mask:0xf bound_ctrl:1
	v_mov_b32_dpp v84, v66 row_ror:8 row_mask:0xf bank_mask:0xf bound_ctrl:1
	v_mov_b32_dpp v85, v67 row_ror:8 row_mask:0xf bank_mask:0xf bound_ctrl:1
	v_max_f32_e32 v62, 0, v62
	v_max_f32_e32 v58, 0, v58
	v_max_f32_e32 v63, 0, v63
	v_max_f32_e32 v59, 0, v59
	v_max_f32_e32 v64, 0, v64
	v_max_f32_e32 v60, 0, v60
	v_max_f32_e32 v65, 0, v65
	v_max_f32_e32 v61, 0, v61
	v_max_f32_e32 v54, 0, v54
	v_max_f32_e32 v50, 0, v50
	v_max_f32_e32 v55, 0, v55
	v_max_f32_e32 v51, 0, v51
	v_max_f32_e32 v56, 0, v56
	v_max_f32_e32 v52, 0, v52
	v_max_f32_e32 v57, 0, v57
	v_max_f32_e32 v53, 0, v53
	v_lshl_add_u64 v[76:77], v[74:75], 0, v[140:141]
	v_cndmask_b32_e64 v69, v69, v67, s[8:9]
	v_cndmask_b32_e64 v68, v68, v66, s[8:9]
	v_cndmask_b32_e64 v67, v73, v71, s[8:9]
	v_cndmask_b32_e64 v66, v72, v70, s[8:9]
	v_cndmask_b32_e64 v73, v81, v85, s[8:9]
	v_cndmask_b32_e64 v72, v80, v84, s[8:9]
	v_cndmask_b32_e64 v71, v79, v83, s[8:9]
	v_cndmask_b32_e64 v70, v78, v82, s[8:9]
	v_pk_mul_f32 v[62:63], v[62:63], v[62:63]
	v_pk_mul_f32 v[58:59], v[58:59], v[58:59]
	v_pk_mul_f32 v[64:65], v[64:65], v[64:65]
	v_pk_mul_f32 v[60:61], v[60:61], v[60:61]
	v_pk_mul_f32 v[54:55], v[54:55], v[54:55]
	v_pk_mul_f32 v[50:51], v[50:51], v[50:51]
	v_pk_mul_f32 v[56:57], v[56:57], v[56:57]
	v_pk_mul_f32 v[52:53], v[52:53], v[52:53]
	v_lshl_add_u64 v[74:75], v[74:75], 0, v[142:143]
	global_store_dwordx4 v[76:77], v[70:73], off
	global_store_dwordx4 v[74:75], v[66:69], off
	v_cvt_pk_bf16_f32 v62, v62, v63
	v_cvt_pk_bf16_f32 v63, v64, v65
	v_lshl_add_u64 v[66:67], s[22:23], 0, v[152:153]
	v_cvt_pk_bf16_f32 v64, v58, v59
	v_cvt_pk_bf16_f32 v65, v60, v61
	v_cvt_pk_bf16_f32 v54, v54, v55
	v_cvt_pk_bf16_f32 v55, v56, v57
	v_cvt_pk_bf16_f32 v50, v50, v51
	v_cvt_pk_bf16_f32 v51, v52, v53
	v_lshl_add_u64 v[58:59], v[66:67], 0, v[138:139]
	v_mov_b32_dpp v56, v62 row_ror:8 row_mask:0xf bank_mask:0xf bound_ctrl:1
	v_mov_b32_dpp v57, v63 row_ror:8 row_mask:0xf bank_mask:0xf bound_ctrl:1
	v_mov_b32_dpp v52, v64 row_ror:8 row_mask:0xf bank_mask:0xf bound_ctrl:1
	v_mov_b32_dpp v53, v65 row_ror:8 row_mask:0xf bank_mask:0xf bound_ctrl:1
	v_mov_b32_dpp v66, v54 row_ror:8 row_mask:0xf bank_mask:0xf bound_ctrl:1
	v_mov_b32_dpp v67, v55 row_ror:8 row_mask:0xf bank_mask:0xf bound_ctrl:1
	v_mov_b32_dpp v68, v50 row_ror:8 row_mask:0xf bank_mask:0xf bound_ctrl:1
	v_mov_b32_dpp v69, v51 row_ror:8 row_mask:0xf bank_mask:0xf bound_ctrl:1
	v_max_f32_e32 v46, 0, v46
; __device__ __forceinline__ unsigned pk2(float lo, float hi) { const f32x2 v = {lo, hi}; return __builtin_bit_cast(unsigned, __builtin_convertvector(v, bf16x2_t)); }
; __device__ __forceinline__ u32x4 ror8(u32x4 v) { u32x4 r;
; #pragma unroll
;     for (int i = 0; i < 4; ++i) r[i] = (unsigned)__builtin_amdgcn_mov_dpp((int)v[i], 0x128, 0xf, 0xf, true);
;     return r; }
; __device__ __forceinline__ void store_pair(unsigned char* own, size_t stride8, int hi_off, u32x4 lo, u32x4 hi, bool upper) {
;     const u32x4 tlo = ror8(lo), thi = ror8(hi);
;     const u32x4 A = upper ? thi : lo, B = upper ? hi : tlo;
;     unsigned char* pa = upper ? own - stride8 + hi_off : own;
;     unsigned char* pb = upper ? own + hi_off : own + stride8;
;     *(u32x4*)pa = A; *(u32x4*)pb = B;
; }
;     __device__ __forceinline__ void operator()(const f32x4 (&acc)[2][2][4][2], const Unit& u, int wr, int wc, int fr, int fq) const {
; #pragma unroll
;         for (int ai = 0; ai < 2; ++ai)
; #pragma unroll
;             for (int m = 0; m < 4; ++m) { unsigned char* rowp = (unsigned char*)(H + ((size_t)(u.pm * (FF / 64) + u.pn * 4 + wc) * 256 + (wr * 64 + fr + ai * 128 + m * 16)) * 64 + 8 * fq); u32x4 w[2];
; #pragma unroll
;                 for (int bj = 0; bj < 2; ++bj) { f32x4 v0 = acc[ai][bj][m][0], v1 = acc[ai][bj][m][1];
; #pragma unroll
;                     for (int j = 0; j < 4; ++j) { const float a = fmaxf(v0[j], 0.f), b = fmaxf(v1[j], 0.f); v0[j] = a * a; v1[j] = b * b; }
;                     w[bj].x = pk2(v0[0], v0[1]); w[bj].y = pk2(v0[2], v0[3]); w[bj].z = pk2(v1[0], v1[1]); w[bj].w = pk2(v1[2], v1[3]); }
;                 store_pair(rowp, (size_t)8 * 64 * 2, 64, w[0], w[1], fr >= 8); }
;     }
	v_max_f32_e32 v42, 0, v42
	v_max_f32_e32 v47, 0, v47
	v_max_f32_e32 v43, 0, v43
	v_max_f32_e32 v48, 0, v48
	v_max_f32_e32 v44, 0, v44
	v_max_f32_e32 v49, 0, v49
	v_max_f32_e32 v45, 0, v45
	v_max_f32_e32 v38, 0, v38
	v_max_f32_e32 v34, 0, v34
	v_max_f32_e32 v39, 0, v39
	v_max_f32_e32 v35, 0, v35
	v_max_f32_e32 v40, 0, v40
	v_max_f32_e32 v36, 0, v36
	v_max_f32_e32 v41, 0, v41
	v_max_f32_e32 v37, 0, v37
	v_lshl_add_u64 v[60:61], v[58:59], 0, v[140:141]
	v_cndmask_b32_e64 v53, v53, v51, s[8:9]
	v_cndmask_b32_e64 v52, v52, v50, s[8:9]
	v_cndmask_b32_e64 v51, v57, v55, s[8:9]
	v_cndmask_b32_e64 v50, v56, v54, s[8:9]
	v_cndmask_b32_e64 v57, v65, v69, s[8:9]
	v_cndmask_b32_e64 v56, v64, v68, s[8:9]
	v_cndmask_b32_e64 v55, v63, v67, s[8:9]
	v_cndmask_b32_e64 v54, v62, v66, s[8:9]
	v_pk_mul_f32 v[46:47], v[46:47], v[46:47]
	v_pk_mul_f32 v[42:43], v[42:43], v[42:43]
	v_pk_mul_f32 v[48:49], v[48:49], v[48:49]
	v_pk_mul_f32 v[44:45], v[44:45], v[44:45]
	v_pk_mul_f32 v[38:39], v[38:39], v[38:39]
	v_pk_mul_f32 v[34:35], v[34:35], v[34:35]
	v_pk_mul_f32 v[40:41], v[40:41], v[40:41]
	v_pk_mul_f32 v[36:37], v[36:37], v[36:37]
	v_lshl_add_u64 v[58:59], v[58:59], 0, v[142:143]
	global_store_dwordx4 v[60:61], v[54:57], off
	global_store_dwordx4 v[58:59], v[50:53], off
	v_cvt_pk_bf16_f32 v46, v46, v47
	v_cvt_pk_bf16_f32 v47, v48, v49
	v_lshl_add_u64 v[50:51], s[22:23], 0, v[154:155]
	v_cvt_pk_bf16_f32 v48, v42, v43
	v_cvt_pk_bf16_f32 v49, v44, v45
	v_cvt_pk_bf16_f32 v38, v38, v39
	v_cvt_pk_bf16_f32 v39, v40, v41
	v_cvt_pk_bf16_f32 v34, v34, v35
	v_cvt_pk_bf16_f32 v35, v36, v37
	v_lshl_add_u64 v[42:43], v[50:51], 0, v[138:139]
	v_mov_b32_dpp v40, v46 row_ror:8 row_mask:0xf bank_mask:0xf bound_ctrl:1
	v_mov_b32_dpp v41, v47 row_ror:8 row_mask:0xf bank_mask:0xf bound_ctrl:1
	v_mov_b32_dpp v36, v48 row_ror:8 row_mask:0xf bank_mask:0xf bound_ctrl:1
	v_mov_b32_dpp v37, v49 row_ror:8 row_mask:0xf bank_mask:0xf bound_ctrl:1
	v_mov_b32_dpp v50, v38 row_ror:8 row_mask:0xf bank_mask:0xf bound_ctrl:1
	v_mov_b32_dpp v51, v39 row_ror:8 row_mask:0xf bank_mask:0xf bound_ctrl:1
	v_mov_b32_dpp v52, v34 row_ror:8 row_mask:0xf bank_mask:0xf bound_ctrl:1
	v_mov_b32_dpp v53, v35 row_ror:8 row_mask:0xf bank_mask:0xf bound_ctrl:1
	v_max_f32_e32 v30, 0, v30
	v_max_f32_e32 v26, 0, v26
	v_max_f32_e32 v31, 0, v31
	v_max_f32_e32 v27, 0, v27
	v_max_f32_e32 v32, 0, v32
	v_max_f32_e32 v28, 0, v28
	v_max_f32_e32 v33, 0, v33
	v_max_f32_e32 v29, 0, v29
	v_max_f32_e32 v22, 0, v22
	v_max_f32_e32 v18, 0, v18
	v_max_f32_e32 v23, 0, v23
	v_max_f32_e32 v19, 0, v19
	v_max_f32_e32 v24, 0, v24
	v_max_f32_e32 v20, 0, v20
	v_max_f32_e32 v25, 0, v25
	v_max_f32_e32 v21, 0, v21
	v_lshl_add_u64 v[44:45], v[42:43], 0, v[140:141]
	v_cndmask_b32_e64 v37, v37, v35, s[8:9]
	v_cndmask_b32_e64 v36, v36, v34, s[8:9]
	v_cndmask_b32_e64 v35, v41, v39, s[8:9]
	v_cndmask_b32_e64 v34, v40, v38, s[8:9]
	v_cndmask_b32_e64 v41, v49, v53, s[8:9]
	v_cndmask_b32_e64 v40, v48, v52, s[8:9]
	v_cndmask_b32_e64 v39, v47, v51, s[8:9]
	v_cndmask_b32_e64 v38, v46, v50, s[8:9]
	v_pk_mul_f32 v[30:31], v[30:31], v[30:31]
	v_pk_mul_f32 v[26:27], v[26:27], v[26:27]
	v_pk_mul_f32 v[32:33], v[32:33], v[32:33]
	v_pk_mul_f32 v[28:29], v[28:29], v[28:29]
	v_pk_mul_f32 v[22:23], v[22:23], v[22:23]
	v_pk_mul_f32 v[18:19], v[18:19], v[18:19]
	v_pk_mul_f32 v[24:25], v[24:25], v[24:25]
	v_pk_mul_f32 v[20:21], v[20:21], v[20:21]
	v_lshl_add_u64 v[42:43], v[42:43], 0, v[142:143]
	global_store_dwordx4 v[44:45], v[38:41], off
	global_store_dwordx4 v[42:43], v[34:37], off
	v_cvt_pk_bf16_f32 v30, v30, v31
	v_cvt_pk_bf16_f32 v31, v32, v33
	v_lshl_add_u64 v[34:35], s[22:23], 0, v[156:157]
	v_cvt_pk_bf16_f32 v32, v26, v27
; __device__ __forceinline__ unsigned pk2(float lo, float hi) { const f32x2 v = {lo, hi}; return __builtin_bit_cast(unsigned, __builtin_convertvector(v, bf16x2_t)); }
; template <class Epi, class Sched, bool ABLK = false, bool ALIGN_EPI = true, bool SP2 = true, bool BBLK = true>
; __device__ __forceinline__ void gemm_phase(LAS unsigned char* lds, const Gemm g, const Sched& S, const Epi& E) {
;     ...
;         if (!has_next) break;
; #pragma unroll
;         for (int a = 0; a < 2; ++a)
; #pragma unroll
;             for (int b = 0; b < 2; ++b)
; #pragma unroll
;                 for (int m = 0; m < 4; ++m)
; #pragma unroll
;                     for (int n = 0; n < 2; ++n) acc[a][b][m][n] = (f32x4){0.f, 0.f, 0.f, 0.f};
;         cur = nxt; uA = nuA; tbA = ntbA; cB = nB; ++ui;
;         if constexpr (ALIGN_EPI) { if (wr == 1) PG8_BAR; }
; __device__ __forceinline__ u32x4 ror8(u32x4 v) { u32x4 r;
; #pragma unroll
;     for (int i = 0; i < 4; ++i) r[i] = (unsigned)__builtin_amdgcn_mov_dpp((int)v[i], 0x128, 0xf, 0xf, true);
;     return r; }
; __device__ __forceinline__ void store_pair(unsigned char* own, size_t stride8, int hi_off, u32x4 lo, u32x4 hi, bool upper) {
;     const u32x4 tlo = ror8(lo), thi = ror8(hi);
;     const u32x4 A = upper ? thi : lo, B = upper ? hi : tlo;
;     unsigned char* pa = upper ? own - stride8 + hi_off : own;
;     unsigned char* pb = upper ? own + hi_off : own + stride8;
;     *(u32x4*)pa = A; *(u32x4*)pb = B;
; }
;     __device__ __forceinline__ void operator()(const f32x4 (&acc)[2][2][4][2], const Unit& u, int wr, int wc, int fr, int fq) const {
; #pragma unroll
;         for (int ai = 0; ai < 2; ++ai)
; #pragma unroll
;             for (int m = 0; m < 4; ++m) { unsigned char* rowp = (unsigned char*)(H + ((size_t)(u.pm * (FF / 64) + u.pn * 4 + wc) * 256 + (wr * 64 + fr + ai * 128 + m * 16)) * 64 + 8 * fq); u32x4 w[2];
; #pragma unroll
;                 for (int bj = 0; bj < 2; ++bj) { f32x4 v0 = acc[ai][bj][m][0], v1 = acc[ai][bj][m][1];
; #pragma unroll
;                     for (int j = 0; j < 4; ++j) { const float a = fmaxf(v0[j], 0.f), b = fmaxf(v1[j], 0.f); v0[j] = a * a; v1[j] = b * b; }
;                     w[bj].x = pk2(v0[0], v0[1]); w[bj].y = pk2(v0[2], v0[3]); w[bj].z = pk2(v1[0], v1[1]); w[bj].w = pk2(v1[2], v1[3]); }
;                 store_pair(rowp, (size_t)8 * 64 * 2, 64, w[0], w[1], fr >= 8); }
;     }
	v_cvt_pk_bf16_f32 v33, v28, v29
	v_cvt_pk_bf16_f32 v22, v22, v23
	v_cvt_pk_bf16_f32 v23, v24, v25
	v_cvt_pk_bf16_f32 v18, v18, v19
	v_cvt_pk_bf16_f32 v19, v20, v21
	v_lshl_add_u64 v[26:27], v[34:35], 0, v[138:139]
	v_mov_b32_dpp v24, v30 row_ror:8 row_mask:0xf bank_mask:0xf bound_ctrl:1
	v_mov_b32_dpp v25, v31 row_ror:8 row_mask:0xf bank_mask:0xf bound_ctrl:1
	v_mov_b32_dpp v20, v32 row_ror:8 row_mask:0xf bank_mask:0xf bound_ctrl:1
	v_mov_b32_dpp v21, v33 row_ror:8 row_mask:0xf bank_mask:0xf bound_ctrl:1
	v_mov_b32_dpp v34, v22 row_ror:8 row_mask:0xf bank_mask:0xf bound_ctrl:1
	v_mov_b32_dpp v35, v23 row_ror:8 row_mask:0xf bank_mask:0xf bound_ctrl:1
	v_mov_b32_dpp v36, v18 row_ror:8 row_mask:0xf bank_mask:0xf bound_ctrl:1
	v_mov_b32_dpp v37, v19 row_ror:8 row_mask:0xf bank_mask:0xf bound_ctrl:1
	v_max_f32_e32 v14, 0, v14
	v_max_f32_e32 v10, 0, v10
	v_max_f32_e32 v15, 0, v15
	v_max_f32_e32 v11, 0, v11
	v_max_f32_e32 v16, 0, v16
	v_max_f32_e32 v12, 0, v12
	v_max_f32_e32 v17, 0, v17
	v_max_f32_e32 v13, 0, v13
	v_max_f32_e32 v6, 0, v6
	v_max_f32_e32 v2, 0, v2
	v_max_f32_e32 v7, 0, v7
	v_max_f32_e32 v3, 0, v3
	v_max_f32_e32 v8, 0, v8
	v_max_f32_e32 v4, 0, v4
	v_max_f32_e32 v9, 0, v9
	v_max_f32_e32 v5, 0, v5
	v_lshl_add_u64 v[28:29], v[26:27], 0, v[140:141]
	v_cndmask_b32_e64 v21, v21, v19, s[8:9]
	v_cndmask_b32_e64 v20, v20, v18, s[8:9]
	v_cndmask_b32_e64 v19, v25, v23, s[8:9]
	v_cndmask_b32_e64 v18, v24, v22, s[8:9]
	v_cndmask_b32_e64 v25, v33, v37, s[8:9]
	v_cndmask_b32_e64 v24, v32, v36, s[8:9]
	v_cndmask_b32_e64 v23, v31, v35, s[8:9]
	v_cndmask_b32_e64 v22, v30, v34, s[8:9]
	v_pk_mul_f32 v[14:15], v[14:15], v[14:15]
	v_pk_mul_f32 v[10:11], v[10:11], v[10:11]
	v_pk_mul_f32 v[16:17], v[16:17], v[16:17]
	v_pk_mul_f32 v[12:13], v[12:13], v[12:13]
	v_pk_mul_f32 v[6:7], v[6:7], v[6:7]
	v_pk_mul_f32 v[2:3], v[2:3], v[2:3]
	v_pk_mul_f32 v[8:9], v[8:9], v[8:9]
	v_pk_mul_f32 v[4:5], v[4:5], v[4:5]
	v_lshl_add_u64 v[26:27], v[26:27], 0, v[142:143]
	global_store_dwordx4 v[28:29], v[22:25], off
	global_store_dwordx4 v[26:27], v[18:21], off
	v_cvt_pk_bf16_f32 v14, v14, v15
	v_cvt_pk_bf16_f32 v15, v16, v17
	v_lshl_add_u64 v[18:19], s[22:23], 0, v[158:159]
	v_cvt_pk_bf16_f32 v16, v10, v11
	v_cvt_pk_bf16_f32 v17, v12, v13
	v_cvt_pk_bf16_f32 v6, v6, v7
	v_cvt_pk_bf16_f32 v7, v8, v9
	v_cvt_pk_bf16_f32 v2, v2, v3
	v_cvt_pk_bf16_f32 v3, v4, v5
	v_lshl_add_u64 v[10:11], v[18:19], 0, v[138:139]
	v_mov_b32_dpp v8, v14 row_ror:8 row_mask:0xf bank_mask:0xf bound_ctrl:1
	v_mov_b32_dpp v9, v15 row_ror:8 row_mask:0xf bank_mask:0xf bound_ctrl:1
	v_mov_b32_dpp v4, v16 row_ror:8 row_mask:0xf bank_mask:0xf bound_ctrl:1
	v_mov_b32_dpp v5, v17 row_ror:8 row_mask:0xf bank_mask:0xf bound_ctrl:1
	v_mov_b32_dpp v18, v6 row_ror:8 row_mask:0xf bank_mask:0xf bound_ctrl:1
	v_mov_b32_dpp v19, v7 row_ror:8 row_mask:0xf bank_mask:0xf bound_ctrl:1
	v_mov_b32_dpp v20, v2 row_ror:8 row_mask:0xf bank_mask:0xf bound_ctrl:1
	v_mov_b32_dpp v21, v3 row_ror:8 row_mask:0xf bank_mask:0xf bound_ctrl:1
	v_lshl_add_u64 v[12:13], v[10:11], 0, v[140:141]
	v_cndmask_b32_e64 v5, v5, v3, s[8:9]
	v_cndmask_b32_e64 v4, v4, v2, s[8:9]
	v_cndmask_b32_e64 v3, v9, v7, s[8:9]
	v_cndmask_b32_e64 v2, v8, v6, s[8:9]
	v_cndmask_b32_e64 v9, v17, v21, s[8:9]
	v_cndmask_b32_e64 v8, v16, v20, s[8:9]
	v_cndmask_b32_e64 v7, v15, v19, s[8:9]
	v_cndmask_b32_e64 v6, v14, v18, s[8:9]
	s_andn2_b64 vcc, exec, s[18:19]
	s_mov_b64 s[4:5], -1
	v_lshl_add_u64 v[10:11], v[10:11], 0, v[142:143]
	global_store_dwordx4 v[12:13], v[6:9], off
	global_store_dwordx4 v[10:11], v[2:5], off
	s_cbranch_vccnz .LBB0_1160
	s_andn2_b64 vcc, exec, s[2:3]
	s_cbranch_vccnz .LBB0_1159
	s_barrier
	s_branch .LBB0_1159

; #define PG8_STAGE(bufoff, gbase, voff) do { _Pragma("unroll") for (int _i = 0; _i < 2; ++_i) \
;         __builtin_amdgcn_global_load_lds((const unsigned*)((const char*)(gbase) + (voff)[_i]), (LAS unsigned*)(lds + (bufoff) + ldsw + _i * 8192), 16, 0, 0); } while (0)
; #define PG8_LDA(dst, b, h) do { _Pragma("unroll") for (int m = 0; m < 4; ++m) _Pragma("unroll") for (int k = 0; k < 2; ++k) dst[m][k] = *(const LAS bf16x8*)(lds + PG8_SA(b, h) + aoff + m * 2048 + k * 1024); } while (0)
; #define PG8_LDB(dst, b, h) do { _Pragma("unroll") for (int n = 0; n < 2; ++n) _Pragma("unroll") for (int k = 0; k < 2; ++k) dst[n][k] = *(const LAS bf16x8*)(lds + PG8_SB(b, h) + boff + n * 2048 + k * 1024); } while (0)
; #define PG8_WAIT_V(n) asm volatile("s_waitcnt vmcnt(" #n ")" ::: "memory")
; #define PG8_WAIT_L(n) asm volatile("s_waitcnt lgkmcnt(" #n ")" ::: "memory")
; template <class Epi, class Sched, bool ABLK = false, bool ALIGN_EPI = true, bool SP2 = true, bool BBLK = true>
; __device__ __forceinline__ void gemm_phase(LAS unsigned char* lds, const Gemm g, const Sched& S, const Epi& E) {
;     ...
;         const bool has_next = S.next(ui + 1, nxt);
;         const int nt = cur.nt;
;         const char* nuA = has_next ? a_unit(nxt) : uA; const int ntbA = has_next ? nxt.k0 / BK : tbA; const char* nB = has_next ? (const char*)g.Bt + (size_t)nxt.pn * tstepB + b_k0(nxt.k0) : cB;
;         for (int t = 0; t < nt; t += 2) {
;             const bool last = (t == nt - 2);
;             const char* a1 = a_tile(uA, tbA + t + 1);
;             const char* a2 = last ? a_tile(nuA, ntbA) : a_tile(uA, tbA + t + 2); const char* b2 = last ? nB : cB + (size_t)(t + 2) * kstepB;
;             const char* a3 = last ? a_tile(nuA, ntbA + 1) : a_tile(uA, tbA + t + 3); const char* b3 = b2 + kstepB;
;             if (last && has_next) S.a_ready(nxt);
;             if constexpr (SP2) {
;             PG8_LDB(B0, 0, 0); PG8_LDB(B1, 0, 1); PG8_SCHED; PG8_LDA(At, 0, 0); PG8_STAGE(PG8_SA(1, 1), a1 + hstepA, voffA);
;             PG8_WAIT_V(8); PG8_WAIT_L(0); PG8_BAR; PG8_MMA(0, 0, At, B0); PG8_MMA(0, 1, At, B1); PG8_BAR; PG8_SCHED;
;             PG8_LDA(At, 0, 1); PG8_STAGE(PG8_SB(0, 0), b2, voffB); PG8_STAGE(PG8_SB(0, 1), b2 + hstepB, voffB); PG8_STAGE(PG8_SA(0, 0), a2, voffA);
;             PG8_WAIT_V(8); PG8_WAIT_L(0); PG8_BAR; PG8_MMA(1, 0, At, B0); PG8_MMA(1, 1, At, B1); PG8_BAR; PG8_SCHED;
.LBB0_1228:
	s_ashr_i32 s81, s80, 31
	s_andn2_b64 vcc, exec, s[4:5]
	s_lshl_b64 s[16:17], s[80:81], 22
	s_add_u32 s16, s1, s16
	s_addc_u32 s17, s33, s17
	s_and_b64 s[18:19], s[4:5], exec
	s_cselect_b32 s27, s17, s25
	s_cselect_b32 s46, s16, s24
	s_ashr_i32 s18, s0, 31
	s_lshr_b32 s18, s18, 26
	s_add_i32 s18, s0, s18
	s_ashr_i32 s18, s18, 6
	s_and_b64 s[20:21], s[4:5], exec
	s_cselect_b32 s28, s18, s26
	s_ashr_i32 s79, s78, 31
	s_lshl_b64 s[20:21], s[78:79], 22
	s_add_u32 s29, s30, s20
	s_addc_u32 s47, s31, s21
	s_ashr_i32 s19, s18, 31
	s_lshl_b64 s[20:21], s[18:19], 15
	s_add_u32 s20, s29, s20
	s_addc_u32 s21, s47, s21
	v_cndmask_b32_e64 v2, 0, 1, s[4:5]
	s_and_b64 s[4:5], s[4:5], exec
	s_cselect_b32 s4, s21, s23
	s_cselect_b32 s5, s20, s22
	s_ashr_i32 s29, s28, 31
	s_lshl_b64 s[28:29], s[28:29], 15
	s_add_u32 s19, s46, s28
	s_addc_u32 s46, s27, s29
	s_add_u32 s47, s19, 0x8000
	s_addc_u32 s48, s46, 0
	s_add_u32 s49, s22, 0x10000
	s_addc_u32 s50, s23, 0
	s_ashr_i32 s27, s26, 31
	v_cmp_ne_u32_e64 s[10:11], 1, v2
	s_lshl_b64 s[22:23], s[26:27], 15
	v_lshl_add_u64 v[2:3], s[24:25], 0, v[138:139]
	s_add_u32 s51, s24, s22
	v_lshl_add_u64 v[142:143], v[2:3], 0, s[22:23]
	v_lshl_add_u64 v[2:3], s[24:25], 0, v[140:141]
	s_addc_u32 s55, s25, s23
	v_lshl_add_u64 v[144:145], v[2:3], 0, s[22:23]
	s_lshl_b32 s22, s44, 15
	s_add_i32 s22, s22, 0xfff00000
	v_mov_b32_e32 v2, 0
	s_add_u32 s56, s22, 0xf0000
	s_mov_b32 s57, 0
	s_mov_b64 s[22:23], 0
	ds_read_b128 v[152:155], v149
	ds_read_b128 v[156:159], v149 offset:1024
	ds_read_b128 v[160:163], v149 offset:2048
	ds_read_b128 v[164:167], v149 offset:3072
	ds_read_b128 v[168:171], v150
	ds_read_b128 v[172:175], v150 offset:1024
	ds_read_b128 v[176:179], v150 offset:2048
	ds_read_b128 v[180:183], v150 offset:3072
	s_add_u32 s24, s51, s22
	s_addc_u32 s25, s55, s23
	s_add_u32 s28, s24, 0x10000
	s_addc_u32 s29, s25, 0
	s_add_i32 s57, s57, 2
	s_add_u32 s26, s49, s22
	s_addc_u32 s27, s50, s23
	s_add_u32 s24, s24, 0x18000
	s_addc_u32 s25, s25, 0
	s_cmp_eq_u32 s56, s22
	s_cselect_b32 s25, s48, s25
	s_cselect_b32 s24, s47, s24
	s_cselect_b32 s27, s4, s27
	s_cselect_b32 s26, s5, s26
	s_cselect_b32 s29, s46, s29
	s_cselect_b32 s28, s19, s28
	v_lshl_add_u64 v[216:217], v[142:143], 0, s[22:23]
	s_add_i32 m0, s35, 0xc000
	ds_read_b128 v[184:187], v151
	ds_read_b128 v[188:191], v151 offset:1024
	ds_read_b128 v[192:195], v151 offset:2048
	ds_read_b128 v[196:199], v151 offset:3072
	ds_read_b128 v[200:203], v151 offset:4096
	ds_read_b128 v[204:207], v151 offset:5120
	ds_read_b128 v[208:211], v151 offset:6144
	ds_read_b128 v[212:215], v151 offset:7168
	global_load_lds_dwordx4 v[216:217], off
	v_lshl_add_u64 v[216:217], v[144:145], 0, s[22:23]
	s_add_i32 m0, s35, 0xe000
	s_nop 0
	global_load_lds_dwordx4 v[216:217], off
	s_waitcnt vmcnt(8)
	s_waitcnt lgkmcnt(0)
	s_barrier
	v_mfma_f32_16x16x32_bf16 v[126:129], v[152:155], v[184:187], 0
	v_mfma_f32_16x16x32_bf16 v[122:125], v[160:163], v[184:187], 0
	v_mfma_f32_16x16x32_bf16 v[110:113], v[152:155], v[192:195], 0
	v_mfma_f32_16x16x32_bf16 v[106:109], v[160:163], v[192:195], 0
	v_mfma_f32_16x16x32_bf16 v[94:97], v[152:155], v[200:203], 0
	v_mfma_f32_16x16x32_bf16 v[90:93], v[160:163], v[200:203], 0
	v_mfma_f32_16x16x32_bf16 v[78:81], v[152:155], v[208:211], 0
	v_mfma_f32_16x16x32_bf16 v[74:77], v[160:163], v[208:211], 0
	v_mfma_f32_16x16x32_bf16 v[126:129], v[156:159], v[188:191], v[126:129]
	v_mfma_f32_16x16x32_bf16 v[122:125], v[164:167], v[188:191], v[122:125]
	v_mfma_f32_16x16x32_bf16 v[110:113], v[156:159], v[196:199], v[110:113]
	v_mfma_f32_16x16x32_bf16 v[106:109], v[164:167], v[196:199], v[106:109]
	v_mfma_f32_16x16x32_bf16 v[94:97], v[156:159], v[204:207], v[94:97]
	v_mfma_f32_16x16x32_bf16 v[90:93], v[164:167], v[204:207], v[90:93]
	v_mfma_f32_16x16x32_bf16 v[78:81], v[156:159], v[212:215], v[78:81]
	v_mfma_f32_16x16x32_bf16 v[74:77], v[164:167], v[212:215], v[74:77]
	v_mfma_f32_16x16x32_bf16 v[118:121], v[168:171], v[184:187], 0
	v_mfma_f32_16x16x32_bf16 v[114:117], v[176:179], v[184:187], 0
	v_mfma_f32_16x16x32_bf16 v[102:105], v[168:171], v[192:195], 0
	v_mfma_f32_16x16x32_bf16 v[98:101], v[176:179], v[192:195], 0
	v_mfma_f32_16x16x32_bf16 v[86:89], v[168:171], v[200:203], 0
	v_mfma_f32_16x16x32_bf16 v[82:85], v[176:179], v[200:203], 0
	v_mfma_f32_16x16x32_bf16 v[70:73], v[168:171], v[208:211], 0
	v_mfma_f32_16x16x32_bf16 v[66:69], v[176:179], v[208:211], 0
	v_mfma_f32_16x16x32_bf16 v[118:121], v[172:175], v[188:191], v[118:121]
	v_mfma_f32_16x16x32_bf16 v[114:117], v[180:183], v[188:191], v[114:117]
	v_mfma_f32_16x16x32_bf16 v[102:105], v[172:175], v[196:199], v[102:105]
	v_mfma_f32_16x16x32_bf16 v[98:101], v[180:183], v[196:199], v[98:101]
	v_mfma_f32_16x16x32_bf16 v[86:89], v[172:175], v[204:207], v[86:89]
	v_mfma_f32_16x16x32_bf16 v[82:85], v[180:183], v[204:207], v[82:85]
	v_mfma_f32_16x16x32_bf16 v[70:73], v[172:175], v[212:215], v[70:73]
	v_mfma_f32_16x16x32_bf16 v[66:69], v[180:183], v[212:215], v[66:69]
	s_barrier
	s_add_i32 s59, s72, s34
	v_lshl_add_u64 v[216:217], s[26:27], 0, v[130:131]
	s_mov_b32 m0, s59
	ds_read_b128 v[184:187], v151 offset:16384
	ds_read_b128 v[188:191], v151 offset:17408
	ds_read_b128 v[192:195], v151 offset:18432
	ds_read_b128 v[196:199], v151 offset:19456
	ds_read_b128 v[200:203], v151 offset:20480
	ds_read_b128 v[204:207], v151 offset:21504
	ds_read_b128 v[208:211], v151 offset:22528
	ds_read_b128 v[212:215], v151 offset:23552
	global_load_lds_dwordx4 v[216:217], off
	s_add_i32 m0, s59, 0x2000
	s_add_u32 s64, s26, 0x4000
	v_lshl_add_u64 v[216:217], s[26:27], 0, v[132:133]
	s_addc_u32 s65, s27, 0
	s_add_i32 s59, s73, s34
	global_load_lds_dwordx4 v[216:217], off
	v_lshl_add_u64 v[216:217], s[64:65], 0, v[130:131]
	s_mov_b32 m0, s59
	s_nop 0
	global_load_lds_dwordx4 v[216:217], off
	v_lshl_add_u64 v[216:217], s[64:65], 0, v[132:133]
	s_add_i32 m0, s59, 0x2000
	s_nop 0
	global_load_lds_dwordx4 v[216:217], off
	v_lshl_add_u64 v[216:217], s[28:29], 0, v[130:131]
	s_mov_b32 m0, s35
	s_nop 0
	global_load_lds_dwordx4 v[216:217], off
	v_lshl_add_u64 v[216:217], s[28:29], 0, v[132:133]
	s_mov_b32 m0, s36
	s_nop 0
	global_load_lds_dwordx4 v[216:217], off
	s_waitcnt vmcnt(8)
	s_waitcnt lgkmcnt(0)
	s_barrier
; #define PG8_STAGE(bufoff, gbase, voff) do { _Pragma("unroll") for (int _i = 0; _i < 2; ++_i) \
;         __builtin_amdgcn_global_load_lds((const unsigned*)((const char*)(gbase) + (voff)[_i]), (LAS unsigned*)(lds + (bufoff) + ldsw + _i * 8192), 16, 0, 0); } while (0)
; #define PG8_LDA(dst, b, h) do { _Pragma("unroll") for (int m = 0; m < 4; ++m) _Pragma("unroll") for (int k = 0; k < 2; ++k) dst[m][k] = *(const LAS bf16x8*)(lds + PG8_SA(b, h) + aoff + m * 2048 + k * 1024); } while (0)
; #define PG8_LDB(dst, b, h) do { _Pragma("unroll") for (int n = 0; n < 2; ++n) _Pragma("unroll") for (int k = 0; k < 2; ++k) dst[n][k] = *(const LAS bf16x8*)(lds + PG8_SB(b, h) + boff + n * 2048 + k * 1024); } while (0)
; #define PG8_MMA(ai, bj, At, Bt) do { __builtin_amdgcn_s_setprio(1); _Pragma("unroll") for (int m = 0; m < 4; ++m) _Pragma("unroll") for (int n = 0; n < 2; ++n) _Pragma("unroll") for (int k = 0; k < 2; ++k) \
;         acc[ai][bj][m][n] = __builtin_amdgcn_mfma_f32_16x16x32_bf16(Bt[n][k], At[m][k], acc[ai][bj][m][n], 0, 0, 0); __builtin_amdgcn_s_setprio(0); } while (0)
; #define PG8_WAIT_V(n) asm volatile("s_waitcnt vmcnt(" #n ")" ::: "memory")
; #define PG8_WAIT_L(n) asm volatile("s_waitcnt lgkmcnt(" #n ")" ::: "memory")
; #define PG8_BAR __builtin_amdgcn_s_barrier()
; #define PG8_SCHED __builtin_amdgcn_sched_barrier(0)
; template <class Epi, class Sched, bool ABLK = false, bool ALIGN_EPI = true, bool SP2 = true, bool BBLK = true>
; __device__ __forceinline__ void gemm_phase(LAS unsigned char* lds, const Gemm g, const Sched& S, const Epi& E) {
;     ...
;             PG8_LDA(At, 0, 1); PG8_STAGE(PG8_SB(0, 0), b2, voffB); PG8_STAGE(PG8_SB(0, 1), b2 + hstepB, voffB); PG8_STAGE(PG8_SA(0, 0), a2, voffA);
;             PG8_WAIT_V(8); PG8_WAIT_L(0); PG8_BAR; PG8_MMA(1, 0, At, B0); PG8_MMA(1, 1, At, B1); PG8_BAR; PG8_SCHED;
;             PG8_LDB(B0, 1, 0); PG8_LDB(B1, 1, 1); PG8_SCHED; PG8_LDA(At, 1, 0); PG8_STAGE(PG8_SA(0, 1), a2 + hstepA, voffA);
;             PG8_WAIT_V(8); PG8_WAIT_L(0); PG8_BAR; PG8_MMA(0, 0, At, B0); PG8_MMA(0, 1, At, B1); PG8_BAR; PG8_SCHED;
	v_mfma_f32_16x16x32_bf16 v[62:65], v[152:155], v[184:187], 0
	v_mfma_f32_16x16x32_bf16 v[58:61], v[160:163], v[184:187], 0
	v_mfma_f32_16x16x32_bf16 v[46:49], v[152:155], v[192:195], 0
	v_mfma_f32_16x16x32_bf16 v[42:45], v[160:163], v[192:195], 0
	v_mfma_f32_16x16x32_bf16 v[30:33], v[152:155], v[200:203], 0
	v_mfma_f32_16x16x32_bf16 v[26:29], v[160:163], v[200:203], 0
	v_mfma_f32_16x16x32_bf16 v[14:17], v[152:155], v[208:211], 0
	v_mfma_f32_16x16x32_bf16 v[10:13], v[160:163], v[208:211], 0
	v_mfma_f32_16x16x32_bf16 v[62:65], v[156:159], v[188:191], v[62:65]
	v_mfma_f32_16x16x32_bf16 v[58:61], v[164:167], v[188:191], v[58:61]
	v_mfma_f32_16x16x32_bf16 v[46:49], v[156:159], v[196:199], v[46:49]
	v_mfma_f32_16x16x32_bf16 v[42:45], v[164:167], v[196:199], v[42:45]
	v_mfma_f32_16x16x32_bf16 v[30:33], v[156:159], v[204:207], v[30:33]
	v_mfma_f32_16x16x32_bf16 v[26:29], v[164:167], v[204:207], v[26:29]
	v_mfma_f32_16x16x32_bf16 v[14:17], v[156:159], v[212:215], v[14:17]
	v_mfma_f32_16x16x32_bf16 v[10:13], v[164:167], v[212:215], v[10:13]
	v_mfma_f32_16x16x32_bf16 v[54:57], v[168:171], v[184:187], 0
	v_mfma_f32_16x16x32_bf16 v[50:53], v[176:179], v[184:187], 0
	v_mfma_f32_16x16x32_bf16 v[38:41], v[168:171], v[192:195], 0
	v_mfma_f32_16x16x32_bf16 v[34:37], v[176:179], v[192:195], 0
	v_mfma_f32_16x16x32_bf16 v[22:25], v[168:171], v[200:203], 0
	v_mfma_f32_16x16x32_bf16 v[18:21], v[176:179], v[200:203], 0
	v_mfma_f32_16x16x32_bf16 v[6:9], v[168:171], v[208:211], 0
	v_mfma_f32_16x16x32_bf16 v[2:5], v[176:179], v[208:211], 0
	v_mfma_f32_16x16x32_bf16 v[54:57], v[172:175], v[188:191], v[54:57]
	v_mfma_f32_16x16x32_bf16 v[50:53], v[180:183], v[188:191], v[50:53]
	v_mfma_f32_16x16x32_bf16 v[38:41], v[172:175], v[196:199], v[38:41]
	v_mfma_f32_16x16x32_bf16 v[34:37], v[180:183], v[196:199], v[34:37]
	v_mfma_f32_16x16x32_bf16 v[22:25], v[172:175], v[204:207], v[22:25]
	v_mfma_f32_16x16x32_bf16 v[18:21], v[180:183], v[204:207], v[18:21]
	v_mfma_f32_16x16x32_bf16 v[6:9], v[172:175], v[212:215], v[6:9]
	v_mfma_f32_16x16x32_bf16 v[2:5], v[180:183], v[212:215], v[2:5]
	s_barrier
	v_add_u32_e32 v164, s60, v147
	v_add_u32_e32 v180, s61, v147
	ds_read_b128 v[152:155], v164
	ds_read_b128 v[156:159], v164 offset:1024
	ds_read_b128 v[160:163], v164 offset:2048
	ds_read_b128 v[164:167], v164 offset:3072
	ds_read_b128 v[168:171], v180
	ds_read_b128 v[172:175], v180 offset:1024
	ds_read_b128 v[176:179], v180 offset:2048
	ds_read_b128 v[180:183], v180 offset:3072
	s_add_u32 s28, s28, 0x4000
	s_addc_u32 s29, s29, 0
	s_mov_b32 m0, s37
	v_lshl_add_u64 v[216:217], s[28:29], 0, v[130:131]
	ds_read_b128 v[184:187], v151 offset:32768
	ds_read_b128 v[188:191], v151 offset:33792
	ds_read_b128 v[192:195], v151 offset:34816
	ds_read_b128 v[196:199], v151 offset:35840
	ds_read_b128 v[200:203], v151 offset:36864
	ds_read_b128 v[204:207], v151 offset:37888
	ds_read_b128 v[208:211], v151 offset:38912
	ds_read_b128 v[212:215], v151 offset:39936
	global_load_lds_dwordx4 v[216:217], off
	v_lshl_add_u64 v[216:217], s[28:29], 0, v[132:133]
	s_mov_b32 m0, s40
	s_nop 0
	global_load_lds_dwordx4 v[216:217], off
	s_waitcnt vmcnt(8)
	s_waitcnt lgkmcnt(0)
	s_barrier
	v_mfma_f32_16x16x32_bf16 v[126:129], v[152:155], v[184:187], v[126:129]
	v_mfma_f32_16x16x32_bf16 v[122:125], v[160:163], v[184:187], v[122:125]
	v_mfma_f32_16x16x32_bf16 v[110:113], v[152:155], v[192:195], v[110:113]
	v_mfma_f32_16x16x32_bf16 v[106:109], v[160:163], v[192:195], v[106:109]
	v_mfma_f32_16x16x32_bf16 v[94:97], v[152:155], v[200:203], v[94:97]
	v_mfma_f32_16x16x32_bf16 v[90:93], v[160:163], v[200:203], v[90:93]
	v_mfma_f32_16x16x32_bf16 v[78:81], v[152:155], v[208:211], v[78:81]
	v_mfma_f32_16x16x32_bf16 v[74:77], v[160:163], v[208:211], v[74:77]
	v_mfma_f32_16x16x32_bf16 v[126:129], v[156:159], v[188:191], v[126:129]
	v_mfma_f32_16x16x32_bf16 v[122:125], v[164:167], v[188:191], v[122:125]
	v_mfma_f32_16x16x32_bf16 v[110:113], v[156:159], v[196:199], v[110:113]
	v_mfma_f32_16x16x32_bf16 v[106:109], v[164:167], v[196:199], v[106:109]
	v_mfma_f32_16x16x32_bf16 v[94:97], v[156:159], v[204:207], v[94:97]
	v_mfma_f32_16x16x32_bf16 v[90:93], v[164:167], v[204:207], v[90:93]
	v_mfma_f32_16x16x32_bf16 v[78:81], v[156:159], v[212:215], v[78:81]
	v_mfma_f32_16x16x32_bf16 v[74:77], v[164:167], v[212:215], v[74:77]
	v_mfma_f32_16x16x32_bf16 v[118:121], v[168:171], v[184:187], v[118:121]
	v_mfma_f32_16x16x32_bf16 v[114:117], v[176:179], v[184:187], v[114:117]
	v_mfma_f32_16x16x32_bf16 v[102:105], v[168:171], v[192:195], v[102:105]
	v_mfma_f32_16x16x32_bf16 v[98:101], v[176:179], v[192:195], v[98:101]
	v_mfma_f32_16x16x32_bf16 v[86:89], v[168:171], v[200:203], v[86:89]
	v_mfma_f32_16x16x32_bf16 v[82:85], v[176:179], v[200:203], v[82:85]
	v_mfma_f32_16x16x32_bf16 v[70:73], v[168:171], v[208:211], v[70:73]
	v_mfma_f32_16x16x32_bf16 v[66:69], v[176:179], v[208:211], v[66:69]
	v_mfma_f32_16x16x32_bf16 v[118:121], v[172:175], v[188:191], v[118:121]
	v_mfma_f32_16x16x32_bf16 v[114:117], v[180:183], v[188:191], v[114:117]
	v_mfma_f32_16x16x32_bf16 v[102:105], v[172:175], v[196:199], v[102:105]
	v_mfma_f32_16x16x32_bf16 v[98:101], v[180:183], v[196:199], v[98:101]
	v_mfma_f32_16x16x32_bf16 v[86:89], v[172:175], v[204:207], v[86:89]
	v_mfma_f32_16x16x32_bf16 v[82:85], v[180:183], v[204:207], v[82:85]
	v_mfma_f32_16x16x32_bf16 v[70:73], v[172:175], v[212:215], v[70:73]
	v_mfma_f32_16x16x32_bf16 v[66:69], v[180:183], v[212:215], v[66:69]
	s_barrier
; #define PG8_STAGE(bufoff, gbase, voff) do { _Pragma("unroll") for (int _i = 0; _i < 2; ++_i) \
;         __builtin_amdgcn_global_load_lds((const unsigned*)((const char*)(gbase) + (voff)[_i]), (LAS unsigned*)(lds + (bufoff) + ldsw + _i * 8192), 16, 0, 0); } while (0)
; #define PG8_LDA(dst, b, h) do { _Pragma("unroll") for (int m = 0; m < 4; ++m) _Pragma("unroll") for (int k = 0; k < 2; ++k) dst[m][k] = *(const LAS bf16x8*)(lds + PG8_SA(b, h) + aoff + m * 2048 + k * 1024); } while (0)
; #define PG8_MMA(ai, bj, At, Bt) do { __builtin_amdgcn_s_setprio(1); _Pragma("unroll") for (int m = 0; m < 4; ++m) _Pragma("unroll") for (int n = 0; n < 2; ++n) _Pragma("unroll") for (int k = 0; k < 2; ++k) \
;         acc[ai][bj][m][n] = __builtin_amdgcn_mfma_f32_16x16x32_bf16(Bt[n][k], At[m][k], acc[ai][bj][m][n], 0, 0, 0); __builtin_amdgcn_s_setprio(0); } while (0)
; #define PG8_WAIT_V(n) asm volatile("s_waitcnt vmcnt(" #n ")" ::: "memory")
; #define PG8_WAIT_L(n) asm volatile("s_waitcnt lgkmcnt(" #n ")" ::: "memory")
; #define PG8_BAR __builtin_amdgcn_s_barrier()
; #define PG8_SCHED __builtin_amdgcn_sched_barrier(0)
; template <class Epi, class Sched, bool ABLK = false, bool ALIGN_EPI = true, bool SP2 = true, bool BBLK = true>
; __device__ __forceinline__ void gemm_phase(LAS unsigned char* lds, const Gemm g, const Sched& S, const Epi& E) {
;     ...
;         for (int t = 0; t < nt; t += 2) {
;     ...
;             PG8_LDA(At, 1, 1); PG8_STAGE(PG8_SB(1, 0), b3, voffB); PG8_STAGE(PG8_SB(1, 1), b3 + hstepB, voffB); PG8_STAGE(PG8_SA(1, 0), a3, voffA);
;             PG8_WAIT_V(8); PG8_WAIT_L(0); PG8_BAR; PG8_MMA(1, 0, At, B0); PG8_MMA(1, 1, At, B1); PG8_BAR; PG8_SCHED;
	s_add_u32 s28, s26, 0x8000
	s_addc_u32 s29, s27, 0
	s_add_i32 s59, s60, s34
	v_lshl_add_u64 v[216:217], s[28:29], 0, v[130:131]
	s_mov_b32 m0, s59
	ds_read_b128 v[184:187], v151 offset:49152
	ds_read_b128 v[188:191], v151 offset:50176
	ds_read_b128 v[192:195], v151 offset:51200
	ds_read_b128 v[196:199], v151 offset:52224
	ds_read_b128 v[200:203], v151 offset:53248
	ds_read_b128 v[204:207], v151 offset:54272
	ds_read_b128 v[208:211], v151 offset:55296
	ds_read_b128 v[212:215], v151 offset:56320
	global_load_lds_dwordx4 v[216:217], off
	s_add_i32 m0, s59, 0x2000
	s_add_u32 s26, s26, 0xc000
	v_lshl_add_u64 v[216:217], s[28:29], 0, v[132:133]
	s_addc_u32 s27, s27, 0
	s_add_i32 s28, s61, s34
	global_load_lds_dwordx4 v[216:217], off
	v_lshl_add_u64 v[216:217], s[26:27], 0, v[130:131]
	s_mov_b32 m0, s28
	s_nop 0
	global_load_lds_dwordx4 v[216:217], off
	v_lshl_add_u64 v[216:217], s[26:27], 0, v[132:133]
	s_add_i32 m0, s28, 0x2000
	s_nop 0
	global_load_lds_dwordx4 v[216:217], off
	v_lshl_add_u64 v[216:217], s[24:25], 0, v[130:131]
	s_mov_b32 m0, s41
	s_nop 0
	global_load_lds_dwordx4 v[216:217], off
	v_lshl_add_u64 v[216:217], s[24:25], 0, v[132:133]
	s_mov_b32 m0, s42
	s_nop 0
	global_load_lds_dwordx4 v[216:217], off
	s_waitcnt vmcnt(8)
	s_waitcnt lgkmcnt(0)
	s_barrier
	v_mfma_f32_16x16x32_bf16 v[62:65], v[152:155], v[184:187], v[62:65]
	v_mfma_f32_16x16x32_bf16 v[58:61], v[160:163], v[184:187], v[58:61]
	v_mfma_f32_16x16x32_bf16 v[46:49], v[152:155], v[192:195], v[46:49]
	v_mfma_f32_16x16x32_bf16 v[42:45], v[160:163], v[192:195], v[42:45]
	v_mfma_f32_16x16x32_bf16 v[30:33], v[152:155], v[200:203], v[30:33]
	v_mfma_f32_16x16x32_bf16 v[26:29], v[160:163], v[200:203], v[26:29]
	v_mfma_f32_16x16x32_bf16 v[14:17], v[152:155], v[208:211], v[14:17]
	v_mfma_f32_16x16x32_bf16 v[10:13], v[160:163], v[208:211], v[10:13]
	v_mfma_f32_16x16x32_bf16 v[62:65], v[156:159], v[188:191], v[62:65]
	v_mfma_f32_16x16x32_bf16 v[58:61], v[164:167], v[188:191], v[58:61]
	v_mfma_f32_16x16x32_bf16 v[46:49], v[156:159], v[196:199], v[46:49]
	v_mfma_f32_16x16x32_bf16 v[42:45], v[164:167], v[196:199], v[42:45]
	v_mfma_f32_16x16x32_bf16 v[30:33], v[156:159], v[204:207], v[30:33]
	v_mfma_f32_16x16x32_bf16 v[26:29], v[164:167], v[204:207], v[26:29]
	v_mfma_f32_16x16x32_bf16 v[14:17], v[156:159], v[212:215], v[14:17]
	v_mfma_f32_16x16x32_bf16 v[10:13], v[164:167], v[212:215], v[10:13]
	v_mfma_f32_16x16x32_bf16 v[54:57], v[168:171], v[184:187], v[54:57]
	v_mfma_f32_16x16x32_bf16 v[50:53], v[176:179], v[184:187], v[50:53]
	v_mfma_f32_16x16x32_bf16 v[38:41], v[168:171], v[192:195], v[38:41]
	v_mfma_f32_16x16x32_bf16 v[34:37], v[176:179], v[192:195], v[34:37]
	v_mfma_f32_16x16x32_bf16 v[22:25], v[168:171], v[200:203], v[22:25]
	v_mfma_f32_16x16x32_bf16 v[18:21], v[176:179], v[200:203], v[18:21]
	v_mfma_f32_16x16x32_bf16 v[6:9], v[168:171], v[208:211], v[6:9]
	v_mfma_f32_16x16x32_bf16 v[2:5], v[176:179], v[208:211], v[2:5]
	v_mfma_f32_16x16x32_bf16 v[54:57], v[172:175], v[188:191], v[54:57]
	v_mfma_f32_16x16x32_bf16 v[50:53], v[180:183], v[188:191], v[50:53]
	v_mfma_f32_16x16x32_bf16 v[38:41], v[172:175], v[196:199], v[38:41]
	v_mfma_f32_16x16x32_bf16 v[34:37], v[180:183], v[196:199], v[34:37]
	v_mfma_f32_16x16x32_bf16 v[22:25], v[172:175], v[204:207], v[22:25]
	v_mfma_f32_16x16x32_bf16 v[18:21], v[180:183], v[204:207], v[18:21]
	v_mfma_f32_16x16x32_bf16 v[6:9], v[172:175], v[212:215], v[6:9]
	v_mfma_f32_16x16x32_bf16 v[2:5], v[180:183], v[212:215], v[2:5]
	s_barrier
	s_add_u32 s22, s22, 0x10000
	s_addc_u32 s23, s23, 0
	s_cmp_ge_u32 s57, s44

; #define PG8_STAGE(bufoff, gbase, voff) do { _Pragma("unroll") for (int _i = 0; _i < 2; ++_i) \
;         __builtin_amdgcn_global_load_lds((const unsigned*)((const char*)(gbase) + (voff)[_i]), (LAS unsigned*)(lds + (bufoff) + ldsw + _i * 8192), 16, 0, 0); } while (0)
; #define PG8_LDA(dst, b, h) do { _Pragma("unroll") for (int m = 0; m < 4; ++m) _Pragma("unroll") for (int k = 0; k < 2; ++k) dst[m][k] = *(const LAS bf16x8*)(lds + PG8_SA(b, h) + aoff + m * 2048 + k * 1024); } while (0)
; #define PG8_LDB(dst, b, h) do { _Pragma("unroll") for (int n = 0; n < 2; ++n) _Pragma("unroll") for (int k = 0; k < 2; ++k) dst[n][k] = *(const LAS bf16x8*)(lds + PG8_SB(b, h) + boff + n * 2048 + k * 1024); } while (0)
; #define PG8_WAIT_V(n) asm volatile("s_waitcnt vmcnt(" #n ")" ::: "memory")
; #define PG8_WAIT_L(n) asm volatile("s_waitcnt lgkmcnt(" #n ")" ::: "memory")
; template <class Epi, class Sched, bool ABLK = false, bool ALIGN_EPI = true, bool SP2 = true, bool BBLK = true>
; __device__ __forceinline__ void gemm_phase(LAS unsigned char* lds, const Gemm g, const Sched& S, const Epi& E) {
;     ...
;         const bool has_next = S.next(ui + 1, nxt);
;         const int nt = cur.nt;
;         const char* nuA = has_next ? a_unit(nxt) : uA; const int ntbA = has_next ? nxt.k0 / BK : tbA; const char* nB = has_next ? (const char*)g.Bt + (size_t)nxt.pn * tstepB + b_k0(nxt.k0) : cB;
;         for (int t = 0; t < nt; t += 2) {
;             const bool last = (t == nt - 2);
;             const char* a1 = a_tile(uA, tbA + t + 1);
;             const char* a2 = last ? a_tile(nuA, ntbA) : a_tile(uA, tbA + t + 2); const char* b2 = last ? nB : cB + (size_t)(t + 2) * kstepB;
;             const char* a3 = last ? a_tile(nuA, ntbA + 1) : a_tile(uA, tbA + t + 3); const char* b3 = b2 + kstepB;
;             if (last && has_next) S.a_ready(nxt);
;             if constexpr (SP2) {
;             PG8_LDB(B0, 0, 0); PG8_LDB(B1, 0, 1); PG8_SCHED; PG8_LDA(At, 0, 0); PG8_STAGE(PG8_SA(1, 1), a1 + hstepA, voffA);
;             PG8_WAIT_V(8); PG8_WAIT_L(0); PG8_BAR; PG8_MMA(0, 0, At, B0); PG8_MMA(0, 1, At, B1); PG8_BAR; PG8_SCHED;
;             PG8_LDA(At, 0, 1); PG8_STAGE(PG8_SB(0, 0), b2, voffB); PG8_STAGE(PG8_SB(0, 1), b2 + hstepB, voffB); PG8_STAGE(PG8_SA(0, 0), a2, voffA);
;             PG8_WAIT_V(8); PG8_WAIT_L(0); PG8_BAR; PG8_MMA(1, 0, At, B0); PG8_MMA(1, 1, At, B1); PG8_BAR; PG8_SCHED;
.LBB0_1354:
	s_ashr_i32 s21, s20, 31
	s_lshl_b64 s[4:5], s[20:21], 20
	s_add_u32 s24, s76, s4
	s_addc_u32 s25, s33, s5
	s_and_b64 s[4:5], s[26:27], exec
	s_cselect_b32 s4, s25, s37
	s_cselect_b32 s5, s24, s36
	s_ashr_i32 s23, s22, 31
	s_lshl_b64 s[28:29], s[22:23], 20
	s_add_u32 s28, s1, s28
	s_addc_u32 s29, s48, s29
	s_and_b64 s[42:43], s[26:27], exec
	s_cselect_b32 s21, s29, s41
	s_cselect_b32 s23, s28, s40
	s_add_u32 s56, s5, 0x80
	s_addc_u32 s57, s4, 0
	s_add_u32 s59, s40, 0x10000
	v_mov_b32_e32 v2, 0
	s_addc_u32 s64, s41, 0
	v_lshl_add_u64 v[148:149], s[36:37], 0, v[144:145]
	v_lshl_add_u64 v[150:151], s[36:37], 0, v[146:147]
	s_mov_b32 s65, -2
	s_mov_b64 s[40:41], 0
	ds_read_b128 v[152:155], v163
	ds_read_b128 v[156:159], v163 offset:1024
	ds_read_b128 v[166:169], v163 offset:2048
	ds_read_b128 v[170:173], v163 offset:3072
	ds_read_b128 v[174:177], v164
	ds_read_b128 v[178:181], v164 offset:1024
	ds_read_b128 v[182:185], v164 offset:2048
	ds_read_b128 v[186:189], v164 offset:3072
	s_add_u32 s42, s36, s40
	s_addc_u32 s43, s37, s41
	s_add_u32 s46, s42, 0x100
	s_addc_u32 s47, s43, 0
	s_add_u32 s42, s42, 0x180
	s_addc_u32 s43, s43, 0
	s_cmpk_eq_i32 s40, 0xf00
	s_cselect_b32 s43, s57, s43
	s_cselect_b32 s42, s56, s42
	s_cselect_b32 s45, s21, s64
	s_cselect_b32 s44, s23, s59
	s_cselect_b32 s47, s4, s47
	s_cselect_b32 s46, s5, s46
	v_lshl_add_u64 v[222:223], v[148:149], 0, s[40:41]
	s_add_i32 m0, s31, 0xc000
	ds_read_b128 v[190:193], v165
	ds_read_b128 v[194:197], v165 offset:1024
	ds_read_b128 v[198:201], v165 offset:2048
	ds_read_b128 v[202:205], v165 offset:3072
	ds_read_b128 v[206:209], v165 offset:4096
	ds_read_b128 v[210:213], v165 offset:5120
	ds_read_b128 v[214:217], v165 offset:6144
	ds_read_b128 v[218:221], v165 offset:7168
	global_load_lds_dwordx4 v[222:223], off
	v_lshl_add_u64 v[222:223], v[150:151], 0, s[40:41]
	s_add_i32 m0, s31, 0xe000
	s_nop 0
	global_load_lds_dwordx4 v[222:223], off
	s_waitcnt vmcnt(8)
	s_waitcnt lgkmcnt(0)
	s_barrier
	v_mfma_f32_16x16x32_bf16 v[126:129], v[152:155], v[190:193], 0
	v_mfma_f32_16x16x32_bf16 v[122:125], v[166:169], v[190:193], 0
	v_mfma_f32_16x16x32_bf16 v[110:113], v[152:155], v[198:201], 0
	v_mfma_f32_16x16x32_bf16 v[106:109], v[166:169], v[198:201], 0
	v_mfma_f32_16x16x32_bf16 v[94:97], v[152:155], v[206:209], 0
	v_mfma_f32_16x16x32_bf16 v[90:93], v[166:169], v[206:209], 0
	v_mfma_f32_16x16x32_bf16 v[78:81], v[152:155], v[214:217], 0
	v_mfma_f32_16x16x32_bf16 v[74:77], v[166:169], v[214:217], 0
	v_mfma_f32_16x16x32_bf16 v[126:129], v[156:159], v[194:197], v[126:129]
	v_mfma_f32_16x16x32_bf16 v[122:125], v[170:173], v[194:197], v[122:125]
	v_mfma_f32_16x16x32_bf16 v[110:113], v[156:159], v[202:205], v[110:113]
	v_mfma_f32_16x16x32_bf16 v[106:109], v[170:173], v[202:205], v[106:109]
	v_mfma_f32_16x16x32_bf16 v[94:97], v[156:159], v[210:213], v[94:97]
	v_mfma_f32_16x16x32_bf16 v[90:93], v[170:173], v[210:213], v[90:93]
	v_mfma_f32_16x16x32_bf16 v[78:81], v[156:159], v[218:221], v[78:81]
	v_mfma_f32_16x16x32_bf16 v[74:77], v[170:173], v[218:221], v[74:77]
	v_mfma_f32_16x16x32_bf16 v[118:121], v[174:177], v[190:193], 0
	v_mfma_f32_16x16x32_bf16 v[114:117], v[182:185], v[190:193], 0
	v_mfma_f32_16x16x32_bf16 v[102:105], v[174:177], v[198:201], 0
	v_mfma_f32_16x16x32_bf16 v[98:101], v[182:185], v[198:201], 0
	v_mfma_f32_16x16x32_bf16 v[86:89], v[174:177], v[206:209], 0
	v_mfma_f32_16x16x32_bf16 v[82:85], v[182:185], v[206:209], 0
	v_mfma_f32_16x16x32_bf16 v[70:73], v[174:177], v[214:217], 0
	v_mfma_f32_16x16x32_bf16 v[66:69], v[182:185], v[214:217], 0
	v_mfma_f32_16x16x32_bf16 v[118:121], v[178:181], v[194:197], v[118:121]
	v_mfma_f32_16x16x32_bf16 v[114:117], v[186:189], v[194:197], v[114:117]
	v_mfma_f32_16x16x32_bf16 v[102:105], v[178:181], v[202:205], v[102:105]
	v_mfma_f32_16x16x32_bf16 v[98:101], v[186:189], v[202:205], v[98:101]
	v_mfma_f32_16x16x32_bf16 v[86:89], v[178:181], v[210:213], v[86:89]
	v_mfma_f32_16x16x32_bf16 v[82:85], v[186:189], v[210:213], v[82:85]
	v_mfma_f32_16x16x32_bf16 v[70:73], v[178:181], v[218:221], v[70:73]
	v_mfma_f32_16x16x32_bf16 v[66:69], v[186:189], v[218:221], v[66:69]
	s_barrier
	s_add_i32 s66, s72, s49
	v_lshl_add_u64 v[222:223], s[44:45], 0, v[134:135]
	s_mov_b32 m0, s66
	ds_read_b128 v[190:193], v165 offset:16384
	ds_read_b128 v[194:197], v165 offset:17408
	ds_read_b128 v[198:201], v165 offset:18432
	ds_read_b128 v[202:205], v165 offset:19456
	ds_read_b128 v[206:209], v165 offset:20480
	ds_read_b128 v[210:213], v165 offset:21504
	ds_read_b128 v[214:217], v165 offset:22528
	ds_read_b128 v[218:221], v165 offset:23552
	global_load_lds_dwordx4 v[222:223], off
	s_add_i32 m0, s66, 0x2000
	s_add_u32 s66, s44, 0x4000
	v_lshl_add_u64 v[222:223], s[44:45], 0, v[130:131]
	s_addc_u32 s67, s45, 0
	s_add_i32 s75, s73, s49
	global_load_lds_dwordx4 v[222:223], off
	v_lshl_add_u64 v[222:223], s[66:67], 0, v[134:135]
	s_mov_b32 m0, s75
	s_nop 0
	global_load_lds_dwordx4 v[222:223], off
	v_lshl_add_u64 v[222:223], s[66:67], 0, v[130:131]
	s_add_i32 m0, s75, 0x2000
	s_nop 0
	global_load_lds_dwordx4 v[222:223], off
	v_lshl_add_u64 v[222:223], s[46:47], 0, v[136:137]
	s_mov_b32 m0, s31
	s_nop 0
	global_load_lds_dwordx4 v[222:223], off
	v_lshl_add_u64 v[222:223], s[46:47], 0, v[132:133]
	s_mov_b32 m0, s35
	s_nop 0
	global_load_lds_dwordx4 v[222:223], off
	s_waitcnt vmcnt(8)
	s_waitcnt lgkmcnt(0)
	s_barrier
; #define PG8_STAGE(bufoff, gbase, voff) do { _Pragma("unroll") for (int _i = 0; _i < 2; ++_i) \
;         __builtin_amdgcn_global_load_lds((const unsigned*)((const char*)(gbase) + (voff)[_i]), (LAS unsigned*)(lds + (bufoff) + ldsw + _i * 8192), 16, 0, 0); } while (0)
; #define PG8_LDA(dst, b, h) do { _Pragma("unroll") for (int m = 0; m < 4; ++m) _Pragma("unroll") for (int k = 0; k < 2; ++k) dst[m][k] = *(const LAS bf16x8*)(lds + PG8_SA(b, h) + aoff + m * 2048 + k * 1024); } while (0)
; #define PG8_LDB(dst, b, h) do { _Pragma("unroll") for (int n = 0; n < 2; ++n) _Pragma("unroll") for (int k = 0; k < 2; ++k) dst[n][k] = *(const LAS bf16x8*)(lds + PG8_SB(b, h) + boff + n * 2048 + k * 1024); } while (0)
; #define PG8_MMA(ai, bj, At, Bt) do { __builtin_amdgcn_s_setprio(1); _Pragma("unroll") for (int m = 0; m < 4; ++m) _Pragma("unroll") for (int n = 0; n < 2; ++n) _Pragma("unroll") for (int k = 0; k < 2; ++k) \
;         acc[ai][bj][m][n] = __builtin_amdgcn_mfma_f32_16x16x32_bf16(Bt[n][k], At[m][k], acc[ai][bj][m][n], 0, 0, 0); __builtin_amdgcn_s_setprio(0); } while (0)
; #define PG8_WAIT_V(n) asm volatile("s_waitcnt vmcnt(" #n ")" ::: "memory")
; #define PG8_WAIT_L(n) asm volatile("s_waitcnt lgkmcnt(" #n ")" ::: "memory")
; #define PG8_BAR __builtin_amdgcn_s_barrier()
; #define PG8_SCHED __builtin_amdgcn_sched_barrier(0)
; template <class Epi, class Sched, bool ABLK = false, bool ALIGN_EPI = true, bool SP2 = true, bool BBLK = true>
; __device__ __forceinline__ void gemm_phase(LAS unsigned char* lds, const Gemm g, const Sched& S, const Epi& E) {
;     ...
;             PG8_LDA(At, 0, 1); PG8_STAGE(PG8_SB(0, 0), b2, voffB); PG8_STAGE(PG8_SB(0, 1), b2 + hstepB, voffB); PG8_STAGE(PG8_SA(0, 0), a2, voffA);
;             PG8_WAIT_V(8); PG8_WAIT_L(0); PG8_BAR; PG8_MMA(1, 0, At, B0); PG8_MMA(1, 1, At, B1); PG8_BAR; PG8_SCHED;
;             PG8_LDB(B0, 1, 0); PG8_LDB(B1, 1, 1); PG8_SCHED; PG8_LDA(At, 1, 0); PG8_STAGE(PG8_SA(0, 1), a2 + hstepA, voffA);
;             PG8_WAIT_V(8); PG8_WAIT_L(0); PG8_BAR; PG8_MMA(0, 0, At, B0); PG8_MMA(0, 1, At, B1); PG8_BAR; PG8_SCHED;
	v_mfma_f32_16x16x32_bf16 v[62:65], v[152:155], v[190:193], 0
	v_mfma_f32_16x16x32_bf16 v[58:61], v[166:169], v[190:193], 0
	v_mfma_f32_16x16x32_bf16 v[46:49], v[152:155], v[198:201], 0
	v_mfma_f32_16x16x32_bf16 v[42:45], v[166:169], v[198:201], 0
	v_mfma_f32_16x16x32_bf16 v[30:33], v[152:155], v[206:209], 0
	v_mfma_f32_16x16x32_bf16 v[26:29], v[166:169], v[206:209], 0
	v_mfma_f32_16x16x32_bf16 v[14:17], v[152:155], v[214:217], 0
	v_mfma_f32_16x16x32_bf16 v[10:13], v[166:169], v[214:217], 0
	v_mfma_f32_16x16x32_bf16 v[62:65], v[156:159], v[194:197], v[62:65]
	v_mfma_f32_16x16x32_bf16 v[58:61], v[170:173], v[194:197], v[58:61]
	v_mfma_f32_16x16x32_bf16 v[46:49], v[156:159], v[202:205], v[46:49]
	v_mfma_f32_16x16x32_bf16 v[42:45], v[170:173], v[202:205], v[42:45]
	v_mfma_f32_16x16x32_bf16 v[30:33], v[156:159], v[210:213], v[30:33]
	v_mfma_f32_16x16x32_bf16 v[26:29], v[170:173], v[210:213], v[26:29]
	v_mfma_f32_16x16x32_bf16 v[14:17], v[156:159], v[218:221], v[14:17]
	v_mfma_f32_16x16x32_bf16 v[10:13], v[170:173], v[218:221], v[10:13]
	v_mfma_f32_16x16x32_bf16 v[54:57], v[174:177], v[190:193], 0
	v_mfma_f32_16x16x32_bf16 v[50:53], v[182:185], v[190:193], 0
	v_mfma_f32_16x16x32_bf16 v[38:41], v[174:177], v[198:201], 0
	v_mfma_f32_16x16x32_bf16 v[34:37], v[182:185], v[198:201], 0
	v_mfma_f32_16x16x32_bf16 v[22:25], v[174:177], v[206:209], 0
	v_mfma_f32_16x16x32_bf16 v[18:21], v[182:185], v[206:209], 0
	v_mfma_f32_16x16x32_bf16 v[6:9], v[174:177], v[214:217], 0
	v_mfma_f32_16x16x32_bf16 v[2:5], v[182:185], v[214:217], 0
	v_mfma_f32_16x16x32_bf16 v[54:57], v[178:181], v[194:197], v[54:57]
	v_mfma_f32_16x16x32_bf16 v[50:53], v[186:189], v[194:197], v[50:53]
	v_mfma_f32_16x16x32_bf16 v[38:41], v[178:181], v[202:205], v[38:41]
	v_mfma_f32_16x16x32_bf16 v[34:37], v[186:189], v[202:205], v[34:37]
	v_mfma_f32_16x16x32_bf16 v[22:25], v[178:181], v[210:213], v[22:25]
	v_mfma_f32_16x16x32_bf16 v[18:21], v[186:189], v[210:213], v[18:21]
	v_mfma_f32_16x16x32_bf16 v[6:9], v[178:181], v[218:221], v[6:9]
	v_mfma_f32_16x16x32_bf16 v[2:5], v[186:189], v[218:221], v[2:5]
	s_barrier
	v_add_u32_e32 v138, s60, v161
	ds_read_b128 v[152:155], v138
	ds_read_b128 v[156:159], v138 offset:1024
	ds_read_b128 v[166:169], v138 offset:2048
	ds_read_b128 v[170:173], v138 offset:3072
	v_add_u32_e32 v138, s61, v161
	ds_read_b128 v[174:177], v138
	ds_read_b128 v[178:181], v138 offset:1024
	ds_read_b128 v[182:185], v138 offset:2048
	ds_read_b128 v[186:189], v138 offset:3072
	s_add_u32 s46, s46, 0x80000
	s_addc_u32 s47, s47, 0
	s_mov_b32 m0, s50
	v_lshl_add_u64 v[222:223], s[46:47], 0, v[136:137]
	ds_read_b128 v[190:193], v165 offset:32768
	ds_read_b128 v[194:197], v165 offset:33792
	ds_read_b128 v[198:201], v165 offset:34816
	ds_read_b128 v[202:205], v165 offset:35840
	ds_read_b128 v[206:209], v165 offset:36864
	ds_read_b128 v[210:213], v165 offset:37888
	ds_read_b128 v[214:217], v165 offset:38912
	ds_read_b128 v[218:221], v165 offset:39936
	global_load_lds_dwordx4 v[222:223], off
	v_lshl_add_u64 v[222:223], s[46:47], 0, v[132:133]
	s_mov_b32 m0, s51
	s_nop 0
	global_load_lds_dwordx4 v[222:223], off
	s_waitcnt vmcnt(8)
	s_waitcnt lgkmcnt(0)
	s_barrier
	v_mfma_f32_16x16x32_bf16 v[126:129], v[152:155], v[190:193], v[126:129]
	v_mfma_f32_16x16x32_bf16 v[122:125], v[166:169], v[190:193], v[122:125]
	v_mfma_f32_16x16x32_bf16 v[110:113], v[152:155], v[198:201], v[110:113]
	v_mfma_f32_16x16x32_bf16 v[106:109], v[166:169], v[198:201], v[106:109]
	v_mfma_f32_16x16x32_bf16 v[94:97], v[152:155], v[206:209], v[94:97]
	v_mfma_f32_16x16x32_bf16 v[90:93], v[166:169], v[206:209], v[90:93]
	v_mfma_f32_16x16x32_bf16 v[78:81], v[152:155], v[214:217], v[78:81]
	v_mfma_f32_16x16x32_bf16 v[74:77], v[166:169], v[214:217], v[74:77]
	v_mfma_f32_16x16x32_bf16 v[126:129], v[156:159], v[194:197], v[126:129]
	v_mfma_f32_16x16x32_bf16 v[122:125], v[170:173], v[194:197], v[122:125]
	v_mfma_f32_16x16x32_bf16 v[110:113], v[156:159], v[202:205], v[110:113]
	v_mfma_f32_16x16x32_bf16 v[106:109], v[170:173], v[202:205], v[106:109]
	v_mfma_f32_16x16x32_bf16 v[94:97], v[156:159], v[210:213], v[94:97]
	v_mfma_f32_16x16x32_bf16 v[90:93], v[170:173], v[210:213], v[90:93]
	v_mfma_f32_16x16x32_bf16 v[78:81], v[156:159], v[218:221], v[78:81]
	v_mfma_f32_16x16x32_bf16 v[74:77], v[170:173], v[218:221], v[74:77]
	v_mfma_f32_16x16x32_bf16 v[118:121], v[174:177], v[190:193], v[118:121]
	v_mfma_f32_16x16x32_bf16 v[114:117], v[182:185], v[190:193], v[114:117]
	v_mfma_f32_16x16x32_bf16 v[102:105], v[174:177], v[198:201], v[102:105]
	v_mfma_f32_16x16x32_bf16 v[98:101], v[182:185], v[198:201], v[98:101]
	v_mfma_f32_16x16x32_bf16 v[86:89], v[174:177], v[206:209], v[86:89]
	v_mfma_f32_16x16x32_bf16 v[82:85], v[182:185], v[206:209], v[82:85]
	v_mfma_f32_16x16x32_bf16 v[70:73], v[174:177], v[214:217], v[70:73]
	v_mfma_f32_16x16x32_bf16 v[66:69], v[182:185], v[214:217], v[66:69]
	v_mfma_f32_16x16x32_bf16 v[118:121], v[178:181], v[194:197], v[118:121]
	v_mfma_f32_16x16x32_bf16 v[114:117], v[186:189], v[194:197], v[114:117]
	v_mfma_f32_16x16x32_bf16 v[102:105], v[178:181], v[202:205], v[102:105]
	v_mfma_f32_16x16x32_bf16 v[98:101], v[186:189], v[202:205], v[98:101]
	v_mfma_f32_16x16x32_bf16 v[86:89], v[178:181], v[210:213], v[86:89]
	v_mfma_f32_16x16x32_bf16 v[82:85], v[186:189], v[210:213], v[82:85]
	v_mfma_f32_16x16x32_bf16 v[70:73], v[178:181], v[218:221], v[70:73]
	v_mfma_f32_16x16x32_bf16 v[66:69], v[186:189], v[218:221], v[66:69]
	s_barrier
; #define PG8_STAGE(bufoff, gbase, voff) do { _Pragma("unroll") for (int _i = 0; _i < 2; ++_i) \
;         __builtin_amdgcn_global_load_lds((const unsigned*)((const char*)(gbase) + (voff)[_i]), (LAS unsigned*)(lds + (bufoff) + ldsw + _i * 8192), 16, 0, 0); } while (0)
; #define PG8_LDA(dst, b, h) do { _Pragma("unroll") for (int m = 0; m < 4; ++m) _Pragma("unroll") for (int k = 0; k < 2; ++k) dst[m][k] = *(const LAS bf16x8*)(lds + PG8_SA(b, h) + aoff + m * 2048 + k * 1024); } while (0)
; #define PG8_MMA(ai, bj, At, Bt) do { __builtin_amdgcn_s_setprio(1); _Pragma("unroll") for (int m = 0; m < 4; ++m) _Pragma("unroll") for (int n = 0; n < 2; ++n) _Pragma("unroll") for (int k = 0; k < 2; ++k) \
;         acc[ai][bj][m][n] = __builtin_amdgcn_mfma_f32_16x16x32_bf16(Bt[n][k], At[m][k], acc[ai][bj][m][n], 0, 0, 0); __builtin_amdgcn_s_setprio(0); } while (0)
; #define PG8_WAIT_V(n) asm volatile("s_waitcnt vmcnt(" #n ")" ::: "memory")
; #define PG8_WAIT_L(n) asm volatile("s_waitcnt lgkmcnt(" #n ")" ::: "memory")
; #define PG8_BAR __builtin_amdgcn_s_barrier()
; #define PG8_SCHED __builtin_amdgcn_sched_barrier(0)
; template <class Epi, class Sched, bool ABLK = false, bool ALIGN_EPI = true, bool SP2 = true, bool BBLK = true>
; __device__ __forceinline__ void gemm_phase(LAS unsigned char* lds, const Gemm g, const Sched& S, const Epi& E) {
;     ...
;         for (int t = 0; t < nt; t += 2) {
;     ...
;             PG8_LDA(At, 1, 1); PG8_STAGE(PG8_SB(1, 0), b3, voffB); PG8_STAGE(PG8_SB(1, 1), b3 + hstepB, voffB); PG8_STAGE(PG8_SA(1, 0), a3, voffA);
;             PG8_WAIT_V(8); PG8_WAIT_L(0); PG8_BAR; PG8_MMA(1, 0, At, B0); PG8_MMA(1, 1, At, B1); PG8_BAR; PG8_SCHED;
	s_add_u32 s46, s44, 0x8000
	s_addc_u32 s47, s45, 0
	s_add_i32 s66, s60, s49
	v_lshl_add_u64 v[222:223], s[46:47], 0, v[134:135]
	s_mov_b32 m0, s66
	ds_read_b128 v[190:193], v165 offset:49152
	ds_read_b128 v[194:197], v165 offset:50176
	ds_read_b128 v[198:201], v165 offset:51200
	ds_read_b128 v[202:205], v165 offset:52224
	ds_read_b128 v[206:209], v165 offset:53248
	ds_read_b128 v[210:213], v165 offset:54272
	ds_read_b128 v[214:217], v165 offset:55296
	ds_read_b128 v[218:221], v165 offset:56320
	global_load_lds_dwordx4 v[222:223], off
	s_add_i32 m0, s66, 0x2000
	s_add_u32 s44, s44, 0xc000
	v_lshl_add_u64 v[222:223], s[46:47], 0, v[130:131]
	s_addc_u32 s45, s45, 0
	s_add_i32 s46, s61, s49
	global_load_lds_dwordx4 v[222:223], off
	v_lshl_add_u64 v[222:223], s[44:45], 0, v[134:135]
	s_mov_b32 m0, s46
	s_nop 0
	global_load_lds_dwordx4 v[222:223], off
	v_lshl_add_u64 v[222:223], s[44:45], 0, v[130:131]
	s_add_i32 m0, s46, 0x2000
	s_nop 0
	global_load_lds_dwordx4 v[222:223], off
	v_lshl_add_u64 v[222:223], s[42:43], 0, v[136:137]
	s_mov_b32 m0, s54
	s_nop 0
	global_load_lds_dwordx4 v[222:223], off
	v_lshl_add_u64 v[222:223], s[42:43], 0, v[132:133]
	s_mov_b32 m0, s55
	s_nop 0
	global_load_lds_dwordx4 v[222:223], off
	s_waitcnt vmcnt(8)
	s_waitcnt lgkmcnt(0)
	s_barrier
	v_mfma_f32_16x16x32_bf16 v[62:65], v[152:155], v[190:193], v[62:65]
	v_mfma_f32_16x16x32_bf16 v[58:61], v[166:169], v[190:193], v[58:61]
	v_mfma_f32_16x16x32_bf16 v[46:49], v[152:155], v[198:201], v[46:49]
	v_mfma_f32_16x16x32_bf16 v[42:45], v[166:169], v[198:201], v[42:45]
	v_mfma_f32_16x16x32_bf16 v[30:33], v[152:155], v[206:209], v[30:33]
	v_mfma_f32_16x16x32_bf16 v[26:29], v[166:169], v[206:209], v[26:29]
	v_mfma_f32_16x16x32_bf16 v[14:17], v[152:155], v[214:217], v[14:17]
	v_mfma_f32_16x16x32_bf16 v[10:13], v[166:169], v[214:217], v[10:13]
	v_mfma_f32_16x16x32_bf16 v[62:65], v[156:159], v[194:197], v[62:65]
	v_mfma_f32_16x16x32_bf16 v[58:61], v[170:173], v[194:197], v[58:61]
	v_mfma_f32_16x16x32_bf16 v[46:49], v[156:159], v[202:205], v[46:49]
	v_mfma_f32_16x16x32_bf16 v[42:45], v[170:173], v[202:205], v[42:45]
	v_mfma_f32_16x16x32_bf16 v[30:33], v[156:159], v[210:213], v[30:33]
	v_mfma_f32_16x16x32_bf16 v[26:29], v[170:173], v[210:213], v[26:29]
	v_mfma_f32_16x16x32_bf16 v[14:17], v[156:159], v[218:221], v[14:17]
	v_mfma_f32_16x16x32_bf16 v[10:13], v[170:173], v[218:221], v[10:13]
	v_mfma_f32_16x16x32_bf16 v[54:57], v[174:177], v[190:193], v[54:57]
	v_mfma_f32_16x16x32_bf16 v[50:53], v[182:185], v[190:193], v[50:53]
	v_mfma_f32_16x16x32_bf16 v[38:41], v[174:177], v[198:201], v[38:41]
	v_mfma_f32_16x16x32_bf16 v[34:37], v[182:185], v[198:201], v[34:37]
	v_mfma_f32_16x16x32_bf16 v[22:25], v[174:177], v[206:209], v[22:25]
	v_mfma_f32_16x16x32_bf16 v[18:21], v[182:185], v[206:209], v[18:21]
	v_mfma_f32_16x16x32_bf16 v[6:9], v[174:177], v[214:217], v[6:9]
	v_mfma_f32_16x16x32_bf16 v[2:5], v[182:185], v[214:217], v[2:5]
	v_mfma_f32_16x16x32_bf16 v[54:57], v[178:181], v[194:197], v[54:57]
	v_mfma_f32_16x16x32_bf16 v[50:53], v[186:189], v[194:197], v[50:53]
	v_mfma_f32_16x16x32_bf16 v[38:41], v[178:181], v[202:205], v[38:41]
	v_mfma_f32_16x16x32_bf16 v[34:37], v[186:189], v[202:205], v[34:37]
	v_mfma_f32_16x16x32_bf16 v[22:25], v[178:181], v[210:213], v[22:25]
	v_mfma_f32_16x16x32_bf16 v[18:21], v[186:189], v[210:213], v[18:21]
	v_mfma_f32_16x16x32_bf16 v[6:9], v[178:181], v[218:221], v[6:9]
	v_mfma_f32_16x16x32_bf16 v[2:5], v[186:189], v[218:221], v[2:5]
	s_barrier
	s_add_i32 s65, s65, 2
	s_add_u32 s40, s40, 0x100
	s_addc_u32 s41, s41, 0
	s_add_u32 s59, s59, 0x10000
	s_addc_u32 s64, s64, 0
	s_cmp_gt_u32 s65, 29

; #define PG8_STAGE(bufoff, gbase, voff) do { _Pragma("unroll") for (int _i = 0; _i < 2; ++_i) \
;         __builtin_amdgcn_global_load_lds((const unsigned*)((const char*)(gbase) + (voff)[_i]), (LAS unsigned*)(lds + (bufoff) + ldsw + _i * 8192), 16, 0, 0); } while (0)
; #define PG8_LDA(dst, b, h) do { _Pragma("unroll") for (int m = 0; m < 4; ++m) _Pragma("unroll") for (int k = 0; k < 2; ++k) dst[m][k] = *(const LAS bf16x8*)(lds + PG8_SA(b, h) + aoff + m * 2048 + k * 1024); } while (0)
; #define PG8_LDB(dst, b, h) do { _Pragma("unroll") for (int n = 0; n < 2; ++n) _Pragma("unroll") for (int k = 0; k < 2; ++k) dst[n][k] = *(const LAS bf16x8*)(lds + PG8_SB(b, h) + boff + n * 2048 + k * 1024); } while (0)
; #define PG8_WAIT_V(n) asm volatile("s_waitcnt vmcnt(" #n ")" ::: "memory")
; #define PG8_WAIT_L(n) asm volatile("s_waitcnt lgkmcnt(" #n ")" ::: "memory")
; template <class Epi, class Sched, bool ABLK = false, bool ALIGN_EPI = true, bool SP2 = true, bool BBLK = true>
; __device__ __forceinline__ void gemm_phase(LAS unsigned char* lds, const Gemm g, const Sched& S, const Epi& E) {
;     ...
;         const bool has_next = S.next(ui + 1, nxt);
;         const int nt = cur.nt;
;         const char* nuA = has_next ? a_unit(nxt) : uA; const int ntbA = has_next ? nxt.k0 / BK : tbA; const char* nB = has_next ? (const char*)g.Bt + (size_t)nxt.pn * tstepB + b_k0(nxt.k0) : cB;
;         for (int t = 0; t < nt; t += 2) {
;             const bool last = (t == nt - 2);
;             const char* a1 = a_tile(uA, tbA + t + 1);
;             const char* a2 = last ? a_tile(nuA, ntbA) : a_tile(uA, tbA + t + 2); const char* b2 = last ? nB : cB + (size_t)(t + 2) * kstepB;
;             const char* a3 = last ? a_tile(nuA, ntbA + 1) : a_tile(uA, tbA + t + 3); const char* b3 = b2 + kstepB;
;             if (last && has_next) S.a_ready(nxt);
;             if constexpr (SP2) {
;             PG8_LDB(B0, 0, 0); PG8_LDB(B1, 0, 1); PG8_SCHED; PG8_LDA(At, 0, 0); PG8_STAGE(PG8_SA(1, 1), a1 + hstepA, voffA);
;             PG8_WAIT_V(8); PG8_WAIT_L(0); PG8_BAR; PG8_MMA(0, 0, At, B0); PG8_MMA(0, 1, At, B1); PG8_BAR; PG8_SCHED;
;             PG8_LDA(At, 0, 1); PG8_STAGE(PG8_SB(0, 0), b2, voffB); PG8_STAGE(PG8_SB(0, 1), b2 + hstepB, voffB); PG8_STAGE(PG8_SA(0, 0), a2, voffA);
;             PG8_WAIT_V(8); PG8_WAIT_L(0); PG8_BAR; PG8_MMA(1, 0, At, B0); PG8_MMA(1, 1, At, B1); PG8_BAR; PG8_SCHED;
.LBB0_1715:
	s_ashr_i32 s81, s80, 31
	s_andn2_b64 vcc, exec, s[4:5]
	s_lshl_b64 s[20:21], s[80:81], 20
	s_add_u32 s20, s1, s20
	s_addc_u32 s21, s36, s21
	s_and_b64 s[22:23], s[4:5], exec
	s_cselect_b32 s31, s21, s29
	s_cselect_b32 s49, s20, s28
	s_ashr_i32 s22, s63, 31
	s_lshr_b32 s22, s22, 26
	s_add_i32 s22, s63, s22
	s_ashr_i32 s22, s22, 6
	s_and_b64 s[24:25], s[4:5], exec
	s_cselect_b32 s34, s22, s30
	s_ashr_i32 s79, s78, 31
	s_lshl_b64 s[24:25], s[78:79], 20
	s_add_u32 s35, s37, s24
	s_addc_u32 s50, s38, s25
	s_ashr_i32 s23, s22, 31
	s_lshl_b64 s[24:25], s[22:23], 15
	s_add_u32 s24, s35, s24
	s_addc_u32 s25, s50, s25
	v_cndmask_b32_e64 v2, 0, 1, s[4:5]
	s_and_b64 s[4:5], s[4:5], exec
	s_cselect_b32 s4, s25, s27
	s_cselect_b32 s5, s24, s26
	s_ashr_i32 s35, s34, 31
	s_lshl_b64 s[34:35], s[34:35], 7
	s_add_u32 s23, s49, s34
	s_addc_u32 s49, s31, s35
	s_add_u32 s50, s23, 0x80
	s_addc_u32 s51, s49, 0
	s_add_u32 s52, s26, 0x10000
	s_addc_u32 s53, s27, 0
	s_ashr_i32 s31, s30, 31
	v_cmp_ne_u32_e64 s[10:11], 1, v2
	s_lshl_b64 s[26:27], s[30:31], 7
	v_lshl_add_u64 v[2:3], s[28:29], 0, v[142:143]
	s_add_u32 s54, s28, s26
	v_lshl_add_u64 v[146:147], v[2:3], 0, s[26:27]
	v_lshl_add_u64 v[2:3], s[28:29], 0, v[144:145]
	s_addc_u32 s55, s29, s27
	v_lshl_add_u64 v[148:149], v[2:3], 0, s[26:27]
	s_lshl_b32 s26, s47, 7
	s_addk_i32 s26, 0xfc00
	v_mov_b32_e32 v2, 0
	s_add_u32 s56, s26, 0x300
	s_mov_b32 s57, 0
	s_mov_b64 s[26:27], 0
	ds_read_b128 v[156:159], v152
	ds_read_b128 v[160:163], v152 offset:1024
	ds_read_b128 v[164:167], v152 offset:2048
	ds_read_b128 v[168:171], v152 offset:3072
	ds_read_b128 v[172:175], v153
	ds_read_b128 v[176:179], v153 offset:1024
	ds_read_b128 v[180:183], v153 offset:2048
	ds_read_b128 v[184:187], v153 offset:3072
	s_add_u32 s28, s54, s26
	s_addc_u32 s29, s55, s27
	s_add_u32 s34, s28, 0x100
	s_addc_u32 s35, s29, 0
	s_add_i32 s57, s57, 2
	s_add_u32 s28, s28, 0x180
	s_addc_u32 s29, s29, 0
	s_cmp_eq_u32 s56, s26
	s_cselect_b32 s29, s51, s29
	s_cselect_b32 s28, s50, s28
	s_cselect_b32 s31, s4, s53
	s_cselect_b32 s30, s5, s52
	s_cselect_b32 s35, s49, s35
	s_cselect_b32 s34, s23, s34
	v_lshl_add_u64 v[220:221], v[146:147], 0, s[26:27]
	s_add_i32 m0, s40, 0xc000
	ds_read_b128 v[188:191], v154
	ds_read_b128 v[192:195], v154 offset:1024
	ds_read_b128 v[196:199], v154 offset:2048
	ds_read_b128 v[200:203], v154 offset:3072
	ds_read_b128 v[204:207], v154 offset:4096
	ds_read_b128 v[208:211], v154 offset:5120
	ds_read_b128 v[212:215], v154 offset:6144
	ds_read_b128 v[216:219], v154 offset:7168
	global_load_lds_dwordx4 v[220:221], off
	v_lshl_add_u64 v[220:221], v[148:149], 0, s[26:27]
	s_add_i32 m0, s40, 0xe000
	s_nop 0
	global_load_lds_dwordx4 v[220:221], off
	s_waitcnt vmcnt(8)
	s_waitcnt lgkmcnt(0)
	s_barrier
	v_mfma_f32_16x16x32_bf16 v[126:129], v[156:159], v[188:191], 0
	v_mfma_f32_16x16x32_bf16 v[122:125], v[164:167], v[188:191], 0
	v_mfma_f32_16x16x32_bf16 v[110:113], v[156:159], v[196:199], 0
	v_mfma_f32_16x16x32_bf16 v[106:109], v[164:167], v[196:199], 0
	v_mfma_f32_16x16x32_bf16 v[94:97], v[156:159], v[204:207], 0
	v_mfma_f32_16x16x32_bf16 v[90:93], v[164:167], v[204:207], 0
	v_mfma_f32_16x16x32_bf16 v[78:81], v[156:159], v[212:215], 0
	v_mfma_f32_16x16x32_bf16 v[74:77], v[164:167], v[212:215], 0
	v_mfma_f32_16x16x32_bf16 v[126:129], v[160:163], v[192:195], v[126:129]
	v_mfma_f32_16x16x32_bf16 v[122:125], v[168:171], v[192:195], v[122:125]
	v_mfma_f32_16x16x32_bf16 v[110:113], v[160:163], v[200:203], v[110:113]
	v_mfma_f32_16x16x32_bf16 v[106:109], v[168:171], v[200:203], v[106:109]
	v_mfma_f32_16x16x32_bf16 v[94:97], v[160:163], v[208:211], v[94:97]
	v_mfma_f32_16x16x32_bf16 v[90:93], v[168:171], v[208:211], v[90:93]
	v_mfma_f32_16x16x32_bf16 v[78:81], v[160:163], v[216:219], v[78:81]
	v_mfma_f32_16x16x32_bf16 v[74:77], v[168:171], v[216:219], v[74:77]
	v_mfma_f32_16x16x32_bf16 v[118:121], v[172:175], v[188:191], 0
	v_mfma_f32_16x16x32_bf16 v[114:117], v[180:183], v[188:191], 0
	v_mfma_f32_16x16x32_bf16 v[102:105], v[172:175], v[196:199], 0
	v_mfma_f32_16x16x32_bf16 v[98:101], v[180:183], v[196:199], 0
	v_mfma_f32_16x16x32_bf16 v[86:89], v[172:175], v[204:207], 0
	v_mfma_f32_16x16x32_bf16 v[82:85], v[180:183], v[204:207], 0
	v_mfma_f32_16x16x32_bf16 v[70:73], v[172:175], v[212:215], 0
	v_mfma_f32_16x16x32_bf16 v[66:69], v[180:183], v[212:215], 0
	v_mfma_f32_16x16x32_bf16 v[118:121], v[176:179], v[192:195], v[118:121]
	v_mfma_f32_16x16x32_bf16 v[114:117], v[184:187], v[192:195], v[114:117]
	v_mfma_f32_16x16x32_bf16 v[102:105], v[176:179], v[200:203], v[102:105]
	v_mfma_f32_16x16x32_bf16 v[98:101], v[184:187], v[200:203], v[98:101]
	v_mfma_f32_16x16x32_bf16 v[86:89], v[176:179], v[208:211], v[86:89]
	v_mfma_f32_16x16x32_bf16 v[82:85], v[184:187], v[208:211], v[82:85]
	v_mfma_f32_16x16x32_bf16 v[70:73], v[176:179], v[216:219], v[70:73]
	v_mfma_f32_16x16x32_bf16 v[66:69], v[184:187], v[216:219], v[66:69]
	s_barrier
	s_add_i32 s58, s72, s39
	v_lshl_add_u64 v[220:221], s[30:31], 0, v[132:133]
	s_mov_b32 m0, s58
	ds_read_b128 v[188:191], v154 offset:16384
	ds_read_b128 v[192:195], v154 offset:17408
	ds_read_b128 v[196:199], v154 offset:18432
	ds_read_b128 v[200:203], v154 offset:19456
	ds_read_b128 v[204:207], v154 offset:20480
	ds_read_b128 v[208:211], v154 offset:21504
	ds_read_b128 v[212:215], v154 offset:22528
	ds_read_b128 v[216:219], v154 offset:23552
	global_load_lds_dwordx4 v[220:221], off
	s_add_i32 m0, s58, 0x2000
	s_add_u32 s58, s30, 0x4000
	v_lshl_add_u64 v[220:221], s[30:31], 0, v[136:137]
	s_addc_u32 s59, s31, 0
	s_add_i32 s64, s73, s39
	global_load_lds_dwordx4 v[220:221], off
	v_lshl_add_u64 v[220:221], s[58:59], 0, v[132:133]
	s_mov_b32 m0, s64
	s_nop 0
	global_load_lds_dwordx4 v[220:221], off
	v_lshl_add_u64 v[220:221], s[58:59], 0, v[136:137]
	s_add_i32 m0, s64, 0x2000
	s_nop 0
	global_load_lds_dwordx4 v[220:221], off
	v_lshl_add_u64 v[220:221], s[34:35], 0, v[130:131]
	s_mov_b32 m0, s40
	s_nop 0
	global_load_lds_dwordx4 v[220:221], off
	v_lshl_add_u64 v[220:221], s[34:35], 0, v[134:135]
	s_mov_b32 m0, s41
	s_nop 0
	global_load_lds_dwordx4 v[220:221], off
	s_waitcnt vmcnt(8)
	s_waitcnt lgkmcnt(0)
	s_barrier
; #define PG8_STAGE(bufoff, gbase, voff) do { _Pragma("unroll") for (int _i = 0; _i < 2; ++_i) \
;         __builtin_amdgcn_global_load_lds((const unsigned*)((const char*)(gbase) + (voff)[_i]), (LAS unsigned*)(lds + (bufoff) + ldsw + _i * 8192), 16, 0, 0); } while (0)
; #define PG8_LDA(dst, b, h) do { _Pragma("unroll") for (int m = 0; m < 4; ++m) _Pragma("unroll") for (int k = 0; k < 2; ++k) dst[m][k] = *(const LAS bf16x8*)(lds + PG8_SA(b, h) + aoff + m * 2048 + k * 1024); } while (0)
; #define PG8_LDB(dst, b, h) do { _Pragma("unroll") for (int n = 0; n < 2; ++n) _Pragma("unroll") for (int k = 0; k < 2; ++k) dst[n][k] = *(const LAS bf16x8*)(lds + PG8_SB(b, h) + boff + n * 2048 + k * 1024); } while (0)
; #define PG8_MMA(ai, bj, At, Bt) do { __builtin_amdgcn_s_setprio(1); _Pragma("unroll") for (int m = 0; m < 4; ++m) _Pragma("unroll") for (int n = 0; n < 2; ++n) _Pragma("unroll") for (int k = 0; k < 2; ++k) \
;         acc[ai][bj][m][n] = __builtin_amdgcn_mfma_f32_16x16x32_bf16(Bt[n][k], At[m][k], acc[ai][bj][m][n], 0, 0, 0); __builtin_amdgcn_s_setprio(0); } while (0)
; #define PG8_WAIT_V(n) asm volatile("s_waitcnt vmcnt(" #n ")" ::: "memory")
; #define PG8_WAIT_L(n) asm volatile("s_waitcnt lgkmcnt(" #n ")" ::: "memory")
; #define PG8_BAR __builtin_amdgcn_s_barrier()
; #define PG8_SCHED __builtin_amdgcn_sched_barrier(0)
; template <class Epi, class Sched, bool ABLK = false, bool ALIGN_EPI = true, bool SP2 = true, bool BBLK = true>
; __device__ __forceinline__ void gemm_phase(LAS unsigned char* lds, const Gemm g, const Sched& S, const Epi& E) {
;     ...
;             PG8_LDA(At, 0, 1); PG8_STAGE(PG8_SB(0, 0), b2, voffB); PG8_STAGE(PG8_SB(0, 1), b2 + hstepB, voffB); PG8_STAGE(PG8_SA(0, 0), a2, voffA);
;             PG8_WAIT_V(8); PG8_WAIT_L(0); PG8_BAR; PG8_MMA(1, 0, At, B0); PG8_MMA(1, 1, At, B1); PG8_BAR; PG8_SCHED;
;             PG8_LDB(B0, 1, 0); PG8_LDB(B1, 1, 1); PG8_SCHED; PG8_LDA(At, 1, 0); PG8_STAGE(PG8_SA(0, 1), a2 + hstepA, voffA);
;             PG8_WAIT_V(8); PG8_WAIT_L(0); PG8_BAR; PG8_MMA(0, 0, At, B0); PG8_MMA(0, 1, At, B1); PG8_BAR; PG8_SCHED;
	v_mfma_f32_16x16x32_bf16 v[62:65], v[156:159], v[188:191], 0
	v_mfma_f32_16x16x32_bf16 v[58:61], v[164:167], v[188:191], 0
	v_mfma_f32_16x16x32_bf16 v[46:49], v[156:159], v[196:199], 0
	v_mfma_f32_16x16x32_bf16 v[42:45], v[164:167], v[196:199], 0
	v_mfma_f32_16x16x32_bf16 v[30:33], v[156:159], v[204:207], 0
	v_mfma_f32_16x16x32_bf16 v[26:29], v[164:167], v[204:207], 0
	v_mfma_f32_16x16x32_bf16 v[14:17], v[156:159], v[212:215], 0
	v_mfma_f32_16x16x32_bf16 v[10:13], v[164:167], v[212:215], 0
	v_mfma_f32_16x16x32_bf16 v[62:65], v[160:163], v[192:195], v[62:65]
	v_mfma_f32_16x16x32_bf16 v[58:61], v[168:171], v[192:195], v[58:61]
	v_mfma_f32_16x16x32_bf16 v[46:49], v[160:163], v[200:203], v[46:49]
	v_mfma_f32_16x16x32_bf16 v[42:45], v[168:171], v[200:203], v[42:45]
	v_mfma_f32_16x16x32_bf16 v[30:33], v[160:163], v[208:211], v[30:33]
	v_mfma_f32_16x16x32_bf16 v[26:29], v[168:171], v[208:211], v[26:29]
	v_mfma_f32_16x16x32_bf16 v[14:17], v[160:163], v[216:219], v[14:17]
	v_mfma_f32_16x16x32_bf16 v[10:13], v[168:171], v[216:219], v[10:13]
	v_mfma_f32_16x16x32_bf16 v[54:57], v[172:175], v[188:191], 0
	v_mfma_f32_16x16x32_bf16 v[50:53], v[180:183], v[188:191], 0
	v_mfma_f32_16x16x32_bf16 v[38:41], v[172:175], v[196:199], 0
	v_mfma_f32_16x16x32_bf16 v[34:37], v[180:183], v[196:199], 0
	v_mfma_f32_16x16x32_bf16 v[22:25], v[172:175], v[204:207], 0
	v_mfma_f32_16x16x32_bf16 v[18:21], v[180:183], v[204:207], 0
	v_mfma_f32_16x16x32_bf16 v[6:9], v[172:175], v[212:215], 0
	v_mfma_f32_16x16x32_bf16 v[2:5], v[180:183], v[212:215], 0
	v_mfma_f32_16x16x32_bf16 v[54:57], v[176:179], v[192:195], v[54:57]
	v_mfma_f32_16x16x32_bf16 v[50:53], v[184:187], v[192:195], v[50:53]
	v_mfma_f32_16x16x32_bf16 v[38:41], v[176:179], v[200:203], v[38:41]
	v_mfma_f32_16x16x32_bf16 v[34:37], v[184:187], v[200:203], v[34:37]
	v_mfma_f32_16x16x32_bf16 v[22:25], v[176:179], v[208:211], v[22:25]
	v_mfma_f32_16x16x32_bf16 v[18:21], v[184:187], v[208:211], v[18:21]
	v_mfma_f32_16x16x32_bf16 v[6:9], v[176:179], v[216:219], v[6:9]
	v_mfma_f32_16x16x32_bf16 v[2:5], v[184:187], v[216:219], v[2:5]
	s_barrier
	v_add_u32_e32 v155, s60, v150
	ds_read_b128 v[156:159], v155
	ds_read_b128 v[160:163], v155 offset:1024
	ds_read_b128 v[164:167], v155 offset:2048
	ds_read_b128 v[168:171], v155 offset:3072
	v_add_u32_e32 v155, s61, v150
	ds_read_b128 v[172:175], v155
	ds_read_b128 v[176:179], v155 offset:1024
	ds_read_b128 v[180:183], v155 offset:2048
	ds_read_b128 v[184:187], v155 offset:3072
	s_add_u32 s34, s34, 0x80000
	s_addc_u32 s35, s35, 0
	s_mov_b32 m0, s42
	v_lshl_add_u64 v[220:221], s[34:35], 0, v[130:131]
	ds_read_b128 v[188:191], v154 offset:32768
	ds_read_b128 v[192:195], v154 offset:33792
	ds_read_b128 v[196:199], v154 offset:34816
	ds_read_b128 v[200:203], v154 offset:35840
	ds_read_b128 v[204:207], v154 offset:36864
	ds_read_b128 v[208:211], v154 offset:37888
	ds_read_b128 v[212:215], v154 offset:38912
	ds_read_b128 v[216:219], v154 offset:39936
	global_load_lds_dwordx4 v[220:221], off
	v_lshl_add_u64 v[220:221], s[34:35], 0, v[134:135]
	s_mov_b32 m0, s43
	s_nop 0
	global_load_lds_dwordx4 v[220:221], off
	s_waitcnt vmcnt(8)
	s_waitcnt lgkmcnt(0)
	s_barrier
	v_mfma_f32_16x16x32_bf16 v[126:129], v[156:159], v[188:191], v[126:129]
	v_mfma_f32_16x16x32_bf16 v[122:125], v[164:167], v[188:191], v[122:125]
	v_mfma_f32_16x16x32_bf16 v[110:113], v[156:159], v[196:199], v[110:113]
	v_mfma_f32_16x16x32_bf16 v[106:109], v[164:167], v[196:199], v[106:109]
	v_mfma_f32_16x16x32_bf16 v[94:97], v[156:159], v[204:207], v[94:97]
	v_mfma_f32_16x16x32_bf16 v[90:93], v[164:167], v[204:207], v[90:93]
	v_mfma_f32_16x16x32_bf16 v[78:81], v[156:159], v[212:215], v[78:81]
	v_mfma_f32_16x16x32_bf16 v[74:77], v[164:167], v[212:215], v[74:77]
	v_mfma_f32_16x16x32_bf16 v[126:129], v[160:163], v[192:195], v[126:129]
	v_mfma_f32_16x16x32_bf16 v[122:125], v[168:171], v[192:195], v[122:125]
	v_mfma_f32_16x16x32_bf16 v[110:113], v[160:163], v[200:203], v[110:113]
	v_mfma_f32_16x16x32_bf16 v[106:109], v[168:171], v[200:203], v[106:109]
	v_mfma_f32_16x16x32_bf16 v[94:97], v[160:163], v[208:211], v[94:97]
	v_mfma_f32_16x16x32_bf16 v[90:93], v[168:171], v[208:211], v[90:93]
	v_mfma_f32_16x16x32_bf16 v[78:81], v[160:163], v[216:219], v[78:81]
	v_mfma_f32_16x16x32_bf16 v[74:77], v[168:171], v[216:219], v[74:77]
	v_mfma_f32_16x16x32_bf16 v[118:121], v[172:175], v[188:191], v[118:121]
	v_mfma_f32_16x16x32_bf16 v[114:117], v[180:183], v[188:191], v[114:117]
	v_mfma_f32_16x16x32_bf16 v[102:105], v[172:175], v[196:199], v[102:105]
	v_mfma_f32_16x16x32_bf16 v[98:101], v[180:183], v[196:199], v[98:101]
	v_mfma_f32_16x16x32_bf16 v[86:89], v[172:175], v[204:207], v[86:89]
	v_mfma_f32_16x16x32_bf16 v[82:85], v[180:183], v[204:207], v[82:85]
	v_mfma_f32_16x16x32_bf16 v[70:73], v[172:175], v[212:215], v[70:73]
	v_mfma_f32_16x16x32_bf16 v[66:69], v[180:183], v[212:215], v[66:69]
	v_mfma_f32_16x16x32_bf16 v[118:121], v[176:179], v[192:195], v[118:121]
	v_mfma_f32_16x16x32_bf16 v[114:117], v[184:187], v[192:195], v[114:117]
	v_mfma_f32_16x16x32_bf16 v[102:105], v[176:179], v[200:203], v[102:105]
	v_mfma_f32_16x16x32_bf16 v[98:101], v[184:187], v[200:203], v[98:101]
	v_mfma_f32_16x16x32_bf16 v[86:89], v[176:179], v[208:211], v[86:89]
	v_mfma_f32_16x16x32_bf16 v[82:85], v[184:187], v[208:211], v[82:85]
	v_mfma_f32_16x16x32_bf16 v[70:73], v[176:179], v[216:219], v[70:73]
	v_mfma_f32_16x16x32_bf16 v[66:69], v[184:187], v[216:219], v[66:69]
	s_barrier
; #define PG8_STAGE(bufoff, gbase, voff) do { _Pragma("unroll") for (int _i = 0; _i < 2; ++_i) \
;         __builtin_amdgcn_global_load_lds((const unsigned*)((const char*)(gbase) + (voff)[_i]), (LAS unsigned*)(lds + (bufoff) + ldsw + _i * 8192), 16, 0, 0); } while (0)
; #define PG8_LDA(dst, b, h) do { _Pragma("unroll") for (int m = 0; m < 4; ++m) _Pragma("unroll") for (int k = 0; k < 2; ++k) dst[m][k] = *(const LAS bf16x8*)(lds + PG8_SA(b, h) + aoff + m * 2048 + k * 1024); } while (0)
; #define PG8_MMA(ai, bj, At, Bt) do { __builtin_amdgcn_s_setprio(1); _Pragma("unroll") for (int m = 0; m < 4; ++m) _Pragma("unroll") for (int n = 0; n < 2; ++n) _Pragma("unroll") for (int k = 0; k < 2; ++k) \
;         acc[ai][bj][m][n] = __builtin_amdgcn_mfma_f32_16x16x32_bf16(Bt[n][k], At[m][k], acc[ai][bj][m][n], 0, 0, 0); __builtin_amdgcn_s_setprio(0); } while (0)
; #define PG8_WAIT_V(n) asm volatile("s_waitcnt vmcnt(" #n ")" ::: "memory")
; #define PG8_WAIT_L(n) asm volatile("s_waitcnt lgkmcnt(" #n ")" ::: "memory")
; #define PG8_BAR __builtin_amdgcn_s_barrier()
; #define PG8_SCHED __builtin_amdgcn_sched_barrier(0)
; template <class Epi, class Sched, bool ABLK = false, bool ALIGN_EPI = true, bool SP2 = true, bool BBLK = true>
; __device__ __forceinline__ void gemm_phase(LAS unsigned char* lds, const Gemm g, const Sched& S, const Epi& E) {
;     ...
;         for (int t = 0; t < nt; t += 2) {
;     ...
;             PG8_LDA(At, 1, 1); PG8_STAGE(PG8_SB(1, 0), b3, voffB); PG8_STAGE(PG8_SB(1, 1), b3 + hstepB, voffB); PG8_STAGE(PG8_SA(1, 0), a3, voffA);
;             PG8_WAIT_V(8); PG8_WAIT_L(0); PG8_BAR; PG8_MMA(1, 0, At, B0); PG8_MMA(1, 1, At, B1); PG8_BAR; PG8_SCHED;
	s_add_u32 s34, s30, 0x8000
	s_addc_u32 s35, s31, 0
	s_add_i32 s58, s60, s39
	v_lshl_add_u64 v[220:221], s[34:35], 0, v[132:133]
	s_mov_b32 m0, s58
	ds_read_b128 v[188:191], v154 offset:49152
	ds_read_b128 v[192:195], v154 offset:50176
	ds_read_b128 v[196:199], v154 offset:51200
	ds_read_b128 v[200:203], v154 offset:52224
	ds_read_b128 v[204:207], v154 offset:53248
	ds_read_b128 v[208:211], v154 offset:54272
	ds_read_b128 v[212:215], v154 offset:55296
	ds_read_b128 v[216:219], v154 offset:56320
	global_load_lds_dwordx4 v[220:221], off
	s_add_i32 m0, s58, 0x2000
	s_add_u32 s30, s30, 0xc000
	v_lshl_add_u64 v[220:221], s[34:35], 0, v[136:137]
	s_addc_u32 s31, s31, 0
	s_add_i32 s34, s61, s39
	global_load_lds_dwordx4 v[220:221], off
	v_lshl_add_u64 v[220:221], s[30:31], 0, v[132:133]
	s_mov_b32 m0, s34
	s_nop 0
	global_load_lds_dwordx4 v[220:221], off
	v_lshl_add_u64 v[220:221], s[30:31], 0, v[136:137]
	s_add_i32 m0, s34, 0x2000
	s_nop 0
	global_load_lds_dwordx4 v[220:221], off
	v_lshl_add_u64 v[220:221], s[28:29], 0, v[130:131]
	s_mov_b32 m0, s44
	s_nop 0
	global_load_lds_dwordx4 v[220:221], off
	v_lshl_add_u64 v[220:221], s[28:29], 0, v[134:135]
	s_mov_b32 m0, s45
	s_nop 0
	global_load_lds_dwordx4 v[220:221], off
	s_waitcnt vmcnt(8)
	s_waitcnt lgkmcnt(0)
	s_barrier
	v_mfma_f32_16x16x32_bf16 v[62:65], v[156:159], v[188:191], v[62:65]
	v_mfma_f32_16x16x32_bf16 v[58:61], v[164:167], v[188:191], v[58:61]
	v_mfma_f32_16x16x32_bf16 v[46:49], v[156:159], v[196:199], v[46:49]
	v_mfma_f32_16x16x32_bf16 v[42:45], v[164:167], v[196:199], v[42:45]
	v_mfma_f32_16x16x32_bf16 v[30:33], v[156:159], v[204:207], v[30:33]
	v_mfma_f32_16x16x32_bf16 v[26:29], v[164:167], v[204:207], v[26:29]
	v_mfma_f32_16x16x32_bf16 v[14:17], v[156:159], v[212:215], v[14:17]
	v_mfma_f32_16x16x32_bf16 v[10:13], v[164:167], v[212:215], v[10:13]
	v_mfma_f32_16x16x32_bf16 v[62:65], v[160:163], v[192:195], v[62:65]
	v_mfma_f32_16x16x32_bf16 v[58:61], v[168:171], v[192:195], v[58:61]
	v_mfma_f32_16x16x32_bf16 v[46:49], v[160:163], v[200:203], v[46:49]
	v_mfma_f32_16x16x32_bf16 v[42:45], v[168:171], v[200:203], v[42:45]
	v_mfma_f32_16x16x32_bf16 v[30:33], v[160:163], v[208:211], v[30:33]
	v_mfma_f32_16x16x32_bf16 v[26:29], v[168:171], v[208:211], v[26:29]
	v_mfma_f32_16x16x32_bf16 v[14:17], v[160:163], v[216:219], v[14:17]
	v_mfma_f32_16x16x32_bf16 v[10:13], v[168:171], v[216:219], v[10:13]
	v_mfma_f32_16x16x32_bf16 v[54:57], v[172:175], v[188:191], v[54:57]
	v_mfma_f32_16x16x32_bf16 v[50:53], v[180:183], v[188:191], v[50:53]
	v_mfma_f32_16x16x32_bf16 v[38:41], v[172:175], v[196:199], v[38:41]
	v_mfma_f32_16x16x32_bf16 v[34:37], v[180:183], v[196:199], v[34:37]
	v_mfma_f32_16x16x32_bf16 v[22:25], v[172:175], v[204:207], v[22:25]
	v_mfma_f32_16x16x32_bf16 v[18:21], v[180:183], v[204:207], v[18:21]
	v_mfma_f32_16x16x32_bf16 v[6:9], v[172:175], v[212:215], v[6:9]
	v_mfma_f32_16x16x32_bf16 v[2:5], v[180:183], v[212:215], v[2:5]
	v_mfma_f32_16x16x32_bf16 v[54:57], v[176:179], v[192:195], v[54:57]
	v_mfma_f32_16x16x32_bf16 v[50:53], v[184:187], v[192:195], v[50:53]
	v_mfma_f32_16x16x32_bf16 v[38:41], v[176:179], v[200:203], v[38:41]
	v_mfma_f32_16x16x32_bf16 v[34:37], v[184:187], v[200:203], v[34:37]
	v_mfma_f32_16x16x32_bf16 v[22:25], v[176:179], v[208:211], v[22:25]
	v_mfma_f32_16x16x32_bf16 v[18:21], v[184:187], v[208:211], v[18:21]
	v_mfma_f32_16x16x32_bf16 v[6:9], v[176:179], v[216:219], v[6:9]
	v_mfma_f32_16x16x32_bf16 v[2:5], v[184:187], v[216:219], v[2:5]
	s_barrier
	s_add_u32 s52, s52, 0x10000
	s_addc_u32 s53, s53, 0
	s_add_u32 s26, s26, 0x100
	s_addc_u32 s27, s27, 0
	s_cmp_ge_u32 s57, s47

; #define PG8_STAGE(bufoff, gbase, voff) do { _Pragma("unroll") for (int _i = 0; _i < 2; ++_i) \
;         __builtin_amdgcn_global_load_lds((const unsigned*)((const char*)(gbase) + (voff)[_i]), (LAS unsigned*)(lds + (bufoff) + ldsw + _i * 8192), 16, 0, 0); } while (0)
; #define PG8_LDA(dst, b, h) do { _Pragma("unroll") for (int m = 0; m < 4; ++m) _Pragma("unroll") for (int k = 0; k < 2; ++k) dst[m][k] = *(const LAS bf16x8*)(lds + PG8_SA(b, h) + aoff + m * 2048 + k * 1024); } while (0)
; #define PG8_LDB(dst, b, h) do { _Pragma("unroll") for (int n = 0; n < 2; ++n) _Pragma("unroll") for (int k = 0; k < 2; ++k) dst[n][k] = *(const LAS bf16x8*)(lds + PG8_SB(b, h) + boff + n * 2048 + k * 1024); } while (0)
; #define PG8_WAIT_V(n) asm volatile("s_waitcnt vmcnt(" #n ")" ::: "memory")
; #define PG8_WAIT_L(n) asm volatile("s_waitcnt lgkmcnt(" #n ")" ::: "memory")
; template <class Epi, class Sched, bool ABLK = false, bool ALIGN_EPI = true, bool SP2 = true, bool BBLK = true>
; __device__ __forceinline__ void gemm_phase(LAS unsigned char* lds, const Gemm g, const Sched& S, const Epi& E) {
;     ...
;         const bool has_next = S.next(ui + 1, nxt);
;         const int nt = cur.nt;
;         const char* nuA = has_next ? a_unit(nxt) : uA; const int ntbA = has_next ? nxt.k0 / BK : tbA; const char* nB = has_next ? (const char*)g.Bt + (size_t)nxt.pn * tstepB + b_k0(nxt.k0) : cB;
;         for (int t = 0; t < nt; t += 2) {
;             const bool last = (t == nt - 2);
;             const char* a1 = a_tile(uA, tbA + t + 1);
;             const char* a2 = last ? a_tile(nuA, ntbA) : a_tile(uA, tbA + t + 2); const char* b2 = last ? nB : cB + (size_t)(t + 2) * kstepB;
;             const char* a3 = last ? a_tile(nuA, ntbA + 1) : a_tile(uA, tbA + t + 3); const char* b3 = b2 + kstepB;
;             if (last && has_next) S.a_ready(nxt);
;             if constexpr (SP2) {
;             PG8_LDB(B0, 0, 0); PG8_LDB(B1, 0, 1); PG8_SCHED; PG8_LDA(At, 0, 0); PG8_STAGE(PG8_SA(1, 1), a1 + hstepA, voffA);
;             PG8_WAIT_V(8); PG8_WAIT_L(0); PG8_BAR; PG8_MMA(0, 0, At, B0); PG8_MMA(0, 1, At, B1); PG8_BAR; PG8_SCHED;
;             PG8_LDA(At, 0, 1); PG8_STAGE(PG8_SB(0, 0), b2, voffB); PG8_STAGE(PG8_SB(0, 1), b2 + hstepB, voffB); PG8_STAGE(PG8_SA(0, 0), a2, voffA);
;             PG8_WAIT_V(8); PG8_WAIT_L(0); PG8_BAR; PG8_MMA(1, 0, At, B0); PG8_MMA(1, 1, At, B1); PG8_BAR; PG8_SCHED;
.LBB0_1841:
	s_ashr_i32 s11, s10, 31
	s_lshl_b64 s[4:5], s[10:11], 20
	s_add_u32 s16, s76, s4
	s_addc_u32 s17, s33, s5
	s_and_b64 s[4:5], s[18:19], exec
	s_cselect_b32 s4, s17, s27
	s_cselect_b32 s5, s16, s26
	s_ashr_i32 s15, s14, 31
	s_lshl_b64 s[20:21], s[14:15], 20
	s_add_u32 s20, s1, s20
	s_addc_u32 s21, s38, s21
	s_and_b64 s[30:31], s[18:19], exec
	s_cselect_b32 s11, s21, s29
	s_cselect_b32 s15, s20, s28
	s_add_u32 s23, s5, 0x80
	s_addc_u32 s51, s4, 0
	s_add_u32 s52, s28, 0x10000
	v_mov_b32_e32 v2, 0
	s_addc_u32 s53, s29, 0
	v_lshl_add_u64 v[164:165], s[26:27], 0, v[160:161]
	v_lshl_add_u64 v[166:167], s[26:27], 0, v[162:163]
	s_mov_b32 s54, -2
	s_mov_b64 s[28:29], 0
	ds_read_b128 v[172:175], v168
	ds_read_b128 v[176:179], v168 offset:1024
	ds_read_b128 v[180:183], v168 offset:2048
	ds_read_b128 v[184:187], v168 offset:3072
	ds_read_b128 v[188:191], v169
	ds_read_b128 v[192:195], v169 offset:1024
	ds_read_b128 v[196:199], v169 offset:2048
	ds_read_b128 v[200:203], v169 offset:3072
	s_add_u32 s30, s26, s28
	s_addc_u32 s31, s27, s29
	s_add_u32 s36, s30, 0x100
	s_addc_u32 s37, s31, 0
	s_add_u32 s30, s30, 0x180
	s_addc_u32 s31, s31, 0
	s_cmpk_eq_i32 s28, 0xf00
	s_cselect_b32 s31, s51, s31
	s_cselect_b32 s30, s23, s30
	s_cselect_b32 s35, s11, s53
	s_cselect_b32 s34, s15, s52
	s_cselect_b32 s37, s4, s37
	s_cselect_b32 s36, s5, s36
	s_mov_b32 m0, s47
	v_lshl_add_u64 v[236:237], v[164:165], 0, s[28:29]
	ds_read_b128 v[204:207], v170
	ds_read_b128 v[208:211], v170 offset:1024
	ds_read_b128 v[212:215], v170 offset:2048
	ds_read_b128 v[216:219], v170 offset:3072
	ds_read_b128 v[220:223], v170 offset:4096
	ds_read_b128 v[224:227], v170 offset:5120
	ds_read_b128 v[228:231], v170 offset:6144
	ds_read_b128 v[232:235], v170 offset:7168
	global_load_lds_dwordx4 v[236:237], off
	v_lshl_add_u64 v[236:237], v[166:167], 0, s[28:29]
	s_mov_b32 m0, s48
	s_nop 0
	global_load_lds_dwordx4 v[236:237], off
	s_waitcnt vmcnt(8)
	s_waitcnt lgkmcnt(0)
	s_barrier
	v_mfma_f32_16x16x32_bf16 v[126:129], v[172:175], v[204:207], 0
	v_mfma_f32_16x16x32_bf16 v[122:125], v[180:183], v[204:207], 0
	v_mfma_f32_16x16x32_bf16 v[110:113], v[172:175], v[212:215], 0
	v_mfma_f32_16x16x32_bf16 v[106:109], v[180:183], v[212:215], 0
	v_mfma_f32_16x16x32_bf16 v[94:97], v[172:175], v[220:223], 0
	v_mfma_f32_16x16x32_bf16 v[90:93], v[180:183], v[220:223], 0
	v_mfma_f32_16x16x32_bf16 v[78:81], v[172:175], v[228:231], 0
	v_mfma_f32_16x16x32_bf16 v[74:77], v[180:183], v[228:231], 0
	v_mfma_f32_16x16x32_bf16 v[126:129], v[176:179], v[208:211], v[126:129]
	v_mfma_f32_16x16x32_bf16 v[122:125], v[184:187], v[208:211], v[122:125]
	v_mfma_f32_16x16x32_bf16 v[110:113], v[176:179], v[216:219], v[110:113]
	v_mfma_f32_16x16x32_bf16 v[106:109], v[184:187], v[216:219], v[106:109]
	v_mfma_f32_16x16x32_bf16 v[94:97], v[176:179], v[224:227], v[94:97]
	v_mfma_f32_16x16x32_bf16 v[90:93], v[184:187], v[224:227], v[90:93]
	v_mfma_f32_16x16x32_bf16 v[78:81], v[176:179], v[232:235], v[78:81]
	v_mfma_f32_16x16x32_bf16 v[74:77], v[184:187], v[232:235], v[74:77]
	v_mfma_f32_16x16x32_bf16 v[118:121], v[188:191], v[204:207], 0
	v_mfma_f32_16x16x32_bf16 v[114:117], v[196:199], v[204:207], 0
	v_mfma_f32_16x16x32_bf16 v[102:105], v[188:191], v[212:215], 0
	v_mfma_f32_16x16x32_bf16 v[98:101], v[196:199], v[212:215], 0
	v_mfma_f32_16x16x32_bf16 v[86:89], v[188:191], v[220:223], 0
	v_mfma_f32_16x16x32_bf16 v[82:85], v[196:199], v[220:223], 0
	v_mfma_f32_16x16x32_bf16 v[70:73], v[188:191], v[228:231], 0
	v_mfma_f32_16x16x32_bf16 v[66:69], v[196:199], v[228:231], 0
	v_mfma_f32_16x16x32_bf16 v[118:121], v[192:195], v[208:211], v[118:121]
	v_mfma_f32_16x16x32_bf16 v[114:117], v[200:203], v[208:211], v[114:117]
	v_mfma_f32_16x16x32_bf16 v[102:105], v[192:195], v[216:219], v[102:105]
	v_mfma_f32_16x16x32_bf16 v[98:101], v[200:203], v[216:219], v[98:101]
	v_mfma_f32_16x16x32_bf16 v[86:89], v[192:195], v[224:227], v[86:89]
	v_mfma_f32_16x16x32_bf16 v[82:85], v[200:203], v[224:227], v[82:85]
	v_mfma_f32_16x16x32_bf16 v[70:73], v[192:195], v[232:235], v[70:73]
	v_mfma_f32_16x16x32_bf16 v[66:69], v[200:203], v[232:235], v[66:69]
	s_barrier
	s_mov_b32 m0, s49
	v_lshl_add_u64 v[236:237], s[34:35], 0, v[134:135]
	s_add_u32 s56, s34, 0x4000
	ds_read_b128 v[204:207], v170 offset:16384
	ds_read_b128 v[208:211], v170 offset:17408
	ds_read_b128 v[212:215], v170 offset:18432
	ds_read_b128 v[216:219], v170 offset:19456
	ds_read_b128 v[220:223], v170 offset:20480
	ds_read_b128 v[224:227], v170 offset:21504
	ds_read_b128 v[228:231], v170 offset:22528
	ds_read_b128 v[232:235], v170 offset:23552
	global_load_lds_dwordx4 v[236:237], off
	v_lshl_add_u64 v[236:237], s[34:35], 0, v[130:131]
	s_mov_b32 m0, s50
	s_addc_u32 s57, s35, 0
	s_add_i32 s55, s73, s39
	global_load_lds_dwordx4 v[236:237], off
	v_lshl_add_u64 v[236:237], s[56:57], 0, v[134:135]
	s_mov_b32 m0, s55
	s_nop 0
	global_load_lds_dwordx4 v[236:237], off
	v_lshl_add_u64 v[236:237], s[56:57], 0, v[130:131]
	s_add_i32 m0, s55, 0x2000
	s_nop 0
	global_load_lds_dwordx4 v[236:237], off
	v_lshl_add_u64 v[236:237], s[36:37], 0, v[136:137]
	s_mov_b32 m0, s25
	s_nop 0
	global_load_lds_dwordx4 v[236:237], off
	v_lshl_add_u64 v[236:237], s[36:37], 0, v[132:133]
	s_mov_b32 m0, s40
	s_nop 0
	global_load_lds_dwordx4 v[236:237], off
	s_waitcnt vmcnt(8)
	s_waitcnt lgkmcnt(0)
	s_barrier
; #define PG8_STAGE(bufoff, gbase, voff) do { _Pragma("unroll") for (int _i = 0; _i < 2; ++_i) \
;         __builtin_amdgcn_global_load_lds((const unsigned*)((const char*)(gbase) + (voff)[_i]), (LAS unsigned*)(lds + (bufoff) + ldsw + _i * 8192), 16, 0, 0); } while (0)
; #define PG8_LDA(dst, b, h) do { _Pragma("unroll") for (int m = 0; m < 4; ++m) _Pragma("unroll") for (int k = 0; k < 2; ++k) dst[m][k] = *(const LAS bf16x8*)(lds + PG8_SA(b, h) + aoff + m * 2048 + k * 1024); } while (0)
; #define PG8_LDB(dst, b, h) do { _Pragma("unroll") for (int n = 0; n < 2; ++n) _Pragma("unroll") for (int k = 0; k < 2; ++k) dst[n][k] = *(const LAS bf16x8*)(lds + PG8_SB(b, h) + boff + n * 2048 + k * 1024); } while (0)
; #define PG8_MMA(ai, bj, At, Bt) do { __builtin_amdgcn_s_setprio(1); _Pragma("unroll") for (int m = 0; m < 4; ++m) _Pragma("unroll") for (int n = 0; n < 2; ++n) _Pragma("unroll") for (int k = 0; k < 2; ++k) \
;         acc[ai][bj][m][n] = __builtin_amdgcn_mfma_f32_16x16x32_bf16(Bt[n][k], At[m][k], acc[ai][bj][m][n], 0, 0, 0); __builtin_amdgcn_s_setprio(0); } while (0)
; #define PG8_WAIT_V(n) asm volatile("s_waitcnt vmcnt(" #n ")" ::: "memory")
; #define PG8_WAIT_L(n) asm volatile("s_waitcnt lgkmcnt(" #n ")" ::: "memory")
; #define PG8_BAR __builtin_amdgcn_s_barrier()
; #define PG8_SCHED __builtin_amdgcn_sched_barrier(0)
; template <class Epi, class Sched, bool ABLK = false, bool ALIGN_EPI = true, bool SP2 = true, bool BBLK = true>
; __device__ __forceinline__ void gemm_phase(LAS unsigned char* lds, const Gemm g, const Sched& S, const Epi& E) {
;     ...
;             PG8_LDA(At, 0, 1); PG8_STAGE(PG8_SB(0, 0), b2, voffB); PG8_STAGE(PG8_SB(0, 1), b2 + hstepB, voffB); PG8_STAGE(PG8_SA(0, 0), a2, voffA);
;             PG8_WAIT_V(8); PG8_WAIT_L(0); PG8_BAR; PG8_MMA(1, 0, At, B0); PG8_MMA(1, 1, At, B1); PG8_BAR; PG8_SCHED;
;             PG8_LDB(B0, 1, 0); PG8_LDB(B1, 1, 1); PG8_SCHED; PG8_LDA(At, 1, 0); PG8_STAGE(PG8_SA(0, 1), a2 + hstepA, voffA);
;             PG8_WAIT_V(8); PG8_WAIT_L(0); PG8_BAR; PG8_MMA(0, 0, At, B0); PG8_MMA(0, 1, At, B1); PG8_BAR; PG8_SCHED;
	v_mfma_f32_16x16x32_bf16 v[62:65], v[172:175], v[204:207], 0
	v_mfma_f32_16x16x32_bf16 v[58:61], v[180:183], v[204:207], 0
	v_mfma_f32_16x16x32_bf16 v[46:49], v[172:175], v[212:215], 0
	v_mfma_f32_16x16x32_bf16 v[42:45], v[180:183], v[212:215], 0
	v_mfma_f32_16x16x32_bf16 v[30:33], v[172:175], v[220:223], 0
	v_mfma_f32_16x16x32_bf16 v[26:29], v[180:183], v[220:223], 0
	v_mfma_f32_16x16x32_bf16 v[14:17], v[172:175], v[228:231], 0
	v_mfma_f32_16x16x32_bf16 v[10:13], v[180:183], v[228:231], 0
	v_mfma_f32_16x16x32_bf16 v[62:65], v[176:179], v[208:211], v[62:65]
	v_mfma_f32_16x16x32_bf16 v[58:61], v[184:187], v[208:211], v[58:61]
	v_mfma_f32_16x16x32_bf16 v[46:49], v[176:179], v[216:219], v[46:49]
	v_mfma_f32_16x16x32_bf16 v[42:45], v[184:187], v[216:219], v[42:45]
	v_mfma_f32_16x16x32_bf16 v[30:33], v[176:179], v[224:227], v[30:33]
	v_mfma_f32_16x16x32_bf16 v[26:29], v[184:187], v[224:227], v[26:29]
	v_mfma_f32_16x16x32_bf16 v[14:17], v[176:179], v[232:235], v[14:17]
	v_mfma_f32_16x16x32_bf16 v[10:13], v[184:187], v[232:235], v[10:13]
	v_mfma_f32_16x16x32_bf16 v[54:57], v[188:191], v[204:207], 0
	v_mfma_f32_16x16x32_bf16 v[50:53], v[196:199], v[204:207], 0
	v_mfma_f32_16x16x32_bf16 v[38:41], v[188:191], v[212:215], 0
	v_mfma_f32_16x16x32_bf16 v[34:37], v[196:199], v[212:215], 0
	v_mfma_f32_16x16x32_bf16 v[22:25], v[188:191], v[220:223], 0
	v_mfma_f32_16x16x32_bf16 v[18:21], v[196:199], v[220:223], 0
	v_mfma_f32_16x16x32_bf16 v[6:9], v[188:191], v[228:231], 0
	v_mfma_f32_16x16x32_bf16 v[2:5], v[196:199], v[228:231], 0
	v_mfma_f32_16x16x32_bf16 v[54:57], v[192:195], v[208:211], v[54:57]
	v_mfma_f32_16x16x32_bf16 v[50:53], v[200:203], v[208:211], v[50:53]
	v_mfma_f32_16x16x32_bf16 v[38:41], v[192:195], v[216:219], v[38:41]
	v_mfma_f32_16x16x32_bf16 v[34:37], v[200:203], v[216:219], v[34:37]
	v_mfma_f32_16x16x32_bf16 v[22:25], v[192:195], v[224:227], v[22:25]
	v_mfma_f32_16x16x32_bf16 v[18:21], v[200:203], v[224:227], v[18:21]
	v_mfma_f32_16x16x32_bf16 v[6:9], v[192:195], v[232:235], v[6:9]
	v_mfma_f32_16x16x32_bf16 v[2:5], v[200:203], v[232:235], v[2:5]
	s_barrier
	v_add_u32_e32 v171, s60, v1
	ds_read_b128 v[172:175], v171
	ds_read_b128 v[176:179], v171 offset:1024
	ds_read_b128 v[180:183], v171 offset:2048
	ds_read_b128 v[184:187], v171 offset:3072
	v_add_u32_e32 v171, s61, v1
	ds_read_b128 v[188:191], v171
	ds_read_b128 v[192:195], v171 offset:1024
	ds_read_b128 v[196:199], v171 offset:2048
	ds_read_b128 v[200:203], v171 offset:3072
	s_add_u32 s36, s36, 0x80000
	s_addc_u32 s37, s37, 0
	s_mov_b32 m0, s41
	v_lshl_add_u64 v[236:237], s[36:37], 0, v[136:137]
	ds_read_b128 v[204:207], v170 offset:32768
	ds_read_b128 v[208:211], v170 offset:33792
	ds_read_b128 v[212:215], v170 offset:34816
	ds_read_b128 v[216:219], v170 offset:35840
	ds_read_b128 v[220:223], v170 offset:36864
	ds_read_b128 v[224:227], v170 offset:37888
	ds_read_b128 v[228:231], v170 offset:38912
	ds_read_b128 v[232:235], v170 offset:39936
	global_load_lds_dwordx4 v[236:237], off
	v_lshl_add_u64 v[236:237], s[36:37], 0, v[132:133]
	s_mov_b32 m0, s42
	s_nop 0
	global_load_lds_dwordx4 v[236:237], off
	s_waitcnt vmcnt(8)
	s_waitcnt lgkmcnt(0)
	s_barrier
	v_mfma_f32_16x16x32_bf16 v[126:129], v[172:175], v[204:207], v[126:129]
	v_mfma_f32_16x16x32_bf16 v[122:125], v[180:183], v[204:207], v[122:125]
	v_mfma_f32_16x16x32_bf16 v[110:113], v[172:175], v[212:215], v[110:113]
	v_mfma_f32_16x16x32_bf16 v[106:109], v[180:183], v[212:215], v[106:109]
	v_mfma_f32_16x16x32_bf16 v[94:97], v[172:175], v[220:223], v[94:97]
	v_mfma_f32_16x16x32_bf16 v[90:93], v[180:183], v[220:223], v[90:93]
	v_mfma_f32_16x16x32_bf16 v[78:81], v[172:175], v[228:231], v[78:81]
	v_mfma_f32_16x16x32_bf16 v[74:77], v[180:183], v[228:231], v[74:77]
	v_mfma_f32_16x16x32_bf16 v[126:129], v[176:179], v[208:211], v[126:129]
	v_mfma_f32_16x16x32_bf16 v[122:125], v[184:187], v[208:211], v[122:125]
	v_mfma_f32_16x16x32_bf16 v[110:113], v[176:179], v[216:219], v[110:113]
	v_mfma_f32_16x16x32_bf16 v[106:109], v[184:187], v[216:219], v[106:109]
	v_mfma_f32_16x16x32_bf16 v[94:97], v[176:179], v[224:227], v[94:97]
	v_mfma_f32_16x16x32_bf16 v[90:93], v[184:187], v[224:227], v[90:93]
	v_mfma_f32_16x16x32_bf16 v[78:81], v[176:179], v[232:235], v[78:81]
	v_mfma_f32_16x16x32_bf16 v[74:77], v[184:187], v[232:235], v[74:77]
	v_mfma_f32_16x16x32_bf16 v[118:121], v[188:191], v[204:207], v[118:121]
	v_mfma_f32_16x16x32_bf16 v[114:117], v[196:199], v[204:207], v[114:117]
	v_mfma_f32_16x16x32_bf16 v[102:105], v[188:191], v[212:215], v[102:105]
	v_mfma_f32_16x16x32_bf16 v[98:101], v[196:199], v[212:215], v[98:101]
	v_mfma_f32_16x16x32_bf16 v[86:89], v[188:191], v[220:223], v[86:89]
	v_mfma_f32_16x16x32_bf16 v[82:85], v[196:199], v[220:223], v[82:85]
	v_mfma_f32_16x16x32_bf16 v[70:73], v[188:191], v[228:231], v[70:73]
	v_mfma_f32_16x16x32_bf16 v[66:69], v[196:199], v[228:231], v[66:69]
	v_mfma_f32_16x16x32_bf16 v[118:121], v[192:195], v[208:211], v[118:121]
	v_mfma_f32_16x16x32_bf16 v[114:117], v[200:203], v[208:211], v[114:117]
	v_mfma_f32_16x16x32_bf16 v[102:105], v[192:195], v[216:219], v[102:105]
	v_mfma_f32_16x16x32_bf16 v[98:101], v[200:203], v[216:219], v[98:101]
	v_mfma_f32_16x16x32_bf16 v[86:89], v[192:195], v[224:227], v[86:89]
	v_mfma_f32_16x16x32_bf16 v[82:85], v[200:203], v[224:227], v[82:85]
	v_mfma_f32_16x16x32_bf16 v[70:73], v[192:195], v[232:235], v[70:73]
	v_mfma_f32_16x16x32_bf16 v[66:69], v[200:203], v[232:235], v[66:69]
	s_barrier
; #define PG8_STAGE(bufoff, gbase, voff) do { _Pragma("unroll") for (int _i = 0; _i < 2; ++_i) \
;         __builtin_amdgcn_global_load_lds((const unsigned*)((const char*)(gbase) + (voff)[_i]), (LAS unsigned*)(lds + (bufoff) + ldsw + _i * 8192), 16, 0, 0); } while (0)
; #define PG8_LDA(dst, b, h) do { _Pragma("unroll") for (int m = 0; m < 4; ++m) _Pragma("unroll") for (int k = 0; k < 2; ++k) dst[m][k] = *(const LAS bf16x8*)(lds + PG8_SA(b, h) + aoff + m * 2048 + k * 1024); } while (0)
; #define PG8_MMA(ai, bj, At, Bt) do { __builtin_amdgcn_s_setprio(1); _Pragma("unroll") for (int m = 0; m < 4; ++m) _Pragma("unroll") for (int n = 0; n < 2; ++n) _Pragma("unroll") for (int k = 0; k < 2; ++k) \
;         acc[ai][bj][m][n] = __builtin_amdgcn_mfma_f32_16x16x32_bf16(Bt[n][k], At[m][k], acc[ai][bj][m][n], 0, 0, 0); __builtin_amdgcn_s_setprio(0); } while (0)
; #define PG8_WAIT_V(n) asm volatile("s_waitcnt vmcnt(" #n ")" ::: "memory")
; #define PG8_WAIT_L(n) asm volatile("s_waitcnt lgkmcnt(" #n ")" ::: "memory")
; #define PG8_BAR __builtin_amdgcn_s_barrier()
; #define PG8_SCHED __builtin_amdgcn_sched_barrier(0)
; template <class Epi, class Sched, bool ABLK = false, bool ALIGN_EPI = true, bool SP2 = true, bool BBLK = true>
; __device__ __forceinline__ void gemm_phase(LAS unsigned char* lds, const Gemm g, const Sched& S, const Epi& E) {
;     ...
;         for (int t = 0; t < nt; t += 2) {
;     ...
;             PG8_LDA(At, 1, 1); PG8_STAGE(PG8_SB(1, 0), b3, voffB); PG8_STAGE(PG8_SB(1, 1), b3 + hstepB, voffB); PG8_STAGE(PG8_SA(1, 0), a3, voffA);
;             PG8_WAIT_V(8); PG8_WAIT_L(0); PG8_BAR; PG8_MMA(1, 0, At, B0); PG8_MMA(1, 1, At, B1); PG8_BAR; PG8_SCHED;
	s_add_u32 s36, s34, 0x8000
	s_addc_u32 s37, s35, 0
	s_add_i32 s55, s60, s39
	v_lshl_add_u64 v[236:237], s[36:37], 0, v[134:135]
	s_mov_b32 m0, s55
	ds_read_b128 v[204:207], v170 offset:49152
	ds_read_b128 v[208:211], v170 offset:50176
	ds_read_b128 v[212:215], v170 offset:51200
	ds_read_b128 v[216:219], v170 offset:52224
	ds_read_b128 v[220:223], v170 offset:53248
	ds_read_b128 v[224:227], v170 offset:54272
	ds_read_b128 v[228:231], v170 offset:55296
	ds_read_b128 v[232:235], v170 offset:56320
	global_load_lds_dwordx4 v[236:237], off
	s_add_i32 m0, s55, 0x2000
	s_add_u32 s34, s34, 0xc000
	v_lshl_add_u64 v[236:237], s[36:37], 0, v[130:131]
	s_addc_u32 s35, s35, 0
	s_add_i32 s36, s61, s39
	global_load_lds_dwordx4 v[236:237], off
	v_lshl_add_u64 v[236:237], s[34:35], 0, v[134:135]
	s_mov_b32 m0, s36
	s_nop 0
	global_load_lds_dwordx4 v[236:237], off
	v_lshl_add_u64 v[236:237], s[34:35], 0, v[130:131]
	s_add_i32 m0, s36, 0x2000
	s_nop 0
	global_load_lds_dwordx4 v[236:237], off
	v_lshl_add_u64 v[236:237], s[30:31], 0, v[136:137]
	s_mov_b32 m0, s45
	s_nop 0
	global_load_lds_dwordx4 v[236:237], off
	v_lshl_add_u64 v[236:237], s[30:31], 0, v[132:133]
	s_mov_b32 m0, s46
	s_nop 0
	global_load_lds_dwordx4 v[236:237], off
	s_waitcnt vmcnt(8)
	s_waitcnt lgkmcnt(0)
	s_barrier
	v_mfma_f32_16x16x32_bf16 v[62:65], v[172:175], v[204:207], v[62:65]
	v_mfma_f32_16x16x32_bf16 v[58:61], v[180:183], v[204:207], v[58:61]
	v_mfma_f32_16x16x32_bf16 v[46:49], v[172:175], v[212:215], v[46:49]
	v_mfma_f32_16x16x32_bf16 v[42:45], v[180:183], v[212:215], v[42:45]
	v_mfma_f32_16x16x32_bf16 v[30:33], v[172:175], v[220:223], v[30:33]
	v_mfma_f32_16x16x32_bf16 v[26:29], v[180:183], v[220:223], v[26:29]
	v_mfma_f32_16x16x32_bf16 v[14:17], v[172:175], v[228:231], v[14:17]
	v_mfma_f32_16x16x32_bf16 v[10:13], v[180:183], v[228:231], v[10:13]
	v_mfma_f32_16x16x32_bf16 v[62:65], v[176:179], v[208:211], v[62:65]
	v_mfma_f32_16x16x32_bf16 v[58:61], v[184:187], v[208:211], v[58:61]
	v_mfma_f32_16x16x32_bf16 v[46:49], v[176:179], v[216:219], v[46:49]
	v_mfma_f32_16x16x32_bf16 v[42:45], v[184:187], v[216:219], v[42:45]
	v_mfma_f32_16x16x32_bf16 v[30:33], v[176:179], v[224:227], v[30:33]
	v_mfma_f32_16x16x32_bf16 v[26:29], v[184:187], v[224:227], v[26:29]
	v_mfma_f32_16x16x32_bf16 v[14:17], v[176:179], v[232:235], v[14:17]
	v_mfma_f32_16x16x32_bf16 v[10:13], v[184:187], v[232:235], v[10:13]
	v_mfma_f32_16x16x32_bf16 v[54:57], v[188:191], v[204:207], v[54:57]
	v_mfma_f32_16x16x32_bf16 v[50:53], v[196:199], v[204:207], v[50:53]
	v_mfma_f32_16x16x32_bf16 v[38:41], v[188:191], v[212:215], v[38:41]
	v_mfma_f32_16x16x32_bf16 v[34:37], v[196:199], v[212:215], v[34:37]
	v_mfma_f32_16x16x32_bf16 v[22:25], v[188:191], v[220:223], v[22:25]
	v_mfma_f32_16x16x32_bf16 v[18:21], v[196:199], v[220:223], v[18:21]
	v_mfma_f32_16x16x32_bf16 v[6:9], v[188:191], v[228:231], v[6:9]
	v_mfma_f32_16x16x32_bf16 v[2:5], v[196:199], v[228:231], v[2:5]
	v_mfma_f32_16x16x32_bf16 v[54:57], v[192:195], v[208:211], v[54:57]
	v_mfma_f32_16x16x32_bf16 v[50:53], v[200:203], v[208:211], v[50:53]
	v_mfma_f32_16x16x32_bf16 v[38:41], v[192:195], v[216:219], v[38:41]
	v_mfma_f32_16x16x32_bf16 v[34:37], v[200:203], v[216:219], v[34:37]
	v_mfma_f32_16x16x32_bf16 v[22:25], v[192:195], v[224:227], v[22:25]
	v_mfma_f32_16x16x32_bf16 v[18:21], v[200:203], v[224:227], v[18:21]
	v_mfma_f32_16x16x32_bf16 v[6:9], v[192:195], v[232:235], v[6:9]
	v_mfma_f32_16x16x32_bf16 v[2:5], v[200:203], v[232:235], v[2:5]
	s_barrier
	s_add_i32 s54, s54, 2
	s_add_u32 s28, s28, 0x100
	s_addc_u32 s29, s29, 0
	s_add_u32 s52, s52, 0x10000
	s_addc_u32 s53, s53, 0
	s_cmp_gt_u32 s54, 29

; __device__ __forceinline__ unsigned pk2(float lo, float hi) { const f32x2 v = {lo, hi}; return __builtin_bit_cast(unsigned, __builtin_convertvector(v, bf16x2_t)); }
; __device__ __forceinline__ u32x4 ror8(u32x4 v) { u32x4 r;
; #pragma unroll
;     for (int i = 0; i < 4; ++i) r[i] = (unsigned)__builtin_amdgcn_mov_dpp((int)v[i], 0x128, 0xf, 0xf, true);
;     return r; }
; __device__ __forceinline__ void store_pair(unsigned char* own, size_t stride8, int hi_off, u32x4 lo, u32x4 hi, bool upper) {
;     const u32x4 tlo = ror8(lo), thi = ror8(hi);
;     const u32x4 A = upper ? thi : lo, B = upper ? hi : tlo;
;     unsigned char* pa = upper ? own - stride8 + hi_off : own;
;     unsigned char* pb = upper ? own + hi_off : own + stride8;
;     *(u32x4*)pa = A; *(u32x4*)pb = B;
; }
;     __device__ __forceinline__ void operator()(const f32x4 (&acc)[2][2][4][2], const Unit& u, int wr, int wc, int fr, int fq) const {
; #pragma unroll
;         for (int ai = 0; ai < 2; ++ai)
; #pragma unroll
;             for (int m = 0; m < 4; ++m) { unsigned char* rowp = (unsigned char*)(H + ((size_t)(u.pm * (FF / 64) + u.pn * 4 + wc) * 256 + (wr * 64 + fr + ai * 128 + m * 16)) * 64 + 8 * fq); u32x4 w[2];
; #pragma unroll
;                 for (int bj = 0; bj < 2; ++bj) { f32x4 v0 = acc[ai][bj][m][0], v1 = acc[ai][bj][m][1];
; #pragma unroll
;                     for (int j = 0; j < 4; ++j) { const float a = fmaxf(v0[j], 0.f), b = fmaxf(v1[j], 0.f); v0[j] = a * a; v1[j] = b * b; }
;                     w[bj].x = pk2(v0[0], v0[1]); w[bj].y = pk2(v0[2], v0[3]); w[bj].z = pk2(v1[0], v1[1]); w[bj].w = pk2(v1[2], v1[3]); }
;                 store_pair(rowp, (size_t)8 * 64 * 2, 64, w[0], w[1], fr >= 8); }
;     }
.LBB0_1845:
	s_lshl_b32 s4, s22, 7
	s_lshl_b32 s5, s24, 2
	s_add_i32 s5, s5, s4
	s_or_b32 s4, s5, s44
	s_ashr_i32 s5, s4, 31
	s_lshl_b64 s[4:5], s[4:5], 15
	s_add_u32 s22, s62, s4
	v_max_f32_e32 v126, 0, v126
	v_max_f32_e32 v122, 0, v122
	v_max_f32_e32 v127, 0, v127
	v_max_f32_e32 v123, 0, v123
	v_max_f32_e32 v128, 0, v128
	v_max_f32_e32 v124, 0, v124
	v_max_f32_e32 v129, 0, v129
	v_max_f32_e32 v125, 0, v125
	v_max_f32_e32 v118, 0, v118
	v_max_f32_e32 v114, 0, v114
	v_max_f32_e32 v119, 0, v119
	v_max_f32_e32 v115, 0, v115
	v_max_f32_e32 v120, 0, v120
	v_max_f32_e32 v116, 0, v116
	v_max_f32_e32 v121, 0, v121
	v_max_f32_e32 v117, 0, v117
	s_addc_u32 s23, s83, s5
	v_pk_mul_f32 v[126:127], v[126:127], v[126:127]
	v_pk_mul_f32 v[122:123], v[122:123], v[122:123]
	v_pk_mul_f32 v[128:129], v[128:129], v[128:129]
	v_pk_mul_f32 v[124:125], v[124:125], v[124:125]
	v_pk_mul_f32 v[118:119], v[118:119], v[118:119]
	v_pk_mul_f32 v[114:115], v[114:115], v[114:115]
	v_pk_mul_f32 v[120:121], v[120:121], v[120:121]
	v_pk_mul_f32 v[116:117], v[116:117], v[116:117]
	v_lshl_add_u64 v[164:165], s[22:23], 0, v[144:145]
	v_cvt_pk_bf16_f32 v126, v126, v127
	v_cvt_pk_bf16_f32 v127, v128, v129
	v_cvt_pk_bf16_f32 v128, v122, v123
	v_cvt_pk_bf16_f32 v129, v124, v125
	v_cvt_pk_bf16_f32 v118, v118, v119
	v_cvt_pk_bf16_f32 v119, v120, v121
	v_cvt_pk_bf16_f32 v114, v114, v115
	v_cvt_pk_bf16_f32 v115, v116, v117
	v_lshl_add_u64 v[122:123], v[164:165], 0, v[138:139]
	v_mov_b32_dpp v120, v126 row_ror:8 row_mask:0xf bank_mask:0xf bound_ctrl:1
	v_mov_b32_dpp v121, v127 row_ror:8 row_mask:0xf bank_mask:0xf bound_ctrl:1
	v_mov_b32_dpp v116, v128 row_ror:8 row_mask:0xf bank_mask:0xf bound_ctrl:1
	v_mov_b32_dpp v117, v129 row_ror:8 row_mask:0xf bank_mask:0xf bound_ctrl:1
	v_mov_b32_dpp v164, v118 row_ror:8 row_mask:0xf bank_mask:0xf bound_ctrl:1
	v_mov_b32_dpp v165, v119 row_ror:8 row_mask:0xf bank_mask:0xf bound_ctrl:1
	v_mov_b32_dpp v166, v114 row_ror:8 row_mask:0xf bank_mask:0xf bound_ctrl:1
	v_mov_b32_dpp v167, v115 row_ror:8 row_mask:0xf bank_mask:0xf bound_ctrl:1
	v_max_f32_e32 v110, 0, v110
	v_max_f32_e32 v106, 0, v106
	v_max_f32_e32 v111, 0, v111
	v_max_f32_e32 v107, 0, v107
	v_max_f32_e32 v112, 0, v112
	v_max_f32_e32 v108, 0, v108
	v_max_f32_e32 v113, 0, v113
	v_max_f32_e32 v109, 0, v109
	v_max_f32_e32 v102, 0, v102
	v_max_f32_e32 v98, 0, v98
	v_max_f32_e32 v103, 0, v103
	v_max_f32_e32 v99, 0, v99
	v_max_f32_e32 v104, 0, v104
	v_max_f32_e32 v100, 0, v100
	v_max_f32_e32 v105, 0, v105
	v_max_f32_e32 v101, 0, v101
	v_lshl_add_u64 v[124:125], v[122:123], 0, v[140:141]
	v_cndmask_b32_e64 v117, v117, v115, s[8:9]
	v_cndmask_b32_e64 v116, v116, v114, s[8:9]
	v_cndmask_b32_e64 v115, v121, v119, s[8:9]
	v_cndmask_b32_e64 v114, v120, v118, s[8:9]
	v_cndmask_b32_e64 v121, v129, v167, s[8:9]
	v_cndmask_b32_e64 v120, v128, v166, s[8:9]
	v_cndmask_b32_e64 v119, v127, v165, s[8:9]
	v_cndmask_b32_e64 v118, v126, v164, s[8:9]
	v_pk_mul_f32 v[110:111], v[110:111], v[110:111]
	v_pk_mul_f32 v[106:107], v[106:107], v[106:107]
	v_pk_mul_f32 v[112:113], v[112:113], v[112:113]
	v_pk_mul_f32 v[108:109], v[108:109], v[108:109]
	v_pk_mul_f32 v[102:103], v[102:103], v[102:103]
	v_pk_mul_f32 v[98:99], v[98:99], v[98:99]
	v_pk_mul_f32 v[104:105], v[104:105], v[104:105]
	v_pk_mul_f32 v[100:101], v[100:101], v[100:101]
	v_lshl_add_u64 v[122:123], v[122:123], 0, v[142:143]
	global_store_dwordx4 v[124:125], v[118:121], off
	global_store_dwordx4 v[122:123], v[114:117], off
	v_cvt_pk_bf16_f32 v110, v110, v111
	v_cvt_pk_bf16_f32 v111, v112, v113
	v_lshl_add_u64 v[114:115], s[22:23], 0, v[146:147]
	v_cvt_pk_bf16_f32 v112, v106, v107
	v_cvt_pk_bf16_f32 v113, v108, v109
	v_cvt_pk_bf16_f32 v102, v102, v103
	v_cvt_pk_bf16_f32 v103, v104, v105
	v_cvt_pk_bf16_f32 v98, v98, v99
	v_cvt_pk_bf16_f32 v99, v100, v101
	v_lshl_add_u64 v[106:107], v[114:115], 0, v[138:139]
	v_mov_b32_dpp v104, v110 row_ror:8 row_mask:0xf bank_mask:0xf bound_ctrl:1
	v_mov_b32_dpp v105, v111 row_ror:8 row_mask:0xf bank_mask:0xf bound_ctrl:1
	v_mov_b32_dpp v100, v112 row_ror:8 row_mask:0xf bank_mask:0xf bound_ctrl:1
	v_mov_b32_dpp v101, v113 row_ror:8 row_mask:0xf bank_mask:0xf bound_ctrl:1
	v_mov_b32_dpp v114, v102 row_ror:8 row_mask:0xf bank_mask:0xf bound_ctrl:1
	v_mov_b32_dpp v115, v103 row_ror:8 row_mask:0xf bank_mask:0xf bound_ctrl:1
	v_mov_b32_dpp v116, v98 row_ror:8 row_mask:0xf bank_mask:0xf bound_ctrl:1
	v_mov_b32_dpp v117, v99 row_ror:8 row_mask:0xf bank_mask:0xf bound_ctrl:1
	v_max_f32_e32 v94, 0, v94
	v_max_f32_e32 v90, 0, v90
	v_max_f32_e32 v95, 0, v95
	v_max_f32_e32 v91, 0, v91
	v_max_f32_e32 v96, 0, v96
	v_max_f32_e32 v92, 0, v92
	v_max_f32_e32 v97, 0, v97
	v_max_f32_e32 v93, 0, v93
	v_max_f32_e32 v86, 0, v86
	v_max_f32_e32 v82, 0, v82
	v_max_f32_e32 v87, 0, v87
	v_max_f32_e32 v83, 0, v83
	v_max_f32_e32 v88, 0, v88
	v_max_f32_e32 v84, 0, v84
	v_max_f32_e32 v89, 0, v89
	v_max_f32_e32 v85, 0, v85
	v_lshl_add_u64 v[108:109], v[106:107], 0, v[140:141]
	v_cndmask_b32_e64 v101, v101, v99, s[8:9]
	v_cndmask_b32_e64 v100, v100, v98, s[8:9]
	v_cndmask_b32_e64 v99, v105, v103, s[8:9]
	v_cndmask_b32_e64 v98, v104, v102, s[8:9]
	v_cndmask_b32_e64 v105, v113, v117, s[8:9]
	v_cndmask_b32_e64 v104, v112, v116, s[8:9]
	v_cndmask_b32_e64 v103, v111, v115, s[8:9]
	v_cndmask_b32_e64 v102, v110, v114, s[8:9]
	v_pk_mul_f32 v[94:95], v[94:95], v[94:95]
	v_pk_mul_f32 v[90:91], v[90:91], v[90:91]
	v_pk_mul_f32 v[96:97], v[96:97], v[96:97]
	v_pk_mul_f32 v[92:93], v[92:93], v[92:93]
	v_pk_mul_f32 v[86:87], v[86:87], v[86:87]
	v_pk_mul_f32 v[82:83], v[82:83], v[82:83]
	v_pk_mul_f32 v[88:89], v[88:89], v[88:89]
	v_pk_mul_f32 v[84:85], v[84:85], v[84:85]
; __device__ __forceinline__ unsigned pk2(float lo, float hi) { const f32x2 v = {lo, hi}; return __builtin_bit_cast(unsigned, __builtin_convertvector(v, bf16x2_t)); }
; __device__ __forceinline__ u32x4 ror8(u32x4 v) { u32x4 r;
; #pragma unroll
;     for (int i = 0; i < 4; ++i) r[i] = (unsigned)__builtin_amdgcn_mov_dpp((int)v[i], 0x128, 0xf, 0xf, true);
;     return r; }
; __device__ __forceinline__ void store_pair(unsigned char* own, size_t stride8, int hi_off, u32x4 lo, u32x4 hi, bool upper) {
;     const u32x4 tlo = ror8(lo), thi = ror8(hi);
;     const u32x4 A = upper ? thi : lo, B = upper ? hi : tlo;
;     unsigned char* pa = upper ? own - stride8 + hi_off : own;
;     unsigned char* pb = upper ? own + hi_off : own + stride8;
;     *(u32x4*)pa = A; *(u32x4*)pb = B;
; }
;     __device__ __forceinline__ void operator()(const f32x4 (&acc)[2][2][4][2], const Unit& u, int wr, int wc, int fr, int fq) const {
; #pragma unroll
;         for (int ai = 0; ai < 2; ++ai)
; #pragma unroll
;             for (int m = 0; m < 4; ++m) { unsigned char* rowp = (unsigned char*)(H + ((size_t)(u.pm * (FF / 64) + u.pn * 4 + wc) * 256 + (wr * 64 + fr + ai * 128 + m * 16)) * 64 + 8 * fq); u32x4 w[2];
; #pragma unroll
;                 for (int bj = 0; bj < 2; ++bj) { f32x4 v0 = acc[ai][bj][m][0], v1 = acc[ai][bj][m][1];
; #pragma unroll
;                     for (int j = 0; j < 4; ++j) { const float a = fmaxf(v0[j], 0.f), b = fmaxf(v1[j], 0.f); v0[j] = a * a; v1[j] = b * b; }
;                     w[bj].x = pk2(v0[0], v0[1]); w[bj].y = pk2(v0[2], v0[3]); w[bj].z = pk2(v1[0], v1[1]); w[bj].w = pk2(v1[2], v1[3]); }
;                 store_pair(rowp, (size_t)8 * 64 * 2, 64, w[0], w[1], fr >= 8); }
;     }
	v_lshl_add_u64 v[106:107], v[106:107], 0, v[142:143]
	global_store_dwordx4 v[108:109], v[102:105], off
	global_store_dwordx4 v[106:107], v[98:101], off
	v_cvt_pk_bf16_f32 v94, v94, v95
	v_cvt_pk_bf16_f32 v95, v96, v97
	v_lshl_add_u64 v[98:99], s[22:23], 0, v[148:149]
	v_cvt_pk_bf16_f32 v96, v90, v91
	v_cvt_pk_bf16_f32 v97, v92, v93
	v_cvt_pk_bf16_f32 v86, v86, v87
	v_cvt_pk_bf16_f32 v87, v88, v89
	v_cvt_pk_bf16_f32 v82, v82, v83
	v_cvt_pk_bf16_f32 v83, v84, v85
	v_lshl_add_u64 v[90:91], v[98:99], 0, v[138:139]
	v_mov_b32_dpp v88, v94 row_ror:8 row_mask:0xf bank_mask:0xf bound_ctrl:1
	v_mov_b32_dpp v89, v95 row_ror:8 row_mask:0xf bank_mask:0xf bound_ctrl:1
	v_mov_b32_dpp v84, v96 row_ror:8 row_mask:0xf bank_mask:0xf bound_ctrl:1
	v_mov_b32_dpp v85, v97 row_ror:8 row_mask:0xf bank_mask:0xf bound_ctrl:1
	v_mov_b32_dpp v98, v86 row_ror:8 row_mask:0xf bank_mask:0xf bound_ctrl:1
	v_mov_b32_dpp v99, v87 row_ror:8 row_mask:0xf bank_mask:0xf bound_ctrl:1
	v_mov_b32_dpp v100, v82 row_ror:8 row_mask:0xf bank_mask:0xf bound_ctrl:1
	v_mov_b32_dpp v101, v83 row_ror:8 row_mask:0xf bank_mask:0xf bound_ctrl:1
	v_max_f32_e32 v78, 0, v78
	v_max_f32_e32 v74, 0, v74
	v_max_f32_e32 v79, 0, v79
	v_max_f32_e32 v75, 0, v75
	v_max_f32_e32 v80, 0, v80
	v_max_f32_e32 v76, 0, v76
	v_max_f32_e32 v81, 0, v81
	v_max_f32_e32 v77, 0, v77
	v_max_f32_e32 v70, 0, v70
	v_max_f32_e32 v66, 0, v66
	v_max_f32_e32 v71, 0, v71
	v_max_f32_e32 v67, 0, v67
	v_max_f32_e32 v72, 0, v72
	v_max_f32_e32 v68, 0, v68
	v_max_f32_e32 v73, 0, v73
	v_max_f32_e32 v69, 0, v69
	v_lshl_add_u64 v[92:93], v[90:91], 0, v[140:141]
	v_cndmask_b32_e64 v85, v85, v83, s[8:9]
	v_cndmask_b32_e64 v84, v84, v82, s[8:9]
	v_cndmask_b32_e64 v83, v89, v87, s[8:9]
	v_cndmask_b32_e64 v82, v88, v86, s[8:9]
	v_cndmask_b32_e64 v89, v97, v101, s[8:9]
	v_cndmask_b32_e64 v88, v96, v100, s[8:9]
	v_cndmask_b32_e64 v87, v95, v99, s[8:9]
	v_cndmask_b32_e64 v86, v94, v98, s[8:9]
	v_pk_mul_f32 v[78:79], v[78:79], v[78:79]
	v_pk_mul_f32 v[74:75], v[74:75], v[74:75]
	v_pk_mul_f32 v[80:81], v[80:81], v[80:81]
	v_pk_mul_f32 v[76:77], v[76:77], v[76:77]
	v_pk_mul_f32 v[70:71], v[70:71], v[70:71]
	v_pk_mul_f32 v[66:67], v[66:67], v[66:67]
	v_pk_mul_f32 v[72:73], v[72:73], v[72:73]
	v_pk_mul_f32 v[68:69], v[68:69], v[68:69]
	v_lshl_add_u64 v[90:91], v[90:91], 0, v[142:143]
	global_store_dwordx4 v[92:93], v[86:89], off
	global_store_dwordx4 v[90:91], v[82:85], off
	v_cvt_pk_bf16_f32 v78, v78, v79
	v_cvt_pk_bf16_f32 v79, v80, v81
	v_lshl_add_u64 v[82:83], s[22:23], 0, v[150:151]
	v_cvt_pk_bf16_f32 v80, v74, v75
	v_cvt_pk_bf16_f32 v81, v76, v77
	v_cvt_pk_bf16_f32 v70, v70, v71
	v_cvt_pk_bf16_f32 v71, v72, v73
	v_cvt_pk_bf16_f32 v66, v66, v67
	v_cvt_pk_bf16_f32 v67, v68, v69
	v_lshl_add_u64 v[74:75], v[82:83], 0, v[138:139]
	v_mov_b32_dpp v72, v78 row_ror:8 row_mask:0xf bank_mask:0xf bound_ctrl:1
	v_mov_b32_dpp v73, v79 row_ror:8 row_mask:0xf bank_mask:0xf bound_ctrl:1
	v_mov_b32_dpp v68, v80 row_ror:8 row_mask:0xf bank_mask:0xf bound_ctrl:1
	v_mov_b32_dpp v69, v81 row_ror:8 row_mask:0xf bank_mask:0xf bound_ctrl:1
	v_mov_b32_dpp v82, v70 row_ror:8 row_mask:0xf bank_mask:0xf bound_ctrl:1
	v_mov_b32_dpp v83, v71 row_ror:8 row_mask:0xf bank_mask:0xf bound_ctrl:1
	v_mov_b32_dpp v84, v66 row_ror:8 row_mask:0xf bank_mask:0xf bound_ctrl:1
	v_mov_b32_dpp v85, v67 row_ror:8 row_mask:0xf bank_mask:0xf bound_ctrl:1
	v_max_f32_e32 v62, 0, v62
	v_max_f32_e32 v58, 0, v58
	v_max_f32_e32 v63, 0, v63
	v_max_f32_e32 v59, 0, v59
	v_max_f32_e32 v64, 0, v64
	v_max_f32_e32 v60, 0, v60
	v_max_f32_e32 v65, 0, v65
	v_max_f32_e32 v61, 0, v61
	v_max_f32_e32 v54, 0, v54
	v_max_f32_e32 v50, 0, v50
	v_max_f32_e32 v55, 0, v55
	v_max_f32_e32 v51, 0, v51
	v_max_f32_e32 v56, 0, v56
	v_max_f32_e32 v52, 0, v52
	v_max_f32_e32 v57, 0, v57
	v_max_f32_e32 v53, 0, v53
	v_lshl_add_u64 v[76:77], v[74:75], 0, v[140:141]
	v_cndmask_b32_e64 v69, v69, v67, s[8:9]
	v_cndmask_b32_e64 v68, v68, v66, s[8:9]
	v_cndmask_b32_e64 v67, v73, v71, s[8:9]
	v_cndmask_b32_e64 v66, v72, v70, s[8:9]
	v_cndmask_b32_e64 v73, v81, v85, s[8:9]
	v_cndmask_b32_e64 v72, v80, v84, s[8:9]
	v_cndmask_b32_e64 v71, v79, v83, s[8:9]
	v_cndmask_b32_e64 v70, v78, v82, s[8:9]
	v_pk_mul_f32 v[62:63], v[62:63], v[62:63]
	v_pk_mul_f32 v[58:59], v[58:59], v[58:59]
	v_pk_mul_f32 v[64:65], v[64:65], v[64:65]
	v_pk_mul_f32 v[60:61], v[60:61], v[60:61]
	v_pk_mul_f32 v[54:55], v[54:55], v[54:55]
	v_pk_mul_f32 v[50:51], v[50:51], v[50:51]
	v_pk_mul_f32 v[56:57], v[56:57], v[56:57]
	v_pk_mul_f32 v[52:53], v[52:53], v[52:53]
	v_lshl_add_u64 v[74:75], v[74:75], 0, v[142:143]
	global_store_dwordx4 v[76:77], v[70:73], off
	global_store_dwordx4 v[74:75], v[66:69], off
	v_cvt_pk_bf16_f32 v62, v62, v63
	v_cvt_pk_bf16_f32 v63, v64, v65
	v_lshl_add_u64 v[66:67], s[22:23], 0, v[152:153]
	v_cvt_pk_bf16_f32 v64, v58, v59
	v_cvt_pk_bf16_f32 v65, v60, v61
	v_cvt_pk_bf16_f32 v54, v54, v55
	v_cvt_pk_bf16_f32 v55, v56, v57
	v_cvt_pk_bf16_f32 v50, v50, v51
	v_cvt_pk_bf16_f32 v51, v52, v53
	v_lshl_add_u64 v[58:59], v[66:67], 0, v[138:139]
	v_mov_b32_dpp v56, v62 row_ror:8 row_mask:0xf bank_mask:0xf bound_ctrl:1
	v_mov_b32_dpp v57, v63 row_ror:8 row_mask:0xf bank_mask:0xf bound_ctrl:1
	v_mov_b32_dpp v52, v64 row_ror:8 row_mask:0xf bank_mask:0xf bound_ctrl:1
	v_mov_b32_dpp v53, v65 row_ror:8 row_mask:0xf bank_mask:0xf bound_ctrl:1
	v_mov_b32_dpp v66, v54 row_ror:8 row_mask:0xf bank_mask:0xf bound_ctrl:1
	v_mov_b32_dpp v67, v55 row_ror:8 row_mask:0xf bank_mask:0xf bound_ctrl:1
	v_mov_b32_dpp v68, v50 row_ror:8 row_mask:0xf bank_mask:0xf bound_ctrl:1
	v_mov_b32_dpp v69, v51 row_ror:8 row_mask:0xf bank_mask:0xf bound_ctrl:1
	v_max_f32_e32 v46, 0, v46
; __device__ __forceinline__ unsigned pk2(float lo, float hi) { const f32x2 v = {lo, hi}; return __builtin_bit_cast(unsigned, __builtin_convertvector(v, bf16x2_t)); }
; __device__ __forceinline__ u32x4 ror8(u32x4 v) { u32x4 r;
; #pragma unroll
;     for (int i = 0; i < 4; ++i) r[i] = (unsigned)__builtin_amdgcn_mov_dpp((int)v[i], 0x128, 0xf, 0xf, true);
;     return r; }
; __device__ __forceinline__ void store_pair(unsigned char* own, size_t stride8, int hi_off, u32x4 lo, u32x4 hi, bool upper) {
;     const u32x4 tlo = ror8(lo), thi = ror8(hi);
;     const u32x4 A = upper ? thi : lo, B = upper ? hi : tlo;
;     unsigned char* pa = upper ? own - stride8 + hi_off : own;
;     unsigned char* pb = upper ? own + hi_off : own + stride8;
;     *(u32x4*)pa = A; *(u32x4*)pb = B;
; }
;     __device__ __forceinline__ void operator()(const f32x4 (&acc)[2][2][4][2], const Unit& u, int wr, int wc, int fr, int fq) const {
; #pragma unroll
;         for (int ai = 0; ai < 2; ++ai)
; #pragma unroll
;             for (int m = 0; m < 4; ++m) { unsigned char* rowp = (unsigned char*)(H + ((size_t)(u.pm * (FF / 64) + u.pn * 4 + wc) * 256 + (wr * 64 + fr + ai * 128 + m * 16)) * 64 + 8 * fq); u32x4 w[2];
; #pragma unroll
;                 for (int bj = 0; bj < 2; ++bj) { f32x4 v0 = acc[ai][bj][m][0], v1 = acc[ai][bj][m][1];
; #pragma unroll
;                     for (int j = 0; j < 4; ++j) { const float a = fmaxf(v0[j], 0.f), b = fmaxf(v1[j], 0.f); v0[j] = a * a; v1[j] = b * b; }
;                     w[bj].x = pk2(v0[0], v0[1]); w[bj].y = pk2(v0[2], v0[3]); w[bj].z = pk2(v1[0], v1[1]); w[bj].w = pk2(v1[2], v1[3]); }
;                 store_pair(rowp, (size_t)8 * 64 * 2, 64, w[0], w[1], fr >= 8); }
;     }
	v_max_f32_e32 v42, 0, v42
	v_max_f32_e32 v47, 0, v47
	v_max_f32_e32 v43, 0, v43
	v_max_f32_e32 v48, 0, v48
	v_max_f32_e32 v44, 0, v44
	v_max_f32_e32 v49, 0, v49
	v_max_f32_e32 v45, 0, v45
	v_max_f32_e32 v38, 0, v38
	v_max_f32_e32 v34, 0, v34
	v_max_f32_e32 v39, 0, v39
	v_max_f32_e32 v35, 0, v35
	v_max_f32_e32 v40, 0, v40
	v_max_f32_e32 v36, 0, v36
	v_max_f32_e32 v41, 0, v41
	v_max_f32_e32 v37, 0, v37
	v_lshl_add_u64 v[60:61], v[58:59], 0, v[140:141]
	v_cndmask_b32_e64 v53, v53, v51, s[8:9]
	v_cndmask_b32_e64 v52, v52, v50, s[8:9]
	v_cndmask_b32_e64 v51, v57, v55, s[8:9]
	v_cndmask_b32_e64 v50, v56, v54, s[8:9]
	v_cndmask_b32_e64 v57, v65, v69, s[8:9]
	v_cndmask_b32_e64 v56, v64, v68, s[8:9]
	v_cndmask_b32_e64 v55, v63, v67, s[8:9]
	v_cndmask_b32_e64 v54, v62, v66, s[8:9]
	v_pk_mul_f32 v[46:47], v[46:47], v[46:47]
	v_pk_mul_f32 v[42:43], v[42:43], v[42:43]
	v_pk_mul_f32 v[48:49], v[48:49], v[48:49]
	v_pk_mul_f32 v[44:45], v[44:45], v[44:45]
	v_pk_mul_f32 v[38:39], v[38:39], v[38:39]
	v_pk_mul_f32 v[34:35], v[34:35], v[34:35]
	v_pk_mul_f32 v[40:41], v[40:41], v[40:41]
	v_pk_mul_f32 v[36:37], v[36:37], v[36:37]
	v_lshl_add_u64 v[58:59], v[58:59], 0, v[142:143]
	global_store_dwordx4 v[60:61], v[54:57], off
	global_store_dwordx4 v[58:59], v[50:53], off
	v_cvt_pk_bf16_f32 v46, v46, v47
	v_cvt_pk_bf16_f32 v47, v48, v49
	v_lshl_add_u64 v[50:51], s[22:23], 0, v[154:155]
	v_cvt_pk_bf16_f32 v48, v42, v43
	v_cvt_pk_bf16_f32 v49, v44, v45
	v_cvt_pk_bf16_f32 v38, v38, v39
	v_cvt_pk_bf16_f32 v39, v40, v41
	v_cvt_pk_bf16_f32 v34, v34, v35
	v_cvt_pk_bf16_f32 v35, v36, v37
	v_lshl_add_u64 v[42:43], v[50:51], 0, v[138:139]
	v_mov_b32_dpp v40, v46 row_ror:8 row_mask:0xf bank_mask:0xf bound_ctrl:1
	v_mov_b32_dpp v41, v47 row_ror:8 row_mask:0xf bank_mask:0xf bound_ctrl:1
	v_mov_b32_dpp v36, v48 row_ror:8 row_mask:0xf bank_mask:0xf bound_ctrl:1
	v_mov_b32_dpp v37, v49 row_ror:8 row_mask:0xf bank_mask:0xf bound_ctrl:1
	v_mov_b32_dpp v50, v38 row_ror:8 row_mask:0xf bank_mask:0xf bound_ctrl:1
	v_mov_b32_dpp v51, v39 row_ror:8 row_mask:0xf bank_mask:0xf bound_ctrl:1
	v_mov_b32_dpp v52, v34 row_ror:8 row_mask:0xf bank_mask:0xf bound_ctrl:1
	v_mov_b32_dpp v53, v35 row_ror:8 row_mask:0xf bank_mask:0xf bound_ctrl:1
	v_max_f32_e32 v30, 0, v30
	v_max_f32_e32 v26, 0, v26
	v_max_f32_e32 v31, 0, v31
	v_max_f32_e32 v27, 0, v27
	v_max_f32_e32 v32, 0, v32
	v_max_f32_e32 v28, 0, v28
	v_max_f32_e32 v33, 0, v33
	v_max_f32_e32 v29, 0, v29
	v_max_f32_e32 v22, 0, v22
	v_max_f32_e32 v18, 0, v18
	v_max_f32_e32 v23, 0, v23
	v_max_f32_e32 v19, 0, v19
	v_max_f32_e32 v24, 0, v24
	v_max_f32_e32 v20, 0, v20
	v_max_f32_e32 v25, 0, v25
	v_max_f32_e32 v21, 0, v21
	v_lshl_add_u64 v[44:45], v[42:43], 0, v[140:141]
	v_cndmask_b32_e64 v37, v37, v35, s[8:9]
	v_cndmask_b32_e64 v36, v36, v34, s[8:9]
	v_cndmask_b32_e64 v35, v41, v39, s[8:9]
	v_cndmask_b32_e64 v34, v40, v38, s[8:9]
	v_cndmask_b32_e64 v41, v49, v53, s[8:9]
	v_cndmask_b32_e64 v40, v48, v52, s[8:9]
	v_cndmask_b32_e64 v39, v47, v51, s[8:9]
	v_cndmask_b32_e64 v38, v46, v50, s[8:9]
	v_pk_mul_f32 v[30:31], v[30:31], v[30:31]
	v_pk_mul_f32 v[26:27], v[26:27], v[26:27]
	v_pk_mul_f32 v[32:33], v[32:33], v[32:33]
	v_pk_mul_f32 v[28:29], v[28:29], v[28:29]
	v_pk_mul_f32 v[22:23], v[22:23], v[22:23]
	v_pk_mul_f32 v[18:19], v[18:19], v[18:19]
	v_pk_mul_f32 v[24:25], v[24:25], v[24:25]
	v_pk_mul_f32 v[20:21], v[20:21], v[20:21]
	v_lshl_add_u64 v[42:43], v[42:43], 0, v[142:143]
	global_store_dwordx4 v[44:45], v[38:41], off
	global_store_dwordx4 v[42:43], v[34:37], off
	v_cvt_pk_bf16_f32 v30, v30, v31
	v_cvt_pk_bf16_f32 v31, v32, v33
	v_lshl_add_u64 v[34:35], s[22:23], 0, v[156:157]
	v_cvt_pk_bf16_f32 v32, v26, v27
; __device__ __forceinline__ unsigned pk2(float lo, float hi) { const f32x2 v = {lo, hi}; return __builtin_bit_cast(unsigned, __builtin_convertvector(v, bf16x2_t)); }
; template <class Epi, class Sched, bool ABLK = false, bool ALIGN_EPI = true, bool SP2 = true, bool BBLK = true>
; __device__ __forceinline__ void gemm_phase(LAS unsigned char* lds, const Gemm g, const Sched& S, const Epi& E) {
;     ...
;         if (!has_next) break;
; #pragma unroll
;         for (int a = 0; a < 2; ++a)
; #pragma unroll
;             for (int b = 0; b < 2; ++b)
; #pragma unroll
;                 for (int m = 0; m < 4; ++m)
; #pragma unroll
;                     for (int n = 0; n < 2; ++n) acc[a][b][m][n] = (f32x4){0.f, 0.f, 0.f, 0.f};
;         cur = nxt; uA = nuA; tbA = ntbA; cB = nB; ++ui;
;         if constexpr (ALIGN_EPI) { if (wr == 1) PG8_BAR; }
; __device__ __forceinline__ u32x4 ror8(u32x4 v) { u32x4 r;
; #pragma unroll
;     for (int i = 0; i < 4; ++i) r[i] = (unsigned)__builtin_amdgcn_mov_dpp((int)v[i], 0x128, 0xf, 0xf, true);
;     return r; }
; __device__ __forceinline__ void store_pair(unsigned char* own, size_t stride8, int hi_off, u32x4 lo, u32x4 hi, bool upper) {
;     const u32x4 tlo = ror8(lo), thi = ror8(hi);
;     const u32x4 A = upper ? thi : lo, B = upper ? hi : tlo;
;     unsigned char* pa = upper ? own - stride8 + hi_off : own;
;     unsigned char* pb = upper ? own + hi_off : own + stride8;
;     *(u32x4*)pa = A; *(u32x4*)pb = B;
; }
;     __device__ __forceinline__ void operator()(const f32x4 (&acc)[2][2][4][2], const Unit& u, int wr, int wc, int fr, int fq) const {
; #pragma unroll
;         for (int ai = 0; ai < 2; ++ai)
; #pragma unroll
;             for (int m = 0; m < 4; ++m) { unsigned char* rowp = (unsigned char*)(H + ((size_t)(u.pm * (FF / 64) + u.pn * 4 + wc) * 256 + (wr * 64 + fr + ai * 128 + m * 16)) * 64 + 8 * fq); u32x4 w[2];
; #pragma unroll
;                 for (int bj = 0; bj < 2; ++bj) { f32x4 v0 = acc[ai][bj][m][0], v1 = acc[ai][bj][m][1];
; #pragma unroll
;                     for (int j = 0; j < 4; ++j) { const float a = fmaxf(v0[j], 0.f), b = fmaxf(v1[j], 0.f); v0[j] = a * a; v1[j] = b * b; }
;                     w[bj].x = pk2(v0[0], v0[1]); w[bj].y = pk2(v0[2], v0[3]); w[bj].z = pk2(v1[0], v1[1]); w[bj].w = pk2(v1[2], v1[3]); }
;                 store_pair(rowp, (size_t)8 * 64 * 2, 64, w[0], w[1], fr >= 8); }
;     }
	v_cvt_pk_bf16_f32 v33, v28, v29
	v_cvt_pk_bf16_f32 v22, v22, v23
	v_cvt_pk_bf16_f32 v23, v24, v25
	v_cvt_pk_bf16_f32 v18, v18, v19
	v_cvt_pk_bf16_f32 v19, v20, v21
	v_lshl_add_u64 v[26:27], v[34:35], 0, v[138:139]
	v_mov_b32_dpp v24, v30 row_ror:8 row_mask:0xf bank_mask:0xf bound_ctrl:1
	v_mov_b32_dpp v25, v31 row_ror:8 row_mask:0xf bank_mask:0xf bound_ctrl:1
	v_mov_b32_dpp v20, v32 row_ror:8 row_mask:0xf bank_mask:0xf bound_ctrl:1
	v_mov_b32_dpp v21, v33 row_ror:8 row_mask:0xf bank_mask:0xf bound_ctrl:1
	v_mov_b32_dpp v34, v22 row_ror:8 row_mask:0xf bank_mask:0xf bound_ctrl:1
	v_mov_b32_dpp v35, v23 row_ror:8 row_mask:0xf bank_mask:0xf bound_ctrl:1
	v_mov_b32_dpp v36, v18 row_ror:8 row_mask:0xf bank_mask:0xf bound_ctrl:1
	v_mov_b32_dpp v37, v19 row_ror:8 row_mask:0xf bank_mask:0xf bound_ctrl:1
	v_max_f32_e32 v14, 0, v14
	v_max_f32_e32 v10, 0, v10
	v_max_f32_e32 v15, 0, v15
	v_max_f32_e32 v11, 0, v11
	v_max_f32_e32 v16, 0, v16
	v_max_f32_e32 v12, 0, v12
	v_max_f32_e32 v17, 0, v17
	v_max_f32_e32 v13, 0, v13
	v_max_f32_e32 v6, 0, v6
	v_max_f32_e32 v2, 0, v2
	v_max_f32_e32 v7, 0, v7
	v_max_f32_e32 v3, 0, v3
	v_max_f32_e32 v8, 0, v8
	v_max_f32_e32 v4, 0, v4
	v_max_f32_e32 v9, 0, v9
	v_max_f32_e32 v5, 0, v5
	v_lshl_add_u64 v[28:29], v[26:27], 0, v[140:141]
	v_cndmask_b32_e64 v21, v21, v19, s[8:9]
	v_cndmask_b32_e64 v20, v20, v18, s[8:9]
	v_cndmask_b32_e64 v19, v25, v23, s[8:9]
	v_cndmask_b32_e64 v18, v24, v22, s[8:9]
	v_cndmask_b32_e64 v25, v33, v37, s[8:9]
	v_cndmask_b32_e64 v24, v32, v36, s[8:9]
	v_cndmask_b32_e64 v23, v31, v35, s[8:9]
	v_cndmask_b32_e64 v22, v30, v34, s[8:9]
	v_pk_mul_f32 v[14:15], v[14:15], v[14:15]
	v_pk_mul_f32 v[10:11], v[10:11], v[10:11]
	v_pk_mul_f32 v[16:17], v[16:17], v[16:17]
	v_pk_mul_f32 v[12:13], v[12:13], v[12:13]
	v_pk_mul_f32 v[6:7], v[6:7], v[6:7]
	v_pk_mul_f32 v[2:3], v[2:3], v[2:3]
	v_pk_mul_f32 v[8:9], v[8:9], v[8:9]
	v_pk_mul_f32 v[4:5], v[4:5], v[4:5]
	v_lshl_add_u64 v[26:27], v[26:27], 0, v[142:143]
	global_store_dwordx4 v[28:29], v[22:25], off
	global_store_dwordx4 v[26:27], v[18:21], off
	v_cvt_pk_bf16_f32 v14, v14, v15
	v_cvt_pk_bf16_f32 v15, v16, v17
	v_lshl_add_u64 v[18:19], s[22:23], 0, v[158:159]
	v_cvt_pk_bf16_f32 v16, v10, v11
	v_cvt_pk_bf16_f32 v17, v12, v13
	v_cvt_pk_bf16_f32 v6, v6, v7
	v_cvt_pk_bf16_f32 v7, v8, v9
	v_cvt_pk_bf16_f32 v2, v2, v3
	v_cvt_pk_bf16_f32 v3, v4, v5
	v_lshl_add_u64 v[10:11], v[18:19], 0, v[138:139]
	v_mov_b32_dpp v8, v14 row_ror:8 row_mask:0xf bank_mask:0xf bound_ctrl:1
	v_mov_b32_dpp v9, v15 row_ror:8 row_mask:0xf bank_mask:0xf bound_ctrl:1
	v_mov_b32_dpp v4, v16 row_ror:8 row_mask:0xf bank_mask:0xf bound_ctrl:1
	v_mov_b32_dpp v5, v17 row_ror:8 row_mask:0xf bank_mask:0xf bound_ctrl:1
	v_mov_b32_dpp v18, v6 row_ror:8 row_mask:0xf bank_mask:0xf bound_ctrl:1
	v_mov_b32_dpp v19, v7 row_ror:8 row_mask:0xf bank_mask:0xf bound_ctrl:1
	v_mov_b32_dpp v20, v2 row_ror:8 row_mask:0xf bank_mask:0xf bound_ctrl:1
	v_mov_b32_dpp v21, v3 row_ror:8 row_mask:0xf bank_mask:0xf bound_ctrl:1
	v_lshl_add_u64 v[12:13], v[10:11], 0, v[140:141]
	v_cndmask_b32_e64 v5, v5, v3, s[8:9]
	v_cndmask_b32_e64 v4, v4, v2, s[8:9]
	v_cndmask_b32_e64 v3, v9, v7, s[8:9]
	v_cndmask_b32_e64 v2, v8, v6, s[8:9]
	v_cndmask_b32_e64 v9, v17, v21, s[8:9]
	v_cndmask_b32_e64 v8, v16, v20, s[8:9]
	v_cndmask_b32_e64 v7, v15, v19, s[8:9]
	v_cndmask_b32_e64 v6, v14, v18, s[8:9]
	s_andn2_b64 vcc, exec, s[18:19]
	s_mov_b64 s[4:5], -1
	v_lshl_add_u64 v[10:11], v[10:11], 0, v[142:143]
	global_store_dwordx4 v[12:13], v[6:9], off
	global_store_dwordx4 v[10:11], v[2:5], off
	s_cbranch_vccnz .LBB0_1838
	s_andn2_b64 vcc, exec, s[2:3]
	s_cbranch_vccnz .LBB0_1837
	s_barrier
	s_branch .LBB0_1837

; #define PG8_STAGE(bufoff, gbase, voff) do { _Pragma("unroll") for (int _i = 0; _i < 2; ++_i) \
;         __builtin_amdgcn_global_load_lds((const unsigned*)((const char*)(gbase) + (voff)[_i]), (LAS unsigned*)(lds + (bufoff) + ldsw + _i * 8192), 16, 0, 0); } while (0)
; #define PG8_LDA(dst, b, h) do { _Pragma("unroll") for (int m = 0; m < 4; ++m) _Pragma("unroll") for (int k = 0; k < 2; ++k) dst[m][k] = *(const LAS bf16x8*)(lds + PG8_SA(b, h) + aoff + m * 2048 + k * 1024); } while (0)
; #define PG8_LDB(dst, b, h) do { _Pragma("unroll") for (int n = 0; n < 2; ++n) _Pragma("unroll") for (int k = 0; k < 2; ++k) dst[n][k] = *(const LAS bf16x8*)(lds + PG8_SB(b, h) + boff + n * 2048 + k * 1024); } while (0)
; #define PG8_WAIT_V(n) asm volatile("s_waitcnt vmcnt(" #n ")" ::: "memory")
; #define PG8_WAIT_L(n) asm volatile("s_waitcnt lgkmcnt(" #n ")" ::: "memory")
; template <class Epi, class Sched, bool ABLK = false, bool ALIGN_EPI = true, bool SP2 = true, bool BBLK = true>
; __device__ __forceinline__ void gemm_phase(LAS unsigned char* lds, const Gemm g, const Sched& S, const Epi& E) {
;     ...
;         const bool has_next = S.next(ui + 1, nxt);
;         const int nt = cur.nt;
;         const char* nuA = has_next ? a_unit(nxt) : uA; const int ntbA = has_next ? nxt.k0 / BK : tbA; const char* nB = has_next ? (const char*)g.Bt + (size_t)nxt.pn * tstepB + b_k0(nxt.k0) : cB;
;         for (int t = 0; t < nt; t += 2) {
;             const bool last = (t == nt - 2);
;             const char* a1 = a_tile(uA, tbA + t + 1);
;             const char* a2 = last ? a_tile(nuA, ntbA) : a_tile(uA, tbA + t + 2); const char* b2 = last ? nB : cB + (size_t)(t + 2) * kstepB;
;             const char* a3 = last ? a_tile(nuA, ntbA + 1) : a_tile(uA, tbA + t + 3); const char* b3 = b2 + kstepB;
;             if (last && has_next) S.a_ready(nxt);
;             if constexpr (SP2) {
;             PG8_LDB(B0, 0, 0); PG8_LDB(B1, 0, 1); PG8_SCHED; PG8_LDA(At, 0, 0); PG8_STAGE(PG8_SA(1, 1), a1 + hstepA, voffA);
;             PG8_WAIT_V(8); PG8_WAIT_L(0); PG8_BAR; PG8_MMA(0, 0, At, B0); PG8_MMA(0, 1, At, B1); PG8_BAR; PG8_SCHED;
;             PG8_LDA(At, 0, 1); PG8_STAGE(PG8_SB(0, 0), b2, voffB); PG8_STAGE(PG8_SB(0, 1), b2 + hstepB, voffB); PG8_STAGE(PG8_SA(0, 0), a2, voffA);
;             PG8_WAIT_V(8); PG8_WAIT_L(0); PG8_BAR; PG8_MMA(1, 0, At, B0); PG8_MMA(1, 1, At, B1); PG8_BAR; PG8_SCHED;
.LBB0_1906:
	s_ashr_i32 s81, s80, 31
	s_andn2_b64 vcc, exec, s[4:5]
	s_lshl_b64 s[24:25], s[80:81], 22
	s_add_u32 s24, s62, s24
	s_addc_u32 s25, s83, s25
	s_and_b64 s[26:27], s[4:5], exec
	s_cselect_b32 s37, s25, s35
	s_cselect_b32 s50, s24, s34
	s_ashr_i32 s26, s0, 31
	s_lshr_b32 s26, s26, 26
	s_add_i32 s26, s0, s26
	s_ashr_i32 s26, s26, 6
	s_and_b64 s[28:29], s[4:5], exec
	s_cselect_b32 s38, s26, s36
	s_ashr_i32 s79, s78, 31
	s_lshl_b64 s[28:29], s[78:79], 22
	s_add_u32 s39, s1, s28
	s_addc_u32 s51, s33, s29
	s_ashr_i32 s27, s26, 31
	s_lshl_b64 s[28:29], s[26:27], 15
	s_add_u32 s28, s39, s28
	s_addc_u32 s29, s51, s29
	v_cndmask_b32_e64 v2, 0, 1, s[4:5]
	s_and_b64 s[4:5], s[4:5], exec
	s_cselect_b32 s4, s29, s31
	s_cselect_b32 s5, s28, s30
	s_ashr_i32 s39, s38, 31
	s_lshl_b64 s[38:39], s[38:39], 15
	s_add_u32 s27, s50, s38
	s_addc_u32 s50, s37, s39
	s_add_u32 s51, s27, 0x8000
	s_addc_u32 s52, s50, 0
	s_add_u32 s53, s30, 0x10000
	s_addc_u32 s54, s31, 0
	s_ashr_i32 s37, s36, 31
	v_cmp_ne_u32_e64 s[10:11], 1, v2
	s_lshl_b64 s[30:31], s[36:37], 15
	v_lshl_add_u64 v[2:3], s[34:35], 0, v[138:139]
	s_add_u32 s55, s34, s30
	v_lshl_add_u64 v[142:143], v[2:3], 0, s[30:31]
	v_lshl_add_u64 v[2:3], s[34:35], 0, v[140:141]
	s_addc_u32 s56, s35, s31
	v_lshl_add_u64 v[144:145], v[2:3], 0, s[30:31]
	s_lshl_b32 s30, s48, 15
	s_add_i32 s30, s30, 0xfff00000
	v_mov_b32_e32 v2, 0
	s_add_u32 s57, s30, 0xf0000
	s_mov_b32 s58, 0
	s_mov_b64 s[30:31], 0
	ds_read_b128 v[152:155], v148
	ds_read_b128 v[156:159], v148 offset:1024
	ds_read_b128 v[160:163], v148 offset:2048
	ds_read_b128 v[164:167], v148 offset:3072
	ds_read_b128 v[168:171], v149
	ds_read_b128 v[172:175], v149 offset:1024
	ds_read_b128 v[176:179], v149 offset:2048
	ds_read_b128 v[180:183], v149 offset:3072
	s_add_u32 s34, s55, s30
	s_addc_u32 s35, s56, s31
	s_add_u32 s38, s34, 0x10000
	s_addc_u32 s39, s35, 0
	s_add_i32 s58, s58, 2
	s_add_u32 s36, s53, s30
	s_addc_u32 s37, s54, s31
	s_add_u32 s34, s34, 0x18000
	s_addc_u32 s35, s35, 0
	s_cmp_eq_u32 s57, s30
	s_cselect_b32 s35, s52, s35
	s_cselect_b32 s34, s51, s34
	s_cselect_b32 s37, s4, s37
	s_cselect_b32 s36, s5, s36
	s_cselect_b32 s39, s50, s39
	s_cselect_b32 s38, s27, s38
	v_lshl_add_u64 v[216:217], v[142:143], 0, s[30:31]
	s_add_i32 m0, s41, 0xc000
	ds_read_b128 v[184:187], v150
	ds_read_b128 v[188:191], v150 offset:1024
	ds_read_b128 v[192:195], v150 offset:2048
	ds_read_b128 v[196:199], v150 offset:3072
	ds_read_b128 v[200:203], v150 offset:4096
	ds_read_b128 v[204:207], v150 offset:5120
	ds_read_b128 v[208:211], v150 offset:6144
	ds_read_b128 v[212:215], v150 offset:7168
	global_load_lds_dwordx4 v[216:217], off
	v_lshl_add_u64 v[216:217], v[144:145], 0, s[30:31]
	s_add_i32 m0, s41, 0xe000
	s_nop 0
	global_load_lds_dwordx4 v[216:217], off
	s_waitcnt vmcnt(8)
	s_waitcnt lgkmcnt(0)
	s_barrier
	v_mfma_f32_16x16x32_bf16 v[126:129], v[152:155], v[184:187], 0
	v_mfma_f32_16x16x32_bf16 v[122:125], v[160:163], v[184:187], 0
	v_mfma_f32_16x16x32_bf16 v[110:113], v[152:155], v[192:195], 0
	v_mfma_f32_16x16x32_bf16 v[106:109], v[160:163], v[192:195], 0
	v_mfma_f32_16x16x32_bf16 v[94:97], v[152:155], v[200:203], 0
	v_mfma_f32_16x16x32_bf16 v[90:93], v[160:163], v[200:203], 0
	v_mfma_f32_16x16x32_bf16 v[78:81], v[152:155], v[208:211], 0
	v_mfma_f32_16x16x32_bf16 v[74:77], v[160:163], v[208:211], 0
	v_mfma_f32_16x16x32_bf16 v[126:129], v[156:159], v[188:191], v[126:129]
	v_mfma_f32_16x16x32_bf16 v[122:125], v[164:167], v[188:191], v[122:125]
	v_mfma_f32_16x16x32_bf16 v[110:113], v[156:159], v[196:199], v[110:113]
	v_mfma_f32_16x16x32_bf16 v[106:109], v[164:167], v[196:199], v[106:109]
	v_mfma_f32_16x16x32_bf16 v[94:97], v[156:159], v[204:207], v[94:97]
	v_mfma_f32_16x16x32_bf16 v[90:93], v[164:167], v[204:207], v[90:93]
	v_mfma_f32_16x16x32_bf16 v[78:81], v[156:159], v[212:215], v[78:81]
	v_mfma_f32_16x16x32_bf16 v[74:77], v[164:167], v[212:215], v[74:77]
	v_mfma_f32_16x16x32_bf16 v[118:121], v[168:171], v[184:187], 0
	v_mfma_f32_16x16x32_bf16 v[114:117], v[176:179], v[184:187], 0
	v_mfma_f32_16x16x32_bf16 v[102:105], v[168:171], v[192:195], 0
	v_mfma_f32_16x16x32_bf16 v[98:101], v[176:179], v[192:195], 0
	v_mfma_f32_16x16x32_bf16 v[86:89], v[168:171], v[200:203], 0
	v_mfma_f32_16x16x32_bf16 v[82:85], v[176:179], v[200:203], 0
	v_mfma_f32_16x16x32_bf16 v[70:73], v[168:171], v[208:211], 0
	v_mfma_f32_16x16x32_bf16 v[66:69], v[176:179], v[208:211], 0
	v_mfma_f32_16x16x32_bf16 v[118:121], v[172:175], v[188:191], v[118:121]
	v_mfma_f32_16x16x32_bf16 v[114:117], v[180:183], v[188:191], v[114:117]
	v_mfma_f32_16x16x32_bf16 v[102:105], v[172:175], v[196:199], v[102:105]
	v_mfma_f32_16x16x32_bf16 v[98:101], v[180:183], v[196:199], v[98:101]
	v_mfma_f32_16x16x32_bf16 v[86:89], v[172:175], v[204:207], v[86:89]
	v_mfma_f32_16x16x32_bf16 v[82:85], v[180:183], v[204:207], v[82:85]
	v_mfma_f32_16x16x32_bf16 v[70:73], v[172:175], v[212:215], v[70:73]
	v_mfma_f32_16x16x32_bf16 v[66:69], v[180:183], v[212:215], v[66:69]
	s_barrier
	s_add_i32 s59, s72, s40
	v_lshl_add_u64 v[216:217], s[36:37], 0, v[130:131]
	s_mov_b32 m0, s59
	ds_read_b128 v[184:187], v150 offset:16384
	ds_read_b128 v[188:191], v150 offset:17408
	ds_read_b128 v[192:195], v150 offset:18432
	ds_read_b128 v[196:199], v150 offset:19456
	ds_read_b128 v[200:203], v150 offset:20480
	ds_read_b128 v[204:207], v150 offset:21504
	ds_read_b128 v[208:211], v150 offset:22528
	ds_read_b128 v[212:215], v150 offset:23552
	global_load_lds_dwordx4 v[216:217], off
	s_add_i32 m0, s59, 0x2000
	s_add_u32 s64, s36, 0x4000
	v_lshl_add_u64 v[216:217], s[36:37], 0, v[132:133]
	s_addc_u32 s65, s37, 0
	s_add_i32 s59, s73, s40
	global_load_lds_dwordx4 v[216:217], off
	v_lshl_add_u64 v[216:217], s[64:65], 0, v[130:131]
	s_mov_b32 m0, s59
	s_nop 0
	global_load_lds_dwordx4 v[216:217], off
	v_lshl_add_u64 v[216:217], s[64:65], 0, v[132:133]
	s_add_i32 m0, s59, 0x2000
	s_nop 0
	global_load_lds_dwordx4 v[216:217], off
	v_lshl_add_u64 v[216:217], s[38:39], 0, v[130:131]
	s_mov_b32 m0, s41
	s_nop 0
	global_load_lds_dwordx4 v[216:217], off
	v_lshl_add_u64 v[216:217], s[38:39], 0, v[132:133]
	s_mov_b32 m0, s42
	s_nop 0
	global_load_lds_dwordx4 v[216:217], off
	s_waitcnt vmcnt(8)
	s_waitcnt lgkmcnt(0)
	s_barrier
; #define PG8_STAGE(bufoff, gbase, voff) do { _Pragma("unroll") for (int _i = 0; _i < 2; ++_i) \
;         __builtin_amdgcn_global_load_lds((const unsigned*)((const char*)(gbase) + (voff)[_i]), (LAS unsigned*)(lds + (bufoff) + ldsw + _i * 8192), 16, 0, 0); } while (0)
; #define PG8_LDA(dst, b, h) do { _Pragma("unroll") for (int m = 0; m < 4; ++m) _Pragma("unroll") for (int k = 0; k < 2; ++k) dst[m][k] = *(const LAS bf16x8*)(lds + PG8_SA(b, h) + aoff + m * 2048 + k * 1024); } while (0)
; #define PG8_LDB(dst, b, h) do { _Pragma("unroll") for (int n = 0; n < 2; ++n) _Pragma("unroll") for (int k = 0; k < 2; ++k) dst[n][k] = *(const LAS bf16x8*)(lds + PG8_SB(b, h) + boff + n * 2048 + k * 1024); } while (0)
; #define PG8_MMA(ai, bj, At, Bt) do { __builtin_amdgcn_s_setprio(1); _Pragma("unroll") for (int m = 0; m < 4; ++m) _Pragma("unroll") for (int n = 0; n < 2; ++n) _Pragma("unroll") for (int k = 0; k < 2; ++k) \
;         acc[ai][bj][m][n] = __builtin_amdgcn_mfma_f32_16x16x32_bf16(Bt[n][k], At[m][k], acc[ai][bj][m][n], 0, 0, 0); __builtin_amdgcn_s_setprio(0); } while (0)
; #define PG8_WAIT_V(n) asm volatile("s_waitcnt vmcnt(" #n ")" ::: "memory")
; #define PG8_WAIT_L(n) asm volatile("s_waitcnt lgkmcnt(" #n ")" ::: "memory")
; #define PG8_BAR __builtin_amdgcn_s_barrier()
; #define PG8_SCHED __builtin_amdgcn_sched_barrier(0)
; template <class Epi, class Sched, bool ABLK = false, bool ALIGN_EPI = true, bool SP2 = true, bool BBLK = true>
; __device__ __forceinline__ void gemm_phase(LAS unsigned char* lds, const Gemm g, const Sched& S, const Epi& E) {
;     ...
;             PG8_LDA(At, 0, 1); PG8_STAGE(PG8_SB(0, 0), b2, voffB); PG8_STAGE(PG8_SB(0, 1), b2 + hstepB, voffB); PG8_STAGE(PG8_SA(0, 0), a2, voffA);
;             PG8_WAIT_V(8); PG8_WAIT_L(0); PG8_BAR; PG8_MMA(1, 0, At, B0); PG8_MMA(1, 1, At, B1); PG8_BAR; PG8_SCHED;
;             PG8_LDB(B0, 1, 0); PG8_LDB(B1, 1, 1); PG8_SCHED; PG8_LDA(At, 1, 0); PG8_STAGE(PG8_SA(0, 1), a2 + hstepA, voffA);
;             PG8_WAIT_V(8); PG8_WAIT_L(0); PG8_BAR; PG8_MMA(0, 0, At, B0); PG8_MMA(0, 1, At, B1); PG8_BAR; PG8_SCHED;
	v_mfma_f32_16x16x32_bf16 v[62:65], v[152:155], v[184:187], 0
	v_mfma_f32_16x16x32_bf16 v[58:61], v[160:163], v[184:187], 0
	v_mfma_f32_16x16x32_bf16 v[46:49], v[152:155], v[192:195], 0
	v_mfma_f32_16x16x32_bf16 v[42:45], v[160:163], v[192:195], 0
	v_mfma_f32_16x16x32_bf16 v[30:33], v[152:155], v[200:203], 0
	v_mfma_f32_16x16x32_bf16 v[26:29], v[160:163], v[200:203], 0
	v_mfma_f32_16x16x32_bf16 v[14:17], v[152:155], v[208:211], 0
	v_mfma_f32_16x16x32_bf16 v[10:13], v[160:163], v[208:211], 0
	v_mfma_f32_16x16x32_bf16 v[62:65], v[156:159], v[188:191], v[62:65]
	v_mfma_f32_16x16x32_bf16 v[58:61], v[164:167], v[188:191], v[58:61]
	v_mfma_f32_16x16x32_bf16 v[46:49], v[156:159], v[196:199], v[46:49]
	v_mfma_f32_16x16x32_bf16 v[42:45], v[164:167], v[196:199], v[42:45]
	v_mfma_f32_16x16x32_bf16 v[30:33], v[156:159], v[204:207], v[30:33]
	v_mfma_f32_16x16x32_bf16 v[26:29], v[164:167], v[204:207], v[26:29]
	v_mfma_f32_16x16x32_bf16 v[14:17], v[156:159], v[212:215], v[14:17]
	v_mfma_f32_16x16x32_bf16 v[10:13], v[164:167], v[212:215], v[10:13]
	v_mfma_f32_16x16x32_bf16 v[54:57], v[168:171], v[184:187], 0
	v_mfma_f32_16x16x32_bf16 v[50:53], v[176:179], v[184:187], 0
	v_mfma_f32_16x16x32_bf16 v[38:41], v[168:171], v[192:195], 0
	v_mfma_f32_16x16x32_bf16 v[34:37], v[176:179], v[192:195], 0
	v_mfma_f32_16x16x32_bf16 v[22:25], v[168:171], v[200:203], 0
	v_mfma_f32_16x16x32_bf16 v[18:21], v[176:179], v[200:203], 0
	v_mfma_f32_16x16x32_bf16 v[6:9], v[168:171], v[208:211], 0
	v_mfma_f32_16x16x32_bf16 v[2:5], v[176:179], v[208:211], 0
	v_mfma_f32_16x16x32_bf16 v[54:57], v[172:175], v[188:191], v[54:57]
	v_mfma_f32_16x16x32_bf16 v[50:53], v[180:183], v[188:191], v[50:53]
	v_mfma_f32_16x16x32_bf16 v[38:41], v[172:175], v[196:199], v[38:41]
	v_mfma_f32_16x16x32_bf16 v[34:37], v[180:183], v[196:199], v[34:37]
	v_mfma_f32_16x16x32_bf16 v[22:25], v[172:175], v[204:207], v[22:25]
	v_mfma_f32_16x16x32_bf16 v[18:21], v[180:183], v[204:207], v[18:21]
	v_mfma_f32_16x16x32_bf16 v[6:9], v[172:175], v[212:215], v[6:9]
	v_mfma_f32_16x16x32_bf16 v[2:5], v[180:183], v[212:215], v[2:5]
	s_barrier
	v_add_u32_e32 v151, s60, v146
	ds_read_b128 v[152:155], v151
	ds_read_b128 v[156:159], v151 offset:1024
	ds_read_b128 v[160:163], v151 offset:2048
	ds_read_b128 v[164:167], v151 offset:3072
	v_add_u32_e32 v151, s61, v146
	ds_read_b128 v[168:171], v151
	ds_read_b128 v[172:175], v151 offset:1024
	ds_read_b128 v[176:179], v151 offset:2048
	ds_read_b128 v[180:183], v151 offset:3072
	s_add_u32 s38, s38, 0x4000
	s_addc_u32 s39, s39, 0
	s_mov_b32 m0, s43
	v_lshl_add_u64 v[216:217], s[38:39], 0, v[130:131]
	ds_read_b128 v[184:187], v150 offset:32768
	ds_read_b128 v[188:191], v150 offset:33792
	ds_read_b128 v[192:195], v150 offset:34816
	ds_read_b128 v[196:199], v150 offset:35840
	ds_read_b128 v[200:203], v150 offset:36864
	ds_read_b128 v[204:207], v150 offset:37888
	ds_read_b128 v[208:211], v150 offset:38912
	ds_read_b128 v[212:215], v150 offset:39936
	global_load_lds_dwordx4 v[216:217], off
	v_lshl_add_u64 v[216:217], s[38:39], 0, v[132:133]
	s_mov_b32 m0, s44
	s_nop 0
	global_load_lds_dwordx4 v[216:217], off
	s_waitcnt vmcnt(8)
	s_waitcnt lgkmcnt(0)
	s_barrier
	v_mfma_f32_16x16x32_bf16 v[126:129], v[152:155], v[184:187], v[126:129]
	v_mfma_f32_16x16x32_bf16 v[122:125], v[160:163], v[184:187], v[122:125]
	v_mfma_f32_16x16x32_bf16 v[110:113], v[152:155], v[192:195], v[110:113]
	v_mfma_f32_16x16x32_bf16 v[106:109], v[160:163], v[192:195], v[106:109]
	v_mfma_f32_16x16x32_bf16 v[94:97], v[152:155], v[200:203], v[94:97]
	v_mfma_f32_16x16x32_bf16 v[90:93], v[160:163], v[200:203], v[90:93]
	v_mfma_f32_16x16x32_bf16 v[78:81], v[152:155], v[208:211], v[78:81]
	v_mfma_f32_16x16x32_bf16 v[74:77], v[160:163], v[208:211], v[74:77]
	v_mfma_f32_16x16x32_bf16 v[126:129], v[156:159], v[188:191], v[126:129]
	v_mfma_f32_16x16x32_bf16 v[122:125], v[164:167], v[188:191], v[122:125]
	v_mfma_f32_16x16x32_bf16 v[110:113], v[156:159], v[196:199], v[110:113]
	v_mfma_f32_16x16x32_bf16 v[106:109], v[164:167], v[196:199], v[106:109]
	v_mfma_f32_16x16x32_bf16 v[94:97], v[156:159], v[204:207], v[94:97]
	v_mfma_f32_16x16x32_bf16 v[90:93], v[164:167], v[204:207], v[90:93]
	v_mfma_f32_16x16x32_bf16 v[78:81], v[156:159], v[212:215], v[78:81]
	v_mfma_f32_16x16x32_bf16 v[74:77], v[164:167], v[212:215], v[74:77]
	v_mfma_f32_16x16x32_bf16 v[118:121], v[168:171], v[184:187], v[118:121]
	v_mfma_f32_16x16x32_bf16 v[114:117], v[176:179], v[184:187], v[114:117]
	v_mfma_f32_16x16x32_bf16 v[102:105], v[168:171], v[192:195], v[102:105]
	v_mfma_f32_16x16x32_bf16 v[98:101], v[176:179], v[192:195], v[98:101]
	v_mfma_f32_16x16x32_bf16 v[86:89], v[168:171], v[200:203], v[86:89]
	v_mfma_f32_16x16x32_bf16 v[82:85], v[176:179], v[200:203], v[82:85]
	v_mfma_f32_16x16x32_bf16 v[70:73], v[168:171], v[208:211], v[70:73]
	v_mfma_f32_16x16x32_bf16 v[66:69], v[176:179], v[208:211], v[66:69]
	v_mfma_f32_16x16x32_bf16 v[118:121], v[172:175], v[188:191], v[118:121]
	v_mfma_f32_16x16x32_bf16 v[114:117], v[180:183], v[188:191], v[114:117]
	v_mfma_f32_16x16x32_bf16 v[102:105], v[172:175], v[196:199], v[102:105]
	v_mfma_f32_16x16x32_bf16 v[98:101], v[180:183], v[196:199], v[98:101]
	v_mfma_f32_16x16x32_bf16 v[86:89], v[172:175], v[204:207], v[86:89]
	v_mfma_f32_16x16x32_bf16 v[82:85], v[180:183], v[204:207], v[82:85]
	v_mfma_f32_16x16x32_bf16 v[70:73], v[172:175], v[212:215], v[70:73]
	v_mfma_f32_16x16x32_bf16 v[66:69], v[180:183], v[212:215], v[66:69]
	s_barrier
; #define PG8_STAGE(bufoff, gbase, voff) do { _Pragma("unroll") for (int _i = 0; _i < 2; ++_i) \
;         __builtin_amdgcn_global_load_lds((const unsigned*)((const char*)(gbase) + (voff)[_i]), (LAS unsigned*)(lds + (bufoff) + ldsw + _i * 8192), 16, 0, 0); } while (0)
; #define PG8_LDA(dst, b, h) do { _Pragma("unroll") for (int m = 0; m < 4; ++m) _Pragma("unroll") for (int k = 0; k < 2; ++k) dst[m][k] = *(const LAS bf16x8*)(lds + PG8_SA(b, h) + aoff + m * 2048 + k * 1024); } while (0)
; #define PG8_MMA(ai, bj, At, Bt) do { __builtin_amdgcn_s_setprio(1); _Pragma("unroll") for (int m = 0; m < 4; ++m) _Pragma("unroll") for (int n = 0; n < 2; ++n) _Pragma("unroll") for (int k = 0; k < 2; ++k) \
;         acc[ai][bj][m][n] = __builtin_amdgcn_mfma_f32_16x16x32_bf16(Bt[n][k], At[m][k], acc[ai][bj][m][n], 0, 0, 0); __builtin_amdgcn_s_setprio(0); } while (0)
; #define PG8_WAIT_V(n) asm volatile("s_waitcnt vmcnt(" #n ")" ::: "memory")
; #define PG8_WAIT_L(n) asm volatile("s_waitcnt lgkmcnt(" #n ")" ::: "memory")
; #define PG8_BAR __builtin_amdgcn_s_barrier()
; #define PG8_SCHED __builtin_amdgcn_sched_barrier(0)
; template <class Epi, class Sched, bool ABLK = false, bool ALIGN_EPI = true, bool SP2 = true, bool BBLK = true>
; __device__ __forceinline__ void gemm_phase(LAS unsigned char* lds, const Gemm g, const Sched& S, const Epi& E) {
;     ...
;         for (int t = 0; t < nt; t += 2) {
;     ...
;             PG8_LDA(At, 1, 1); PG8_STAGE(PG8_SB(1, 0), b3, voffB); PG8_STAGE(PG8_SB(1, 1), b3 + hstepB, voffB); PG8_STAGE(PG8_SA(1, 0), a3, voffA);
;             PG8_WAIT_V(8); PG8_WAIT_L(0); PG8_BAR; PG8_MMA(1, 0, At, B0); PG8_MMA(1, 1, At, B1); PG8_BAR; PG8_SCHED;
	s_add_u32 s38, s36, 0x8000
	s_addc_u32 s39, s37, 0
	s_add_i32 s59, s60, s40
	v_lshl_add_u64 v[216:217], s[38:39], 0, v[130:131]
	s_mov_b32 m0, s59
	ds_read_b128 v[184:187], v150 offset:49152
	ds_read_b128 v[188:191], v150 offset:50176
	ds_read_b128 v[192:195], v150 offset:51200
	ds_read_b128 v[196:199], v150 offset:52224
	ds_read_b128 v[200:203], v150 offset:53248
	ds_read_b128 v[204:207], v150 offset:54272
	ds_read_b128 v[208:211], v150 offset:55296
	ds_read_b128 v[212:215], v150 offset:56320
	global_load_lds_dwordx4 v[216:217], off
	s_add_i32 m0, s59, 0x2000
	s_add_u32 s36, s36, 0xc000
	v_lshl_add_u64 v[216:217], s[38:39], 0, v[132:133]
	s_addc_u32 s37, s37, 0
	s_add_i32 s38, s61, s40
	global_load_lds_dwordx4 v[216:217], off
	v_lshl_add_u64 v[216:217], s[36:37], 0, v[130:131]
	s_mov_b32 m0, s38
	s_nop 0
	global_load_lds_dwordx4 v[216:217], off
	v_lshl_add_u64 v[216:217], s[36:37], 0, v[132:133]
	s_add_i32 m0, s38, 0x2000
	s_nop 0
	global_load_lds_dwordx4 v[216:217], off
	v_lshl_add_u64 v[216:217], s[34:35], 0, v[130:131]
	s_mov_b32 m0, s45
	s_nop 0
	global_load_lds_dwordx4 v[216:217], off
	v_lshl_add_u64 v[216:217], s[34:35], 0, v[132:133]
	s_mov_b32 m0, s46
	s_nop 0
	global_load_lds_dwordx4 v[216:217], off
	s_waitcnt vmcnt(8)
	s_waitcnt lgkmcnt(0)
	s_barrier
	v_mfma_f32_16x16x32_bf16 v[62:65], v[152:155], v[184:187], v[62:65]
	v_mfma_f32_16x16x32_bf16 v[58:61], v[160:163], v[184:187], v[58:61]
	v_mfma_f32_16x16x32_bf16 v[46:49], v[152:155], v[192:195], v[46:49]
	v_mfma_f32_16x16x32_bf16 v[42:45], v[160:163], v[192:195], v[42:45]
	v_mfma_f32_16x16x32_bf16 v[30:33], v[152:155], v[200:203], v[30:33]
	v_mfma_f32_16x16x32_bf16 v[26:29], v[160:163], v[200:203], v[26:29]
	v_mfma_f32_16x16x32_bf16 v[14:17], v[152:155], v[208:211], v[14:17]
	v_mfma_f32_16x16x32_bf16 v[10:13], v[160:163], v[208:211], v[10:13]
	v_mfma_f32_16x16x32_bf16 v[62:65], v[156:159], v[188:191], v[62:65]
	v_mfma_f32_16x16x32_bf16 v[58:61], v[164:167], v[188:191], v[58:61]
	v_mfma_f32_16x16x32_bf16 v[46:49], v[156:159], v[196:199], v[46:49]
	v_mfma_f32_16x16x32_bf16 v[42:45], v[164:167], v[196:199], v[42:45]
	v_mfma_f32_16x16x32_bf16 v[30:33], v[156:159], v[204:207], v[30:33]
	v_mfma_f32_16x16x32_bf16 v[26:29], v[164:167], v[204:207], v[26:29]
	v_mfma_f32_16x16x32_bf16 v[14:17], v[156:159], v[212:215], v[14:17]
	v_mfma_f32_16x16x32_bf16 v[10:13], v[164:167], v[212:215], v[10:13]
	v_mfma_f32_16x16x32_bf16 v[54:57], v[168:171], v[184:187], v[54:57]
	v_mfma_f32_16x16x32_bf16 v[50:53], v[176:179], v[184:187], v[50:53]
	v_mfma_f32_16x16x32_bf16 v[38:41], v[168:171], v[192:195], v[38:41]
	v_mfma_f32_16x16x32_bf16 v[34:37], v[176:179], v[192:195], v[34:37]
	v_mfma_f32_16x16x32_bf16 v[22:25], v[168:171], v[200:203], v[22:25]
	v_mfma_f32_16x16x32_bf16 v[18:21], v[176:179], v[200:203], v[18:21]
	v_mfma_f32_16x16x32_bf16 v[6:9], v[168:171], v[208:211], v[6:9]
	v_mfma_f32_16x16x32_bf16 v[2:5], v[176:179], v[208:211], v[2:5]
	v_mfma_f32_16x16x32_bf16 v[54:57], v[172:175], v[188:191], v[54:57]
	v_mfma_f32_16x16x32_bf16 v[50:53], v[180:183], v[188:191], v[50:53]
	v_mfma_f32_16x16x32_bf16 v[38:41], v[172:175], v[196:199], v[38:41]
	v_mfma_f32_16x16x32_bf16 v[34:37], v[180:183], v[196:199], v[34:37]
	v_mfma_f32_16x16x32_bf16 v[22:25], v[172:175], v[204:207], v[22:25]
	v_mfma_f32_16x16x32_bf16 v[18:21], v[180:183], v[204:207], v[18:21]
	v_mfma_f32_16x16x32_bf16 v[6:9], v[172:175], v[212:215], v[6:9]
	v_mfma_f32_16x16x32_bf16 v[2:5], v[180:183], v[212:215], v[2:5]
	s_barrier
	s_add_u32 s30, s30, 0x10000
	s_addc_u32 s31, s31, 0
	s_cmp_ge_u32 s58, s48

.LBB0_2137:
	s_ashr_i32 s11, s10, 31
	s_lshl_b64 s[4:5], s[10:11], 20
	s_add_u32 s14, s37, s4
	s_addc_u32 s15, s38, s5
	s_and_b64 s[4:5], s[16:17], exec
	s_cselect_b32 s4, s15, s25
	s_cselect_b32 s5, s14, s24
	s_ashr_i32 s13, s12, 31
	s_lshl_b64 s[18:19], s[12:13], 20
	s_add_u32 s18, s1, s18
	s_addc_u32 s19, s33, s19
	s_and_b64 s[28:29], s[16:17], exec
	s_cselect_b32 s11, s19, s27
	s_cselect_b32 s13, s18, s26
	s_add_u32 s48, s5, 0x80
	s_addc_u32 s49, s4, 0
	s_add_u32 s50, s26, 0x10000
	v_mov_b32_e32 v2, 0
	s_addc_u32 s51, s27, 0
	v_lshl_add_u64 v[142:143], s[24:25], 0, v[138:139]
	v_lshl_add_u64 v[144:145], s[24:25], 0, v[140:141]
	s_mov_b32 s52, -2
	s_mov_b64 s[26:27], 0
	ds_read_b128 v[152:155], v148
	ds_read_b128 v[156:159], v148 offset:1024
	ds_read_b128 v[160:163], v148 offset:2048
	ds_read_b128 v[164:167], v148 offset:3072
	ds_read_b128 v[168:171], v149
	ds_read_b128 v[172:175], v149 offset:1024
	ds_read_b128 v[176:179], v149 offset:2048
	ds_read_b128 v[180:183], v149 offset:3072
	s_add_u32 s28, s24, s26
	s_addc_u32 s29, s25, s27
	s_add_u32 s34, s28, 0x100
	s_addc_u32 s35, s29, 0
	s_add_u32 s28, s28, 0x180
	s_addc_u32 s29, s29, 0
	s_cmpk_eq_i32 s26, 0xf00
	s_cselect_b32 s29, s49, s29
	s_cselect_b32 s28, s48, s28
	s_cselect_b32 s31, s11, s51
	s_cselect_b32 s30, s13, s50
	s_cselect_b32 s35, s4, s35
	s_cselect_b32 s34, s5, s34
	s_mov_b32 m0, s47
	v_lshl_add_u64 v[216:217], v[142:143], 0, s[26:27]
	ds_read_b128 v[184:187], v150
	ds_read_b128 v[188:191], v150 offset:1024
	ds_read_b128 v[192:195], v150 offset:2048
	ds_read_b128 v[196:199], v150 offset:3072
	ds_read_b128 v[200:203], v150 offset:4096
	ds_read_b128 v[204:207], v150 offset:5120
	ds_read_b128 v[208:211], v150 offset:6144
	ds_read_b128 v[212:215], v150 offset:7168
	global_load_lds_dwordx4 v[216:217], off
	v_lshl_add_u64 v[216:217], v[144:145], 0, s[26:27]
	s_add_i32 m0, s21, 0xe000
	s_nop 0
	global_load_lds_dwordx4 v[216:217], off
	s_waitcnt vmcnt(8)
	s_waitcnt lgkmcnt(0)
	s_barrier
	v_mfma_f32_16x16x32_bf16 v[122:125], v[152:155], v[184:187], 0
	v_mfma_f32_16x16x32_bf16 v[118:121], v[160:163], v[184:187], 0
	v_mfma_f32_16x16x32_bf16 v[106:109], v[152:155], v[192:195], 0
	v_mfma_f32_16x16x32_bf16 v[102:105], v[160:163], v[192:195], 0
	v_mfma_f32_16x16x32_bf16 v[90:93], v[152:155], v[200:203], 0
	v_mfma_f32_16x16x32_bf16 v[86:89], v[160:163], v[200:203], 0
	v_mfma_f32_16x16x32_bf16 v[74:77], v[152:155], v[208:211], 0
	v_mfma_f32_16x16x32_bf16 v[70:73], v[160:163], v[208:211], 0
	v_mfma_f32_16x16x32_bf16 v[122:125], v[156:159], v[188:191], v[122:125]
	v_mfma_f32_16x16x32_bf16 v[118:121], v[164:167], v[188:191], v[118:121]
	v_mfma_f32_16x16x32_bf16 v[106:109], v[156:159], v[196:199], v[106:109]
	v_mfma_f32_16x16x32_bf16 v[102:105], v[164:167], v[196:199], v[102:105]
	v_mfma_f32_16x16x32_bf16 v[90:93], v[156:159], v[204:207], v[90:93]
	v_mfma_f32_16x16x32_bf16 v[86:89], v[164:167], v[204:207], v[86:89]
	v_mfma_f32_16x16x32_bf16 v[74:77], v[156:159], v[212:215], v[74:77]
	v_mfma_f32_16x16x32_bf16 v[70:73], v[164:167], v[212:215], v[70:73]
	v_mfma_f32_16x16x32_bf16 v[126:129], v[168:171], v[184:187], 0
	v_mfma_f32_16x16x32_bf16 v[114:117], v[176:179], v[184:187], 0
	v_mfma_f32_16x16x32_bf16 v[110:113], v[168:171], v[192:195], 0
	v_mfma_f32_16x16x32_bf16 v[98:101], v[176:179], v[192:195], 0
	v_mfma_f32_16x16x32_bf16 v[94:97], v[168:171], v[200:203], 0
	v_mfma_f32_16x16x32_bf16 v[82:85], v[176:179], v[200:203], 0
	v_mfma_f32_16x16x32_bf16 v[78:81], v[168:171], v[208:211], 0
	v_mfma_f32_16x16x32_bf16 v[66:69], v[176:179], v[208:211], 0
	v_mfma_f32_16x16x32_bf16 v[126:129], v[172:175], v[188:191], v[126:129]
	v_mfma_f32_16x16x32_bf16 v[114:117], v[180:183], v[188:191], v[114:117]
	v_mfma_f32_16x16x32_bf16 v[110:113], v[172:175], v[196:199], v[110:113]
	v_mfma_f32_16x16x32_bf16 v[98:101], v[180:183], v[196:199], v[98:101]
	v_mfma_f32_16x16x32_bf16 v[94:97], v[172:175], v[204:207], v[94:97]
	v_mfma_f32_16x16x32_bf16 v[82:85], v[180:183], v[204:207], v[82:85]
	v_mfma_f32_16x16x32_bf16 v[78:81], v[172:175], v[212:215], v[78:81]
	v_mfma_f32_16x16x32_bf16 v[66:69], v[180:183], v[212:215], v[66:69]
	s_barrier
	s_add_i32 s53, s72, s36
	v_lshl_add_u64 v[216:217], s[30:31], 0, v[134:135]
	s_mov_b32 m0, s53
	ds_read_b128 v[184:187], v150 offset:16384
	ds_read_b128 v[188:191], v150 offset:17408
	ds_read_b128 v[192:195], v150 offset:18432
	ds_read_b128 v[196:199], v150 offset:19456
	ds_read_b128 v[200:203], v150 offset:20480
	ds_read_b128 v[204:207], v150 offset:21504
	ds_read_b128 v[208:211], v150 offset:22528
	ds_read_b128 v[212:215], v150 offset:23552
	global_load_lds_dwordx4 v[216:217], off
	s_add_i32 m0, s53, 0x2000
	s_add_u32 s54, s30, 0x4000
	v_lshl_add_u64 v[216:217], s[30:31], 0, v[130:131]
	s_addc_u32 s55, s31, 0
	s_add_i32 s53, s73, s36
	global_load_lds_dwordx4 v[216:217], off
	v_lshl_add_u64 v[216:217], s[54:55], 0, v[134:135]
	s_mov_b32 m0, s53
	s_nop 0
	global_load_lds_dwordx4 v[216:217], off
	v_lshl_add_u64 v[216:217], s[54:55], 0, v[130:131]
	s_add_i32 m0, s53, 0x2000
	s_nop 0
	global_load_lds_dwordx4 v[216:217], off
	v_lshl_add_u64 v[216:217], s[34:35], 0, v[136:137]
	s_mov_b32 m0, s21
	s_nop 0
	global_load_lds_dwordx4 v[216:217], off
	v_lshl_add_u64 v[216:217], s[34:35], 0, v[132:133]
	s_mov_b32 m0, s23
	s_nop 0
	global_load_lds_dwordx4 v[216:217], off
	s_waitcnt vmcnt(8)
	s_waitcnt lgkmcnt(0)
	s_barrier
	v_mfma_f32_16x16x32_bf16 v[58:61], v[152:155], v[184:187], 0
	v_mfma_f32_16x16x32_bf16 v[54:57], v[160:163], v[184:187], 0
	v_mfma_f32_16x16x32_bf16 v[42:45], v[152:155], v[192:195], 0
	v_mfma_f32_16x16x32_bf16 v[38:41], v[160:163], v[192:195], 0
	v_mfma_f32_16x16x32_bf16 v[26:29], v[152:155], v[200:203], 0
	v_mfma_f32_16x16x32_bf16 v[22:25], v[160:163], v[200:203], 0
	v_mfma_f32_16x16x32_bf16 v[10:13], v[152:155], v[208:211], 0
	v_mfma_f32_16x16x32_bf16 v[6:9], v[160:163], v[208:211], 0
	v_mfma_f32_16x16x32_bf16 v[58:61], v[156:159], v[188:191], v[58:61]
	v_mfma_f32_16x16x32_bf16 v[54:57], v[164:167], v[188:191], v[54:57]
	v_mfma_f32_16x16x32_bf16 v[42:45], v[156:159], v[196:199], v[42:45]
	v_mfma_f32_16x16x32_bf16 v[38:41], v[164:167], v[196:199], v[38:41]
	v_mfma_f32_16x16x32_bf16 v[26:29], v[156:159], v[204:207], v[26:29]
	v_mfma_f32_16x16x32_bf16 v[22:25], v[164:167], v[204:207], v[22:25]
	v_mfma_f32_16x16x32_bf16 v[10:13], v[156:159], v[212:215], v[10:13]
	v_mfma_f32_16x16x32_bf16 v[6:9], v[164:167], v[212:215], v[6:9]
	v_mfma_f32_16x16x32_bf16 v[62:65], v[168:171], v[184:187], 0
	v_mfma_f32_16x16x32_bf16 v[50:53], v[176:179], v[184:187], 0
	v_mfma_f32_16x16x32_bf16 v[46:49], v[168:171], v[192:195], 0
	v_mfma_f32_16x16x32_bf16 v[34:37], v[176:179], v[192:195], 0
	v_mfma_f32_16x16x32_bf16 v[30:33], v[168:171], v[200:203], 0
	v_mfma_f32_16x16x32_bf16 v[18:21], v[176:179], v[200:203], 0
	v_mfma_f32_16x16x32_bf16 v[14:17], v[168:171], v[208:211], 0
	v_mfma_f32_16x16x32_bf16 v[2:5], v[176:179], v[208:211], 0
	v_mfma_f32_16x16x32_bf16 v[62:65], v[172:175], v[188:191], v[62:65]
	v_mfma_f32_16x16x32_bf16 v[50:53], v[180:183], v[188:191], v[50:53]
	v_mfma_f32_16x16x32_bf16 v[46:49], v[172:175], v[196:199], v[46:49]
	v_mfma_f32_16x16x32_bf16 v[34:37], v[180:183], v[196:199], v[34:37]
	v_mfma_f32_16x16x32_bf16 v[30:33], v[172:175], v[204:207], v[30:33]
	v_mfma_f32_16x16x32_bf16 v[18:21], v[180:183], v[204:207], v[18:21]
	v_mfma_f32_16x16x32_bf16 v[14:17], v[172:175], v[212:215], v[14:17]
	v_mfma_f32_16x16x32_bf16 v[2:5], v[180:183], v[212:215], v[2:5]
	s_barrier
	v_add_u32_e32 v151, s60, v146
	ds_read_b128 v[152:155], v151
	ds_read_b128 v[156:159], v151 offset:1024
	ds_read_b128 v[160:163], v151 offset:2048
	ds_read_b128 v[164:167], v151 offset:3072
	v_add_u32_e32 v151, s61, v146
	ds_read_b128 v[168:171], v151
	ds_read_b128 v[172:175], v151 offset:1024
	ds_read_b128 v[176:179], v151 offset:2048
	ds_read_b128 v[180:183], v151 offset:3072
	s_add_u32 s34, s34, 0x80000
	s_addc_u32 s35, s35, 0
	s_mov_b32 m0, s39
	v_lshl_add_u64 v[216:217], s[34:35], 0, v[136:137]
	ds_read_b128 v[184:187], v150 offset:32768
	ds_read_b128 v[188:191], v150 offset:33792
	ds_read_b128 v[192:195], v150 offset:34816
	ds_read_b128 v[196:199], v150 offset:35840
	ds_read_b128 v[200:203], v150 offset:36864
	ds_read_b128 v[204:207], v150 offset:37888
	ds_read_b128 v[208:211], v150 offset:38912
	ds_read_b128 v[212:215], v150 offset:39936
	global_load_lds_dwordx4 v[216:217], off
	v_lshl_add_u64 v[216:217], s[34:35], 0, v[132:133]
	s_mov_b32 m0, s40
	s_nop 0
	global_load_lds_dwordx4 v[216:217], off
	s_waitcnt vmcnt(8)
	s_waitcnt lgkmcnt(0)
	s_barrier
	v_mfma_f32_16x16x32_bf16 v[122:125], v[152:155], v[184:187], v[122:125]
	v_mfma_f32_16x16x32_bf16 v[118:121], v[160:163], v[184:187], v[118:121]
	v_mfma_f32_16x16x32_bf16 v[106:109], v[152:155], v[192:195], v[106:109]
	v_mfma_f32_16x16x32_bf16 v[102:105], v[160:163], v[192:195], v[102:105]
	v_mfma_f32_16x16x32_bf16 v[90:93], v[152:155], v[200:203], v[90:93]
	v_mfma_f32_16x16x32_bf16 v[86:89], v[160:163], v[200:203], v[86:89]
	v_mfma_f32_16x16x32_bf16 v[74:77], v[152:155], v[208:211], v[74:77]
	v_mfma_f32_16x16x32_bf16 v[70:73], v[160:163], v[208:211], v[70:73]
	v_mfma_f32_16x16x32_bf16 v[122:125], v[156:159], v[188:191], v[122:125]
	v_mfma_f32_16x16x32_bf16 v[118:121], v[164:167], v[188:191], v[118:121]
	v_mfma_f32_16x16x32_bf16 v[106:109], v[156:159], v[196:199], v[106:109]
	v_mfma_f32_16x16x32_bf16 v[102:105], v[164:167], v[196:199], v[102:105]
	v_mfma_f32_16x16x32_bf16 v[90:93], v[156:159], v[204:207], v[90:93]
	v_mfma_f32_16x16x32_bf16 v[86:89], v[164:167], v[204:207], v[86:89]
	v_mfma_f32_16x16x32_bf16 v[74:77], v[156:159], v[212:215], v[74:77]
	v_mfma_f32_16x16x32_bf16 v[70:73], v[164:167], v[212:215], v[70:73]
	v_mfma_f32_16x16x32_bf16 v[126:129], v[168:171], v[184:187], v[126:129]
	v_mfma_f32_16x16x32_bf16 v[114:117], v[176:179], v[184:187], v[114:117]
	v_mfma_f32_16x16x32_bf16 v[110:113], v[168:171], v[192:195], v[110:113]
	v_mfma_f32_16x16x32_bf16 v[98:101], v[176:179], v[192:195], v[98:101]
	v_mfma_f32_16x16x32_bf16 v[94:97], v[168:171], v[200:203], v[94:97]
	v_mfma_f32_16x16x32_bf16 v[82:85], v[176:179], v[200:203], v[82:85]
	v_mfma_f32_16x16x32_bf16 v[78:81], v[168:171], v[208:211], v[78:81]
	v_mfma_f32_16x16x32_bf16 v[66:69], v[176:179], v[208:211], v[66:69]
	v_mfma_f32_16x16x32_bf16 v[126:129], v[172:175], v[188:191], v[126:129]
	v_mfma_f32_16x16x32_bf16 v[114:117], v[180:183], v[188:191], v[114:117]
	v_mfma_f32_16x16x32_bf16 v[110:113], v[172:175], v[196:199], v[110:113]
	v_mfma_f32_16x16x32_bf16 v[98:101], v[180:183], v[196:199], v[98:101]
	v_mfma_f32_16x16x32_bf16 v[94:97], v[172:175], v[204:207], v[94:97]
	v_mfma_f32_16x16x32_bf16 v[82:85], v[180:183], v[204:207], v[82:85]
	v_mfma_f32_16x16x32_bf16 v[78:81], v[172:175], v[212:215], v[78:81]
	v_mfma_f32_16x16x32_bf16 v[66:69], v[180:183], v[212:215], v[66:69]
	s_barrier
	s_add_u32 s34, s30, 0x8000
	s_addc_u32 s35, s31, 0
	s_add_i32 s53, s60, s36
	v_lshl_add_u64 v[216:217], s[34:35], 0, v[134:135]
	s_mov_b32 m0, s53
	ds_read_b128 v[184:187], v150 offset:49152
	ds_read_b128 v[188:191], v150 offset:50176
	ds_read_b128 v[192:195], v150 offset:51200
	ds_read_b128 v[196:199], v150 offset:52224
	ds_read_b128 v[200:203], v150 offset:53248
	ds_read_b128 v[204:207], v150 offset:54272
	ds_read_b128 v[208:211], v150 offset:55296
	ds_read_b128 v[212:215], v150 offset:56320
	global_load_lds_dwordx4 v[216:217], off
	s_add_i32 m0, s53, 0x2000
	s_add_u32 s30, s30, 0xc000
	v_lshl_add_u64 v[216:217], s[34:35], 0, v[130:131]
	s_addc_u32 s31, s31, 0
	s_add_i32 s34, s61, s36
	global_load_lds_dwordx4 v[216:217], off
	v_lshl_add_u64 v[216:217], s[30:31], 0, v[134:135]
	s_mov_b32 m0, s34
	s_nop 0
	global_load_lds_dwordx4 v[216:217], off
	v_lshl_add_u64 v[216:217], s[30:31], 0, v[130:131]
	s_add_i32 m0, s34, 0x2000
	s_nop 0
	global_load_lds_dwordx4 v[216:217], off
	v_lshl_add_u64 v[216:217], s[28:29], 0, v[136:137]
	s_mov_b32 m0, s42
	s_nop 0
	global_load_lds_dwordx4 v[216:217], off
	v_lshl_add_u64 v[216:217], s[28:29], 0, v[132:133]
	s_mov_b32 m0, s43
	s_nop 0
	global_load_lds_dwordx4 v[216:217], off
	s_waitcnt vmcnt(8)
	s_waitcnt lgkmcnt(0)
	s_barrier
	v_mfma_f32_16x16x32_bf16 v[58:61], v[152:155], v[184:187], v[58:61]
	v_mfma_f32_16x16x32_bf16 v[54:57], v[160:163], v[184:187], v[54:57]
	v_mfma_f32_16x16x32_bf16 v[42:45], v[152:155], v[192:195], v[42:45]
	v_mfma_f32_16x16x32_bf16 v[38:41], v[160:163], v[192:195], v[38:41]
	v_mfma_f32_16x16x32_bf16 v[26:29], v[152:155], v[200:203], v[26:29]
	v_mfma_f32_16x16x32_bf16 v[22:25], v[160:163], v[200:203], v[22:25]
	v_mfma_f32_16x16x32_bf16 v[10:13], v[152:155], v[208:211], v[10:13]
	v_mfma_f32_16x16x32_bf16 v[6:9], v[160:163], v[208:211], v[6:9]
	v_mfma_f32_16x16x32_bf16 v[58:61], v[156:159], v[188:191], v[58:61]
	v_mfma_f32_16x16x32_bf16 v[54:57], v[164:167], v[188:191], v[54:57]
	v_mfma_f32_16x16x32_bf16 v[42:45], v[156:159], v[196:199], v[42:45]
	v_mfma_f32_16x16x32_bf16 v[38:41], v[164:167], v[196:199], v[38:41]
	v_mfma_f32_16x16x32_bf16 v[26:29], v[156:159], v[204:207], v[26:29]
	v_mfma_f32_16x16x32_bf16 v[22:25], v[164:167], v[204:207], v[22:25]
	v_mfma_f32_16x16x32_bf16 v[10:13], v[156:159], v[212:215], v[10:13]
	v_mfma_f32_16x16x32_bf16 v[6:9], v[164:167], v[212:215], v[6:9]
	v_mfma_f32_16x16x32_bf16 v[62:65], v[168:171], v[184:187], v[62:65]
	v_mfma_f32_16x16x32_bf16 v[50:53], v[176:179], v[184:187], v[50:53]
	v_mfma_f32_16x16x32_bf16 v[46:49], v[168:171], v[192:195], v[46:49]
	v_mfma_f32_16x16x32_bf16 v[34:37], v[176:179], v[192:195], v[34:37]
	v_mfma_f32_16x16x32_bf16 v[30:33], v[168:171], v[200:203], v[30:33]
	v_mfma_f32_16x16x32_bf16 v[18:21], v[176:179], v[200:203], v[18:21]
	v_mfma_f32_16x16x32_bf16 v[14:17], v[168:171], v[208:211], v[14:17]
	v_mfma_f32_16x16x32_bf16 v[2:5], v[176:179], v[208:211], v[2:5]
	v_mfma_f32_16x16x32_bf16 v[62:65], v[172:175], v[188:191], v[62:65]
	v_mfma_f32_16x16x32_bf16 v[50:53], v[180:183], v[188:191], v[50:53]
	v_mfma_f32_16x16x32_bf16 v[46:49], v[172:175], v[196:199], v[46:49]
	v_mfma_f32_16x16x32_bf16 v[34:37], v[180:183], v[196:199], v[34:37]
	v_mfma_f32_16x16x32_bf16 v[30:33], v[172:175], v[204:207], v[30:33]
	v_mfma_f32_16x16x32_bf16 v[18:21], v[180:183], v[204:207], v[18:21]
	v_mfma_f32_16x16x32_bf16 v[14:17], v[172:175], v[212:215], v[14:17]
	v_mfma_f32_16x16x32_bf16 v[2:5], v[180:183], v[212:215], v[2:5]
	s_barrier
	s_add_i32 s52, s52, 2
	s_add_u32 s26, s26, 0x100
	s_addc_u32 s27, s27, 0
	s_add_u32 s50, s50, 0x10000
	s_addc_u32 s51, s51, 0
	s_cmp_gt_u32 s52, 29

.LBB0_2262:
	s_ashr_i32 s13, s12, 31
	s_lshl_b64 s[4:5], s[12:13], 20
	s_add_u32 s16, s41, s4
	s_addc_u32 s17, s42, s5
	s_and_b64 s[4:5], s[18:19], exec
	s_cselect_b32 s4, s17, s27
	s_cselect_b32 s5, s16, s26
	s_ashr_i32 s15, s14, 31
	s_lshl_b64 s[20:21], s[14:15], 20
	s_add_u32 s20, s38, s20
	s_addc_u32 s21, s39, s21
	s_and_b64 s[30:31], s[18:19], exec
	s_cselect_b32 s13, s21, s29
	s_cselect_b32 s15, s20, s28
	s_add_u32 s23, s5, 0x80
	s_addc_u32 s54, s4, 0
	s_add_u32 s55, s28, 0x10000
	v_mov_b32_e32 v2, 0
	s_addc_u32 s56, s29, 0
	v_lshl_add_u64 v[164:165], s[26:27], 0, v[160:161]
	v_lshl_add_u64 v[166:167], s[26:27], 0, v[162:163]
	s_mov_b32 s57, -2
	s_mov_b64 s[28:29], 0
	ds_read_b128 v[172:175], v168
	ds_read_b128 v[176:179], v168 offset:1024
	ds_read_b128 v[180:183], v168 offset:2048
	ds_read_b128 v[184:187], v168 offset:3072
	ds_read_b128 v[188:191], v169
	ds_read_b128 v[192:195], v169 offset:1024
	ds_read_b128 v[196:199], v169 offset:2048
	ds_read_b128 v[200:203], v169 offset:3072
	s_add_u32 s30, s26, s28
	s_addc_u32 s31, s27, s29
	s_add_u32 s36, s30, 0x100
	s_addc_u32 s37, s31, 0
	s_add_u32 s30, s30, 0x180
	s_addc_u32 s31, s31, 0
	s_cmpk_eq_i32 s28, 0xf00
	s_cselect_b32 s31, s54, s31
	s_cselect_b32 s30, s23, s30
	s_cselect_b32 s35, s13, s56
	s_cselect_b32 s34, s15, s55
	s_cselect_b32 s37, s4, s37
	s_cselect_b32 s36, s5, s36
	s_mov_b32 m0, s50
	v_lshl_add_u64 v[236:237], v[164:165], 0, s[28:29]
	ds_read_b128 v[204:207], v170
	ds_read_b128 v[208:211], v170 offset:1024
	ds_read_b128 v[212:215], v170 offset:2048
	ds_read_b128 v[216:219], v170 offset:3072
	ds_read_b128 v[220:223], v170 offset:4096
	ds_read_b128 v[224:227], v170 offset:5120
	ds_read_b128 v[228:231], v170 offset:6144
	ds_read_b128 v[232:235], v170 offset:7168
	global_load_lds_dwordx4 v[236:237], off
	v_lshl_add_u64 v[236:237], v[166:167], 0, s[28:29]
	s_mov_b32 m0, s51
	s_nop 0
	global_load_lds_dwordx4 v[236:237], off
	s_waitcnt vmcnt(8)
	s_waitcnt lgkmcnt(0)
	s_barrier
	v_mfma_f32_16x16x32_bf16 v[126:129], v[172:175], v[204:207], 0
	v_mfma_f32_16x16x32_bf16 v[122:125], v[180:183], v[204:207], 0
	v_mfma_f32_16x16x32_bf16 v[110:113], v[172:175], v[212:215], 0
	v_mfma_f32_16x16x32_bf16 v[106:109], v[180:183], v[212:215], 0
	v_mfma_f32_16x16x32_bf16 v[94:97], v[172:175], v[220:223], 0
	v_mfma_f32_16x16x32_bf16 v[90:93], v[180:183], v[220:223], 0
	v_mfma_f32_16x16x32_bf16 v[78:81], v[172:175], v[228:231], 0
	v_mfma_f32_16x16x32_bf16 v[74:77], v[180:183], v[228:231], 0
	v_mfma_f32_16x16x32_bf16 v[126:129], v[176:179], v[208:211], v[126:129]
	v_mfma_f32_16x16x32_bf16 v[122:125], v[184:187], v[208:211], v[122:125]
	v_mfma_f32_16x16x32_bf16 v[110:113], v[176:179], v[216:219], v[110:113]
	v_mfma_f32_16x16x32_bf16 v[106:109], v[184:187], v[216:219], v[106:109]
	v_mfma_f32_16x16x32_bf16 v[94:97], v[176:179], v[224:227], v[94:97]
	v_mfma_f32_16x16x32_bf16 v[90:93], v[184:187], v[224:227], v[90:93]
	v_mfma_f32_16x16x32_bf16 v[78:81], v[176:179], v[232:235], v[78:81]
	v_mfma_f32_16x16x32_bf16 v[74:77], v[184:187], v[232:235], v[74:77]
	v_mfma_f32_16x16x32_bf16 v[118:121], v[188:191], v[204:207], 0
	v_mfma_f32_16x16x32_bf16 v[114:117], v[196:199], v[204:207], 0
	v_mfma_f32_16x16x32_bf16 v[102:105], v[188:191], v[212:215], 0
	v_mfma_f32_16x16x32_bf16 v[98:101], v[196:199], v[212:215], 0
	v_mfma_f32_16x16x32_bf16 v[86:89], v[188:191], v[220:223], 0
	v_mfma_f32_16x16x32_bf16 v[82:85], v[196:199], v[220:223], 0
	v_mfma_f32_16x16x32_bf16 v[70:73], v[188:191], v[228:231], 0
	v_mfma_f32_16x16x32_bf16 v[66:69], v[196:199], v[228:231], 0
	v_mfma_f32_16x16x32_bf16 v[118:121], v[192:195], v[208:211], v[118:121]
	v_mfma_f32_16x16x32_bf16 v[114:117], v[200:203], v[208:211], v[114:117]
	v_mfma_f32_16x16x32_bf16 v[102:105], v[192:195], v[216:219], v[102:105]
	v_mfma_f32_16x16x32_bf16 v[98:101], v[200:203], v[216:219], v[98:101]
	v_mfma_f32_16x16x32_bf16 v[86:89], v[192:195], v[224:227], v[86:89]
	v_mfma_f32_16x16x32_bf16 v[82:85], v[200:203], v[224:227], v[82:85]
	v_mfma_f32_16x16x32_bf16 v[70:73], v[192:195], v[232:235], v[70:73]
	v_mfma_f32_16x16x32_bf16 v[66:69], v[200:203], v[232:235], v[66:69]
	s_barrier
	s_mov_b32 m0, s52
	v_lshl_add_u64 v[236:237], s[34:35], 0, v[134:135]
	s_add_u32 s58, s34, 0x4000
	ds_read_b128 v[204:207], v170 offset:16384
	ds_read_b128 v[208:211], v170 offset:17408
	ds_read_b128 v[212:215], v170 offset:18432
	ds_read_b128 v[216:219], v170 offset:19456
	ds_read_b128 v[220:223], v170 offset:20480
	ds_read_b128 v[224:227], v170 offset:21504
	ds_read_b128 v[228:231], v170 offset:22528
	ds_read_b128 v[232:235], v170 offset:23552
	global_load_lds_dwordx4 v[236:237], off
	v_lshl_add_u64 v[236:237], s[34:35], 0, v[130:131]
	s_mov_b32 m0, s53
	s_addc_u32 s59, s35, 0
	s_add_i32 s62, s73, s40
	global_load_lds_dwordx4 v[236:237], off
	v_lshl_add_u64 v[236:237], s[58:59], 0, v[134:135]
	s_mov_b32 m0, s62
	s_nop 0
	global_load_lds_dwordx4 v[236:237], off
	v_lshl_add_u64 v[236:237], s[58:59], 0, v[130:131]
	s_add_i32 m0, s62, 0x2000
	s_nop 0
	global_load_lds_dwordx4 v[236:237], off
	v_lshl_add_u64 v[236:237], s[36:37], 0, v[136:137]
	s_mov_b32 m0, s25
	s_nop 0
	global_load_lds_dwordx4 v[236:237], off
	v_lshl_add_u64 v[236:237], s[36:37], 0, v[132:133]
	s_mov_b32 m0, s43
	s_nop 0
	global_load_lds_dwordx4 v[236:237], off
	s_waitcnt vmcnt(8)
	s_waitcnt lgkmcnt(0)
	s_barrier
	v_mfma_f32_16x16x32_bf16 v[62:65], v[172:175], v[204:207], 0
	v_mfma_f32_16x16x32_bf16 v[58:61], v[180:183], v[204:207], 0
	v_mfma_f32_16x16x32_bf16 v[46:49], v[172:175], v[212:215], 0
	v_mfma_f32_16x16x32_bf16 v[42:45], v[180:183], v[212:215], 0
	v_mfma_f32_16x16x32_bf16 v[30:33], v[172:175], v[220:223], 0
	v_mfma_f32_16x16x32_bf16 v[26:29], v[180:183], v[220:223], 0
	v_mfma_f32_16x16x32_bf16 v[14:17], v[172:175], v[228:231], 0
	v_mfma_f32_16x16x32_bf16 v[10:13], v[180:183], v[228:231], 0
	v_mfma_f32_16x16x32_bf16 v[62:65], v[176:179], v[208:211], v[62:65]
	v_mfma_f32_16x16x32_bf16 v[58:61], v[184:187], v[208:211], v[58:61]
	v_mfma_f32_16x16x32_bf16 v[46:49], v[176:179], v[216:219], v[46:49]
	v_mfma_f32_16x16x32_bf16 v[42:45], v[184:187], v[216:219], v[42:45]
	v_mfma_f32_16x16x32_bf16 v[30:33], v[176:179], v[224:227], v[30:33]
	v_mfma_f32_16x16x32_bf16 v[26:29], v[184:187], v[224:227], v[26:29]
	v_mfma_f32_16x16x32_bf16 v[14:17], v[176:179], v[232:235], v[14:17]
	v_mfma_f32_16x16x32_bf16 v[10:13], v[184:187], v[232:235], v[10:13]
	v_mfma_f32_16x16x32_bf16 v[54:57], v[188:191], v[204:207], 0
	v_mfma_f32_16x16x32_bf16 v[50:53], v[196:199], v[204:207], 0
	v_mfma_f32_16x16x32_bf16 v[38:41], v[188:191], v[212:215], 0
	v_mfma_f32_16x16x32_bf16 v[34:37], v[196:199], v[212:215], 0
	v_mfma_f32_16x16x32_bf16 v[22:25], v[188:191], v[220:223], 0
	v_mfma_f32_16x16x32_bf16 v[18:21], v[196:199], v[220:223], 0
	v_mfma_f32_16x16x32_bf16 v[6:9], v[188:191], v[228:231], 0
	v_mfma_f32_16x16x32_bf16 v[2:5], v[196:199], v[228:231], 0
	v_mfma_f32_16x16x32_bf16 v[54:57], v[192:195], v[208:211], v[54:57]
	v_mfma_f32_16x16x32_bf16 v[50:53], v[200:203], v[208:211], v[50:53]
	v_mfma_f32_16x16x32_bf16 v[38:41], v[192:195], v[216:219], v[38:41]
	v_mfma_f32_16x16x32_bf16 v[34:37], v[200:203], v[216:219], v[34:37]
	v_mfma_f32_16x16x32_bf16 v[22:25], v[192:195], v[224:227], v[22:25]
	v_mfma_f32_16x16x32_bf16 v[18:21], v[200:203], v[224:227], v[18:21]
	v_mfma_f32_16x16x32_bf16 v[6:9], v[192:195], v[232:235], v[6:9]
	v_mfma_f32_16x16x32_bf16 v[2:5], v[200:203], v[232:235], v[2:5]
	s_barrier
	v_add_u32_e32 v171, s60, v1
	ds_read_b128 v[172:175], v171
	ds_read_b128 v[176:179], v171 offset:1024
	ds_read_b128 v[180:183], v171 offset:2048
	ds_read_b128 v[184:187], v171 offset:3072
	v_add_u32_e32 v171, s61, v1
	ds_read_b128 v[188:191], v171
	ds_read_b128 v[192:195], v171 offset:1024
	ds_read_b128 v[196:199], v171 offset:2048
	ds_read_b128 v[200:203], v171 offset:3072
	s_add_u32 s36, s36, 0x80000
	s_addc_u32 s37, s37, 0
	s_mov_b32 m0, s44
	v_lshl_add_u64 v[236:237], s[36:37], 0, v[136:137]
	ds_read_b128 v[204:207], v170 offset:32768
	ds_read_b128 v[208:211], v170 offset:33792
	ds_read_b128 v[212:215], v170 offset:34816
	ds_read_b128 v[216:219], v170 offset:35840
	ds_read_b128 v[220:223], v170 offset:36864
	ds_read_b128 v[224:227], v170 offset:37888
	ds_read_b128 v[228:231], v170 offset:38912
	ds_read_b128 v[232:235], v170 offset:39936
	global_load_lds_dwordx4 v[236:237], off
	v_lshl_add_u64 v[236:237], s[36:37], 0, v[132:133]
	s_mov_b32 m0, s45
	s_nop 0
	global_load_lds_dwordx4 v[236:237], off
	s_waitcnt vmcnt(8)
	s_waitcnt lgkmcnt(0)
	s_barrier
	v_mfma_f32_16x16x32_bf16 v[126:129], v[172:175], v[204:207], v[126:129]
	v_mfma_f32_16x16x32_bf16 v[122:125], v[180:183], v[204:207], v[122:125]
	v_mfma_f32_16x16x32_bf16 v[110:113], v[172:175], v[212:215], v[110:113]
	v_mfma_f32_16x16x32_bf16 v[106:109], v[180:183], v[212:215], v[106:109]
	v_mfma_f32_16x16x32_bf16 v[94:97], v[172:175], v[220:223], v[94:97]
	v_mfma_f32_16x16x32_bf16 v[90:93], v[180:183], v[220:223], v[90:93]
	v_mfma_f32_16x16x32_bf16 v[78:81], v[172:175], v[228:231], v[78:81]
	v_mfma_f32_16x16x32_bf16 v[74:77], v[180:183], v[228:231], v[74:77]
	v_mfma_f32_16x16x32_bf16 v[126:129], v[176:179], v[208:211], v[126:129]
	v_mfma_f32_16x16x32_bf16 v[122:125], v[184:187], v[208:211], v[122:125]
	v_mfma_f32_16x16x32_bf16 v[110:113], v[176:179], v[216:219], v[110:113]
	v_mfma_f32_16x16x32_bf16 v[106:109], v[184:187], v[216:219], v[106:109]
	v_mfma_f32_16x16x32_bf16 v[94:97], v[176:179], v[224:227], v[94:97]
	v_mfma_f32_16x16x32_bf16 v[90:93], v[184:187], v[224:227], v[90:93]
	v_mfma_f32_16x16x32_bf16 v[78:81], v[176:179], v[232:235], v[78:81]
	v_mfma_f32_16x16x32_bf16 v[74:77], v[184:187], v[232:235], v[74:77]
	v_mfma_f32_16x16x32_bf16 v[118:121], v[188:191], v[204:207], v[118:121]
	v_mfma_f32_16x16x32_bf16 v[114:117], v[196:199], v[204:207], v[114:117]
	v_mfma_f32_16x16x32_bf16 v[102:105], v[188:191], v[212:215], v[102:105]
	v_mfma_f32_16x16x32_bf16 v[98:101], v[196:199], v[212:215], v[98:101]
	v_mfma_f32_16x16x32_bf16 v[86:89], v[188:191], v[220:223], v[86:89]
	v_mfma_f32_16x16x32_bf16 v[82:85], v[196:199], v[220:223], v[82:85]
	v_mfma_f32_16x16x32_bf16 v[70:73], v[188:191], v[228:231], v[70:73]
	v_mfma_f32_16x16x32_bf16 v[66:69], v[196:199], v[228:231], v[66:69]
	v_mfma_f32_16x16x32_bf16 v[118:121], v[192:195], v[208:211], v[118:121]
	v_mfma_f32_16x16x32_bf16 v[114:117], v[200:203], v[208:211], v[114:117]
	v_mfma_f32_16x16x32_bf16 v[102:105], v[192:195], v[216:219], v[102:105]
	v_mfma_f32_16x16x32_bf16 v[98:101], v[200:203], v[216:219], v[98:101]
	v_mfma_f32_16x16x32_bf16 v[86:89], v[192:195], v[224:227], v[86:89]
	v_mfma_f32_16x16x32_bf16 v[82:85], v[200:203], v[224:227], v[82:85]
	v_mfma_f32_16x16x32_bf16 v[70:73], v[192:195], v[232:235], v[70:73]
	v_mfma_f32_16x16x32_bf16 v[66:69], v[200:203], v[232:235], v[66:69]
	s_barrier
	s_add_u32 s36, s34, 0x8000
	s_addc_u32 s37, s35, 0
	s_add_i32 s58, s60, s40
	v_lshl_add_u64 v[236:237], s[36:37], 0, v[134:135]
	s_mov_b32 m0, s58
	ds_read_b128 v[204:207], v170 offset:49152
	ds_read_b128 v[208:211], v170 offset:50176
	ds_read_b128 v[212:215], v170 offset:51200
	ds_read_b128 v[216:219], v170 offset:52224
	ds_read_b128 v[220:223], v170 offset:53248
	ds_read_b128 v[224:227], v170 offset:54272
	ds_read_b128 v[228:231], v170 offset:55296
	ds_read_b128 v[232:235], v170 offset:56320
	global_load_lds_dwordx4 v[236:237], off
	s_add_i32 m0, s58, 0x2000
	s_add_u32 s34, s34, 0xc000
	v_lshl_add_u64 v[236:237], s[36:37], 0, v[130:131]
	s_addc_u32 s35, s35, 0
	s_add_i32 s36, s61, s40
	global_load_lds_dwordx4 v[236:237], off
	v_lshl_add_u64 v[236:237], s[34:35], 0, v[134:135]
	s_mov_b32 m0, s36
	s_nop 0
	global_load_lds_dwordx4 v[236:237], off
	v_lshl_add_u64 v[236:237], s[34:35], 0, v[130:131]
	s_add_i32 m0, s36, 0x2000
	s_nop 0
	global_load_lds_dwordx4 v[236:237], off
	v_lshl_add_u64 v[236:237], s[30:31], 0, v[136:137]
	s_mov_b32 m0, s48
	s_nop 0
	global_load_lds_dwordx4 v[236:237], off
	v_lshl_add_u64 v[236:237], s[30:31], 0, v[132:133]
	s_mov_b32 m0, s49
	s_nop 0
	global_load_lds_dwordx4 v[236:237], off
	s_waitcnt vmcnt(8)
	s_waitcnt lgkmcnt(0)
	s_barrier
	v_mfma_f32_16x16x32_bf16 v[62:65], v[172:175], v[204:207], v[62:65]
	v_mfma_f32_16x16x32_bf16 v[58:61], v[180:183], v[204:207], v[58:61]
	v_mfma_f32_16x16x32_bf16 v[46:49], v[172:175], v[212:215], v[46:49]
	v_mfma_f32_16x16x32_bf16 v[42:45], v[180:183], v[212:215], v[42:45]
	v_mfma_f32_16x16x32_bf16 v[30:33], v[172:175], v[220:223], v[30:33]
	v_mfma_f32_16x16x32_bf16 v[26:29], v[180:183], v[220:223], v[26:29]
	v_mfma_f32_16x16x32_bf16 v[14:17], v[172:175], v[228:231], v[14:17]
	v_mfma_f32_16x16x32_bf16 v[10:13], v[180:183], v[228:231], v[10:13]
	v_mfma_f32_16x16x32_bf16 v[62:65], v[176:179], v[208:211], v[62:65]
	v_mfma_f32_16x16x32_bf16 v[58:61], v[184:187], v[208:211], v[58:61]
	v_mfma_f32_16x16x32_bf16 v[46:49], v[176:179], v[216:219], v[46:49]
	v_mfma_f32_16x16x32_bf16 v[42:45], v[184:187], v[216:219], v[42:45]
	v_mfma_f32_16x16x32_bf16 v[30:33], v[176:179], v[224:227], v[30:33]
	v_mfma_f32_16x16x32_bf16 v[26:29], v[184:187], v[224:227], v[26:29]
	v_mfma_f32_16x16x32_bf16 v[14:17], v[176:179], v[232:235], v[14:17]
	v_mfma_f32_16x16x32_bf16 v[10:13], v[184:187], v[232:235], v[10:13]
	v_mfma_f32_16x16x32_bf16 v[54:57], v[188:191], v[204:207], v[54:57]
	v_mfma_f32_16x16x32_bf16 v[50:53], v[196:199], v[204:207], v[50:53]
	v_mfma_f32_16x16x32_bf16 v[38:41], v[188:191], v[212:215], v[38:41]
	v_mfma_f32_16x16x32_bf16 v[34:37], v[196:199], v[212:215], v[34:37]
	v_mfma_f32_16x16x32_bf16 v[22:25], v[188:191], v[220:223], v[22:25]
	v_mfma_f32_16x16x32_bf16 v[18:21], v[196:199], v[220:223], v[18:21]
	v_mfma_f32_16x16x32_bf16 v[6:9], v[188:191], v[228:231], v[6:9]
	v_mfma_f32_16x16x32_bf16 v[2:5], v[196:199], v[228:231], v[2:5]
	v_mfma_f32_16x16x32_bf16 v[54:57], v[192:195], v[208:211], v[54:57]
	v_mfma_f32_16x16x32_bf16 v[50:53], v[200:203], v[208:211], v[50:53]
	v_mfma_f32_16x16x32_bf16 v[38:41], v[192:195], v[216:219], v[38:41]
	v_mfma_f32_16x16x32_bf16 v[34:37], v[200:203], v[216:219], v[34:37]
	v_mfma_f32_16x16x32_bf16 v[22:25], v[192:195], v[224:227], v[22:25]
	v_mfma_f32_16x16x32_bf16 v[18:21], v[200:203], v[224:227], v[18:21]
	v_mfma_f32_16x16x32_bf16 v[6:9], v[192:195], v[232:235], v[6:9]
	v_mfma_f32_16x16x32_bf16 v[2:5], v[200:203], v[232:235], v[2:5]
	s_barrier
	s_add_i32 s57, s57, 2
	s_add_u32 s28, s28, 0x100
	s_addc_u32 s29, s29, 0
	s_add_u32 s55, s55, 0x10000
	s_addc_u32 s56, s56, 0
	s_cmp_gt_u32 s57, 29

.LBB0_2266:
	s_lshl_b32 s4, s22, 7
	s_lshl_b32 s5, s24, 2
	s_add_i32 s5, s5, s4
	s_or_b32 s4, s5, s47
	s_ashr_i32 s5, s4, 31
	s_lshl_b64 s[4:5], s[4:5], 15
	s_add_u32 s22, s1, s4
	v_max_f32_e32 v126, 0, v126
	v_max_f32_e32 v122, 0, v122
	v_max_f32_e32 v127, 0, v127
	v_max_f32_e32 v123, 0, v123
	v_max_f32_e32 v128, 0, v128
	v_max_f32_e32 v124, 0, v124
	v_max_f32_e32 v129, 0, v129
	v_max_f32_e32 v125, 0, v125
	v_max_f32_e32 v118, 0, v118
	v_max_f32_e32 v114, 0, v114
	v_max_f32_e32 v119, 0, v119
	v_max_f32_e32 v115, 0, v115
	v_max_f32_e32 v120, 0, v120
	v_max_f32_e32 v116, 0, v116
	v_max_f32_e32 v121, 0, v121
	v_max_f32_e32 v117, 0, v117
	s_addc_u32 s23, s33, s5
	v_pk_mul_f32 v[126:127], v[126:127], v[126:127]
	v_pk_mul_f32 v[122:123], v[122:123], v[122:123]
	v_pk_mul_f32 v[128:129], v[128:129], v[128:129]
	v_pk_mul_f32 v[124:125], v[124:125], v[124:125]
	v_pk_mul_f32 v[118:119], v[118:119], v[118:119]
	v_pk_mul_f32 v[114:115], v[114:115], v[114:115]
	v_pk_mul_f32 v[120:121], v[120:121], v[120:121]
	v_pk_mul_f32 v[116:117], v[116:117], v[116:117]
	v_lshl_add_u64 v[164:165], s[22:23], 0, v[144:145]
	v_cvt_pk_bf16_f32 v126, v126, v127
	v_cvt_pk_bf16_f32 v127, v128, v129
	v_cvt_pk_bf16_f32 v128, v122, v123
	v_cvt_pk_bf16_f32 v129, v124, v125
	v_cvt_pk_bf16_f32 v118, v118, v119
	v_cvt_pk_bf16_f32 v119, v120, v121
	v_cvt_pk_bf16_f32 v114, v114, v115
	v_cvt_pk_bf16_f32 v115, v116, v117
	v_lshl_add_u64 v[122:123], v[164:165], 0, v[138:139]
	v_mov_b32_dpp v120, v126 row_ror:8 row_mask:0xf bank_mask:0xf bound_ctrl:1
	v_mov_b32_dpp v121, v127 row_ror:8 row_mask:0xf bank_mask:0xf bound_ctrl:1
	v_mov_b32_dpp v116, v128 row_ror:8 row_mask:0xf bank_mask:0xf bound_ctrl:1
	v_mov_b32_dpp v117, v129 row_ror:8 row_mask:0xf bank_mask:0xf bound_ctrl:1
	v_mov_b32_dpp v164, v118 row_ror:8 row_mask:0xf bank_mask:0xf bound_ctrl:1
	v_mov_b32_dpp v165, v119 row_ror:8 row_mask:0xf bank_mask:0xf bound_ctrl:1
	v_mov_b32_dpp v166, v114 row_ror:8 row_mask:0xf bank_mask:0xf bound_ctrl:1
	v_mov_b32_dpp v167, v115 row_ror:8 row_mask:0xf bank_mask:0xf bound_ctrl:1
	v_max_f32_e32 v110, 0, v110
	v_max_f32_e32 v106, 0, v106
	v_max_f32_e32 v111, 0, v111
	v_max_f32_e32 v107, 0, v107
	v_max_f32_e32 v112, 0, v112
	v_max_f32_e32 v108, 0, v108
	v_max_f32_e32 v113, 0, v113
	v_max_f32_e32 v109, 0, v109
	v_max_f32_e32 v102, 0, v102
	v_max_f32_e32 v98, 0, v98
	v_max_f32_e32 v103, 0, v103
	v_max_f32_e32 v99, 0, v99
	v_max_f32_e32 v104, 0, v104
	v_max_f32_e32 v100, 0, v100
	v_max_f32_e32 v105, 0, v105
	v_max_f32_e32 v101, 0, v101
	v_lshl_add_u64 v[124:125], v[122:123], 0, v[140:141]
	v_cndmask_b32_e64 v117, v117, v115, s[2:3]
	v_cndmask_b32_e64 v116, v116, v114, s[2:3]
	v_cndmask_b32_e64 v115, v121, v119, s[2:3]
	v_cndmask_b32_e64 v114, v120, v118, s[2:3]
	v_cndmask_b32_e64 v121, v129, v167, s[2:3]
	v_cndmask_b32_e64 v120, v128, v166, s[2:3]
	v_cndmask_b32_e64 v119, v127, v165, s[2:3]
	v_cndmask_b32_e64 v118, v126, v164, s[2:3]
	v_pk_mul_f32 v[110:111], v[110:111], v[110:111]
	v_pk_mul_f32 v[106:107], v[106:107], v[106:107]
	v_pk_mul_f32 v[112:113], v[112:113], v[112:113]
	v_pk_mul_f32 v[108:109], v[108:109], v[108:109]
	v_pk_mul_f32 v[102:103], v[102:103], v[102:103]
	v_pk_mul_f32 v[98:99], v[98:99], v[98:99]
	v_pk_mul_f32 v[104:105], v[104:105], v[104:105]
	v_pk_mul_f32 v[100:101], v[100:101], v[100:101]
	v_lshl_add_u64 v[122:123], v[122:123], 0, v[142:143]
	global_store_dwordx4 v[124:125], v[118:121], off
	global_store_dwordx4 v[122:123], v[114:117], off
	v_cvt_pk_bf16_f32 v110, v110, v111
	v_cvt_pk_bf16_f32 v111, v112, v113
	v_lshl_add_u64 v[114:115], s[22:23], 0, v[146:147]
	v_cvt_pk_bf16_f32 v112, v106, v107
	v_cvt_pk_bf16_f32 v113, v108, v109
	v_cvt_pk_bf16_f32 v102, v102, v103
	v_cvt_pk_bf16_f32 v103, v104, v105
	v_cvt_pk_bf16_f32 v98, v98, v99
	v_cvt_pk_bf16_f32 v99, v100, v101
	v_lshl_add_u64 v[106:107], v[114:115], 0, v[138:139]
	v_mov_b32_dpp v104, v110 row_ror:8 row_mask:0xf bank_mask:0xf bound_ctrl:1
	v_mov_b32_dpp v105, v111 row_ror:8 row_mask:0xf bank_mask:0xf bound_ctrl:1
	v_mov_b32_dpp v100, v112 row_ror:8 row_mask:0xf bank_mask:0xf bound_ctrl:1
	v_mov_b32_dpp v101, v113 row_ror:8 row_mask:0xf bank_mask:0xf bound_ctrl:1
	v_mov_b32_dpp v114, v102 row_ror:8 row_mask:0xf bank_mask:0xf bound_ctrl:1
	v_mov_b32_dpp v115, v103 row_ror:8 row_mask:0xf bank_mask:0xf bound_ctrl:1
	v_mov_b32_dpp v116, v98 row_ror:8 row_mask:0xf bank_mask:0xf bound_ctrl:1
	v_mov_b32_dpp v117, v99 row_ror:8 row_mask:0xf bank_mask:0xf bound_ctrl:1
	v_max_f32_e32 v94, 0, v94
	v_max_f32_e32 v90, 0, v90
	v_max_f32_e32 v95, 0, v95
	v_max_f32_e32 v91, 0, v91
	v_max_f32_e32 v96, 0, v96
	v_max_f32_e32 v92, 0, v92
	v_max_f32_e32 v97, 0, v97
	v_max_f32_e32 v93, 0, v93
	v_max_f32_e32 v86, 0, v86
	v_max_f32_e32 v82, 0, v82
	v_max_f32_e32 v87, 0, v87
	v_max_f32_e32 v83, 0, v83
	v_max_f32_e32 v88, 0, v88
	v_max_f32_e32 v84, 0, v84
	v_max_f32_e32 v89, 0, v89
	v_max_f32_e32 v85, 0, v85
	v_lshl_add_u64 v[108:109], v[106:107], 0, v[140:141]
	v_cndmask_b32_e64 v101, v101, v99, s[2:3]
	v_cndmask_b32_e64 v100, v100, v98, s[2:3]
	v_cndmask_b32_e64 v99, v105, v103, s[2:3]
	v_cndmask_b32_e64 v98, v104, v102, s[2:3]
	v_cndmask_b32_e64 v105, v113, v117, s[2:3]
	v_cndmask_b32_e64 v104, v112, v116, s[2:3]
	v_cndmask_b32_e64 v103, v111, v115, s[2:3]
	v_cndmask_b32_e64 v102, v110, v114, s[2:3]
	v_pk_mul_f32 v[94:95], v[94:95], v[94:95]
	v_pk_mul_f32 v[90:91], v[90:91], v[90:91]
	v_pk_mul_f32 v[96:97], v[96:97], v[96:97]
	v_pk_mul_f32 v[92:93], v[92:93], v[92:93]
	v_pk_mul_f32 v[86:87], v[86:87], v[86:87]
	v_pk_mul_f32 v[82:83], v[82:83], v[82:83]
	v_pk_mul_f32 v[88:89], v[88:89], v[88:89]
	v_pk_mul_f32 v[84:85], v[84:85], v[84:85]
	v_lshl_add_u64 v[106:107], v[106:107], 0, v[142:143]
	global_store_dwordx4 v[108:109], v[102:105], off
	global_store_dwordx4 v[106:107], v[98:101], off
	v_cvt_pk_bf16_f32 v94, v94, v95
	v_cvt_pk_bf16_f32 v95, v96, v97
	v_lshl_add_u64 v[98:99], s[22:23], 0, v[148:149]
	v_cvt_pk_bf16_f32 v96, v90, v91
	v_cvt_pk_bf16_f32 v97, v92, v93
	v_cvt_pk_bf16_f32 v86, v86, v87
	v_cvt_pk_bf16_f32 v87, v88, v89
	v_cvt_pk_bf16_f32 v82, v82, v83
	v_cvt_pk_bf16_f32 v83, v84, v85
	v_lshl_add_u64 v[90:91], v[98:99], 0, v[138:139]
	v_mov_b32_dpp v88, v94 row_ror:8 row_mask:0xf bank_mask:0xf bound_ctrl:1
	v_mov_b32_dpp v89, v95 row_ror:8 row_mask:0xf bank_mask:0xf bound_ctrl:1
	v_mov_b32_dpp v84, v96 row_ror:8 row_mask:0xf bank_mask:0xf bound_ctrl:1
	v_mov_b32_dpp v85, v97 row_ror:8 row_mask:0xf bank_mask:0xf bound_ctrl:1
	v_mov_b32_dpp v98, v86 row_ror:8 row_mask:0xf bank_mask:0xf bound_ctrl:1
	v_mov_b32_dpp v99, v87 row_ror:8 row_mask:0xf bank_mask:0xf bound_ctrl:1
	v_mov_b32_dpp v100, v82 row_ror:8 row_mask:0xf bank_mask:0xf bound_ctrl:1
	v_mov_b32_dpp v101, v83 row_ror:8 row_mask:0xf bank_mask:0xf bound_ctrl:1
	v_max_f32_e32 v78, 0, v78
	v_max_f32_e32 v74, 0, v74
	v_max_f32_e32 v79, 0, v79
	v_max_f32_e32 v75, 0, v75
	v_max_f32_e32 v80, 0, v80
	v_max_f32_e32 v76, 0, v76
	v_max_f32_e32 v81, 0, v81
	v_max_f32_e32 v77, 0, v77
	v_max_f32_e32 v70, 0, v70
	v_max_f32_e32 v66, 0, v66
	v_max_f32_e32 v71, 0, v71
	v_max_f32_e32 v67, 0, v67
	v_max_f32_e32 v72, 0, v72
	v_max_f32_e32 v68, 0, v68
	v_max_f32_e32 v73, 0, v73
	v_max_f32_e32 v69, 0, v69
	v_lshl_add_u64 v[92:93], v[90:91], 0, v[140:141]
	v_cndmask_b32_e64 v85, v85, v83, s[2:3]
	v_cndmask_b32_e64 v84, v84, v82, s[2:3]
	v_cndmask_b32_e64 v83, v89, v87, s[2:3]
	v_cndmask_b32_e64 v82, v88, v86, s[2:3]
	v_cndmask_b32_e64 v89, v97, v101, s[2:3]
	v_cndmask_b32_e64 v88, v96, v100, s[2:3]
	v_cndmask_b32_e64 v87, v95, v99, s[2:3]
	v_cndmask_b32_e64 v86, v94, v98, s[2:3]
	v_pk_mul_f32 v[78:79], v[78:79], v[78:79]
	v_pk_mul_f32 v[74:75], v[74:75], v[74:75]
	v_pk_mul_f32 v[80:81], v[80:81], v[80:81]
	v_pk_mul_f32 v[76:77], v[76:77], v[76:77]
	v_pk_mul_f32 v[70:71], v[70:71], v[70:71]
	v_pk_mul_f32 v[66:67], v[66:67], v[66:67]
	v_pk_mul_f32 v[72:73], v[72:73], v[72:73]
	v_pk_mul_f32 v[68:69], v[68:69], v[68:69]
	v_lshl_add_u64 v[90:91], v[90:91], 0, v[142:143]
	global_store_dwordx4 v[92:93], v[86:89], off
	global_store_dwordx4 v[90:91], v[82:85], off
	v_cvt_pk_bf16_f32 v78, v78, v79
	v_cvt_pk_bf16_f32 v79, v80, v81
	v_lshl_add_u64 v[82:83], s[22:23], 0, v[150:151]
	v_cvt_pk_bf16_f32 v80, v74, v75
	v_cvt_pk_bf16_f32 v81, v76, v77
	v_cvt_pk_bf16_f32 v70, v70, v71
	v_cvt_pk_bf16_f32 v71, v72, v73
	v_cvt_pk_bf16_f32 v66, v66, v67
	v_cvt_pk_bf16_f32 v67, v68, v69
	v_lshl_add_u64 v[74:75], v[82:83], 0, v[138:139]
	v_mov_b32_dpp v72, v78 row_ror:8 row_mask:0xf bank_mask:0xf bound_ctrl:1
	v_mov_b32_dpp v73, v79 row_ror:8 row_mask:0xf bank_mask:0xf bound_ctrl:1
	v_mov_b32_dpp v68, v80 row_ror:8 row_mask:0xf bank_mask:0xf bound_ctrl:1
	v_mov_b32_dpp v69, v81 row_ror:8 row_mask:0xf bank_mask:0xf bound_ctrl:1
	v_mov_b32_dpp v82, v70 row_ror:8 row_mask:0xf bank_mask:0xf bound_ctrl:1
	v_mov_b32_dpp v83, v71 row_ror:8 row_mask:0xf bank_mask:0xf bound_ctrl:1
	v_mov_b32_dpp v84, v66 row_ror:8 row_mask:0xf bank_mask:0xf bound_ctrl:1
	v_mov_b32_dpp v85, v67 row_ror:8 row_mask:0xf bank_mask:0xf bound_ctrl:1
	v_max_f32_e32 v62, 0, v62
	v_max_f32_e32 v58, 0, v58
	v_max_f32_e32 v63, 0, v63
	v_max_f32_e32 v59, 0, v59
	v_max_f32_e32 v64, 0, v64
	v_max_f32_e32 v60, 0, v60
	v_max_f32_e32 v65, 0, v65
	v_max_f32_e32 v61, 0, v61
	v_max_f32_e32 v54, 0, v54
	v_max_f32_e32 v50, 0, v50
	v_max_f32_e32 v55, 0, v55
	v_max_f32_e32 v51, 0, v51
	v_max_f32_e32 v56, 0, v56
	v_max_f32_e32 v52, 0, v52
	v_max_f32_e32 v57, 0, v57
	v_max_f32_e32 v53, 0, v53
	v_lshl_add_u64 v[76:77], v[74:75], 0, v[140:141]
	v_cndmask_b32_e64 v69, v69, v67, s[2:3]
	v_cndmask_b32_e64 v68, v68, v66, s[2:3]
	v_cndmask_b32_e64 v67, v73, v71, s[2:3]
	v_cndmask_b32_e64 v66, v72, v70, s[2:3]
	v_cndmask_b32_e64 v73, v81, v85, s[2:3]
	v_cndmask_b32_e64 v72, v80, v84, s[2:3]
	v_cndmask_b32_e64 v71, v79, v83, s[2:3]
	v_cndmask_b32_e64 v70, v78, v82, s[2:3]
	v_pk_mul_f32 v[62:63], v[62:63], v[62:63]
	v_pk_mul_f32 v[58:59], v[58:59], v[58:59]
	v_pk_mul_f32 v[64:65], v[64:65], v[64:65]
	v_pk_mul_f32 v[60:61], v[60:61], v[60:61]
	v_pk_mul_f32 v[54:55], v[54:55], v[54:55]
	v_pk_mul_f32 v[50:51], v[50:51], v[50:51]
	v_pk_mul_f32 v[56:57], v[56:57], v[56:57]
	v_pk_mul_f32 v[52:53], v[52:53], v[52:53]
	v_lshl_add_u64 v[74:75], v[74:75], 0, v[142:143]
	global_store_dwordx4 v[76:77], v[70:73], off
	global_store_dwordx4 v[74:75], v[66:69], off
	v_cvt_pk_bf16_f32 v62, v62, v63
	v_cvt_pk_bf16_f32 v63, v64, v65
	v_lshl_add_u64 v[66:67], s[22:23], 0, v[152:153]
	v_cvt_pk_bf16_f32 v64, v58, v59
	v_cvt_pk_bf16_f32 v65, v60, v61
	v_cvt_pk_bf16_f32 v54, v54, v55
	v_cvt_pk_bf16_f32 v55, v56, v57
	v_cvt_pk_bf16_f32 v50, v50, v51
	v_cvt_pk_bf16_f32 v51, v52, v53
	v_lshl_add_u64 v[58:59], v[66:67], 0, v[138:139]
	v_mov_b32_dpp v56, v62 row_ror:8 row_mask:0xf bank_mask:0xf bound_ctrl:1
	v_mov_b32_dpp v57, v63 row_ror:8 row_mask:0xf bank_mask:0xf bound_ctrl:1
	v_mov_b32_dpp v52, v64 row_ror:8 row_mask:0xf bank_mask:0xf bound_ctrl:1
	v_mov_b32_dpp v53, v65 row_ror:8 row_mask:0xf bank_mask:0xf bound_ctrl:1
	v_mov_b32_dpp v66, v54 row_ror:8 row_mask:0xf bank_mask:0xf bound_ctrl:1
	v_mov_b32_dpp v67, v55 row_ror:8 row_mask:0xf bank_mask:0xf bound_ctrl:1
	v_mov_b32_dpp v68, v50 row_ror:8 row_mask:0xf bank_mask:0xf bound_ctrl:1
	v_mov_b32_dpp v69, v51 row_ror:8 row_mask:0xf bank_mask:0xf bound_ctrl:1
	v_max_f32_e32 v46, 0, v46
	v_max_f32_e32 v42, 0, v42
	v_max_f32_e32 v47, 0, v47
	v_max_f32_e32 v43, 0, v43
	v_max_f32_e32 v48, 0, v48
	v_max_f32_e32 v44, 0, v44
	v_max_f32_e32 v49, 0, v49
	v_max_f32_e32 v45, 0, v45
	v_max_f32_e32 v38, 0, v38
	v_max_f32_e32 v34, 0, v34
	v_max_f32_e32 v39, 0, v39
	v_max_f32_e32 v35, 0, v35
	v_max_f32_e32 v40, 0, v40
	v_max_f32_e32 v36, 0, v36
	v_max_f32_e32 v41, 0, v41
	v_max_f32_e32 v37, 0, v37
	v_lshl_add_u64 v[60:61], v[58:59], 0, v[140:141]
	v_cndmask_b32_e64 v53, v53, v51, s[2:3]
	v_cndmask_b32_e64 v52, v52, v50, s[2:3]
	v_cndmask_b32_e64 v51, v57, v55, s[2:3]
	v_cndmask_b32_e64 v50, v56, v54, s[2:3]
	v_cndmask_b32_e64 v57, v65, v69, s[2:3]
	v_cndmask_b32_e64 v56, v64, v68, s[2:3]
	v_cndmask_b32_e64 v55, v63, v67, s[2:3]
	v_cndmask_b32_e64 v54, v62, v66, s[2:3]
	v_pk_mul_f32 v[46:47], v[46:47], v[46:47]
	v_pk_mul_f32 v[42:43], v[42:43], v[42:43]
	v_pk_mul_f32 v[48:49], v[48:49], v[48:49]
	v_pk_mul_f32 v[44:45], v[44:45], v[44:45]
	v_pk_mul_f32 v[38:39], v[38:39], v[38:39]
	v_pk_mul_f32 v[34:35], v[34:35], v[34:35]
	v_pk_mul_f32 v[40:41], v[40:41], v[40:41]
	v_pk_mul_f32 v[36:37], v[36:37], v[36:37]
	v_lshl_add_u64 v[58:59], v[58:59], 0, v[142:143]
	global_store_dwordx4 v[60:61], v[54:57], off
	global_store_dwordx4 v[58:59], v[50:53], off
	v_cvt_pk_bf16_f32 v46, v46, v47
	v_cvt_pk_bf16_f32 v47, v48, v49
	v_lshl_add_u64 v[50:51], s[22:23], 0, v[154:155]
	v_cvt_pk_bf16_f32 v48, v42, v43
	v_cvt_pk_bf16_f32 v49, v44, v45
	v_cvt_pk_bf16_f32 v38, v38, v39
	v_cvt_pk_bf16_f32 v39, v40, v41
	v_cvt_pk_bf16_f32 v34, v34, v35
	v_cvt_pk_bf16_f32 v35, v36, v37
	v_lshl_add_u64 v[42:43], v[50:51], 0, v[138:139]
	v_mov_b32_dpp v40, v46 row_ror:8 row_mask:0xf bank_mask:0xf bound_ctrl:1
	v_mov_b32_dpp v41, v47 row_ror:8 row_mask:0xf bank_mask:0xf bound_ctrl:1
	v_mov_b32_dpp v36, v48 row_ror:8 row_mask:0xf bank_mask:0xf bound_ctrl:1
	v_mov_b32_dpp v37, v49 row_ror:8 row_mask:0xf bank_mask:0xf bound_ctrl:1
	v_mov_b32_dpp v50, v38 row_ror:8 row_mask:0xf bank_mask:0xf bound_ctrl:1
	v_mov_b32_dpp v51, v39 row_ror:8 row_mask:0xf bank_mask:0xf bound_ctrl:1
	v_mov_b32_dpp v52, v34 row_ror:8 row_mask:0xf bank_mask:0xf bound_ctrl:1
	v_mov_b32_dpp v53, v35 row_ror:8 row_mask:0xf bank_mask:0xf bound_ctrl:1
	v_max_f32_e32 v30, 0, v30
	v_max_f32_e32 v26, 0, v26
	v_max_f32_e32 v31, 0, v31
	v_max_f32_e32 v27, 0, v27
	v_max_f32_e32 v32, 0, v32
	v_max_f32_e32 v28, 0, v28
	v_max_f32_e32 v33, 0, v33
	v_max_f32_e32 v29, 0, v29
	v_max_f32_e32 v22, 0, v22
	v_max_f32_e32 v18, 0, v18
	v_max_f32_e32 v23, 0, v23
	v_max_f32_e32 v19, 0, v19
	v_max_f32_e32 v24, 0, v24
	v_max_f32_e32 v20, 0, v20
	v_max_f32_e32 v25, 0, v25
	v_max_f32_e32 v21, 0, v21
	v_lshl_add_u64 v[44:45], v[42:43], 0, v[140:141]
	v_cndmask_b32_e64 v37, v37, v35, s[2:3]
	v_cndmask_b32_e64 v36, v36, v34, s[2:3]
	v_cndmask_b32_e64 v35, v41, v39, s[2:3]
	v_cndmask_b32_e64 v34, v40, v38, s[2:3]
	v_cndmask_b32_e64 v41, v49, v53, s[2:3]
	v_cndmask_b32_e64 v40, v48, v52, s[2:3]
	v_cndmask_b32_e64 v39, v47, v51, s[2:3]
	v_cndmask_b32_e64 v38, v46, v50, s[2:3]
	v_pk_mul_f32 v[30:31], v[30:31], v[30:31]
	v_pk_mul_f32 v[26:27], v[26:27], v[26:27]
	v_pk_mul_f32 v[32:33], v[32:33], v[32:33]
	v_pk_mul_f32 v[28:29], v[28:29], v[28:29]
	v_pk_mul_f32 v[22:23], v[22:23], v[22:23]
	v_pk_mul_f32 v[18:19], v[18:19], v[18:19]
	v_pk_mul_f32 v[24:25], v[24:25], v[24:25]
	v_pk_mul_f32 v[20:21], v[20:21], v[20:21]
	v_lshl_add_u64 v[42:43], v[42:43], 0, v[142:143]
	global_store_dwordx4 v[44:45], v[38:41], off
	global_store_dwordx4 v[42:43], v[34:37], off
	v_cvt_pk_bf16_f32 v30, v30, v31
	v_cvt_pk_bf16_f32 v31, v32, v33
	v_lshl_add_u64 v[34:35], s[22:23], 0, v[156:157]
	v_cvt_pk_bf16_f32 v32, v26, v27
	v_cvt_pk_bf16_f32 v33, v28, v29
	v_cvt_pk_bf16_f32 v22, v22, v23
	v_cvt_pk_bf16_f32 v23, v24, v25
	v_cvt_pk_bf16_f32 v18, v18, v19
	v_cvt_pk_bf16_f32 v19, v20, v21
	v_lshl_add_u64 v[26:27], v[34:35], 0, v[138:139]
	v_mov_b32_dpp v24, v30 row_ror:8 row_mask:0xf bank_mask:0xf bound_ctrl:1
	v_mov_b32_dpp v25, v31 row_ror:8 row_mask:0xf bank_mask:0xf bound_ctrl:1
	v_mov_b32_dpp v20, v32 row_ror:8 row_mask:0xf bank_mask:0xf bound_ctrl:1
	v_mov_b32_dpp v21, v33 row_ror:8 row_mask:0xf bank_mask:0xf bound_ctrl:1
	v_mov_b32_dpp v34, v22 row_ror:8 row_mask:0xf bank_mask:0xf bound_ctrl:1
	v_mov_b32_dpp v35, v23 row_ror:8 row_mask:0xf bank_mask:0xf bound_ctrl:1
	v_mov_b32_dpp v36, v18 row_ror:8 row_mask:0xf bank_mask:0xf bound_ctrl:1
	v_mov_b32_dpp v37, v19 row_ror:8 row_mask:0xf bank_mask:0xf bound_ctrl:1
	v_max_f32_e32 v14, 0, v14
	v_max_f32_e32 v10, 0, v10
	v_max_f32_e32 v15, 0, v15
	v_max_f32_e32 v11, 0, v11
	v_max_f32_e32 v16, 0, v16
	v_max_f32_e32 v12, 0, v12
	v_max_f32_e32 v17, 0, v17
	v_max_f32_e32 v13, 0, v13
	v_max_f32_e32 v6, 0, v6
	v_max_f32_e32 v2, 0, v2
	v_max_f32_e32 v7, 0, v7
	v_max_f32_e32 v3, 0, v3
	v_max_f32_e32 v8, 0, v8
	v_max_f32_e32 v4, 0, v4
	v_max_f32_e32 v9, 0, v9
	v_max_f32_e32 v5, 0, v5
	v_lshl_add_u64 v[28:29], v[26:27], 0, v[140:141]
	v_cndmask_b32_e64 v21, v21, v19, s[2:3]
	v_cndmask_b32_e64 v20, v20, v18, s[2:3]
	v_cndmask_b32_e64 v19, v25, v23, s[2:3]
	v_cndmask_b32_e64 v18, v24, v22, s[2:3]
	v_cndmask_b32_e64 v25, v33, v37, s[2:3]
	v_cndmask_b32_e64 v24, v32, v36, s[2:3]
	v_cndmask_b32_e64 v23, v31, v35, s[2:3]
	v_cndmask_b32_e64 v22, v30, v34, s[2:3]
	v_pk_mul_f32 v[14:15], v[14:15], v[14:15]
	v_pk_mul_f32 v[10:11], v[10:11], v[10:11]
	v_pk_mul_f32 v[16:17], v[16:17], v[16:17]
	v_pk_mul_f32 v[12:13], v[12:13], v[12:13]
	v_pk_mul_f32 v[6:7], v[6:7], v[6:7]
	v_pk_mul_f32 v[2:3], v[2:3], v[2:3]
	v_pk_mul_f32 v[8:9], v[8:9], v[8:9]
	v_pk_mul_f32 v[4:5], v[4:5], v[4:5]
	v_lshl_add_u64 v[26:27], v[26:27], 0, v[142:143]
	global_store_dwordx4 v[28:29], v[22:25], off
	global_store_dwordx4 v[26:27], v[18:21], off
	v_cvt_pk_bf16_f32 v14, v14, v15
	v_cvt_pk_bf16_f32 v15, v16, v17
	v_lshl_add_u64 v[18:19], s[22:23], 0, v[158:159]
	v_cvt_pk_bf16_f32 v16, v10, v11
	v_cvt_pk_bf16_f32 v17, v12, v13
	v_cvt_pk_bf16_f32 v6, v6, v7
	v_cvt_pk_bf16_f32 v7, v8, v9
	v_cvt_pk_bf16_f32 v2, v2, v3
	v_cvt_pk_bf16_f32 v3, v4, v5
	v_lshl_add_u64 v[10:11], v[18:19], 0, v[138:139]
	v_mov_b32_dpp v8, v14 row_ror:8 row_mask:0xf bank_mask:0xf bound_ctrl:1
	v_mov_b32_dpp v9, v15 row_ror:8 row_mask:0xf bank_mask:0xf bound_ctrl:1
	v_mov_b32_dpp v4, v16 row_ror:8 row_mask:0xf bank_mask:0xf bound_ctrl:1
	v_mov_b32_dpp v5, v17 row_ror:8 row_mask:0xf bank_mask:0xf bound_ctrl:1
	v_mov_b32_dpp v18, v6 row_ror:8 row_mask:0xf bank_mask:0xf bound_ctrl:1
	v_mov_b32_dpp v19, v7 row_ror:8 row_mask:0xf bank_mask:0xf bound_ctrl:1
	v_mov_b32_dpp v20, v2 row_ror:8 row_mask:0xf bank_mask:0xf bound_ctrl:1
	v_mov_b32_dpp v21, v3 row_ror:8 row_mask:0xf bank_mask:0xf bound_ctrl:1
	v_lshl_add_u64 v[12:13], v[10:11], 0, v[140:141]
	v_cndmask_b32_e64 v5, v5, v3, s[2:3]
	v_cndmask_b32_e64 v4, v4, v2, s[2:3]
	v_cndmask_b32_e64 v3, v9, v7, s[2:3]
	v_cndmask_b32_e64 v2, v8, v6, s[2:3]
	v_cndmask_b32_e64 v9, v17, v21, s[2:3]
	v_cndmask_b32_e64 v8, v16, v20, s[2:3]
	v_cndmask_b32_e64 v7, v15, v19, s[2:3]
	v_cndmask_b32_e64 v6, v14, v18, s[2:3]
	s_andn2_b64 vcc, exec, s[18:19]
	s_mov_b64 s[4:5], -1
	v_lshl_add_u64 v[10:11], v[10:11], 0, v[142:143]
	global_store_dwordx4 v[12:13], v[6:9], off
	global_store_dwordx4 v[10:11], v[2:5], off
	s_cbranch_vccnz .LBB0_2259
	s_andn2_b64 vcc, exec, s[6:7]
	s_cbranch_vccnz .LBB0_2258
	s_barrier
	s_branch .LBB0_2258

.LBB0_2327:
	s_ashr_i32 s81, s80, 31
	s_andn2_b64 vcc, exec, s[4:5]
	s_lshl_b64 s[30:31], s[80:81], 22
	s_add_u32 s30, s1, s30
	s_addc_u32 s31, s33, s31
	s_and_b64 s[34:35], s[4:5], exec
	s_cselect_b32 s43, s31, s41
	s_cselect_b32 s57, s30, s40
	s_ashr_i32 s34, s0, 31
	s_lshr_b32 s34, s34, 26
	s_add_i32 s34, s0, s34
	s_ashr_i32 s34, s34, 6
	s_and_b64 s[36:37], s[4:5], exec
	s_cselect_b32 s44, s34, s42
	s_ashr_i32 s79, s78, 31
	s_lshl_b64 s[36:37], s[78:79], 22
	s_add_u32 s45, s46, s36
	s_addc_u32 s58, s47, s37
	s_ashr_i32 s35, s34, 31
	s_lshl_b64 s[36:37], s[34:35], 15
	s_add_u32 s36, s45, s36
	s_addc_u32 s37, s58, s37
	v_cndmask_b32_e64 v2, 0, 1, s[4:5]
	s_and_b64 s[4:5], s[4:5], exec
	s_cselect_b32 s4, s37, s39
	s_cselect_b32 s5, s36, s38
	s_ashr_i32 s45, s44, 31
	s_lshl_b64 s[44:45], s[44:45], 15
	s_add_u32 s35, s57, s44
	s_addc_u32 s57, s43, s45
	s_add_u32 s58, s35, 0x8000
	s_addc_u32 s59, s57, 0
	s_add_u32 s62, s38, 0x10000
	s_addc_u32 s63, s39, 0
	s_ashr_i32 s43, s42, 31
	v_cmp_ne_u32_e64 s[6:7], 1, v2
	s_lshl_b64 s[38:39], s[42:43], 15
	v_lshl_add_u64 v[2:3], s[40:41], 0, v[138:139]
	s_add_u32 s64, s40, s38
	v_lshl_add_u64 v[142:143], v[2:3], 0, s[38:39]
	v_lshl_add_u64 v[2:3], s[40:41], 0, v[140:141]
	s_addc_u32 s65, s41, s39
	v_lshl_add_u64 v[144:145], v[2:3], 0, s[38:39]
	s_lshl_b32 s38, s56, 15
	s_add_i32 s38, s38, 0xfff00000
	v_mov_b32_e32 v2, 0
	s_add_u32 s66, s38, 0xf0000
	s_mov_b32 s67, 0
	s_mov_b64 s[38:39], 0
	ds_read_b128 v[152:155], v148
	ds_read_b128 v[156:159], v148 offset:1024
	ds_read_b128 v[160:163], v148 offset:2048
	ds_read_b128 v[164:167], v148 offset:3072
	ds_read_b128 v[168:171], v149
	ds_read_b128 v[172:175], v149 offset:1024
	ds_read_b128 v[176:179], v149 offset:2048
	ds_read_b128 v[180:183], v149 offset:3072
	s_add_u32 s40, s64, s38
	s_addc_u32 s41, s65, s39
	s_add_u32 s44, s40, 0x10000
	s_addc_u32 s45, s41, 0
	s_add_i32 s67, s67, 2
	s_add_u32 s42, s62, s38
	s_addc_u32 s43, s63, s39
	s_add_u32 s40, s40, 0x18000
	s_addc_u32 s41, s41, 0
	s_cmp_eq_u32 s66, s38
	s_cselect_b32 s41, s59, s41
	s_cselect_b32 s40, s58, s40
	s_cselect_b32 s43, s4, s43
	s_cselect_b32 s42, s5, s42
	s_cselect_b32 s45, s57, s45
	s_cselect_b32 s44, s35, s44
	v_lshl_add_u64 v[216:217], v[142:143], 0, s[38:39]
	s_add_i32 m0, s49, 0xc000
	ds_read_b128 v[184:187], v150
	ds_read_b128 v[188:191], v150 offset:1024
	ds_read_b128 v[192:195], v150 offset:2048
	ds_read_b128 v[196:199], v150 offset:3072
	ds_read_b128 v[200:203], v150 offset:4096
	ds_read_b128 v[204:207], v150 offset:5120
	ds_read_b128 v[208:211], v150 offset:6144
	ds_read_b128 v[212:215], v150 offset:7168
	global_load_lds_dwordx4 v[216:217], off
	v_lshl_add_u64 v[216:217], v[144:145], 0, s[38:39]
	s_add_i32 m0, s49, 0xe000
	s_nop 0
	global_load_lds_dwordx4 v[216:217], off
	s_waitcnt vmcnt(8)
	s_waitcnt lgkmcnt(0)
	s_barrier
	v_mfma_f32_16x16x32_bf16 v[126:129], v[152:155], v[184:187], 0
	v_mfma_f32_16x16x32_bf16 v[122:125], v[160:163], v[184:187], 0
	v_mfma_f32_16x16x32_bf16 v[110:113], v[152:155], v[192:195], 0
	v_mfma_f32_16x16x32_bf16 v[106:109], v[160:163], v[192:195], 0
	v_mfma_f32_16x16x32_bf16 v[94:97], v[152:155], v[200:203], 0
	v_mfma_f32_16x16x32_bf16 v[90:93], v[160:163], v[200:203], 0
	v_mfma_f32_16x16x32_bf16 v[78:81], v[152:155], v[208:211], 0
	v_mfma_f32_16x16x32_bf16 v[74:77], v[160:163], v[208:211], 0
	v_mfma_f32_16x16x32_bf16 v[126:129], v[156:159], v[188:191], v[126:129]
	v_mfma_f32_16x16x32_bf16 v[122:125], v[164:167], v[188:191], v[122:125]
	v_mfma_f32_16x16x32_bf16 v[110:113], v[156:159], v[196:199], v[110:113]
	v_mfma_f32_16x16x32_bf16 v[106:109], v[164:167], v[196:199], v[106:109]
	v_mfma_f32_16x16x32_bf16 v[94:97], v[156:159], v[204:207], v[94:97]
	v_mfma_f32_16x16x32_bf16 v[90:93], v[164:167], v[204:207], v[90:93]
	v_mfma_f32_16x16x32_bf16 v[78:81], v[156:159], v[212:215], v[78:81]
	v_mfma_f32_16x16x32_bf16 v[74:77], v[164:167], v[212:215], v[74:77]
	v_mfma_f32_16x16x32_bf16 v[118:121], v[168:171], v[184:187], 0
	v_mfma_f32_16x16x32_bf16 v[114:117], v[176:179], v[184:187], 0
	v_mfma_f32_16x16x32_bf16 v[102:105], v[168:171], v[192:195], 0
	v_mfma_f32_16x16x32_bf16 v[98:101], v[176:179], v[192:195], 0
	v_mfma_f32_16x16x32_bf16 v[86:89], v[168:171], v[200:203], 0
	v_mfma_f32_16x16x32_bf16 v[82:85], v[176:179], v[200:203], 0
	v_mfma_f32_16x16x32_bf16 v[70:73], v[168:171], v[208:211], 0
	v_mfma_f32_16x16x32_bf16 v[66:69], v[176:179], v[208:211], 0
	v_mfma_f32_16x16x32_bf16 v[118:121], v[172:175], v[188:191], v[118:121]
	v_mfma_f32_16x16x32_bf16 v[114:117], v[180:183], v[188:191], v[114:117]
	v_mfma_f32_16x16x32_bf16 v[102:105], v[172:175], v[196:199], v[102:105]
	v_mfma_f32_16x16x32_bf16 v[98:101], v[180:183], v[196:199], v[98:101]
	v_mfma_f32_16x16x32_bf16 v[86:89], v[172:175], v[204:207], v[86:89]
	v_mfma_f32_16x16x32_bf16 v[82:85], v[180:183], v[204:207], v[82:85]
	v_mfma_f32_16x16x32_bf16 v[70:73], v[172:175], v[212:215], v[70:73]
	v_mfma_f32_16x16x32_bf16 v[66:69], v[180:183], v[212:215], v[66:69]
	s_barrier
	s_add_i32 s70, s72, s48
	v_lshl_add_u64 v[216:217], s[42:43], 0, v[130:131]
	s_mov_b32 m0, s70
	ds_read_b128 v[184:187], v150 offset:16384
	ds_read_b128 v[188:191], v150 offset:17408
	ds_read_b128 v[192:195], v150 offset:18432
	ds_read_b128 v[196:199], v150 offset:19456
	ds_read_b128 v[200:203], v150 offset:20480
	ds_read_b128 v[204:207], v150 offset:21504
	ds_read_b128 v[208:211], v150 offset:22528
	ds_read_b128 v[212:215], v150 offset:23552
	global_load_lds_dwordx4 v[216:217], off
	s_add_i32 m0, s70, 0x2000
	s_add_u32 s76, s42, 0x4000
	v_lshl_add_u64 v[216:217], s[42:43], 0, v[132:133]
	s_addc_u32 s77, s43, 0
	s_add_i32 s70, s73, s48
	global_load_lds_dwordx4 v[216:217], off
	v_lshl_add_u64 v[216:217], s[76:77], 0, v[130:131]
	s_mov_b32 m0, s70
	s_nop 0
	global_load_lds_dwordx4 v[216:217], off
	v_lshl_add_u64 v[216:217], s[76:77], 0, v[132:133]
	s_add_i32 m0, s70, 0x2000
	s_nop 0
	global_load_lds_dwordx4 v[216:217], off
	v_lshl_add_u64 v[216:217], s[44:45], 0, v[130:131]
	s_mov_b32 m0, s49
	s_nop 0
	global_load_lds_dwordx4 v[216:217], off
	v_lshl_add_u64 v[216:217], s[44:45], 0, v[132:133]
	s_mov_b32 m0, s50
	s_nop 0
	global_load_lds_dwordx4 v[216:217], off
	s_waitcnt vmcnt(8)
	s_waitcnt lgkmcnt(0)
	s_barrier
	v_mfma_f32_16x16x32_bf16 v[62:65], v[152:155], v[184:187], 0
	v_mfma_f32_16x16x32_bf16 v[58:61], v[160:163], v[184:187], 0
	v_mfma_f32_16x16x32_bf16 v[46:49], v[152:155], v[192:195], 0
	v_mfma_f32_16x16x32_bf16 v[42:45], v[160:163], v[192:195], 0
	v_mfma_f32_16x16x32_bf16 v[30:33], v[152:155], v[200:203], 0
	v_mfma_f32_16x16x32_bf16 v[26:29], v[160:163], v[200:203], 0
	v_mfma_f32_16x16x32_bf16 v[14:17], v[152:155], v[208:211], 0
	v_mfma_f32_16x16x32_bf16 v[10:13], v[160:163], v[208:211], 0
	v_mfma_f32_16x16x32_bf16 v[62:65], v[156:159], v[188:191], v[62:65]
	v_mfma_f32_16x16x32_bf16 v[58:61], v[164:167], v[188:191], v[58:61]
	v_mfma_f32_16x16x32_bf16 v[46:49], v[156:159], v[196:199], v[46:49]
	v_mfma_f32_16x16x32_bf16 v[42:45], v[164:167], v[196:199], v[42:45]
	v_mfma_f32_16x16x32_bf16 v[30:33], v[156:159], v[204:207], v[30:33]
	v_mfma_f32_16x16x32_bf16 v[26:29], v[164:167], v[204:207], v[26:29]
	v_mfma_f32_16x16x32_bf16 v[14:17], v[156:159], v[212:215], v[14:17]
	v_mfma_f32_16x16x32_bf16 v[10:13], v[164:167], v[212:215], v[10:13]
	v_mfma_f32_16x16x32_bf16 v[54:57], v[168:171], v[184:187], 0
	v_mfma_f32_16x16x32_bf16 v[50:53], v[176:179], v[184:187], 0
	v_mfma_f32_16x16x32_bf16 v[38:41], v[168:171], v[192:195], 0
	v_mfma_f32_16x16x32_bf16 v[34:37], v[176:179], v[192:195], 0
	v_mfma_f32_16x16x32_bf16 v[22:25], v[168:171], v[200:203], 0
	v_mfma_f32_16x16x32_bf16 v[18:21], v[176:179], v[200:203], 0
	v_mfma_f32_16x16x32_bf16 v[6:9], v[168:171], v[208:211], 0
	v_mfma_f32_16x16x32_bf16 v[2:5], v[176:179], v[208:211], 0
	v_mfma_f32_16x16x32_bf16 v[54:57], v[172:175], v[188:191], v[54:57]
	v_mfma_f32_16x16x32_bf16 v[50:53], v[180:183], v[188:191], v[50:53]
	v_mfma_f32_16x16x32_bf16 v[38:41], v[172:175], v[196:199], v[38:41]
	v_mfma_f32_16x16x32_bf16 v[34:37], v[180:183], v[196:199], v[34:37]
	v_mfma_f32_16x16x32_bf16 v[22:25], v[172:175], v[204:207], v[22:25]
	v_mfma_f32_16x16x32_bf16 v[18:21], v[180:183], v[204:207], v[18:21]
	v_mfma_f32_16x16x32_bf16 v[6:9], v[172:175], v[212:215], v[6:9]
	v_mfma_f32_16x16x32_bf16 v[2:5], v[180:183], v[212:215], v[2:5]
	s_barrier
	v_add_u32_e32 v151, s60, v146
	ds_read_b128 v[152:155], v151
	ds_read_b128 v[156:159], v151 offset:1024
	ds_read_b128 v[160:163], v151 offset:2048
	ds_read_b128 v[164:167], v151 offset:3072
	v_add_u32_e32 v151, s61, v146
	ds_read_b128 v[168:171], v151
	ds_read_b128 v[172:175], v151 offset:1024
	ds_read_b128 v[176:179], v151 offset:2048
	ds_read_b128 v[180:183], v151 offset:3072
	s_add_u32 s44, s44, 0x4000
	s_addc_u32 s45, s45, 0
	s_mov_b32 m0, s51
	v_lshl_add_u64 v[216:217], s[44:45], 0, v[130:131]
	ds_read_b128 v[184:187], v150 offset:32768
	ds_read_b128 v[188:191], v150 offset:33792
	ds_read_b128 v[192:195], v150 offset:34816
	ds_read_b128 v[196:199], v150 offset:35840
	ds_read_b128 v[200:203], v150 offset:36864
	ds_read_b128 v[204:207], v150 offset:37888
	ds_read_b128 v[208:211], v150 offset:38912
	ds_read_b128 v[212:215], v150 offset:39936
	global_load_lds_dwordx4 v[216:217], off
	v_lshl_add_u64 v[216:217], s[44:45], 0, v[132:133]
	s_mov_b32 m0, s52
	s_nop 0
	global_load_lds_dwordx4 v[216:217], off
	s_waitcnt vmcnt(8)
	s_waitcnt lgkmcnt(0)
	s_barrier
	v_mfma_f32_16x16x32_bf16 v[126:129], v[152:155], v[184:187], v[126:129]
	v_mfma_f32_16x16x32_bf16 v[122:125], v[160:163], v[184:187], v[122:125]
	v_mfma_f32_16x16x32_bf16 v[110:113], v[152:155], v[192:195], v[110:113]
	v_mfma_f32_16x16x32_bf16 v[106:109], v[160:163], v[192:195], v[106:109]
	v_mfma_f32_16x16x32_bf16 v[94:97], v[152:155], v[200:203], v[94:97]
	v_mfma_f32_16x16x32_bf16 v[90:93], v[160:163], v[200:203], v[90:93]
	v_mfma_f32_16x16x32_bf16 v[78:81], v[152:155], v[208:211], v[78:81]
	v_mfma_f32_16x16x32_bf16 v[74:77], v[160:163], v[208:211], v[74:77]
	v_mfma_f32_16x16x32_bf16 v[126:129], v[156:159], v[188:191], v[126:129]
	v_mfma_f32_16x16x32_bf16 v[122:125], v[164:167], v[188:191], v[122:125]
	v_mfma_f32_16x16x32_bf16 v[110:113], v[156:159], v[196:199], v[110:113]
	v_mfma_f32_16x16x32_bf16 v[106:109], v[164:167], v[196:199], v[106:109]
	v_mfma_f32_16x16x32_bf16 v[94:97], v[156:159], v[204:207], v[94:97]
	v_mfma_f32_16x16x32_bf16 v[90:93], v[164:167], v[204:207], v[90:93]
	v_mfma_f32_16x16x32_bf16 v[78:81], v[156:159], v[212:215], v[78:81]
	v_mfma_f32_16x16x32_bf16 v[74:77], v[164:167], v[212:215], v[74:77]
	v_mfma_f32_16x16x32_bf16 v[118:121], v[168:171], v[184:187], v[118:121]
	v_mfma_f32_16x16x32_bf16 v[114:117], v[176:179], v[184:187], v[114:117]
	v_mfma_f32_16x16x32_bf16 v[102:105], v[168:171], v[192:195], v[102:105]
	v_mfma_f32_16x16x32_bf16 v[98:101], v[176:179], v[192:195], v[98:101]
	v_mfma_f32_16x16x32_bf16 v[86:89], v[168:171], v[200:203], v[86:89]
	v_mfma_f32_16x16x32_bf16 v[82:85], v[176:179], v[200:203], v[82:85]
	v_mfma_f32_16x16x32_bf16 v[70:73], v[168:171], v[208:211], v[70:73]
	v_mfma_f32_16x16x32_bf16 v[66:69], v[176:179], v[208:211], v[66:69]
	v_mfma_f32_16x16x32_bf16 v[118:121], v[172:175], v[188:191], v[118:121]
	v_mfma_f32_16x16x32_bf16 v[114:117], v[180:183], v[188:191], v[114:117]
	v_mfma_f32_16x16x32_bf16 v[102:105], v[172:175], v[196:199], v[102:105]
	v_mfma_f32_16x16x32_bf16 v[98:101], v[180:183], v[196:199], v[98:101]
	v_mfma_f32_16x16x32_bf16 v[86:89], v[172:175], v[204:207], v[86:89]
	v_mfma_f32_16x16x32_bf16 v[82:85], v[180:183], v[204:207], v[82:85]
	v_mfma_f32_16x16x32_bf16 v[70:73], v[172:175], v[212:215], v[70:73]
	v_mfma_f32_16x16x32_bf16 v[66:69], v[180:183], v[212:215], v[66:69]
	s_barrier
	s_add_u32 s44, s42, 0x8000
	s_addc_u32 s45, s43, 0
	s_add_i32 s70, s60, s48
	v_lshl_add_u64 v[216:217], s[44:45], 0, v[130:131]
	s_mov_b32 m0, s70
	ds_read_b128 v[184:187], v150 offset:49152
	ds_read_b128 v[188:191], v150 offset:50176
	ds_read_b128 v[192:195], v150 offset:51200
	ds_read_b128 v[196:199], v150 offset:52224
	ds_read_b128 v[200:203], v150 offset:53248
	ds_read_b128 v[204:207], v150 offset:54272
	ds_read_b128 v[208:211], v150 offset:55296
	ds_read_b128 v[212:215], v150 offset:56320
	global_load_lds_dwordx4 v[216:217], off
	s_add_i32 m0, s70, 0x2000
	s_add_u32 s42, s42, 0xc000
	v_lshl_add_u64 v[216:217], s[44:45], 0, v[132:133]
	s_addc_u32 s43, s43, 0
	s_add_i32 s44, s61, s48
	global_load_lds_dwordx4 v[216:217], off
	v_lshl_add_u64 v[216:217], s[42:43], 0, v[130:131]
	s_mov_b32 m0, s44
	s_nop 0
	global_load_lds_dwordx4 v[216:217], off
	v_lshl_add_u64 v[216:217], s[42:43], 0, v[132:133]
	s_add_i32 m0, s44, 0x2000
	s_nop 0
	global_load_lds_dwordx4 v[216:217], off
	v_lshl_add_u64 v[216:217], s[40:41], 0, v[130:131]
	s_mov_b32 m0, s53
	s_nop 0
	global_load_lds_dwordx4 v[216:217], off
	v_lshl_add_u64 v[216:217], s[40:41], 0, v[132:133]
	s_mov_b32 m0, s54
	s_nop 0
	global_load_lds_dwordx4 v[216:217], off
	s_waitcnt vmcnt(8)
	s_waitcnt lgkmcnt(0)
	s_barrier
	v_mfma_f32_16x16x32_bf16 v[62:65], v[152:155], v[184:187], v[62:65]
	v_mfma_f32_16x16x32_bf16 v[58:61], v[160:163], v[184:187], v[58:61]
	v_mfma_f32_16x16x32_bf16 v[46:49], v[152:155], v[192:195], v[46:49]
	v_mfma_f32_16x16x32_bf16 v[42:45], v[160:163], v[192:195], v[42:45]
	v_mfma_f32_16x16x32_bf16 v[30:33], v[152:155], v[200:203], v[30:33]
	v_mfma_f32_16x16x32_bf16 v[26:29], v[160:163], v[200:203], v[26:29]
	v_mfma_f32_16x16x32_bf16 v[14:17], v[152:155], v[208:211], v[14:17]
	v_mfma_f32_16x16x32_bf16 v[10:13], v[160:163], v[208:211], v[10:13]
	v_mfma_f32_16x16x32_bf16 v[62:65], v[156:159], v[188:191], v[62:65]
	v_mfma_f32_16x16x32_bf16 v[58:61], v[164:167], v[188:191], v[58:61]
	v_mfma_f32_16x16x32_bf16 v[46:49], v[156:159], v[196:199], v[46:49]
	v_mfma_f32_16x16x32_bf16 v[42:45], v[164:167], v[196:199], v[42:45]
	v_mfma_f32_16x16x32_bf16 v[30:33], v[156:159], v[204:207], v[30:33]
	v_mfma_f32_16x16x32_bf16 v[26:29], v[164:167], v[204:207], v[26:29]
	v_mfma_f32_16x16x32_bf16 v[14:17], v[156:159], v[212:215], v[14:17]
	v_mfma_f32_16x16x32_bf16 v[10:13], v[164:167], v[212:215], v[10:13]
	v_mfma_f32_16x16x32_bf16 v[54:57], v[168:171], v[184:187], v[54:57]
	v_mfma_f32_16x16x32_bf16 v[50:53], v[176:179], v[184:187], v[50:53]
	v_mfma_f32_16x16x32_bf16 v[38:41], v[168:171], v[192:195], v[38:41]
	v_mfma_f32_16x16x32_bf16 v[34:37], v[176:179], v[192:195], v[34:37]
	v_mfma_f32_16x16x32_bf16 v[22:25], v[168:171], v[200:203], v[22:25]
	v_mfma_f32_16x16x32_bf16 v[18:21], v[176:179], v[200:203], v[18:21]
	v_mfma_f32_16x16x32_bf16 v[6:9], v[168:171], v[208:211], v[6:9]
	v_mfma_f32_16x16x32_bf16 v[2:5], v[176:179], v[208:211], v[2:5]
	v_mfma_f32_16x16x32_bf16 v[54:57], v[172:175], v[188:191], v[54:57]
	v_mfma_f32_16x16x32_bf16 v[50:53], v[180:183], v[188:191], v[50:53]
	v_mfma_f32_16x16x32_bf16 v[38:41], v[172:175], v[196:199], v[38:41]
	v_mfma_f32_16x16x32_bf16 v[34:37], v[180:183], v[196:199], v[34:37]
	v_mfma_f32_16x16x32_bf16 v[22:25], v[172:175], v[204:207], v[22:25]
	v_mfma_f32_16x16x32_bf16 v[18:21], v[180:183], v[204:207], v[18:21]
	v_mfma_f32_16x16x32_bf16 v[6:9], v[172:175], v[212:215], v[6:9]
	v_mfma_f32_16x16x32_bf16 v[2:5], v[180:183], v[212:215], v[2:5]
	s_barrier
	s_add_u32 s38, s38, 0x10000
	s_addc_u32 s39, s39, 0
	s_cmp_ge_u32 s67, s56
